# stagger CU start (0..17us by blockIdx hash) in E1 layer0 GEMM phase to de-lockstep epilogue store bursts
# speedup vs baseline: 1.0186x; 1.0186x over previous
; __device__ __forceinline__ unsigned xb_ld(unsigned* p)              { return __hip_atomic_load(p, __ATOMIC_RELAXED, __HIP_MEMORY_SCOPE_AGENT); }
; template <int layer>
; __device__ __forceinline__ void run_layer(LAS unsigned char* lds, const XcdBarrier& xb) {
;     ...
;             { pg8::GemmSched S; S.init(T, 5120, G, blockIdx.x, XB, 2048, WIN, 2048); EpiIn<false> E{RSS, ws}; pg8::gemm_phase(lds, 2048, 2048, 2048, S, E); }
; __global__ void __launch_bounds__(512, 2) hybrid_fwd(Params p) {
;     ...
;     { unsigned mine = 0u, cnt = 0u;
; #pragma unroll
;       for (unsigned j = 0; j < 16; ++j) { const unsigned c = xb_ld(&xb.bar[XB_XCNT(j)]); cnt += (c > 0u) ? 1u : 0u; mine = (j == xb.x) ? c : mine; }
;       xb.nloc = __builtin_amdgcn_readfirstlane(mine > 0u ? mine : 1u); xb.nx = __builtin_amdgcn_readfirstlane(cnt > 0u ? cnt : 1u); }
.LBB0_200:
	s_or_b64 exec, exec, s[4:5]
	v_mov_b32_e32 v0, 0x180000
	s_barrier
	global_load_dword v1, v0, s[86:87] offset:1024 sc1
	global_load_dword v2, v0, s[86:87] offset:1280 sc1
	global_load_dword v3, v0, s[86:87] offset:1536 sc1
	v_mov_b32_e32 v4, 0x181000
	global_load_dword v5, v0, s[86:87] offset:1792 sc1
	global_load_dword v6, v0, s[86:87] offset:2048 sc1
	global_load_dword v7, v0, s[86:87] offset:2304 sc1
	global_load_dword v8, v0, s[86:87] offset:2560 sc1
	global_load_dword v9, v0, s[86:87] offset:2816 sc1
	global_load_dword v10, v0, s[86:87] offset:3072 sc1
	global_load_dword v11, v0, s[86:87] offset:3328 sc1
	global_load_dword v12, v0, s[86:87] offset:3584 sc1
	global_load_dword v13, v0, s[86:87] offset:3840 sc1
	global_load_dword v14, v4, s[86:87] sc1
	global_load_dword v15, v4, s[86:87] offset:256 sc1
	global_load_dword v16, v4, s[86:87] offset:512 sc1
	s_cmp_eq_u32 s73, 0
	global_load_dword v0, v4, s[86:87] offset:768 sc1
	s_cselect_b64 vcc, -1, 0
	s_cmp_eq_u32 s73, 1
	s_mov_b64 s[0:1], s[74:75]
	s_load_dwordx2 s[36:37], s[0:1], 0x90
	s_waitcnt lgkmcnt(0)
	s_barrier
	s_waitcnt vmcnt(15)
	v_cndmask_b32_e32 v4, 0, v1, vcc
	s_waitcnt vmcnt(14)
	v_cmp_ne_u32_e32 vcc, 0, v2
	s_waitcnt vmcnt(13)
	v_cmp_ne_u32_e64 s[4:5], 0, v3
	v_cndmask_b32_e64 v17, 0, 1, vcc
	s_nop 0
	v_cndmask_b32_e64 v18, 0, 1, s[4:5]
	s_waitcnt vmcnt(11)
	v_cmp_ne_u32_e64 s[4:5], 0, v6
	s_cselect_b64 vcc, -1, 0
	s_cmp_eq_u32 s73, 2
	v_cndmask_b32_e64 v19, 0, 1, s[4:5]
	s_waitcnt vmcnt(9)
	v_cmp_ne_u32_e64 s[4:5], 0, v8
	v_cndmask_b32_e32 v2, v4, v2, vcc
	s_cselect_b64 vcc, -1, 0
	v_cndmask_b32_e64 v20, 0, 1, s[4:5]
	s_waitcnt vmcnt(7)
	v_cmp_ne_u32_e64 s[4:5], 0, v10
	v_cndmask_b32_e32 v2, v2, v3, vcc
	v_cmp_ne_u32_e32 vcc, 0, v5
	v_cndmask_b32_e64 v21, 0, 1, s[4:5]
	s_waitcnt vmcnt(5)
	v_cmp_ne_u32_e64 s[4:5], 0, v12
	s_cmp_eq_u32 s73, 3
	s_nop 0
	v_cndmask_b32_e64 v22, 0, 1, s[4:5]
	s_waitcnt vmcnt(3)
	v_cmp_ne_u32_e64 s[4:5], 0, v14
	s_nop 1
	v_cndmask_b32_e64 v23, 0, 1, s[4:5]
	v_cmp_ne_u32_e64 s[4:5], 0, v1
	s_nop 1
	v_addc_co_u32_e64 v1, s[4:5], 0, v17, s[4:5]
	v_addc_co_u32_e32 v1, vcc, v1, v18, vcc
	s_cselect_b64 vcc, -1, 0
	s_cmp_eq_u32 s73, 4
	v_cndmask_b32_e32 v2, v2, v5, vcc
	s_cselect_b64 vcc, -1, 0
	s_cmp_eq_u32 s73, 5
	v_cndmask_b32_e32 v2, v2, v6, vcc
	s_cselect_b64 vcc, -1, 0
	s_cmp_eq_u32 s73, 6
	v_cndmask_b32_e32 v2, v2, v7, vcc
	s_cselect_b64 vcc, -1, 0
	s_cmp_eq_u32 s73, 7
	v_cmp_ne_u32_e64 s[4:5], 0, v7
	v_cndmask_b32_e32 v2, v2, v8, vcc
	s_cselect_b64 vcc, -1, 0
	s_cmp_eq_u32 s73, 8
	v_addc_co_u32_e64 v1, s[4:5], v1, v19, s[4:5]
	v_cndmask_b32_e32 v2, v2, v9, vcc
	s_cselect_b64 vcc, -1, 0
	s_cmp_eq_u32 s73, 9
	v_cmp_ne_u32_e64 s[4:5], 0, v9
	v_cndmask_b32_e32 v2, v2, v10, vcc
	s_cselect_b64 vcc, -1, 0
	s_cmp_eq_u32 s73, 10
	v_addc_co_u32_e64 v1, s[4:5], v1, v20, s[4:5]
	v_cndmask_b32_e32 v2, v2, v11, vcc
	s_cselect_b64 vcc, -1, 0
	s_cmp_eq_u32 s73, 11
	v_cmp_ne_u32_e64 s[4:5], 0, v11
	v_cndmask_b32_e32 v2, v2, v12, vcc
	s_cselect_b64 vcc, -1, 0
	s_cmp_eq_u32 s73, 12
	v_addc_co_u32_e64 v1, s[4:5], v1, v21, s[4:5]
	v_cndmask_b32_e32 v2, v2, v13, vcc
	s_cselect_b64 vcc, -1, 0
	s_cmp_eq_u32 s73, 13
	v_cmp_ne_u32_e64 s[4:5], 0, v13
	v_cndmask_b32_e32 v2, v2, v14, vcc
	s_cselect_b64 vcc, -1, 0
	v_addc_co_u32_e64 v1, s[4:5], v1, v22, s[4:5]
	s_waitcnt vmcnt(2)
	v_cndmask_b32_e32 v2, v2, v15, vcc
	s_waitcnt vmcnt(1)
	v_cmp_ne_u32_e32 vcc, 0, v16
	s_cmp_eq_u32 s73, 14
	v_cmp_ne_u32_e64 s[4:5], 0, v15
	v_cndmask_b32_e64 v3, 0, 1, vcc
	s_cselect_b64 vcc, -1, 0
	v_addc_co_u32_e64 v1, s[4:5], v1, v23, s[4:5]
	v_cndmask_b32_e32 v2, v2, v16, vcc
	s_waitcnt vmcnt(0)
	v_cmp_ne_u32_e32 vcc, 0, v0
	s_cmp_eq_u32 s73, 15
	v_mov_b32_e32 v10, v254
	v_addc_co_u32_e32 v1, vcc, v1, v3, vcc
	s_cselect_b64 vcc, -1, 0
	s_add_u32 s12, s36, 0x2e00000
	s_addc_u32 s13, s37, 0
	s_add_u32 s30, s36, 0x200000
	v_cndmask_b32_e32 v0, v2, v0, vcc
	s_addc_u32 s31, s37, 0
	v_max_u32_e32 v0, 1, v0
	s_add_u32 s8, s36, 0xa00000
	v_readfirstlane_b32 s0, v0
	v_max_u32_e32 v0, 1, v1
	s_addc_u32 s9, s37, 0
	v_writelane_b32 v255, s0, 1
	v_readfirstlane_b32 s0, v0
	s_cmpk_lt_i32 s33, 0xa00
	s_nop 0
	v_writelane_b32 v255, s0, 2
	s_cselect_b64 s[0:1], -1, 0
	v_writelane_b32 v255, s0, 3
	v_readfirstlane_b32 s5, v10
	s_and_b64 vcc, exec, s[0:1]
	v_writelane_b32 v255, s1, 4
	s_cbranch_vccz .LBB0_235
	s_mul_i32 s98, s33, 37
	s_and_b32 s98, s98, 0xff
; #define PG8_STAGE(bufoff, gbase, voff) do { _Pragma("unroll") for (int _i = 0; _i < 2; ++_i) \
;         __builtin_amdgcn_global_load_lds((const unsigned*)((const char*)(gbase) + (voff)[_i]), (LAS unsigned*)(lds + (bufoff) + ldsw + _i * 8192), 16, 0, 0); } while (0)
; #define PG8_BAR __builtin_amdgcn_s_barrier()
;     __device__ bool next(int i, Unit& u) const {
;     ...
;         int wgid = (int)L; { const int q = nwg / NXCD, r = nwg % NXCD, xcd = wgid % NXCD, off = wgid / NXCD; wgid = (xcd < r ? xcd * (q + 1) : r * (q + 1) + (xcd - r) * q) + off; }
;         const int nig = WGM * nN, gid = wgid / nig, fm = gid * WGM, gsz = (nM - fm) < WGM ? (nM - fm) : WGM;
;         u.pm = fm + ((wgid % nig) % gsz); u.pn = (wgid % nig) / gsz; u.aux = 0; return true;
; template <class Epi, class Sched>
; __device__ __forceinline__ void gemm_phase(LAS unsigned char* lds, const int K, const int lda, const int ldb, const Sched& S, const Epi& E) {
;     ...
;     for (int i = 0; i < 2; ++i) { int R, C; stage_rc(tid * 16 + i * 8192, R, C); const int Rb = (R & ~31) + perm32(R & 31);
;         voffA[i] = (unsigned)(R * lda + C) * 2u; voffB[i] = (unsigned)(Rb * ldb + C) * 2u; }
;     const size_t kstep = (size_t)(BK * 2);
;     const size_t hA = (size_t)HALF * lda * 2, hB = (size_t)HALF * ldb * 2;
;     const unsigned ldsw = (unsigned)wid * 1024u;
;     const int aoff = lds_byte(wr * 64 + fr, fq * 8), boff = lds_byte(wc * 32 + fr, fq * 8);
;     ...
;     Unit cur, nxt; int ui = 0;
;     if (!S.next(0, cur)) return;
;     f32x4 acc[2][2][4][2];
; #pragma unroll
;     for (int a = 0; a < 2; ++a)
; #pragma unroll
;         for (int b = 0; b < 2; ++b)
; #pragma unroll
;             for (int m = 0; m < 4; ++m)
; #pragma unroll
;                 for (int n = 0; n < 2; ++n) acc[a][b][m][n] = (f32x4){0.f, 0.f, 0.f, 0.f};
;     bf16x8 At[4][2], B0[2][2], B1[2][2];
;     const char* cA = S.aptr(cur); const char* cB = S.bptr(cur);
;     PG8_STAGE(PG8_SB(0, 0), cB, voffB); PG8_STAGE(PG8_SB(0, 1), cB + hB, voffB); PG8_STAGE(PG8_SA(0, 0), cA, voffA); PG8_STAGE(PG8_SA(0, 1), cA + hA, voffA);
;     if (wr == 1) PG8_BAR;
.Lstag0_loop:
	s_cmp_eq_u32 s98, 0
	s_cbranch_scc1 .Lstag0_done
	s_sleep 2
	s_sub_u32 s98, s98, 1
	s_branch .Lstag0_loop
.Lstag0_done:
	v_lshlrev_b32_e32 v0, 4, v10
	v_add_u32_e32 v1, 0x2000, v0
	v_ashrrev_i32_e32 v2, 31, v1
	v_lshrrev_b32_e32 v2, 22, v2
	v_add_u32_e32 v2, v1, v2
	v_ashrrev_i32_e32 v8, 10, v2
	v_mul_i32_i24_e32 v2, 0x400, v8
	v_sub_u32_e32 v1, v1, v2
	v_lshrrev_b32_e32 v2, 4, v1
	v_bitop3_b32 v1, v2, v1, 32 bitop3:0x6c
	v_ashrrev_i32_e32 v2, 31, v1
	v_lshrrev_b32_e32 v2, 26, v2
	v_add_u32_e32 v2, v1, v2
	v_lshlrev_b32_e32 v3, 3, v8
	v_ashrrev_i32_e32 v9, 6, v2
	v_and_b32_e32 v3, -16, v3
	v_add_u32_e32 v3, v9, v3
	v_and_b32_e32 v4, 3, v9
	s_mov_b32 s0, 0xfffe0
	v_lshrrev_b32_e32 v5, 2, v3
	v_lshlrev_b32_e32 v6, 1, v3
	v_and_b32_e32 v2, 0xc0, v2
	v_and_or_b32 v4, v3, s0, v4
	v_and_b32_e32 v5, 4, v5
	v_and_b32_e32 v6, 24, v6
	v_sub_u32_e32 v1, v1, v2
	v_mov_b32_e32 v2, 1
	v_or3_b32 v4, v4, v5, v6
	v_lshlrev_b32_e32 v5, 5, v8
	v_ashrrev_i16_sdwa v1, v2, sext(v1) dst_sel:DWORD dst_unused:UNUSED_PAD src0_sel:DWORD src1_sel:BYTE_0
	v_and_b32_e32 v5, 32, v5
	v_bfe_i32 v11, v1, 0, 16
	v_add_lshl_u32 v1, v5, v11, 1
	v_lshl_add_u32 v128, v4, 12, v1
	v_lshl_add_u32 v130, v3, 12, v1
	v_bfe_i32 v1, v10, 27, 1
	v_lshrrev_b32_e32 v1, 22, v1
	v_add_u32_e32 v1, v0, v1
	v_and_b32_e32 v1, 0xfffffc00, v1
	v_sub_u32_e32 v0, v0, v1
	v_lshrrev_b32_e32 v1, 4, v0
	v_ashrrev_i32_e32 v3, 31, v10
	v_bitop3_b32 v0, v1, v0, 32 bitop3:0x6c
	v_lshrrev_b32_e32 v3, 26, v3
	v_ashrrev_i32_e32 v1, 31, v0
	v_add_u32_e32 v3, v10, v3
	v_lshrrev_b32_e32 v1, 26, v1
	v_ashrrev_i32_e32 v13, 6, v3
	v_add_u32_e32 v1, v0, v1
	v_lshlrev_b32_e32 v3, 3, v13
	v_ashrrev_i32_e32 v12, 6, v1
	v_and_b32_e32 v3, -16, v3
	v_add_u32_e32 v3, v12, v3
	v_and_b32_e32 v4, 3, v12
	s_ashr_i32 s14, s33, 31
	v_and_or_b32 v4, v3, s0, v4
	s_lshr_b32 s0, s14, 29
	s_add_i32 s0, s33, s0
	s_ashr_i32 s18, s5, 6
	s_ashr_i32 s1, s0, 3
	s_and_b32 s0, s0, -8
	s_ashr_i32 s19, s5, 8
	s_lshl_b32 s2, s18, 10
	s_sub_i32 s0, s33, s0
	s_cmp_lt_i32 s0, 0
	s_movk_i32 s15, 0x141
	s_cselect_b32 s4, s15, 0x140
	s_mul_i32 s0, s4, s0
	s_add_i32 s0, s0, s1
	s_mul_hi_i32 s1, s0, 0x66666667
	s_lshr_b32 s4, s1, 31
	s_ashr_i32 s1, s1, 6
	s_add_i32 s1, s1, s4
	s_lshl_b32 s6, s1, 3
	s_mulk_i32 s1, 0xa0
	s_sub_i32 s0, s0, s1
	s_sext_i32_i16 s1, s0
	s_bfe_u32 s1, s1, 0x3001c
	s_add_i32 s1, s0, s1
	s_sext_i32_i16 s4, s1
	s_and_b32 s1, s1, 0xfff8
	s_sub_i32 s0, s0, s1
	s_sext_i32_i16 s0, s0
	v_lshrrev_b32_e32 v5, 2, v3
	v_lshlrev_b32_e32 v6, 1, v3
	v_and_b32_e32 v1, 0xc0, v1
	s_lshr_b32 s4, s4, 3
	s_add_i32 s6, s6, s0
	v_and_b32_e32 v5, 4, v5
	v_and_b32_e32 v6, 24, v6
	v_sub_u32_e32 v0, v0, v1
	s_ashr_i32 s7, s6, 31
	s_bfe_i64 s[0:1], s[4:5], 0x100000
	v_or3_b32 v4, v4, v5, v6
	v_lshlrev_b32_e32 v5, 5, v13
	v_ashrrev_i16_sdwa v0, v2, sext(v0) dst_sel:DWORD dst_unused:UNUSED_PAD src0_sel:DWORD src1_sel:BYTE_0
	s_lshl_b64 s[10:11], s[6:7], 20
	s_lshl_b64 s[0:1], s[0:1], 20
	v_and_b32_e32 v5, 32, v5
	v_bfe_i32 v14, v0, 0, 16
	s_add_u32 s54, s8, s0
	v_add_lshl_u32 v0, v5, v14, 1
	s_addc_u32 s55, s9, s1
	s_add_i32 s1, s2, 0
	v_lshl_add_u32 v132, v4, 12, v0
	s_add_i32 m0, s1, 0x10000
	v_lshl_add_u32 v134, v3, 12, v0
	global_load_lds_dwordx4 v132, s[54:55]
	s_add_i32 m0, s1, 0x12000
	s_add_u32 s20, s54, 0x80000
	global_load_lds_dwordx4 v128, s[54:55]
	s_addc_u32 s21, s55, 0
	s_add_i32 m0, s1, 0x14000
	v_mov_b32_e32 v137, 0
	global_load_lds_dwordx4 v132, s[20:21]
	s_add_i32 m0, s1, 0x16000
	s_add_u32 s56, s12, s10
	s_addc_u32 s57, s13, s11
	s_add_i32 s17, s1, 0x2000
	global_load_lds_dwordx4 v128, s[20:21]
	s_mov_b32 m0, s1
	s_add_u32 s10, s56, 0x80000
	global_load_lds_dwordx4 v134, s[56:57]
	s_mov_b32 m0, s17
	s_addc_u32 s11, s57, 0
	s_add_i32 s29, s1, 0x4000
	global_load_lds_dwordx4 v130, s[56:57]
	s_mov_b32 m0, s29
	s_add_i32 s34, s1, 0x6000
	global_load_lds_dwordx4 v134, s[10:11]
	s_mov_b32 m0, s34
	v_mov_b32_e32 v133, v137
	global_load_lds_dwordx4 v130, s[10:11]
	v_mov_b32_e32 v129, v137
	v_mov_b32_e32 v135, v137
	v_mov_b32_e32 v131, v137
	s_cmp_eq_u32 s19, 1
	v_lshl_add_u64 v[6:7], s[54:55], 0, v[132:133]
	v_lshl_add_u64 v[4:5], s[54:55], 0, v[128:129]
	v_lshl_add_u64 v[0:1], s[56:57], 0, v[134:135]
	s_cselect_b64 s[10:11], -1, 0
	s_cmp_lg_u32 s19, 1
	v_lshl_add_u64 v[2:3], s[56:57], 0, v[130:131]
	s_cbranch_scc1 .LBB0_203
	s_barrier

; #define LAS __attribute__((address_space(3)))
; __device__ __forceinline__ unsigned cvt_pk_bf16(float lo, float hi) { unsigned r; asm("v_cvt_pk_bf16_f32 %0, %1, %2" : "=v"(r) : "v"(lo), "v"(hi)); return r; }
; #define LDS_WAIT() asm volatile("s_waitcnt lgkmcnt(0)" ::: "memory")
; __device__ __forceinline__ void tstore_sub(const f32x4 (&v)[4][2], bf16_t* dst  , LAS unsigned char* x, int fr, int fq, int lane) {
; #pragma unroll
;     for (int m = 0; m < 4; ++m)
; #pragma unroll
;         for (int n = 0; n < 2; ++n)
; #pragma unroll
;             for (int j = 0; j < 4; ++j) {
;                 const int ch = 8 * fq + 4 * n + j, tok = 16 * m + fr;
;                 const unsigned b = cvt_pk_bf16(v[m][n][j], 0.f);
;                 *(LAS unsigned short*)(x + ch * 128 + ((((tok >> 3) ^ fq) << 4) | ((tok & 7) << 1))) = (unsigned short)b;
;             }
;     LDS_WAIT();
; #pragma unroll
;     for (int i = 0; i < 4; ++i) {
;         const int q = lane + 64 * i, ch = q >> 3, tc = q & 7;
;         const u32x4 o = *(const LAS u32x4*)(x + ch * 128 + ((tc ^ ((ch >> 3) & 3)) << 4));
;         *(u32x4*)(dst + (size_t)ch * T + tc * 8) = o;
;     }
;     LDS_WAIT();
;     __device__ __forceinline__ void operator()(const f32x4 (&acc)[2][2][4][2], const Unit& u, int wr, int wc, int fr, int fq, LAS unsigned char* xs, int wid, int lane) const {
;     ...
;                     for (int m = 0; m < 4; ++m) { v[m][0] = acc[ai][bj][m][0] * rs[ai][m]; v[m][1] = acc[ai][bj][m][1] * rs[ai][m]; }
.LBB0_230:
	s_waitcnt lgkmcnt(7)
	v_pk_mul_f32 v[176:177], v[124:125], v[172:173] op_sel_hi:[1,0]
	v_pk_mul_f32 v[174:175], v[126:127], v[172:173] op_sel_hi:[1,0]
	v_cvt_pk_bf16_f32 v143, v176, v137
	ds_write_b16 v167, v143
	v_cvt_pk_bf16_f32 v143, v177, v137
	ds_write_b16 v167, v143 offset:128
	v_cvt_pk_bf16_f32 v143, v174, v137
	ds_write_b16 v167, v143 offset:256
	v_cvt_pk_bf16_f32 v143, v175, v137
	v_pk_mul_f32 v[180:181], v[120:121], v[172:173] op_sel_hi:[1,0]
	ds_write_b16 v167, v143 offset:384
	v_cvt_pk_bf16_f32 v143, v180, v137
	ds_write_b16 v167, v143 offset:512
	v_cvt_pk_bf16_f32 v143, v181, v137
	v_pk_mul_f32 v[178:179], v[122:123], v[172:173] op_sel_hi:[1,0]
	ds_write_b16 v167, v143 offset:640
	v_cvt_pk_bf16_f32 v143, v178, v137
	ds_write_b16 v167, v143 offset:768
	v_cvt_pk_bf16_f32 v143, v179, v137
	s_waitcnt lgkmcnt(13)
	v_pk_mul_f32 v[192:193], v[108:109], v[170:171] op_sel_hi:[1,0]
	ds_write_b16 v167, v143 offset:896
	v_cvt_pk_bf16_f32 v143, v192, v137
	ds_write_b16 v169, v143
	v_cvt_pk_bf16_f32 v143, v193, v137
	v_pk_mul_f32 v[190:191], v[110:111], v[170:171] op_sel_hi:[1,0]
	ds_write_b16 v169, v143 offset:128
	v_cvt_pk_bf16_f32 v143, v190, v137
	ds_write_b16 v169, v143 offset:256
	v_cvt_pk_bf16_f32 v143, v191, v137
	v_pk_mul_f32 v[196:197], v[104:105], v[170:171] op_sel_hi:[1,0]
	ds_write_b16 v169, v143 offset:384
	v_cvt_pk_bf16_f32 v143, v196, v137
	ds_write_b16 v169, v143 offset:512
	v_cvt_pk_bf16_f32 v143, v197, v137
	v_pk_mul_f32 v[194:195], v[106:107], v[170:171] op_sel_hi:[1,0]
	ds_write_b16 v169, v143 offset:640
	v_cvt_pk_bf16_f32 v143, v194, v137
	ds_write_b16 v169, v143 offset:768
	v_cvt_pk_bf16_f32 v143, v195, v137
	s_waitcnt lgkmcnt(14)
	v_pk_mul_f32 v[200:201], v[92:93], v[168:169] op_sel_hi:[1,0]
	ds_write_b16 v169, v143 offset:896
	v_cvt_pk_bf16_f32 v143, v200, v137
	ds_write_b16 v171, v143
	v_cvt_pk_bf16_f32 v143, v201, v137
	v_pk_mul_f32 v[198:199], v[94:95], v[168:169] op_sel_hi:[1,0]
	ds_write_b16 v171, v143 offset:128
	v_cvt_pk_bf16_f32 v143, v198, v137
	ds_write_b16 v171, v143 offset:256
	v_cvt_pk_bf16_f32 v143, v199, v137
	v_pk_mul_f32 v[204:205], v[88:89], v[168:169] op_sel_hi:[1,0]
	ds_write_b16 v171, v143 offset:384
	v_cvt_pk_bf16_f32 v143, v204, v137
	ds_write_b16 v171, v143 offset:512
	v_cvt_pk_bf16_f32 v143, v205, v137
	v_pk_mul_f32 v[202:203], v[90:91], v[168:169] op_sel_hi:[1,0]
	ds_write_b16 v171, v143 offset:640
	v_cvt_pk_bf16_f32 v143, v202, v137
	ds_write_b16 v171, v143 offset:768
	v_cvt_pk_bf16_f32 v143, v203, v137
	v_pk_mul_f32 v[208:209], v[76:77], v[166:167] op_sel_hi:[1,0]
	ds_write_b16 v171, v143 offset:896
	v_cvt_pk_bf16_f32 v143, v208, v137
	ds_write_b16 v173, v143
	v_cvt_pk_bf16_f32 v143, v209, v137
	v_pk_mul_f32 v[206:207], v[78:79], v[166:167] op_sel_hi:[1,0]
	ds_write_b16 v173, v143 offset:128
	v_cvt_pk_bf16_f32 v143, v206, v137
	ds_write_b16 v173, v143 offset:256
	v_cvt_pk_bf16_f32 v143, v207, v137
	v_pk_mul_f32 v[212:213], v[72:73], v[166:167] op_sel_hi:[1,0]
	ds_write_b16 v173, v143 offset:384
	v_cvt_pk_bf16_f32 v143, v212, v137
	ds_write_b16 v173, v143 offset:512
	v_cvt_pk_bf16_f32 v143, v213, v137
	v_pk_mul_f32 v[210:211], v[74:75], v[166:167] op_sel_hi:[1,0]
	ds_write_b16 v173, v143 offset:640
	v_cvt_pk_bf16_f32 v143, v210, v137
	s_ashr_i32 s55, s54, 31
	ds_write_b16 v173, v143 offset:768
	v_cvt_pk_bf16_f32 v143, v211, v137
	ds_write_b16 v173, v143 offset:896
	s_lshl_b64 s[18:19], s[54:55], 1
	s_waitcnt lgkmcnt(0)
	s_add_u32 s18, s56, s18
	ds_read_b128 v[176:179], v184
	ds_read_b128 v[190:193], v185
	s_addc_u32 s19, s57, s19
	v_lshl_add_u64 v[182:183], s[18:19], 0, v[136:137]
	s_mov_b32 s43, s21
	v_lshl_add_u64 v[180:181], v[182:183], 0, s[42:43]
	v_mov_b32_e32 v143, v137
	v_lshl_add_u64 v[174:175], v[180:181], 0, v[142:143]
	v_mov_b32_e32 v145, v137
	s_waitcnt lgkmcnt(1)
	global_store_dwordx4 v[174:175], v[176:179], off
	ds_read_b128 v[194:197], v186
	v_mov_b32_e32 v147, v137
	v_lshl_add_u64 v[176:177], v[180:181], 0, v[144:145]
	s_waitcnt lgkmcnt(1)
	global_store_dwordx4 v[176:177], v[190:193], off
	ds_read_b128 v[190:193], v187
	v_mov_b32_e32 v149, v137
	v_lshl_add_u64 v[178:179], v[180:181], 0, v[146:147]
	v_lshl_add_u64 v[180:181], v[180:181], 0, v[148:149]
	s_waitcnt lgkmcnt(1)
	global_store_dwordx4 v[178:179], v[194:197], off
	s_waitcnt lgkmcnt(0)
	global_store_dwordx4 v[180:181], v[190:193], off
	s_waitcnt lgkmcnt(0)
; #define LAS __attribute__((address_space(3)))
; __device__ __forceinline__ unsigned cvt_pk_bf16(float lo, float hi) { unsigned r; asm("v_cvt_pk_bf16_f32 %0, %1, %2" : "=v"(r) : "v"(lo), "v"(hi)); return r; }
; #define LDS_WAIT() asm volatile("s_waitcnt lgkmcnt(0)" ::: "memory")
; __device__ __forceinline__ void tstore_sub(const f32x4 (&v)[4][2], bf16_t* dst  , LAS unsigned char* x, int fr, int fq, int lane) {
; #pragma unroll
;     for (int m = 0; m < 4; ++m)
; #pragma unroll
;         for (int n = 0; n < 2; ++n)
; #pragma unroll
;             for (int j = 0; j < 4; ++j) {
;                 const int ch = 8 * fq + 4 * n + j, tok = 16 * m + fr;
;                 const unsigned b = cvt_pk_bf16(v[m][n][j], 0.f);
;                 *(LAS unsigned short*)(x + ch * 128 + ((((tok >> 3) ^ fq) << 4) | ((tok & 7) << 1))) = (unsigned short)b;
;             }
;     LDS_WAIT();
; #pragma unroll
;     for (int i = 0; i < 4; ++i) {
;         const int q = lane + 64 * i, ch = q >> 3, tc = q & 7;
;         const u32x4 o = *(const LAS u32x4*)(x + ch * 128 + ((tc ^ ((ch >> 3) & 3)) << 4));
;         *(u32x4*)(dst + (size_t)ch * T + tc * 8) = o;
;     }
;     LDS_WAIT();
;     __device__ __forceinline__ void operator()(const f32x4 (&acc)[2][2][4][2], const Unit& u, int wr, int wc, int fr, int fq, LAS unsigned char* xs, int wid, int lane) const {
;     ...
;                     for (int m = 0; m < 4; ++m) { v[m][0] = acc[ai][bj][m][0] * rs[ai][m]; v[m][1] = acc[ai][bj][m][1] * rs[ai][m]; }
	v_pk_mul_f32 v[200:201], v[100:101], v[170:171] op_sel_hi:[1,0]
	v_pk_mul_f32 v[196:197], v[112:113], v[172:173] op_sel_hi:[1,0]
	v_pk_mul_f32 v[192:193], v[116:117], v[172:173] op_sel_hi:[1,0]
	v_pk_mul_f32 v[190:191], v[118:119], v[172:173] op_sel_hi:[1,0]
	v_cvt_pk_bf16_f32 v151, v192, v137
	ds_write_b16 v167, v151
	v_cvt_pk_bf16_f32 v151, v193, v137
	ds_write_b16 v167, v151 offset:128
	v_cvt_pk_bf16_f32 v151, v190, v137
	ds_write_b16 v167, v151 offset:256
	v_cvt_pk_bf16_f32 v151, v191, v137
	ds_write_b16 v167, v151 offset:384
	v_cvt_pk_bf16_f32 v151, v196, v137
	ds_write_b16 v167, v151 offset:512
	v_cvt_pk_bf16_f32 v151, v197, v137
	v_pk_mul_f32 v[194:195], v[114:115], v[172:173] op_sel_hi:[1,0]
	ds_write_b16 v167, v151 offset:640
	v_cvt_pk_bf16_f32 v151, v194, v137
	ds_write_b16 v167, v151 offset:768
	v_cvt_pk_bf16_f32 v151, v195, v137
	ds_write_b16 v167, v151 offset:896
	v_cvt_pk_bf16_f32 v151, v200, v137
	ds_write_b16 v169, v151
	v_cvt_pk_bf16_f32 v151, v201, v137
	v_pk_mul_f32 v[198:199], v[102:103], v[170:171] op_sel_hi:[1,0]
	ds_write_b16 v169, v151 offset:128
	v_cvt_pk_bf16_f32 v151, v198, v137
	ds_write_b16 v169, v151 offset:256
	v_cvt_pk_bf16_f32 v151, v199, v137
	v_pk_mul_f32 v[204:205], v[96:97], v[170:171] op_sel_hi:[1,0]
	ds_write_b16 v169, v151 offset:384
	v_cvt_pk_bf16_f32 v151, v204, v137
	ds_write_b16 v169, v151 offset:512
	v_cvt_pk_bf16_f32 v151, v205, v137
	v_pk_mul_f32 v[202:203], v[98:99], v[170:171] op_sel_hi:[1,0]
	ds_write_b16 v169, v151 offset:640
	v_cvt_pk_bf16_f32 v151, v202, v137
	ds_write_b16 v169, v151 offset:768
	v_cvt_pk_bf16_f32 v151, v203, v137
	v_pk_mul_f32 v[208:209], v[84:85], v[168:169] op_sel_hi:[1,0]
	ds_write_b16 v169, v151 offset:896
	v_cvt_pk_bf16_f32 v151, v208, v137
	ds_write_b16 v171, v151
	v_cvt_pk_bf16_f32 v151, v209, v137
	v_pk_mul_f32 v[206:207], v[86:87], v[168:169] op_sel_hi:[1,0]
	ds_write_b16 v171, v151 offset:128
	v_cvt_pk_bf16_f32 v151, v206, v137
	ds_write_b16 v171, v151 offset:256
	v_cvt_pk_bf16_f32 v151, v207, v137
	v_pk_mul_f32 v[212:213], v[80:81], v[168:169] op_sel_hi:[1,0]
	ds_write_b16 v171, v151 offset:384
	v_cvt_pk_bf16_f32 v151, v212, v137
	ds_write_b16 v171, v151 offset:512
	v_cvt_pk_bf16_f32 v151, v213, v137
	v_pk_mul_f32 v[210:211], v[82:83], v[168:169] op_sel_hi:[1,0]
	ds_write_b16 v171, v151 offset:640
	v_cvt_pk_bf16_f32 v151, v210, v137
	ds_write_b16 v171, v151 offset:768
	v_cvt_pk_bf16_f32 v151, v211, v137
	v_pk_mul_f32 v[216:217], v[68:69], v[166:167] op_sel_hi:[1,0]
	ds_write_b16 v171, v151 offset:896
	v_cvt_pk_bf16_f32 v151, v216, v137
	ds_write_b16 v173, v151
	v_cvt_pk_bf16_f32 v151, v217, v137
	v_pk_mul_f32 v[214:215], v[70:71], v[166:167] op_sel_hi:[1,0]
	ds_write_b16 v173, v151 offset:128
	v_cvt_pk_bf16_f32 v151, v214, v137
	ds_write_b16 v173, v151 offset:256
	v_cvt_pk_bf16_f32 v151, v215, v137
	v_pk_mul_f32 v[220:221], v[64:65], v[166:167] op_sel_hi:[1,0]
	ds_write_b16 v173, v151 offset:384
	v_cvt_pk_bf16_f32 v151, v220, v137
	ds_write_b16 v173, v151 offset:512
	v_cvt_pk_bf16_f32 v151, v221, v137
	v_pk_mul_f32 v[218:219], v[66:67], v[166:167] op_sel_hi:[1,0]
	ds_write_b16 v173, v151 offset:640
	v_cvt_pk_bf16_f32 v151, v218, v137
	ds_write_b16 v173, v151 offset:768
	v_cvt_pk_bf16_f32 v151, v219, v137
	ds_write_b16 v173, v151 offset:896
	s_waitcnt lgkmcnt(0)
	ds_read_b128 v[190:193], v184
	ds_read_b128 v[194:197], v185
	s_mov_b32 s45, s21
	v_lshl_add_u64 v[182:183], v[182:183], 0, s[44:45]
	v_lshl_add_u64 v[198:199], v[182:183], 0, v[142:143]
	s_waitcnt lgkmcnt(1)
	global_store_dwordx4 v[198:199], v[190:193], off
	ds_read_b128 v[190:193], v186
	ds_read_b128 v[198:201], v187
	v_lshl_add_u64 v[202:203], v[182:183], 0, v[144:145]
	s_waitcnt lgkmcnt(2)
	global_store_dwordx4 v[202:203], v[194:197], off
	v_pk_mul_f32 v[204:205], v[40:41], v[162:163] op_sel_hi:[1,0]
	v_pk_mul_f32 v[202:203], v[42:43], v[162:163] op_sel_hi:[1,0]
	v_lshl_add_u64 v[194:195], v[182:183], 0, v[146:147]
	s_waitcnt lgkmcnt(1)
	global_store_dwordx4 v[194:195], v[190:193], off
	v_pk_mul_f32 v[196:197], v[56:57], v[164:165] op_sel_hi:[1,0]
	v_pk_mul_f32 v[194:195], v[58:59], v[164:165] op_sel_hi:[1,0]
	v_lshl_add_u64 v[190:191], v[182:183], 0, v[148:149]
	s_waitcnt lgkmcnt(0)
	global_store_dwordx4 v[190:191], v[198:201], off
	v_pk_mul_f32 v[192:193], v[60:61], v[164:165] op_sel_hi:[1,0]
	s_waitcnt lgkmcnt(0)
; #define LAS __attribute__((address_space(3)))
; __device__ __forceinline__ unsigned cvt_pk_bf16(float lo, float hi) { unsigned r; asm("v_cvt_pk_bf16_f32 %0, %1, %2" : "=v"(r) : "v"(lo), "v"(hi)); return r; }
; #define LDS_WAIT() asm volatile("s_waitcnt lgkmcnt(0)" ::: "memory")
; __device__ __forceinline__ void tstore_sub(const f32x4 (&v)[4][2], bf16_t* dst  , LAS unsigned char* x, int fr, int fq, int lane) {
; #pragma unroll
;     for (int m = 0; m < 4; ++m)
; #pragma unroll
;         for (int n = 0; n < 2; ++n)
; #pragma unroll
;             for (int j = 0; j < 4; ++j) {
;                 const int ch = 8 * fq + 4 * n + j, tok = 16 * m + fr;
;                 const unsigned b = cvt_pk_bf16(v[m][n][j], 0.f);
;                 *(LAS unsigned short*)(x + ch * 128 + ((((tok >> 3) ^ fq) << 4) | ((tok & 7) << 1))) = (unsigned short)b;
;             }
;     LDS_WAIT();
; #pragma unroll
;     for (int i = 0; i < 4; ++i) {
;         const int q = lane + 64 * i, ch = q >> 3, tc = q & 7;
;         const u32x4 o = *(const LAS u32x4*)(x + ch * 128 + ((tc ^ ((ch >> 3) & 3)) << 4));
;         *(u32x4*)(dst + (size_t)ch * T + tc * 8) = o;
;     }
;     LDS_WAIT();
;     __device__ __forceinline__ void operator()(const f32x4 (&acc)[2][2][4][2], const Unit& u, int wr, int wc, int fr, int fq, LAS unsigned char* xs, int wid, int lane) const {
;     ...
;                     for (int m = 0; m < 4; ++m) { v[m][0] = acc[ai][bj][m][0] * rs[ai][m]; v[m][1] = acc[ai][bj][m][1] * rs[ai][m]; }
	v_pk_mul_f32 v[190:191], v[62:63], v[164:165] op_sel_hi:[1,0]
	v_cvt_pk_bf16_f32 v151, v192, v137
	ds_write_b16 v167, v151
	v_cvt_pk_bf16_f32 v151, v193, v137
	ds_write_b16 v167, v151 offset:128
	v_cvt_pk_bf16_f32 v151, v190, v137
	ds_write_b16 v167, v151 offset:256
	v_cvt_pk_bf16_f32 v151, v191, v137
	ds_write_b16 v167, v151 offset:384
	v_cvt_pk_bf16_f32 v151, v196, v137
	ds_write_b16 v167, v151 offset:512
	v_cvt_pk_bf16_f32 v151, v197, v137
	ds_write_b16 v167, v151 offset:640
	v_cvt_pk_bf16_f32 v151, v194, v137
	ds_write_b16 v167, v151 offset:768
	v_cvt_pk_bf16_f32 v151, v195, v137
	v_pk_mul_f32 v[200:201], v[44:45], v[162:163] op_sel_hi:[1,0]
	ds_write_b16 v167, v151 offset:896
	v_cvt_pk_bf16_f32 v151, v200, v137
	ds_write_b16 v169, v151
	v_cvt_pk_bf16_f32 v151, v201, v137
	v_pk_mul_f32 v[198:199], v[46:47], v[162:163] op_sel_hi:[1,0]
	ds_write_b16 v169, v151 offset:128
	v_cvt_pk_bf16_f32 v151, v198, v137
	ds_write_b16 v169, v151 offset:256
	v_cvt_pk_bf16_f32 v151, v199, v137
	ds_write_b16 v169, v151 offset:384
	v_cvt_pk_bf16_f32 v151, v204, v137
	ds_write_b16 v169, v151 offset:512
	v_cvt_pk_bf16_f32 v151, v205, v137
	ds_write_b16 v169, v151 offset:640
	v_cvt_pk_bf16_f32 v151, v202, v137
	ds_write_b16 v169, v151 offset:768
	v_cvt_pk_bf16_f32 v151, v203, v137
	v_pk_mul_f32 v[208:209], v[28:29], v[160:161] op_sel_hi:[1,0]
	ds_write_b16 v169, v151 offset:896
	v_cvt_pk_bf16_f32 v151, v208, v137
	ds_write_b16 v171, v151
	v_cvt_pk_bf16_f32 v151, v209, v137
	v_pk_mul_f32 v[206:207], v[30:31], v[160:161] op_sel_hi:[1,0]
	ds_write_b16 v171, v151 offset:128
	v_cvt_pk_bf16_f32 v151, v206, v137
	ds_write_b16 v171, v151 offset:256
	v_cvt_pk_bf16_f32 v151, v207, v137
	v_pk_mul_f32 v[212:213], v[24:25], v[160:161] op_sel_hi:[1,0]
	ds_write_b16 v171, v151 offset:384
	v_cvt_pk_bf16_f32 v151, v212, v137
	ds_write_b16 v171, v151 offset:512
	v_cvt_pk_bf16_f32 v151, v213, v137
	v_pk_mul_f32 v[210:211], v[26:27], v[160:161] op_sel_hi:[1,0]
	ds_write_b16 v171, v151 offset:640
	v_cvt_pk_bf16_f32 v151, v210, v137
	ds_write_b16 v171, v151 offset:768
	v_cvt_pk_bf16_f32 v151, v211, v137
	v_pk_mul_f32 v[216:217], v[12:13], v[158:159] op_sel_hi:[1,0]
	ds_write_b16 v171, v151 offset:896
	v_cvt_pk_bf16_f32 v151, v216, v137
	ds_write_b16 v173, v151
	v_cvt_pk_bf16_f32 v151, v217, v137
	v_pk_mul_f32 v[214:215], v[14:15], v[158:159] op_sel_hi:[1,0]
	ds_write_b16 v173, v151 offset:128
	v_cvt_pk_bf16_f32 v151, v214, v137
	ds_write_b16 v173, v151 offset:256
	v_cvt_pk_bf16_f32 v151, v215, v137
	v_pk_mul_f32 v[220:221], v[8:9], v[158:159] op_sel_hi:[1,0]
	ds_write_b16 v173, v151 offset:384
	v_cvt_pk_bf16_f32 v151, v220, v137
	ds_write_b16 v173, v151 offset:512
	v_cvt_pk_bf16_f32 v151, v221, v137
	v_pk_mul_f32 v[218:219], v[10:11], v[158:159] op_sel_hi:[1,0]
	ds_write_b16 v173, v151 offset:640
	v_cvt_pk_bf16_f32 v151, v218, v137
	ds_write_b16 v173, v151 offset:768
	v_cvt_pk_bf16_f32 v151, v219, v137
	ds_write_b16 v173, v151 offset:896
	s_waitcnt lgkmcnt(0)
	ds_read_b128 v[190:193], v184
	ds_read_b128 v[194:197], v185
	ds_read_b128 v[198:201], v186
	ds_read_b128 v[202:205], v187
	s_waitcnt lgkmcnt(3)
	global_store_dwordx4 v[174:175], v[190:193], off offset:256
	s_waitcnt lgkmcnt(2)
	global_store_dwordx4 v[176:177], v[194:197], off offset:256
	s_waitcnt lgkmcnt(1)
	global_store_dwordx4 v[178:179], v[198:201], off offset:256
	s_waitcnt lgkmcnt(0)
	global_store_dwordx4 v[180:181], v[202:205], off offset:256
	v_pk_mul_f32 v[176:177], v[52:53], v[164:165] op_sel_hi:[1,0]
	s_waitcnt lgkmcnt(0)
	v_pk_mul_f32 v[174:175], v[54:55], v[164:165] op_sel_hi:[1,0]
	v_cvt_pk_bf16_f32 v151, v176, v137
	ds_write_b16 v167, v151
	v_cvt_pk_bf16_f32 v151, v177, v137
	ds_write_b16 v167, v151 offset:128
	v_cvt_pk_bf16_f32 v151, v174, v137
	ds_write_b16 v167, v151 offset:256
	v_cvt_pk_bf16_f32 v151, v175, v137
	v_pk_mul_f32 v[180:181], v[48:49], v[164:165] op_sel_hi:[1,0]
	ds_write_b16 v167, v151 offset:384
	v_cvt_pk_bf16_f32 v151, v180, v137
	ds_write_b16 v167, v151 offset:512
	v_cvt_pk_bf16_f32 v151, v181, v137
	v_pk_mul_f32 v[178:179], v[50:51], v[164:165] op_sel_hi:[1,0]
	ds_write_b16 v167, v151 offset:640
	v_cvt_pk_bf16_f32 v151, v178, v137
	ds_write_b16 v167, v151 offset:768
	v_cvt_pk_bf16_f32 v151, v179, v137
	v_pk_mul_f32 v[192:193], v[36:37], v[162:163] op_sel_hi:[1,0]
	ds_write_b16 v167, v151 offset:896
	v_cvt_pk_bf16_f32 v151, v192, v137
	ds_write_b16 v169, v151
	v_cvt_pk_bf16_f32 v151, v193, v137
	v_pk_mul_f32 v[190:191], v[38:39], v[162:163] op_sel_hi:[1,0]
	ds_write_b16 v169, v151 offset:128
	v_cvt_pk_bf16_f32 v151, v190, v137
	ds_write_b16 v169, v151 offset:256
	v_cvt_pk_bf16_f32 v151, v191, v137
	v_pk_mul_f32 v[196:197], v[32:33], v[162:163] op_sel_hi:[1,0]
	ds_write_b16 v169, v151 offset:384
	v_cvt_pk_bf16_f32 v151, v196, v137
	ds_write_b16 v169, v151 offset:512
	v_cvt_pk_bf16_f32 v151, v197, v137
	v_pk_mul_f32 v[194:195], v[34:35], v[162:163] op_sel_hi:[1,0]
	ds_write_b16 v169, v151 offset:640
	v_cvt_pk_bf16_f32 v151, v194, v137
	ds_write_b16 v169, v151 offset:768
	v_cvt_pk_bf16_f32 v151, v195, v137
	v_pk_mul_f32 v[200:201], v[20:21], v[160:161] op_sel_hi:[1,0]
	ds_write_b16 v169, v151 offset:896
	v_cvt_pk_bf16_f32 v151, v200, v137
	ds_write_b16 v171, v151
	v_cvt_pk_bf16_f32 v151, v201, v137
	v_pk_mul_f32 v[198:199], v[22:23], v[160:161] op_sel_hi:[1,0]
	ds_write_b16 v171, v151 offset:128
	v_cvt_pk_bf16_f32 v151, v198, v137
	ds_write_b16 v171, v151 offset:256
	v_cvt_pk_bf16_f32 v151, v199, v137
	v_pk_mul_f32 v[204:205], v[16:17], v[160:161] op_sel_hi:[1,0]
	ds_write_b16 v171, v151 offset:384
	v_cvt_pk_bf16_f32 v151, v204, v137
	ds_write_b16 v171, v151 offset:512
	v_cvt_pk_bf16_f32 v151, v205, v137
	v_pk_mul_f32 v[202:203], v[18:19], v[160:161] op_sel_hi:[1,0]
	ds_write_b16 v171, v151 offset:640
	v_cvt_pk_bf16_f32 v151, v202, v137
	ds_write_b16 v171, v151 offset:768
	v_cvt_pk_bf16_f32 v151, v203, v137
	v_pk_mul_f32 v[208:209], v[4:5], v[158:159] op_sel_hi:[1,0]
	ds_write_b16 v171, v151 offset:896
	v_cvt_pk_bf16_f32 v151, v208, v137
	ds_write_b16 v173, v151
	v_cvt_pk_bf16_f32 v151, v209, v137
	v_pk_mul_f32 v[206:207], v[6:7], v[158:159] op_sel_hi:[1,0]
	ds_write_b16 v173, v151 offset:128
	v_cvt_pk_bf16_f32 v151, v206, v137
	ds_write_b16 v173, v151 offset:256
	v_cvt_pk_bf16_f32 v151, v207, v137
	v_pk_mul_f32 v[212:213], v[0:1], v[158:159] op_sel_hi:[1,0]
	ds_write_b16 v173, v151 offset:384
	v_cvt_pk_bf16_f32 v151, v212, v137
	ds_write_b16 v173, v151 offset:512
	v_cvt_pk_bf16_f32 v151, v213, v137
	v_pk_mul_f32 v[210:211], v[2:3], v[158:159] op_sel_hi:[1,0]
	ds_write_b16 v173, v151 offset:640
	v_cvt_pk_bf16_f32 v151, v210, v137
	ds_write_b16 v173, v151 offset:768
	v_cvt_pk_bf16_f32 v151, v211, v137
	ds_write_b16 v173, v151 offset:896
	s_waitcnt lgkmcnt(0)
; #define LAS __attribute__((address_space(3)))
; __device__ __forceinline__ unsigned cvt_pk_bf16(float lo, float hi) { unsigned r; asm("v_cvt_pk_bf16_f32 %0, %1, %2" : "=v"(r) : "v"(lo), "v"(hi)); return r; }
; __device__ __forceinline__ void tstore_sub(const f32x4 (&v)[4][2], bf16_t* dst  , LAS unsigned char* x, int fr, int fq, int lane) {
;     ...
;     for (int i = 0; i < 4; ++i) {
;         const int q = lane + 64 * i, ch = q >> 3, tc = q & 7;
;         const u32x4 o = *(const LAS u32x4*)(x + ch * 128 + ((tc ^ ((ch >> 3) & 3)) << 4));
;         *(u32x4*)(dst + (size_t)ch * T + tc * 8) = o;
;     }
;     __device__ __forceinline__ void operator()(const f32x4 (&acc)[2][2][4][2], const Unit& u, int wr, int wc, int fr, int fq, LAS unsigned char* xs, int wid, int lane) const {
;     ...
;         if (mode == 0) {
; #pragma unroll
;             for (int ai = 0; ai < 2; ++ai)
; #pragma unroll
;                 for (int m = 0; m < 4; ++m) {
;                     const float r = rs[ai][m];
;                     bf16_t* rowp = base + (size_t)(row0 + ai * 128 + m * 16 + fr) * ldc + wc * 32 + 8 * fq;
; #pragma unroll
;                     for (int bj = 0; bj < 2; ++bj) { const f32x4 v0 = acc[ai][bj][m][0] * r, v1 = acc[ai][bj][m][1] * r;
;                         u32x4 w; w.x = cvt_pk_bf16(v0[0], v0[1]); w.y = cvt_pk_bf16(v0[2], v0[3]); w.z = cvt_pk_bf16(v1[0], v1[1]); w.w = cvt_pk_bf16(v1[2], v1[3]);
;                         *(u32x4*)(rowp + bj * 128) = w; }
;                     __builtin_amdgcn_sched_barrier(0);
;                 }
	ds_read_b128 v[174:177], v184
	ds_read_b128 v[178:181], v185
	v_lshl_add_u64 v[182:183], v[182:183], 0, s[26:27]
	v_lshl_add_u64 v[190:191], v[182:183], 0, v[142:143]
	v_lshl_add_u64 v[194:195], v[182:183], 0, v[144:145]
	s_waitcnt lgkmcnt(1)
	global_store_dwordx4 v[190:191], v[174:177], off
	ds_read_b128 v[174:177], v186
	ds_read_b128 v[190:193], v187
	s_waitcnt lgkmcnt(2)
	global_store_dwordx4 v[194:195], v[178:181], off
	s_nop 1
	v_lshl_add_u64 v[178:179], v[182:183], 0, v[146:147]
	s_waitcnt lgkmcnt(1)
	global_store_dwordx4 v[178:179], v[174:177], off
	s_nop 1
	v_lshl_add_u64 v[174:175], v[182:183], 0, v[148:149]
	s_waitcnt lgkmcnt(0)
	global_store_dwordx4 v[174:175], v[190:193], off
	s_waitcnt lgkmcnt(0)
	s_cbranch_execnz .LBB0_216
.LBB0_231:
	s_add_u32 s18, s56, s71
	v_or_b32_e32 v143, s54, v157
	s_addc_u32 s19, s57, 0
	v_mov_b32_e32 v151, v137
	s_ashr_i32 s0, s54, 31
	v_lshl_add_u64 v[174:175], s[18:19], 0, v[150:151]
	v_mul_lo_u32 v145, s7, v143
	s_mul_i32 s0, s6, s0
	v_mad_u64_u32 v[176:177], s[18:19], s6, v143, 0
	v_add3_u32 v177, v177, s0, v145
	v_lshl_add_u64 v[176:177], v[176:177], 1, v[174:175]
	s_waitcnt lgkmcnt(7)
	v_pk_mul_f32 v[126:127], v[126:127], v[172:173] op_sel_hi:[1,0]
	v_pk_mul_f32 v[124:125], v[124:125], v[172:173] op_sel_hi:[1,0]
	v_pk_mul_f32 v[178:179], v[122:123], v[172:173] op_sel_hi:[1,0]
	v_pk_mul_f32 v[122:123], v[120:121], v[172:173] op_sel_hi:[1,0]
	v_cvt_pk_bf16_f32 v120, v124, v125
	v_cvt_pk_bf16_f32 v121, v126, v127
	v_pk_mul_f32 v[118:119], v[118:119], v[172:173] op_sel_hi:[1,0]
	v_cvt_pk_bf16_f32 v122, v122, v123
	v_cvt_pk_bf16_f32 v123, v178, v179
	global_store_dwordx4 v[176:177], v[120:123], off
	v_pk_mul_f32 v[116:117], v[116:117], v[172:173] op_sel_hi:[1,0]
	s_nop 0
	v_pk_mul_f32 v[120:121], v[114:115], v[172:173] op_sel_hi:[1,0]
	v_pk_mul_f32 v[114:115], v[112:113], v[172:173] op_sel_hi:[1,0]
	v_cvt_pk_bf16_f32 v112, v116, v117
	v_cvt_pk_bf16_f32 v113, v118, v119
	s_nop 0
	v_cvt_pk_bf16_f32 v114, v114, v115
	v_cvt_pk_bf16_f32 v115, v120, v121
	global_store_dwordx4 v[176:177], v[112:115], off offset:256
	s_nop 1
	v_or_b32_e32 v112, 16, v143
	v_mul_lo_u32 v114, s7, v112
	v_mad_u64_u32 v[112:113], s[18:19], s6, v112, 0
	v_add3_u32 v113, v113, s0, v114
	v_lshl_add_u64 v[112:113], v[112:113], 1, v[174:175]
	s_waitcnt lgkmcnt(6)
	v_pk_mul_f32 v[110:111], v[110:111], v[170:171] op_sel_hi:[1,0]
	v_pk_mul_f32 v[108:109], v[108:109], v[170:171] op_sel_hi:[1,0]
	v_pk_mul_f32 v[114:115], v[106:107], v[170:171] op_sel_hi:[1,0]
	v_pk_mul_f32 v[106:107], v[104:105], v[170:171] op_sel_hi:[1,0]
	v_cvt_pk_bf16_f32 v104, v108, v109
	v_cvt_pk_bf16_f32 v105, v110, v111
	v_pk_mul_f32 v[102:103], v[102:103], v[170:171] op_sel_hi:[1,0]
	v_cvt_pk_bf16_f32 v106, v106, v107
	v_cvt_pk_bf16_f32 v107, v114, v115
	global_store_dwordx4 v[112:113], v[104:107], off
	v_pk_mul_f32 v[100:101], v[100:101], v[170:171] op_sel_hi:[1,0]
	s_nop 0
	v_pk_mul_f32 v[104:105], v[98:99], v[170:171] op_sel_hi:[1,0]
	v_pk_mul_f32 v[98:99], v[96:97], v[170:171] op_sel_hi:[1,0]
	v_cvt_pk_bf16_f32 v96, v100, v101
	v_cvt_pk_bf16_f32 v97, v102, v103
	s_nop 0
	v_cvt_pk_bf16_f32 v98, v98, v99
	v_cvt_pk_bf16_f32 v99, v104, v105
	global_store_dwordx4 v[112:113], v[96:99], off offset:256
	s_nop 1
	v_or_b32_e32 v96, 32, v143
	v_mul_lo_u32 v98, s7, v96
	v_mad_u64_u32 v[96:97], s[18:19], s6, v96, 0
	v_add3_u32 v97, v97, s0, v98
	v_lshl_add_u64 v[96:97], v[96:97], 1, v[174:175]
	s_waitcnt lgkmcnt(5)
	v_pk_mul_f32 v[94:95], v[94:95], v[168:169] op_sel_hi:[1,0]
	v_pk_mul_f32 v[92:93], v[92:93], v[168:169] op_sel_hi:[1,0]
	v_pk_mul_f32 v[98:99], v[90:91], v[168:169] op_sel_hi:[1,0]
	v_pk_mul_f32 v[90:91], v[88:89], v[168:169] op_sel_hi:[1,0]
	v_cvt_pk_bf16_f32 v88, v92, v93
	v_cvt_pk_bf16_f32 v89, v94, v95
	v_pk_mul_f32 v[86:87], v[86:87], v[168:169] op_sel_hi:[1,0]
	v_cvt_pk_bf16_f32 v90, v90, v91
	v_cvt_pk_bf16_f32 v91, v98, v99
	global_store_dwordx4 v[96:97], v[88:91], off
	v_pk_mul_f32 v[84:85], v[84:85], v[168:169] op_sel_hi:[1,0]
	s_nop 0
	v_pk_mul_f32 v[88:89], v[82:83], v[168:169] op_sel_hi:[1,0]
	v_pk_mul_f32 v[82:83], v[80:81], v[168:169] op_sel_hi:[1,0]
	v_cvt_pk_bf16_f32 v80, v84, v85
	v_cvt_pk_bf16_f32 v81, v86, v87
	s_nop 0
	v_cvt_pk_bf16_f32 v82, v82, v83
	v_cvt_pk_bf16_f32 v83, v88, v89
	global_store_dwordx4 v[96:97], v[80:83], off offset:256
	s_nop 1
	v_or_b32_e32 v80, 48, v143
	v_mul_lo_u32 v82, s7, v80
	v_mad_u64_u32 v[80:81], s[18:19], s6, v80, 0
	v_add3_u32 v81, v81, s0, v82
	v_lshl_add_u64 v[80:81], v[80:81], 1, v[174:175]
	s_waitcnt lgkmcnt(4)
; __device__ __forceinline__ unsigned cvt_pk_bf16(float lo, float hi) { unsigned r; asm("v_cvt_pk_bf16_f32 %0, %1, %2" : "=v"(r) : "v"(lo), "v"(hi)); return r; }
;     __device__ __forceinline__ void operator()(const f32x4 (&acc)[2][2][4][2], const Unit& u, int wr, int wc, int fr, int fq, LAS unsigned char* xs, int wid, int lane) const {
;     ...
;         if (mode == 0) {
; #pragma unroll
;             for (int ai = 0; ai < 2; ++ai)
; #pragma unroll
;                 for (int m = 0; m < 4; ++m) {
;                     const float r = rs[ai][m];
;                     bf16_t* rowp = base + (size_t)(row0 + ai * 128 + m * 16 + fr) * ldc + wc * 32 + 8 * fq;
; #pragma unroll
;                     for (int bj = 0; bj < 2; ++bj) { const f32x4 v0 = acc[ai][bj][m][0] * r, v1 = acc[ai][bj][m][1] * r;
;                         u32x4 w; w.x = cvt_pk_bf16(v0[0], v0[1]); w.y = cvt_pk_bf16(v0[2], v0[3]); w.z = cvt_pk_bf16(v1[0], v1[1]); w.w = cvt_pk_bf16(v1[2], v1[3]);
;                         *(u32x4*)(rowp + bj * 128) = w; }
;                     __builtin_amdgcn_sched_barrier(0);
;                 }
	v_pk_mul_f32 v[78:79], v[78:79], v[166:167] op_sel_hi:[1,0]
	v_pk_mul_f32 v[76:77], v[76:77], v[166:167] op_sel_hi:[1,0]
	v_pk_mul_f32 v[82:83], v[74:75], v[166:167] op_sel_hi:[1,0]
	v_pk_mul_f32 v[74:75], v[72:73], v[166:167] op_sel_hi:[1,0]
	v_cvt_pk_bf16_f32 v72, v76, v77
	v_cvt_pk_bf16_f32 v73, v78, v79
	v_pk_mul_f32 v[70:71], v[70:71], v[166:167] op_sel_hi:[1,0]
	v_cvt_pk_bf16_f32 v74, v74, v75
	v_cvt_pk_bf16_f32 v75, v82, v83
	global_store_dwordx4 v[80:81], v[72:75], off
	v_pk_mul_f32 v[68:69], v[68:69], v[166:167] op_sel_hi:[1,0]
	s_nop 0
	v_pk_mul_f32 v[72:73], v[66:67], v[166:167] op_sel_hi:[1,0]
	v_pk_mul_f32 v[66:67], v[64:65], v[166:167] op_sel_hi:[1,0]
	v_cvt_pk_bf16_f32 v64, v68, v69
	v_cvt_pk_bf16_f32 v65, v70, v71
	s_nop 0
	v_cvt_pk_bf16_f32 v66, v66, v67
	v_cvt_pk_bf16_f32 v67, v72, v73
	global_store_dwordx4 v[80:81], v[64:67], off offset:256
	s_nop 1
	v_add_u32_e32 v64, 0x80, v143
	v_ashrrev_i32_e32 v65, 31, v64
	v_mul_lo_u32 v66, s6, v65
	v_mul_lo_u32 v67, s7, v64
	v_mad_u64_u32 v[64:65], s[18:19], s6, v64, 0
	v_add3_u32 v65, v65, v66, v67
	v_lshl_add_u64 v[64:65], v[64:65], 1, v[174:175]
	s_waitcnt lgkmcnt(3)
	v_pk_mul_f32 v[62:63], v[62:63], v[164:165] op_sel_hi:[1,0]
	v_pk_mul_f32 v[60:61], v[60:61], v[164:165] op_sel_hi:[1,0]
	v_pk_mul_f32 v[66:67], v[58:59], v[164:165] op_sel_hi:[1,0]
	v_pk_mul_f32 v[58:59], v[56:57], v[164:165] op_sel_hi:[1,0]
	v_cvt_pk_bf16_f32 v56, v60, v61
	v_cvt_pk_bf16_f32 v57, v62, v63
	v_pk_mul_f32 v[54:55], v[54:55], v[164:165] op_sel_hi:[1,0]
	v_cvt_pk_bf16_f32 v58, v58, v59
	v_cvt_pk_bf16_f32 v59, v66, v67
	global_store_dwordx4 v[64:65], v[56:59], off
	v_pk_mul_f32 v[52:53], v[52:53], v[164:165] op_sel_hi:[1,0]
	s_nop 0
	v_pk_mul_f32 v[56:57], v[50:51], v[164:165] op_sel_hi:[1,0]
	v_pk_mul_f32 v[50:51], v[48:49], v[164:165] op_sel_hi:[1,0]
	v_cvt_pk_bf16_f32 v48, v52, v53
	v_cvt_pk_bf16_f32 v49, v54, v55
	s_nop 0
	v_cvt_pk_bf16_f32 v50, v50, v51
	v_cvt_pk_bf16_f32 v51, v56, v57
	global_store_dwordx4 v[64:65], v[48:51], off offset:256
	s_nop 1
	v_add_u32_e32 v48, 0x90, v143
	v_ashrrev_i32_e32 v49, 31, v48
	v_mul_lo_u32 v50, s6, v49
	v_mul_lo_u32 v51, s7, v48
	v_mad_u64_u32 v[48:49], s[18:19], s6, v48, 0
	v_add3_u32 v49, v49, v50, v51
	v_lshl_add_u64 v[48:49], v[48:49], 1, v[174:175]
	s_waitcnt lgkmcnt(2)
	v_pk_mul_f32 v[46:47], v[46:47], v[162:163] op_sel_hi:[1,0]
	v_pk_mul_f32 v[44:45], v[44:45], v[162:163] op_sel_hi:[1,0]
	v_pk_mul_f32 v[50:51], v[42:43], v[162:163] op_sel_hi:[1,0]
	v_pk_mul_f32 v[42:43], v[40:41], v[162:163] op_sel_hi:[1,0]
	v_cvt_pk_bf16_f32 v40, v44, v45
	v_cvt_pk_bf16_f32 v41, v46, v47
	v_pk_mul_f32 v[38:39], v[38:39], v[162:163] op_sel_hi:[1,0]
	v_cvt_pk_bf16_f32 v42, v42, v43
	v_cvt_pk_bf16_f32 v43, v50, v51
	global_store_dwordx4 v[48:49], v[40:43], off
	v_pk_mul_f32 v[36:37], v[36:37], v[162:163] op_sel_hi:[1,0]
	s_nop 0
	v_pk_mul_f32 v[40:41], v[34:35], v[162:163] op_sel_hi:[1,0]
	v_pk_mul_f32 v[34:35], v[32:33], v[162:163] op_sel_hi:[1,0]
	v_cvt_pk_bf16_f32 v32, v36, v37
	v_cvt_pk_bf16_f32 v33, v38, v39
	s_nop 0
	v_cvt_pk_bf16_f32 v34, v34, v35
	v_cvt_pk_bf16_f32 v35, v40, v41
	global_store_dwordx4 v[48:49], v[32:35], off offset:256
	s_nop 1
	v_add_u32_e32 v32, 0xa0, v143
	v_ashrrev_i32_e32 v33, 31, v32
	v_mul_lo_u32 v34, s6, v33
	v_mul_lo_u32 v35, s7, v32
	v_mad_u64_u32 v[32:33], s[18:19], s6, v32, 0
	v_add3_u32 v33, v33, v34, v35
	v_lshl_add_u64 v[32:33], v[32:33], 1, v[174:175]
	s_waitcnt lgkmcnt(1)
	v_pk_mul_f32 v[30:31], v[30:31], v[160:161] op_sel_hi:[1,0]
	v_pk_mul_f32 v[28:29], v[28:29], v[160:161] op_sel_hi:[1,0]
	v_pk_mul_f32 v[34:35], v[26:27], v[160:161] op_sel_hi:[1,0]
	v_pk_mul_f32 v[26:27], v[24:25], v[160:161] op_sel_hi:[1,0]
	v_cvt_pk_bf16_f32 v24, v28, v29
	v_cvt_pk_bf16_f32 v25, v30, v31
	v_pk_mul_f32 v[22:23], v[22:23], v[160:161] op_sel_hi:[1,0]
	v_cvt_pk_bf16_f32 v26, v26, v27
	v_cvt_pk_bf16_f32 v27, v34, v35
	global_store_dwordx4 v[32:33], v[24:27], off
	v_pk_mul_f32 v[20:21], v[20:21], v[160:161] op_sel_hi:[1,0]
	s_nop 0
	v_pk_mul_f32 v[24:25], v[18:19], v[160:161] op_sel_hi:[1,0]
	v_pk_mul_f32 v[18:19], v[16:17], v[160:161] op_sel_hi:[1,0]
	v_cvt_pk_bf16_f32 v16, v20, v21
	v_cvt_pk_bf16_f32 v17, v22, v23
	s_nop 0
	v_cvt_pk_bf16_f32 v18, v18, v19
	v_cvt_pk_bf16_f32 v19, v24, v25
	global_store_dwordx4 v[32:33], v[16:19], off offset:256
	s_nop 1
	v_add_u32_e32 v16, 0xb0, v143
	v_ashrrev_i32_e32 v17, 31, v16
	v_mul_lo_u32 v18, s6, v17
	v_mul_lo_u32 v19, s7, v16
	v_mad_u64_u32 v[16:17], s[6:7], s6, v16, 0
	v_add3_u32 v17, v17, v18, v19
	v_lshl_add_u64 v[16:17], v[16:17], 1, v[174:175]
	s_waitcnt lgkmcnt(0)
	v_pk_mul_f32 v[14:15], v[14:15], v[158:159] op_sel_hi:[1,0]
	v_pk_mul_f32 v[12:13], v[12:13], v[158:159] op_sel_hi:[1,0]
	v_pk_mul_f32 v[18:19], v[10:11], v[158:159] op_sel_hi:[1,0]
	v_pk_mul_f32 v[10:11], v[8:9], v[158:159] op_sel_hi:[1,0]
	v_cvt_pk_bf16_f32 v8, v12, v13
	v_cvt_pk_bf16_f32 v9, v14, v15
	v_pk_mul_f32 v[6:7], v[6:7], v[158:159] op_sel_hi:[1,0]
	v_cvt_pk_bf16_f32 v10, v10, v11
	v_cvt_pk_bf16_f32 v11, v18, v19
	global_store_dwordx4 v[16:17], v[8:11], off
	v_pk_mul_f32 v[4:5], v[4:5], v[158:159] op_sel_hi:[1,0]
	s_nop 0
	v_pk_mul_f32 v[8:9], v[2:3], v[158:159] op_sel_hi:[1,0]
	v_pk_mul_f32 v[2:3], v[0:1], v[158:159] op_sel_hi:[1,0]
	v_cvt_pk_bf16_f32 v0, v4, v5
	v_cvt_pk_bf16_f32 v1, v6, v7
	s_nop 0
	v_cvt_pk_bf16_f32 v2, v2, v3
	v_cvt_pk_bf16_f32 v3, v8, v9
	global_store_dwordx4 v[16:17], v[0:3], off offset:256
	s_andn2_b64 vcc, exec, s[4:5]
	s_mov_b64 s[4:5], -1
	s_cbranch_vccnz .LBB0_205

; __device__ __forceinline__ unsigned cvt_pk_bf16(float lo, float hi) { unsigned r; asm("v_cvt_pk_bf16_f32 %0, %1, %2" : "=v"(r) : "v"(lo), "v"(hi)); return r; }
;     __device__ __forceinline__ void operator()(const f32x4 (&acc)[2][2][4][2], const Unit& u, int wr, int wc, int fr, int fq, LAS unsigned char* xs, int wid, int lane) const {
;         const int S = lng ? 4096 : 2048, hp = lng ? 8 : 4;
;         const int cs = u.pm >= hp, k0 = (u.pm - hp * cs) * 256 + wr * 64;
;         const size_t tok0 = lng ? (size_t)TP + (size_t)u.aux * 4096 : (size_t)u.aux * 2048;
;         const float sc = lng ? 0.015625f : 0.02209708691207961f;
;         const float scm = cs ? -sc : sc;
;         float hv[2][8];
;         const float csm = cs ? 0.f : 1.f;
; #pragma unroll
;         for (int bj = 0; bj < 2; ++bj)
; #pragma unroll
;             for (int e = 0; e < 8; ++e) {
;                 const unsigned short h = ft[(size_t)(u.pn * 256 + bj * 128 + wc * 32 + 8 * fq + e) * T + tok0 + S / 2];
;                 const float v = __builtin_bit_cast(float, (unsigned)h << 16) * csm;
;                 hv[bj][e] = (fr & 1) ? -v : v;
;             }
; #pragma unroll
;         for (int ai = 0; ai < 2; ++ai)
; #pragma unroll
;             for (int m = 0; m < 4; ++m) {
;                 const int k = k0 + ai * 128 + m * 16 + fr;
; #pragma unroll
;                 for (int bj = 0; bj < 2; ++bj) {
;                     const int col = (2 * u.pn + bj) * 256 + cs * 128 + wc * 32 + 8 * fq;
;                     f32x4 a = acc[ai][bj][m][0], b = acc[ai][bj][m][1];
; #pragma unroll
;                     for (int j = 0; j < 4; ++j) { a[j] += hv[bj][j]; b[j] += hv[bj][4 + j]; }
;                     u32x4 w; w.x = cvt_pk_bf16(a[0] * sc, a[1] * sc); w.y = cvt_pk_bf16(a[2] * sc, a[3] * sc); w.z = cvt_pk_bf16(b[0] * sc, b[1] * sc); w.w = cvt_pk_bf16(b[2] * sc, b[3] * sc);
;                     *(u32x4*)(pq + (tok0 + k) * 1024 + col) = w;
;                     if (k > 0) {
;                         u32x4 w2; w2.x = cvt_pk_bf16(a[0] * scm, a[1] * scm); w2.y = cvt_pk_bf16(a[2] * scm, a[3] * scm); w2.z = cvt_pk_bf16(b[0] * scm, b[1] * scm); w2.w = cvt_pk_bf16(b[2] * scm, b[3] * scm);
;                         *(u32x4*)(pq + (tok0 + S - k) * 1024 + col) = w2;
;                     }
;                 }
.LBB0_430:
	s_lshl_b32 s8, s19, 8
	s_and_b32 s62, s8, 0x700
	s_ashr_i32 s59, s58, 31
	s_add_i32 s62, s62, s34
	s_lshl_b64 s[8:9], s[58:59], 12
	s_add_u32 s58, s8, 0x4000
	s_addc_u32 s59, s9, 0
	s_lshl_b64 s[60:61], s[58:59], 1
	s_add_u32 s60, s44, s60
	v_lshlrev_b32_e32 v136, 16, v150
	s_addc_u32 s61, s45, s61
	v_lshl_or_b32 v136, s18, 24, v136
	v_lshl_add_u64 v[146:147], s[60:61], 0, v[136:137]
	s_movk_i32 s55, 0x1000
	v_add_co_u32_e32 v156, vcc, s55, v146
	s_mov_b32 s55, 0x11000
	s_nop 0
	v_addc_co_u32_e32 v157, vcc, 0, v147, vcc
	global_load_ushort v136, v[156:157], off
	v_add_co_u32_e32 v156, vcc, s55, v146
	s_mov_b32 s55, 0x21000
	s_nop 0
	v_addc_co_u32_e32 v157, vcc, 0, v147, vcc
	global_load_ushort v158, v[156:157], off
	v_add_co_u32_e32 v156, vcc, s55, v146
	s_mov_b32 s55, 0x31000
	s_nop 0
	v_addc_co_u32_e32 v157, vcc, 0, v147, vcc
	global_load_ushort v159, v[156:157], off
	v_add_co_u32_e32 v156, vcc, s55, v146
	s_mov_b32 s55, 0x41000
	s_nop 0
	v_addc_co_u32_e32 v157, vcc, 0, v147, vcc
	global_load_ushort v160, v[156:157], off
	v_add_co_u32_e32 v156, vcc, s55, v146
	s_mov_b32 s55, 0x51000
	s_nop 0
	v_addc_co_u32_e32 v157, vcc, 0, v147, vcc
	global_load_ushort v161, v[156:157], off
	v_add_co_u32_e32 v156, vcc, s55, v146
	s_mov_b32 s55, 0x61000
	s_nop 0
	v_addc_co_u32_e32 v157, vcc, 0, v147, vcc
	global_load_ushort v162, v[156:157], off
	v_add_co_u32_e32 v156, vcc, s55, v146
	s_mov_b32 s55, 0x71000
	s_nop 0
	v_addc_co_u32_e32 v157, vcc, 0, v147, vcc
	global_load_ushort v163, v[156:157], off
	v_add_co_u32_e32 v156, vcc, s55, v146
	s_mov_b32 s55, 0x801000
	s_nop 0
	v_addc_co_u32_e32 v157, vcc, 0, v147, vcc
	global_load_ushort v164, v[156:157], off
	v_add_co_u32_e32 v156, vcc, s55, v146
	s_cmp_lt_u32 s19, 8
	s_nop 0
	v_addc_co_u32_e32 v157, vcc, 0, v147, vcc
	global_load_ushort v165, v[156:157], off
	v_add_co_u32_e32 v156, vcc, s65, v146
	s_waitcnt vmcnt(0)
	v_lshlrev_b32_e32 v136, 16, v136
	v_addc_co_u32_e32 v157, vcc, 0, v147, vcc
	global_load_ushort v166, v[156:157], off
	v_add_co_u32_e32 v156, vcc, s66, v146
	s_nop 1
	v_addc_co_u32_e32 v157, vcc, 0, v147, vcc
	global_load_ushort v167, v[156:157], off
	v_add_co_u32_e32 v156, vcc, s67, v146
	s_nop 1
	v_addc_co_u32_e32 v157, vcc, 0, v147, vcc
	global_load_ushort v168, v[156:157], off
	v_add_co_u32_e32 v156, vcc, s68, v146
	s_nop 1
	v_addc_co_u32_e32 v157, vcc, 0, v147, vcc
	global_load_ushort v169, v[156:157], off
	v_add_co_u32_e32 v156, vcc, s69, v146
	s_nop 1
	v_addc_co_u32_e32 v157, vcc, 0, v147, vcc
	global_load_ushort v170, v[156:157], off
	v_add_co_u32_e32 v156, vcc, s70, v146
	s_nop 1
	v_addc_co_u32_e32 v157, vcc, 0, v147, vcc
	v_add_co_u32_e32 v146, vcc, s71, v146
	global_load_ushort v171, v[156:157], off
	s_nop 0
	v_addc_co_u32_e32 v147, vcc, 0, v147, vcc
	global_load_ushort v172, v[146:147], off
	s_cselect_b64 vcc, -1, 0
	v_cndmask_b32_e64 v173, 0, 1.0, vcc
	v_mul_f32_e32 v136, v173, v136
	v_cndmask_b32_e64 v157, -v136, v136, s[4:5]
	v_lshlrev_b32_e32 v136, 16, v158
	v_mul_f32_e32 v136, v173, v136
	v_cndmask_b32_e64 v158, -v136, v136, s[4:5]
	v_lshlrev_b32_e32 v136, 16, v159
	v_mul_f32_e32 v136, v173, v136
	v_cndmask_b32_e64 v159, -v136, v136, s[4:5]
	v_lshlrev_b32_e32 v136, 16, v160
	v_mul_f32_e32 v136, v173, v136
	v_cndmask_b32_e64 v160, -v136, v136, s[4:5]
	v_lshlrev_b32_e32 v136, 16, v161
	v_mul_f32_e32 v136, v173, v136
	v_cndmask_b32_e64 v161, -v136, v136, s[4:5]
	v_lshlrev_b32_e32 v136, 16, v162
	v_mul_f32_e32 v136, v173, v136
	v_cndmask_b32_e64 v162, -v136, v136, s[4:5]
	v_lshlrev_b32_e32 v136, 16, v163
	v_mul_f32_e32 v136, v173, v136
	v_or_b32_e32 v146, s62, v148
	s_and_b64 s[60:61], vcc, exec
	v_cndmask_b32_e64 v163, -v136, v136, s[4:5]
	v_lshlrev_b32_e32 v136, 16, v164
	s_cselect_b32 s60, 0, 0x80
	s_add_u32 s19, s8, 0x5000
	v_ashrrev_i32_e32 v147, 31, v146
	v_mul_f32_e32 v136, v173, v136
	s_addc_u32 s55, s9, 0
	v_lshl_add_u64 v[174:175], s[58:59], 0, v[146:147]
	v_cndmask_b32_e64 v164, -v136, v136, s[4:5]
	v_lshlrev_b64 v[182:183], 11, v[174:175]
	v_sub_co_u32_e64 v174, s[8:9], s19, v146
	v_mov_b32_e32 v136, s55
	s_nop 0
	v_subb_co_u32_e64 v175, s[8:9], v136, v147, s[8:9]
	v_lshlrev_b64 v[184:185], 11, v[174:175]
	v_add_f32_e32 v147, v124, v157
	v_add_f32_e32 v174, v125, v158
	v_add_f32_e32 v124, v120, v161
	v_add_f32_e32 v125, v121, v162
	v_add_f32_e32 v175, v126, v159
	v_add_f32_e32 v176, v127, v160
	v_mul_f32_e32 v120, 0x3c800000, v147
	v_mul_f32_e32 v121, 0x3c800000, v174
	s_lshl_b32 s8, s18, 9
	v_cvt_pk_bf16_f32 v178, v120, v121
	v_mul_f32_e32 v120, 0x3c800000, v175
	v_mul_f32_e32 v121, 0x3c800000, v176
	v_add_f32_e32 v126, v122, v163
	v_add_f32_e32 v127, v123, v164
	s_or_b32 s8, s60, s8
	v_cvt_pk_bf16_f32 v179, v120, v121
	v_mul_f32_e32 v120, 0x3c800000, v124
	v_mul_f32_e32 v121, 0x3c800000, v125
	v_or_b32_e32 v122, s8, v150
	v_cvt_pk_bf16_f32 v180, v120, v121
	v_mul_f32_e32 v120, 0x3c800000, v126
	v_mul_f32_e32 v121, 0x3c800000, v127
	v_cvt_pk_bf16_f32 v181, v120, v121
	v_lshl_add_u64 v[120:121], s[10:11], 0, v[182:183]
	v_lshlrev_b32_e32 v136, 1, v122
	v_cndmask_b32_e32 v156, v154, v155, vcc
	v_cmp_lt_i32_e32 vcc, 0, v146
	v_lshl_add_u64 v[122:123], v[120:121], 0, v[136:137]
	v_lshl_add_u64 v[120:121], s[10:11], 0, v[184:185]
	global_store_dwordx4 v[122:123], v[178:181], off
	s_and_saveexec_b64 s[8:9], vcc
	s_cbranch_execz .LBB0_432
	v_mul_f32_e32 v147, v156, v147
	v_mul_f32_e32 v174, v156, v174
	v_mul_f32_e32 v124, v156, v124
	v_mul_f32_e32 v125, v156, v125
	v_cvt_pk_bf16_f32 v174, v147, v174
	v_mul_f32_e32 v147, v156, v175
	v_mul_f32_e32 v175, v156, v176
	v_cvt_pk_bf16_f32 v176, v124, v125
	v_mul_f32_e32 v124, v156, v126
	v_mul_f32_e32 v125, v156, v127
	v_cvt_pk_bf16_f32 v177, v124, v125
	v_lshl_add_u64 v[124:125], v[120:121], 0, v[136:137]
	v_cvt_pk_bf16_f32 v175, v147, v175
	global_store_dwordx4 v[124:125], v[174:177], off
; __device__ __forceinline__ unsigned cvt_pk_bf16(float lo, float hi) { unsigned r; asm("v_cvt_pk_bf16_f32 %0, %1, %2" : "=v"(r) : "v"(lo), "v"(hi)); return r; }
;     __device__ __forceinline__ void operator()(const f32x4 (&acc)[2][2][4][2], const Unit& u, int wr, int wc, int fr, int fq, LAS unsigned char* xs, int wid, int lane) const {
;     ...
;         for (int ai = 0; ai < 2; ++ai)
; #pragma unroll
;             for (int m = 0; m < 4; ++m) {
;                 const int k = k0 + ai * 128 + m * 16 + fr;
; #pragma unroll
;                 for (int bj = 0; bj < 2; ++bj) {
;                     const int col = (2 * u.pn + bj) * 256 + cs * 128 + wc * 32 + 8 * fq;
;                     f32x4 a = acc[ai][bj][m][0], b = acc[ai][bj][m][1];
; #pragma unroll
;                     for (int j = 0; j < 4; ++j) { a[j] += hv[bj][j]; b[j] += hv[bj][4 + j]; }
;                     u32x4 w; w.x = cvt_pk_bf16(a[0] * sc, a[1] * sc); w.y = cvt_pk_bf16(a[2] * sc, a[3] * sc); w.z = cvt_pk_bf16(b[0] * sc, b[1] * sc); w.w = cvt_pk_bf16(b[2] * sc, b[3] * sc);
;                     *(u32x4*)(pq + (tok0 + k) * 1024 + col) = w;
;                     if (k > 0) {
;                         u32x4 w2; w2.x = cvt_pk_bf16(a[0] * scm, a[1] * scm); w2.y = cvt_pk_bf16(a[2] * scm, a[3] * scm); w2.z = cvt_pk_bf16(b[0] * scm, b[1] * scm); w2.w = cvt_pk_bf16(b[2] * scm, b[3] * scm);
;                         *(u32x4*)(pq + (tok0 + S - k) * 1024 + col) = w2;
;                     }
;                 }
.LBB0_432:
	s_or_b64 exec, exec, s[8:9]
	v_lshlrev_b32_e32 v124, 16, v165
	s_waitcnt vmcnt(7)
	v_lshlrev_b32_e32 v125, 16, v166
	v_mul_f32_e32 v124, v173, v124
	v_mul_f32_e32 v125, v173, v125
	s_waitcnt vmcnt(6)
	v_lshlrev_b32_e32 v126, 16, v167
	s_waitcnt vmcnt(5)
	v_lshlrev_b32_e32 v127, 16, v168
	v_cndmask_b32_e64 v124, -v124, v124, s[4:5]
	v_cndmask_b32_e64 v125, -v125, v125, s[4:5]
	v_mul_f32_e32 v126, v173, v126
	v_mul_f32_e32 v127, v173, v127
	s_waitcnt vmcnt(4)
	v_lshlrev_b32_e32 v147, 16, v169
	s_waitcnt vmcnt(3)
	v_lshlrev_b32_e32 v165, 16, v170
	v_cndmask_b32_e64 v126, -v126, v126, s[4:5]
	v_cndmask_b32_e64 v127, -v127, v127, s[4:5]
	v_mul_f32_e32 v147, v173, v147
	v_mul_f32_e32 v165, v173, v165
	s_waitcnt vmcnt(2)
	v_lshlrev_b32_e32 v166, 16, v171
	v_add_f32_e32 v116, v116, v124
	v_add_f32_e32 v117, v117, v125
	v_cndmask_b32_e64 v147, -v147, v147, s[4:5]
	v_cndmask_b32_e64 v165, -v165, v165, s[4:5]
	v_mul_f32_e32 v166, v173, v166
	s_waitcnt vmcnt(1)
	v_lshlrev_b32_e32 v167, 16, v172
	v_add_f32_e32 v118, v118, v126
	v_add_f32_e32 v119, v119, v127
	v_mul_f32_e32 v168, 0x3c800000, v116
	v_mul_f32_e32 v169, 0x3c800000, v117
	v_cndmask_b32_e64 v166, -v166, v166, s[4:5]
	v_mul_f32_e32 v167, v173, v167
	v_add_f32_e32 v112, v112, v147
	v_add_f32_e32 v113, v113, v165
	v_cvt_pk_bf16_f32 v168, v168, v169
	v_mul_f32_e32 v169, 0x3c800000, v118
	v_mul_f32_e32 v170, 0x3c800000, v119
	v_cndmask_b32_e64 v167, -v167, v167, s[4:5]
	v_add_f32_e32 v114, v114, v166
	v_cvt_pk_bf16_f32 v169, v169, v170
	v_mul_f32_e32 v170, 0x3c800000, v112
	v_mul_f32_e32 v171, 0x3c800000, v113
	v_add_f32_e32 v115, v115, v167
	v_cvt_pk_bf16_f32 v170, v170, v171
	v_mul_f32_e32 v171, 0x3c800000, v114
	v_mul_f32_e32 v172, 0x3c800000, v115
	v_cvt_pk_bf16_f32 v171, v171, v172
	global_store_dwordx4 v[122:123], v[168:171], off offset:512
	s_and_saveexec_b64 s[8:9], vcc
	s_cbranch_execz .LBB0_434
	v_mul_f32_e32 v116, v156, v116
	v_mul_f32_e32 v117, v156, v117
	v_cvt_pk_bf16_f32 v116, v116, v117
	v_mul_f32_e32 v117, v156, v118
	v_mul_f32_e32 v118, v156, v119
	v_mul_f32_e32 v112, v156, v112
	v_mul_f32_e32 v113, v156, v113
	v_cvt_pk_bf16_f32 v117, v117, v118
	v_cvt_pk_bf16_f32 v118, v112, v113
	v_mul_f32_e32 v112, v156, v114
	v_mul_f32_e32 v113, v156, v115
	v_cvt_pk_bf16_f32 v119, v112, v113
	v_lshl_add_u64 v[112:113], v[120:121], 0, v[136:137]
	global_store_dwordx4 v[112:113], v[116:119], off offset:512
.LBB0_434:
	s_or_b64 exec, exec, s[8:9]
	v_or_b32_e32 v112, 16, v146
	v_ashrrev_i32_e32 v113, 31, v112
	v_lshl_add_u64 v[114:115], s[58:59], 0, v[112:113]
	v_lshlrev_b64 v[120:121], 11, v[114:115]
	v_mov_b32_e32 v114, s55
	v_sub_co_u32_e32 v112, vcc, s19, v112
	v_add_f32_e32 v115, v111, v160
	s_nop 0
	v_subb_co_u32_e32 v113, vcc, v114, v113, vcc
	v_lshlrev_b64 v[122:123], 11, v[112:113]
	v_add_f32_e32 v112, v108, v157
	v_add_f32_e32 v113, v109, v158
	v_add_f32_e32 v108, v104, v161
	v_add_f32_e32 v109, v105, v162
	v_add_f32_e32 v114, v110, v159
	v_mul_f32_e32 v104, 0x3c800000, v112
	v_mul_f32_e32 v105, 0x3c800000, v113
	v_cvt_pk_bf16_f32 v116, v104, v105
	v_mul_f32_e32 v104, 0x3c800000, v114
	v_mul_f32_e32 v105, 0x3c800000, v115
	v_add_f32_e32 v110, v106, v163
	v_add_f32_e32 v111, v107, v164
	v_cvt_pk_bf16_f32 v117, v104, v105
	v_mul_f32_e32 v104, 0x3c800000, v108
	v_mul_f32_e32 v105, 0x3c800000, v109
	v_cvt_pk_bf16_f32 v118, v104, v105
	v_mul_f32_e32 v104, 0x3c800000, v110
	v_mul_f32_e32 v105, 0x3c800000, v111
	s_cmp_gt_i32 s62, -1
	v_cvt_pk_bf16_f32 v119, v104, v105
	v_lshl_add_u64 v[104:105], s[10:11], 0, v[120:121]
	s_cselect_b64 s[60:61], -1, 0
	s_cmp_lt_i32 s62, 0
	v_lshl_add_u64 v[106:107], v[104:105], 0, v[136:137]
	v_lshl_add_u64 v[104:105], s[10:11], 0, v[122:123]
	global_store_dwordx4 v[106:107], v[116:119], off
	s_cbranch_scc1 .LBB0_436
	v_mul_f32_e32 v112, v156, v112
	v_mul_f32_e32 v113, v156, v113
	v_cvt_pk_bf16_f32 v112, v112, v113
	v_mul_f32_e32 v113, v156, v114
	v_mul_f32_e32 v114, v156, v115
	v_mul_f32_e32 v108, v156, v108
	v_mul_f32_e32 v109, v156, v109
	v_cvt_pk_bf16_f32 v113, v113, v114
	v_cvt_pk_bf16_f32 v114, v108, v109
	v_mul_f32_e32 v108, v156, v110
	v_mul_f32_e32 v109, v156, v111
	v_cvt_pk_bf16_f32 v115, v108, v109
	v_lshl_add_u64 v[108:109], v[104:105], 0, v[136:137]
	global_store_dwordx4 v[108:109], v[112:115], off
.LBB0_436:
	v_add_f32_e32 v100, v100, v124
	v_add_f32_e32 v101, v101, v125
	v_add_f32_e32 v102, v102, v126
	v_add_f32_e32 v103, v103, v127
	v_mul_f32_e32 v108, 0x3c800000, v100
	v_mul_f32_e32 v109, 0x3c800000, v101
	v_add_f32_e32 v96, v96, v147
	v_add_f32_e32 v97, v97, v165
	v_cvt_pk_bf16_f32 v108, v108, v109
	v_mul_f32_e32 v109, 0x3c800000, v102
	v_mul_f32_e32 v110, 0x3c800000, v103
	v_add_f32_e32 v98, v98, v166
	v_add_f32_e32 v99, v99, v167
	v_cvt_pk_bf16_f32 v109, v109, v110
	v_mul_f32_e32 v110, 0x3c800000, v96
	v_mul_f32_e32 v111, 0x3c800000, v97
	v_cvt_pk_bf16_f32 v110, v110, v111
	v_mul_f32_e32 v111, 0x3c800000, v98
	v_mul_f32_e32 v112, 0x3c800000, v99
	v_cvt_pk_bf16_f32 v111, v111, v112
	v_cndmask_b32_e64 v112, 0, 1, s[60:61]
	v_cmp_ne_u32_e64 s[8:9], 1, v112
	s_andn2_b64 vcc, exec, s[60:61]
	global_store_dwordx4 v[106:107], v[108:111], off offset:512
	s_cbranch_vccnz .LBB0_438
	v_mul_f32_e32 v100, v156, v100
	v_mul_f32_e32 v101, v156, v101
	v_cvt_pk_bf16_f32 v100, v100, v101
	v_mul_f32_e32 v101, v156, v102
	v_mul_f32_e32 v102, v156, v103
	v_mul_f32_e32 v96, v156, v96
	v_mul_f32_e32 v97, v156, v97
	v_cvt_pk_bf16_f32 v101, v101, v102
	v_cvt_pk_bf16_f32 v102, v96, v97
	v_mul_f32_e32 v96, v156, v98
	v_mul_f32_e32 v97, v156, v99
	v_cvt_pk_bf16_f32 v103, v96, v97
	v_lshl_add_u64 v[96:97], v[104:105], 0, v[136:137]
	global_store_dwordx4 v[96:97], v[100:103], off offset:512
; __device__ __forceinline__ unsigned cvt_pk_bf16(float lo, float hi) { unsigned r; asm("v_cvt_pk_bf16_f32 %0, %1, %2" : "=v"(r) : "v"(lo), "v"(hi)); return r; }
;     __device__ __forceinline__ void operator()(const f32x4 (&acc)[2][2][4][2], const Unit& u, int wr, int wc, int fr, int fq, LAS unsigned char* xs, int wid, int lane) const {
;     ...
;         for (int ai = 0; ai < 2; ++ai)
; #pragma unroll
;             for (int m = 0; m < 4; ++m) {
;                 const int k = k0 + ai * 128 + m * 16 + fr;
; #pragma unroll
;                 for (int bj = 0; bj < 2; ++bj) {
;                     const int col = (2 * u.pn + bj) * 256 + cs * 128 + wc * 32 + 8 * fq;
;                     f32x4 a = acc[ai][bj][m][0], b = acc[ai][bj][m][1];
; #pragma unroll
;                     for (int j = 0; j < 4; ++j) { a[j] += hv[bj][j]; b[j] += hv[bj][4 + j]; }
;                     u32x4 w; w.x = cvt_pk_bf16(a[0] * sc, a[1] * sc); w.y = cvt_pk_bf16(a[2] * sc, a[3] * sc); w.z = cvt_pk_bf16(b[0] * sc, b[1] * sc); w.w = cvt_pk_bf16(b[2] * sc, b[3] * sc);
;                     *(u32x4*)(pq + (tok0 + k) * 1024 + col) = w;
;                     if (k > 0) {
;                         u32x4 w2; w2.x = cvt_pk_bf16(a[0] * scm, a[1] * scm); w2.y = cvt_pk_bf16(a[2] * scm, a[3] * scm); w2.z = cvt_pk_bf16(b[0] * scm, b[1] * scm); w2.w = cvt_pk_bf16(b[2] * scm, b[3] * scm);
;                         *(u32x4*)(pq + (tok0 + S - k) * 1024 + col) = w2;
;                     }
;                 }
.LBB0_438:
	v_or_b32_e32 v96, 32, v146
	v_ashrrev_i32_e32 v97, 31, v96
	v_lshl_add_u64 v[98:99], s[58:59], 0, v[96:97]
	v_lshlrev_b64 v[104:105], 11, v[98:99]
	v_mov_b32_e32 v98, s55
	v_sub_co_u32_e32 v96, vcc, s19, v96
	v_add_f32_e32 v99, v95, v160
	s_nop 0
	v_subb_co_u32_e32 v97, vcc, v98, v97, vcc
	v_lshlrev_b64 v[106:107], 11, v[96:97]
	v_add_f32_e32 v96, v92, v157
	v_add_f32_e32 v97, v93, v158
	v_add_f32_e32 v92, v88, v161
	v_add_f32_e32 v93, v89, v162
	v_add_f32_e32 v98, v94, v159
	v_mul_f32_e32 v88, 0x3c800000, v96
	v_mul_f32_e32 v89, 0x3c800000, v97
	v_cvt_pk_bf16_f32 v100, v88, v89
	v_mul_f32_e32 v88, 0x3c800000, v98
	v_mul_f32_e32 v89, 0x3c800000, v99
	v_add_f32_e32 v94, v90, v163
	v_add_f32_e32 v95, v91, v164
	v_cvt_pk_bf16_f32 v101, v88, v89
	v_mul_f32_e32 v88, 0x3c800000, v92
	v_mul_f32_e32 v89, 0x3c800000, v93
	v_cvt_pk_bf16_f32 v102, v88, v89
	v_mul_f32_e32 v88, 0x3c800000, v94
	v_mul_f32_e32 v89, 0x3c800000, v95
	v_cvt_pk_bf16_f32 v103, v88, v89
	v_lshl_add_u64 v[88:89], s[10:11], 0, v[104:105]
	v_lshl_add_u64 v[90:91], v[88:89], 0, v[136:137]
	s_and_b64 vcc, exec, s[8:9]
	v_lshl_add_u64 v[88:89], s[10:11], 0, v[106:107]
	global_store_dwordx4 v[90:91], v[100:103], off
	s_cbranch_vccnz .LBB0_440
	v_mul_f32_e32 v96, v156, v96
	v_mul_f32_e32 v97, v156, v97
	v_cvt_pk_bf16_f32 v96, v96, v97
	v_mul_f32_e32 v97, v156, v98
	v_mul_f32_e32 v98, v156, v99
	v_mul_f32_e32 v92, v156, v92
	v_mul_f32_e32 v93, v156, v93
	v_cvt_pk_bf16_f32 v97, v97, v98
	v_cvt_pk_bf16_f32 v98, v92, v93
	v_mul_f32_e32 v92, v156, v94
	v_mul_f32_e32 v93, v156, v95
	v_cvt_pk_bf16_f32 v99, v92, v93
	v_lshl_add_u64 v[92:93], v[88:89], 0, v[136:137]
	global_store_dwordx4 v[92:93], v[96:99], off
.LBB0_440:
	v_add_f32_e32 v84, v84, v124
	v_add_f32_e32 v85, v85, v125
	v_add_f32_e32 v86, v86, v126
	v_add_f32_e32 v87, v87, v127
	v_mul_f32_e32 v92, 0x3c800000, v84
	v_mul_f32_e32 v93, 0x3c800000, v85
	v_add_f32_e32 v80, v80, v147
	v_add_f32_e32 v81, v81, v165
	v_cvt_pk_bf16_f32 v92, v92, v93
	v_mul_f32_e32 v93, 0x3c800000, v86
	v_mul_f32_e32 v94, 0x3c800000, v87
	v_add_f32_e32 v82, v82, v166
	v_cvt_pk_bf16_f32 v93, v93, v94
	v_mul_f32_e32 v94, 0x3c800000, v80
	v_mul_f32_e32 v95, 0x3c800000, v81
	v_add_f32_e32 v83, v83, v167
	v_cvt_pk_bf16_f32 v94, v94, v95
	v_mul_f32_e32 v95, 0x3c800000, v82
	s_and_b64 vcc, exec, s[8:9]
	v_mul_f32_e32 v96, 0x3c800000, v83
	v_cvt_pk_bf16_f32 v95, v95, v96
	global_store_dwordx4 v[90:91], v[92:95], off offset:512
	s_cbranch_vccnz .LBB0_442
	v_mul_f32_e32 v84, v156, v84
	v_mul_f32_e32 v85, v156, v85
	v_cvt_pk_bf16_f32 v84, v84, v85
	v_mul_f32_e32 v85, v156, v86
	v_mul_f32_e32 v86, v156, v87
	v_mul_f32_e32 v80, v156, v80
	v_mul_f32_e32 v81, v156, v81
	v_cvt_pk_bf16_f32 v85, v85, v86
	v_cvt_pk_bf16_f32 v86, v80, v81
	v_mul_f32_e32 v80, v156, v82
	v_mul_f32_e32 v81, v156, v83
	v_cvt_pk_bf16_f32 v87, v80, v81
	v_lshl_add_u64 v[80:81], v[88:89], 0, v[136:137]
	global_store_dwordx4 v[80:81], v[84:87], off offset:512
.LBB0_442:
	v_or_b32_e32 v80, 48, v146
	v_ashrrev_i32_e32 v81, 31, v80
	v_lshl_add_u64 v[82:83], s[58:59], 0, v[80:81]
	v_lshlrev_b64 v[88:89], 11, v[82:83]
	v_mov_b32_e32 v82, s55
	v_sub_co_u32_e32 v80, vcc, s19, v80
	v_add_f32_e32 v83, v79, v160
	s_nop 0
	v_subb_co_u32_e32 v81, vcc, v82, v81, vcc
	v_lshlrev_b64 v[90:91], 11, v[80:81]
	v_add_f32_e32 v80, v76, v157
	v_add_f32_e32 v81, v77, v158
	v_add_f32_e32 v76, v72, v161
	v_add_f32_e32 v77, v73, v162
	v_add_f32_e32 v82, v78, v159
	v_mul_f32_e32 v72, 0x3c800000, v80
	v_mul_f32_e32 v73, 0x3c800000, v81
	v_cvt_pk_bf16_f32 v84, v72, v73
	v_mul_f32_e32 v72, 0x3c800000, v82
	v_mul_f32_e32 v73, 0x3c800000, v83
	v_add_f32_e32 v78, v74, v163
	v_add_f32_e32 v79, v75, v164
	v_cvt_pk_bf16_f32 v85, v72, v73
	v_mul_f32_e32 v72, 0x3c800000, v76
	v_mul_f32_e32 v73, 0x3c800000, v77
	v_cvt_pk_bf16_f32 v86, v72, v73
	v_mul_f32_e32 v72, 0x3c800000, v78
	v_mul_f32_e32 v73, 0x3c800000, v79
	v_cvt_pk_bf16_f32 v87, v72, v73
	v_lshl_add_u64 v[72:73], s[10:11], 0, v[88:89]
	v_lshl_add_u64 v[74:75], v[72:73], 0, v[136:137]
	s_and_b64 vcc, exec, s[8:9]
	v_lshl_add_u64 v[72:73], s[10:11], 0, v[90:91]
	global_store_dwordx4 v[74:75], v[84:87], off
	s_cbranch_vccnz .LBB0_444
	v_mul_f32_e32 v80, v156, v80
	v_mul_f32_e32 v81, v156, v81
	v_cvt_pk_bf16_f32 v80, v80, v81
	v_mul_f32_e32 v81, v156, v82
	v_mul_f32_e32 v82, v156, v83
	v_mul_f32_e32 v76, v156, v76
	v_mul_f32_e32 v77, v156, v77
	v_cvt_pk_bf16_f32 v81, v81, v82
	v_cvt_pk_bf16_f32 v82, v76, v77
	v_mul_f32_e32 v76, v156, v78
	v_mul_f32_e32 v77, v156, v79
	v_cvt_pk_bf16_f32 v83, v76, v77
	v_lshl_add_u64 v[76:77], v[72:73], 0, v[136:137]
	global_store_dwordx4 v[76:77], v[80:83], off
.LBB0_444:
	v_add_f32_e32 v68, v68, v124
	v_add_f32_e32 v69, v69, v125
	v_add_f32_e32 v70, v70, v126
	v_add_f32_e32 v71, v71, v127
	v_mul_f32_e32 v76, 0x3c800000, v68
	v_mul_f32_e32 v77, 0x3c800000, v69
	v_add_f32_e32 v64, v64, v147
	v_add_f32_e32 v65, v65, v165
	v_cvt_pk_bf16_f32 v76, v76, v77
	v_mul_f32_e32 v77, 0x3c800000, v70
	v_mul_f32_e32 v78, 0x3c800000, v71
	v_add_f32_e32 v66, v66, v166
	v_cvt_pk_bf16_f32 v77, v77, v78
	v_mul_f32_e32 v78, 0x3c800000, v64
	v_mul_f32_e32 v79, 0x3c800000, v65
	v_add_f32_e32 v67, v67, v167
	v_cvt_pk_bf16_f32 v78, v78, v79
	v_mul_f32_e32 v79, 0x3c800000, v66
	s_and_b64 vcc, exec, s[8:9]
	v_mul_f32_e32 v80, 0x3c800000, v67
	v_cvt_pk_bf16_f32 v79, v79, v80
	global_store_dwordx4 v[74:75], v[76:79], off offset:512
	s_cbranch_vccnz .LBB0_446
	v_mul_f32_e32 v68, v156, v68
	v_mul_f32_e32 v69, v156, v69
	v_cvt_pk_bf16_f32 v68, v68, v69
	v_mul_f32_e32 v69, v156, v70
	v_mul_f32_e32 v70, v156, v71
	v_mul_f32_e32 v64, v156, v64
	v_mul_f32_e32 v65, v156, v65
	v_cvt_pk_bf16_f32 v69, v69, v70
	v_cvt_pk_bf16_f32 v70, v64, v65
	v_mul_f32_e32 v64, v156, v66
	v_mul_f32_e32 v65, v156, v67
	v_cvt_pk_bf16_f32 v71, v64, v65
	v_lshl_add_u64 v[64:65], v[72:73], 0, v[136:137]
	global_store_dwordx4 v[64:65], v[68:71], off offset:512
; __device__ __forceinline__ unsigned cvt_pk_bf16(float lo, float hi) { unsigned r; asm("v_cvt_pk_bf16_f32 %0, %1, %2" : "=v"(r) : "v"(lo), "v"(hi)); return r; }
;     __device__ __forceinline__ void operator()(const f32x4 (&acc)[2][2][4][2], const Unit& u, int wr, int wc, int fr, int fq, LAS unsigned char* xs, int wid, int lane) const {
;     ...
;         for (int ai = 0; ai < 2; ++ai)
; #pragma unroll
;             for (int m = 0; m < 4; ++m) {
;                 const int k = k0 + ai * 128 + m * 16 + fr;
; #pragma unroll
;                 for (int bj = 0; bj < 2; ++bj) {
;                     const int col = (2 * u.pn + bj) * 256 + cs * 128 + wc * 32 + 8 * fq;
;                     f32x4 a = acc[ai][bj][m][0], b = acc[ai][bj][m][1];
; #pragma unroll
;                     for (int j = 0; j < 4; ++j) { a[j] += hv[bj][j]; b[j] += hv[bj][4 + j]; }
;                     u32x4 w; w.x = cvt_pk_bf16(a[0] * sc, a[1] * sc); w.y = cvt_pk_bf16(a[2] * sc, a[3] * sc); w.z = cvt_pk_bf16(b[0] * sc, b[1] * sc); w.w = cvt_pk_bf16(b[2] * sc, b[3] * sc);
;                     *(u32x4*)(pq + (tok0 + k) * 1024 + col) = w;
;                     if (k > 0) {
;                         u32x4 w2; w2.x = cvt_pk_bf16(a[0] * scm, a[1] * scm); w2.y = cvt_pk_bf16(a[2] * scm, a[3] * scm); w2.z = cvt_pk_bf16(b[0] * scm, b[1] * scm); w2.w = cvt_pk_bf16(b[2] * scm, b[3] * scm);
;                         *(u32x4*)(pq + (tok0 + S - k) * 1024 + col) = w2;
;                     }
;                 }
.LBB0_446:
	v_add_u32_e32 v64, 0x80, v146
	v_ashrrev_i32_e32 v65, 31, v64
	v_lshl_add_u64 v[66:67], s[58:59], 0, v[64:65]
	v_lshlrev_b64 v[72:73], 11, v[66:67]
	v_mov_b32_e32 v66, s55
	v_sub_co_u32_e64 v64, s[8:9], s19, v64
	v_add_f32_e32 v67, v63, v160
	s_nop 0
	v_subb_co_u32_e64 v65, s[8:9], v66, v65, s[8:9]
	v_lshlrev_b64 v[74:75], 11, v[64:65]
	v_add_f32_e32 v64, v60, v157
	v_add_f32_e32 v65, v61, v158
	v_add_f32_e32 v60, v56, v161
	v_add_f32_e32 v61, v57, v162
	v_add_f32_e32 v66, v62, v159
	v_mul_f32_e32 v56, 0x3c800000, v64
	v_mul_f32_e32 v57, 0x3c800000, v65
	v_cvt_pk_bf16_f32 v68, v56, v57
	v_mul_f32_e32 v56, 0x3c800000, v66
	v_mul_f32_e32 v57, 0x3c800000, v67
	v_add_f32_e32 v62, v58, v163
	v_add_f32_e32 v63, v59, v164
	v_cvt_pk_bf16_f32 v69, v56, v57
	v_mul_f32_e32 v56, 0x3c800000, v60
	v_mul_f32_e32 v57, 0x3c800000, v61
	v_cvt_pk_bf16_f32 v70, v56, v57
	v_mul_f32_e32 v56, 0x3c800000, v62
	v_mul_f32_e32 v57, 0x3c800000, v63
	v_cvt_pk_bf16_f32 v71, v56, v57
	v_lshl_add_u64 v[56:57], s[10:11], 0, v[72:73]
	v_cmp_lt_i32_e32 vcc, s72, v146
	v_lshl_add_u64 v[58:59], v[56:57], 0, v[136:137]
	v_lshl_add_u64 v[56:57], s[10:11], 0, v[74:75]
	global_store_dwordx4 v[58:59], v[68:71], off
	s_and_saveexec_b64 s[8:9], vcc
	s_cbranch_execz .LBB0_448
	v_mul_f32_e32 v64, v156, v64
	v_mul_f32_e32 v65, v156, v65
	v_cvt_pk_bf16_f32 v64, v64, v65
	v_mul_f32_e32 v65, v156, v66
	v_mul_f32_e32 v66, v156, v67
	v_mul_f32_e32 v60, v156, v60
	v_mul_f32_e32 v61, v156, v61
	v_cvt_pk_bf16_f32 v65, v65, v66
	v_cvt_pk_bf16_f32 v66, v60, v61
	v_mul_f32_e32 v60, v156, v62
	v_mul_f32_e32 v61, v156, v63
	v_cvt_pk_bf16_f32 v67, v60, v61
	v_lshl_add_u64 v[60:61], v[56:57], 0, v[136:137]
	global_store_dwordx4 v[60:61], v[64:67], off
.LBB0_448:
	s_or_b64 exec, exec, s[8:9]
	v_add_f32_e32 v52, v52, v124
	v_add_f32_e32 v53, v53, v125
	v_add_f32_e32 v54, v54, v126
	v_add_f32_e32 v55, v55, v127
	v_mul_f32_e32 v60, 0x3c800000, v52
	v_mul_f32_e32 v61, 0x3c800000, v53
	v_add_f32_e32 v48, v48, v147
	v_add_f32_e32 v49, v49, v165
	v_cvt_pk_bf16_f32 v60, v60, v61
	v_mul_f32_e32 v61, 0x3c800000, v54
	v_mul_f32_e32 v62, 0x3c800000, v55
	v_add_f32_e32 v50, v50, v166
	v_cvt_pk_bf16_f32 v61, v61, v62
	v_mul_f32_e32 v62, 0x3c800000, v48
	v_mul_f32_e32 v63, 0x3c800000, v49
	v_add_f32_e32 v51, v51, v167
	v_cvt_pk_bf16_f32 v62, v62, v63
	v_mul_f32_e32 v63, 0x3c800000, v50
	v_mul_f32_e32 v64, 0x3c800000, v51
	v_cvt_pk_bf16_f32 v63, v63, v64
	global_store_dwordx4 v[58:59], v[60:63], off offset:512
	s_and_saveexec_b64 s[8:9], vcc
	s_cbranch_execz .LBB0_450
	v_mul_f32_e32 v52, v156, v52
	v_mul_f32_e32 v53, v156, v53
	v_cvt_pk_bf16_f32 v52, v52, v53
	v_mul_f32_e32 v53, v156, v54
	v_mul_f32_e32 v54, v156, v55
	v_mul_f32_e32 v48, v156, v48
	v_mul_f32_e32 v49, v156, v49
	v_cvt_pk_bf16_f32 v53, v53, v54
	v_cvt_pk_bf16_f32 v54, v48, v49
	v_mul_f32_e32 v48, v156, v50
	v_mul_f32_e32 v49, v156, v51
	v_cvt_pk_bf16_f32 v55, v48, v49
	v_lshl_add_u64 v[48:49], v[56:57], 0, v[136:137]
	global_store_dwordx4 v[48:49], v[52:55], off offset:512
.LBB0_450:
	s_or_b64 exec, exec, s[8:9]
	v_add_u32_e32 v48, 0x90, v146
	v_ashrrev_i32_e32 v49, 31, v48
	v_lshl_add_u64 v[50:51], s[58:59], 0, v[48:49]
	v_lshlrev_b64 v[56:57], 11, v[50:51]
	v_mov_b32_e32 v50, s55
	v_sub_co_u32_e64 v48, s[8:9], s19, v48
	v_add_f32_e32 v51, v47, v160
	s_nop 0
	v_subb_co_u32_e64 v49, s[8:9], v50, v49, s[8:9]
	v_lshlrev_b64 v[58:59], 11, v[48:49]
	v_add_f32_e32 v48, v44, v157
	v_add_f32_e32 v49, v45, v158
	v_add_f32_e32 v44, v40, v161
	v_add_f32_e32 v45, v41, v162
	v_add_f32_e32 v50, v46, v159
	v_mul_f32_e32 v40, 0x3c800000, v48
	v_mul_f32_e32 v41, 0x3c800000, v49
	v_cvt_pk_bf16_f32 v52, v40, v41
	v_mul_f32_e32 v40, 0x3c800000, v50
	v_mul_f32_e32 v41, 0x3c800000, v51
	v_add_f32_e32 v46, v42, v163
	v_add_f32_e32 v47, v43, v164
	v_cvt_pk_bf16_f32 v53, v40, v41
	v_mul_f32_e32 v40, 0x3c800000, v44
	v_mul_f32_e32 v41, 0x3c800000, v45
	v_cvt_pk_bf16_f32 v54, v40, v41
	v_mul_f32_e32 v40, 0x3c800000, v46
	v_mul_f32_e32 v41, 0x3c800000, v47
	v_cvt_pk_bf16_f32 v55, v40, v41
	v_lshl_add_u64 v[40:41], s[10:11], 0, v[56:57]
	v_cmp_lt_i32_e32 vcc, s73, v146
	v_lshl_add_u64 v[42:43], v[40:41], 0, v[136:137]
	v_lshl_add_u64 v[40:41], s[10:11], 0, v[58:59]
	global_store_dwordx4 v[42:43], v[52:55], off
	s_and_saveexec_b64 s[8:9], vcc
	s_cbranch_execz .LBB0_452
	v_mul_f32_e32 v48, v156, v48
	v_mul_f32_e32 v49, v156, v49
	v_cvt_pk_bf16_f32 v48, v48, v49
	v_mul_f32_e32 v49, v156, v50
	v_mul_f32_e32 v50, v156, v51
	v_mul_f32_e32 v44, v156, v44
	v_mul_f32_e32 v45, v156, v45
	v_cvt_pk_bf16_f32 v49, v49, v50
	v_cvt_pk_bf16_f32 v50, v44, v45
	v_mul_f32_e32 v44, v156, v46
	v_mul_f32_e32 v45, v156, v47
	v_cvt_pk_bf16_f32 v51, v44, v45
	v_lshl_add_u64 v[44:45], v[40:41], 0, v[136:137]
	global_store_dwordx4 v[44:45], v[48:51], off
.LBB0_452:
	s_or_b64 exec, exec, s[8:9]
	v_add_f32_e32 v36, v36, v124
	v_add_f32_e32 v37, v37, v125
	v_add_f32_e32 v38, v38, v126
	v_add_f32_e32 v39, v39, v127
	v_mul_f32_e32 v44, 0x3c800000, v36
	v_mul_f32_e32 v45, 0x3c800000, v37
	v_add_f32_e32 v32, v32, v147
	v_add_f32_e32 v33, v33, v165
	v_cvt_pk_bf16_f32 v44, v44, v45
	v_mul_f32_e32 v45, 0x3c800000, v38
	v_mul_f32_e32 v46, 0x3c800000, v39
	v_add_f32_e32 v34, v34, v166
	v_cvt_pk_bf16_f32 v45, v45, v46
	v_mul_f32_e32 v46, 0x3c800000, v32
	v_mul_f32_e32 v47, 0x3c800000, v33
	v_add_f32_e32 v35, v35, v167
	v_cvt_pk_bf16_f32 v46, v46, v47
	v_mul_f32_e32 v47, 0x3c800000, v34
	v_mul_f32_e32 v48, 0x3c800000, v35
	v_cvt_pk_bf16_f32 v47, v47, v48
	global_store_dwordx4 v[42:43], v[44:47], off offset:512
	s_and_saveexec_b64 s[8:9], vcc
	s_cbranch_execz .LBB0_454
	v_mul_f32_e32 v36, v156, v36
	v_mul_f32_e32 v37, v156, v37
	v_cvt_pk_bf16_f32 v36, v36, v37
	v_mul_f32_e32 v37, v156, v38
	v_mul_f32_e32 v38, v156, v39
	v_mul_f32_e32 v32, v156, v32
	v_mul_f32_e32 v33, v156, v33
	v_cvt_pk_bf16_f32 v37, v37, v38
	v_cvt_pk_bf16_f32 v38, v32, v33
	v_mul_f32_e32 v32, v156, v34
	v_mul_f32_e32 v33, v156, v35
	v_cvt_pk_bf16_f32 v39, v32, v33
	v_lshl_add_u64 v[32:33], v[40:41], 0, v[136:137]
	global_store_dwordx4 v[32:33], v[36:39], off offset:512
; __device__ __forceinline__ unsigned cvt_pk_bf16(float lo, float hi) { unsigned r; asm("v_cvt_pk_bf16_f32 %0, %1, %2" : "=v"(r) : "v"(lo), "v"(hi)); return r; }
;     __device__ __forceinline__ void operator()(const f32x4 (&acc)[2][2][4][2], const Unit& u, int wr, int wc, int fr, int fq, LAS unsigned char* xs, int wid, int lane) const {
;     ...
;         for (int ai = 0; ai < 2; ++ai)
; #pragma unroll
;             for (int m = 0; m < 4; ++m) {
;                 const int k = k0 + ai * 128 + m * 16 + fr;
; #pragma unroll
;                 for (int bj = 0; bj < 2; ++bj) {
;                     const int col = (2 * u.pn + bj) * 256 + cs * 128 + wc * 32 + 8 * fq;
;                     f32x4 a = acc[ai][bj][m][0], b = acc[ai][bj][m][1];
; #pragma unroll
;                     for (int j = 0; j < 4; ++j) { a[j] += hv[bj][j]; b[j] += hv[bj][4 + j]; }
;                     u32x4 w; w.x = cvt_pk_bf16(a[0] * sc, a[1] * sc); w.y = cvt_pk_bf16(a[2] * sc, a[3] * sc); w.z = cvt_pk_bf16(b[0] * sc, b[1] * sc); w.w = cvt_pk_bf16(b[2] * sc, b[3] * sc);
;                     *(u32x4*)(pq + (tok0 + k) * 1024 + col) = w;
;                     if (k > 0) {
;                         u32x4 w2; w2.x = cvt_pk_bf16(a[0] * scm, a[1] * scm); w2.y = cvt_pk_bf16(a[2] * scm, a[3] * scm); w2.z = cvt_pk_bf16(b[0] * scm, b[1] * scm); w2.w = cvt_pk_bf16(b[2] * scm, b[3] * scm);
;                         *(u32x4*)(pq + (tok0 + S - k) * 1024 + col) = w2;
;                     }
;                 }
.LBB0_454:
	s_or_b64 exec, exec, s[8:9]
	v_add_u32_e32 v32, 0xa0, v146
	v_ashrrev_i32_e32 v33, 31, v32
	v_lshl_add_u64 v[34:35], s[58:59], 0, v[32:33]
	v_lshlrev_b64 v[40:41], 11, v[34:35]
	v_mov_b32_e32 v34, s55
	v_sub_co_u32_e64 v32, s[8:9], s19, v32
	v_add_f32_e32 v35, v31, v160
	s_nop 0
	v_subb_co_u32_e64 v33, s[8:9], v34, v33, s[8:9]
	v_lshlrev_b64 v[42:43], 11, v[32:33]
	v_add_f32_e32 v32, v28, v157
	v_add_f32_e32 v33, v29, v158
	v_add_f32_e32 v28, v24, v161
	v_add_f32_e32 v29, v25, v162
	v_add_f32_e32 v34, v30, v159
	v_mul_f32_e32 v24, 0x3c800000, v32
	v_mul_f32_e32 v25, 0x3c800000, v33
	v_cvt_pk_bf16_f32 v36, v24, v25
	v_mul_f32_e32 v24, 0x3c800000, v34
	v_mul_f32_e32 v25, 0x3c800000, v35
	v_add_f32_e32 v30, v26, v163
	v_add_f32_e32 v31, v27, v164
	v_cvt_pk_bf16_f32 v37, v24, v25
	v_mul_f32_e32 v24, 0x3c800000, v28
	v_mul_f32_e32 v25, 0x3c800000, v29
	v_cvt_pk_bf16_f32 v38, v24, v25
	v_mul_f32_e32 v24, 0x3c800000, v30
	v_mul_f32_e32 v25, 0x3c800000, v31
	v_cvt_pk_bf16_f32 v39, v24, v25
	v_lshl_add_u64 v[24:25], s[10:11], 0, v[40:41]
	v_cmp_lt_i32_e32 vcc, s74, v146
	v_lshl_add_u64 v[26:27], v[24:25], 0, v[136:137]
	v_lshl_add_u64 v[24:25], s[10:11], 0, v[42:43]
	global_store_dwordx4 v[26:27], v[36:39], off
	s_and_saveexec_b64 s[8:9], vcc
	s_cbranch_execz .LBB0_456
	v_mul_f32_e32 v32, v156, v32
	v_mul_f32_e32 v33, v156, v33
	v_cvt_pk_bf16_f32 v32, v32, v33
	v_mul_f32_e32 v33, v156, v34
	v_mul_f32_e32 v34, v156, v35
	v_mul_f32_e32 v28, v156, v28
	v_mul_f32_e32 v29, v156, v29
	v_cvt_pk_bf16_f32 v33, v33, v34
	v_cvt_pk_bf16_f32 v34, v28, v29
	v_mul_f32_e32 v28, v156, v30
	v_mul_f32_e32 v29, v156, v31
	v_cvt_pk_bf16_f32 v35, v28, v29
	v_lshl_add_u64 v[28:29], v[24:25], 0, v[136:137]
	global_store_dwordx4 v[28:29], v[32:35], off
.LBB0_456:
	s_or_b64 exec, exec, s[8:9]
	v_add_f32_e32 v20, v20, v124
	v_add_f32_e32 v21, v21, v125
	v_add_f32_e32 v22, v22, v126
	v_add_f32_e32 v23, v23, v127
	v_mul_f32_e32 v28, 0x3c800000, v20
	v_mul_f32_e32 v29, 0x3c800000, v21
	v_add_f32_e32 v16, v16, v147
	v_add_f32_e32 v17, v17, v165
	v_cvt_pk_bf16_f32 v28, v28, v29
	v_mul_f32_e32 v29, 0x3c800000, v22
	v_mul_f32_e32 v30, 0x3c800000, v23
	v_add_f32_e32 v18, v18, v166
	v_cvt_pk_bf16_f32 v29, v29, v30
	v_mul_f32_e32 v30, 0x3c800000, v16
	v_mul_f32_e32 v31, 0x3c800000, v17
	v_add_f32_e32 v19, v19, v167
	v_cvt_pk_bf16_f32 v30, v30, v31
	v_mul_f32_e32 v31, 0x3c800000, v18
	v_mul_f32_e32 v32, 0x3c800000, v19
	v_cvt_pk_bf16_f32 v31, v31, v32
	global_store_dwordx4 v[26:27], v[28:31], off offset:512
	s_and_saveexec_b64 s[8:9], vcc
	s_cbranch_execz .LBB0_458
	v_mul_f32_e32 v20, v156, v20
	v_mul_f32_e32 v21, v156, v21
	v_cvt_pk_bf16_f32 v20, v20, v21
	v_mul_f32_e32 v21, v156, v22
	v_mul_f32_e32 v22, v156, v23
	v_mul_f32_e32 v16, v156, v16
	v_mul_f32_e32 v17, v156, v17
	v_cvt_pk_bf16_f32 v21, v21, v22
	v_cvt_pk_bf16_f32 v22, v16, v17
	v_mul_f32_e32 v16, v156, v18
	v_mul_f32_e32 v17, v156, v19
	v_cvt_pk_bf16_f32 v23, v16, v17
	v_lshl_add_u64 v[16:17], v[24:25], 0, v[136:137]
	global_store_dwordx4 v[16:17], v[20:23], off offset:512
.LBB0_458:
	s_or_b64 exec, exec, s[8:9]
	v_add_u32_e32 v16, 0xb0, v146
	v_ashrrev_i32_e32 v17, 31, v16
	v_lshl_add_u64 v[18:19], s[58:59], 0, v[16:17]
	v_lshlrev_b64 v[24:25], 11, v[18:19]
	v_mov_b32_e32 v18, s55
	v_sub_co_u32_e64 v16, s[8:9], s19, v16
	v_add_f32_e32 v19, v15, v160
	s_nop 0
	v_subb_co_u32_e64 v17, s[8:9], v18, v17, s[8:9]
	v_lshlrev_b64 v[26:27], 11, v[16:17]
	v_add_f32_e32 v16, v12, v157
	v_add_f32_e32 v17, v13, v158
	v_add_f32_e32 v12, v8, v161
	v_add_f32_e32 v13, v9, v162
	v_add_f32_e32 v18, v14, v159
	v_mul_f32_e32 v8, 0x3c800000, v16
	v_mul_f32_e32 v9, 0x3c800000, v17
	v_cvt_pk_bf16_f32 v20, v8, v9
	v_mul_f32_e32 v8, 0x3c800000, v18
	v_mul_f32_e32 v9, 0x3c800000, v19
	v_add_f32_e32 v14, v10, v163
	v_add_f32_e32 v15, v11, v164
	v_cvt_pk_bf16_f32 v21, v8, v9
	v_mul_f32_e32 v8, 0x3c800000, v12
	v_mul_f32_e32 v9, 0x3c800000, v13
	v_cvt_pk_bf16_f32 v22, v8, v9
	v_mul_f32_e32 v8, 0x3c800000, v14
	v_mul_f32_e32 v9, 0x3c800000, v15
	v_cvt_pk_bf16_f32 v23, v8, v9
	v_lshl_add_u64 v[8:9], s[10:11], 0, v[24:25]
	v_cmp_lt_i32_e32 vcc, s75, v146
	v_lshl_add_u64 v[10:11], v[8:9], 0, v[136:137]
	v_lshl_add_u64 v[8:9], s[10:11], 0, v[26:27]
	global_store_dwordx4 v[10:11], v[20:23], off
	s_and_saveexec_b64 s[8:9], vcc
	s_cbranch_execz .LBB0_460
	v_mul_f32_e32 v16, v156, v16
	v_mul_f32_e32 v17, v156, v17
	v_cvt_pk_bf16_f32 v16, v16, v17
	v_mul_f32_e32 v17, v156, v18
	v_mul_f32_e32 v18, v156, v19
	v_mul_f32_e32 v12, v156, v12
	v_mul_f32_e32 v13, v156, v13
	v_cvt_pk_bf16_f32 v17, v17, v18
	v_cvt_pk_bf16_f32 v18, v12, v13
	v_mul_f32_e32 v12, v156, v14
	v_mul_f32_e32 v13, v156, v15
	v_cvt_pk_bf16_f32 v19, v12, v13
	v_lshl_add_u64 v[12:13], v[8:9], 0, v[136:137]
	global_store_dwordx4 v[12:13], v[16:19], off
.LBB0_460:
	s_or_b64 exec, exec, s[8:9]
	v_add_f32_e32 v4, v4, v124
	v_add_f32_e32 v5, v5, v125
	v_add_f32_e32 v6, v6, v126
	v_add_f32_e32 v7, v7, v127
	v_mul_f32_e32 v12, 0x3c800000, v4
	v_mul_f32_e32 v13, 0x3c800000, v5
	v_add_f32_e32 v0, v0, v147
	v_add_f32_e32 v1, v1, v165
	v_cvt_pk_bf16_f32 v12, v12, v13
	v_mul_f32_e32 v13, 0x3c800000, v6
	v_mul_f32_e32 v14, 0x3c800000, v7
	v_add_f32_e32 v2, v2, v166
	v_cvt_pk_bf16_f32 v13, v13, v14
	v_mul_f32_e32 v14, 0x3c800000, v0
	v_mul_f32_e32 v15, 0x3c800000, v1
	v_add_f32_e32 v3, v3, v167
	v_cvt_pk_bf16_f32 v14, v14, v15
	v_mul_f32_e32 v15, 0x3c800000, v2
	v_mul_f32_e32 v16, 0x3c800000, v3
	v_cvt_pk_bf16_f32 v15, v15, v16
	global_store_dwordx4 v[10:11], v[12:15], off offset:512
	s_and_saveexec_b64 s[8:9], vcc
	s_cbranch_execz .LBB0_462
	v_mul_f32_e32 v4, v156, v4
	v_mul_f32_e32 v5, v156, v5
	v_cvt_pk_bf16_f32 v4, v4, v5
	v_mul_f32_e32 v5, v156, v6
	v_mul_f32_e32 v6, v156, v7
	v_mul_f32_e32 v0, v156, v0
	v_mul_f32_e32 v1, v156, v1
	v_cvt_pk_bf16_f32 v5, v5, v6
	v_cvt_pk_bf16_f32 v6, v0, v1
	v_mul_f32_e32 v0, v156, v2
	v_mul_f32_e32 v1, v156, v3
	v_cvt_pk_bf16_f32 v7, v0, v1
	v_lshl_add_u64 v[0:1], v[8:9], 0, v[136:137]
	global_store_dwordx4 v[0:1], v[4:7], off offset:512

; __device__ __forceinline__ unsigned cvt_pk_bf16(float lo, float hi) { unsigned r; asm("v_cvt_pk_bf16_f32 %0, %1, %2" : "=v"(r) : "v"(lo), "v"(hi)); return r; }
;     __device__ __forceinline__ void operator()(const f32x4 (&acc)[2][2][4][2], const Unit& u, int wr, int wc, int fr, int fq, LAS unsigned char* xs, int wid, int lane) const {
;         const int S = lng ? 4096 : 2048, hp = lng ? 8 : 4;
;         const int cs = u.pm >= hp, k0 = (u.pm - hp * cs) * 256 + wr * 64;
;         const size_t tok0 = lng ? (size_t)TP + (size_t)u.aux * 4096 : (size_t)u.aux * 2048;
;         const float sc = lng ? 0.015625f : 0.02209708691207961f;
;         const float scm = cs ? -sc : sc;
;         float hv[2][8];
;         const float csm = cs ? 0.f : 1.f;
; #pragma unroll
;         for (int bj = 0; bj < 2; ++bj)
; #pragma unroll
;             for (int e = 0; e < 8; ++e) {
;                 const unsigned short h = ft[(size_t)(u.pn * 256 + bj * 128 + wc * 32 + 8 * fq + e) * T + tok0 + S / 2];
;                 const float v = __builtin_bit_cast(float, (unsigned)h << 16) * csm;
;                 hv[bj][e] = (fr & 1) ? -v : v;
;             }
; #pragma unroll
;         for (int ai = 0; ai < 2; ++ai)
; #pragma unroll
;             for (int m = 0; m < 4; ++m) {
;                 const int k = k0 + ai * 128 + m * 16 + fr;
; #pragma unroll
;                 for (int bj = 0; bj < 2; ++bj) {
;                     const int col = (2 * u.pn + bj) * 256 + cs * 128 + wc * 32 + 8 * fq;
;                     f32x4 a = acc[ai][bj][m][0], b = acc[ai][bj][m][1];
; #pragma unroll
;                     for (int j = 0; j < 4; ++j) { a[j] += hv[bj][j]; b[j] += hv[bj][4 + j]; }
;                     u32x4 w; w.x = cvt_pk_bf16(a[0] * sc, a[1] * sc); w.y = cvt_pk_bf16(a[2] * sc, a[3] * sc); w.z = cvt_pk_bf16(b[0] * sc, b[1] * sc); w.w = cvt_pk_bf16(b[2] * sc, b[3] * sc);
;                     *(u32x4*)(pq + (tok0 + k) * 1024 + col) = w;
;                     if (k > 0) {
;                         u32x4 w2; w2.x = cvt_pk_bf16(a[0] * scm, a[1] * scm); w2.y = cvt_pk_bf16(a[2] * scm, a[3] * scm); w2.z = cvt_pk_bf16(b[0] * scm, b[1] * scm); w2.w = cvt_pk_bf16(b[2] * scm, b[3] * scm);
;                         *(u32x4*)(pq + (tok0 + S - k) * 1024 + col) = w2;
;                     }
;                 }
.LBB0_480:
	s_lshl_b32 s8, s18, 8
	s_and_b32 s57, s8, 0x300
	s_ashr_i32 s63, s62, 31
	s_add_i32 s57, s57, s29
	s_lshl_b64 s[60:61], s[62:63], 11
	s_lshl_b64 s[8:9], s[62:63], 12
	s_add_u32 s8, s44, s8
	v_lshlrev_b32_e32 v136, 16, v150
	s_addc_u32 s9, s45, s9
	v_lshl_or_b32 v136, s0, 24, v136
	v_lshl_add_u64 v[146:147], s[8:9], 0, v[136:137]
	global_load_ushort v136, v136, s[8:9] offset:2048
	s_cmp_lt_u32 s18, 4
	s_cselect_b64 vcc, -1, 0
	s_mov_b32 s8, 0x10000
	v_cndmask_b32_e64 v167, 0, 1.0, vcc
	v_add_co_u32_e64 v158, s[8:9], s8, v146
	s_waitcnt vmcnt(0)
	v_lshlrev_b32_e32 v136, 16, v136
	v_mul_f32_e32 v136, v167, v136
	v_addc_co_u32_e64 v159, s[8:9], 0, v147, s[8:9]
	v_cndmask_b32_e64 v156, -v136, v136, s[4:5]
	global_load_ushort v136, v[158:159], off offset:2048
	s_mov_b32 s8, 0x20000
	v_add_co_u32_e64 v158, s[8:9], s8, v146
	s_waitcnt vmcnt(0)
	v_lshlrev_b32_e32 v136, 16, v136
	v_mul_f32_e32 v136, v167, v136
	v_addc_co_u32_e64 v159, s[8:9], 0, v147, s[8:9]
	v_cndmask_b32_e64 v157, -v136, v136, s[4:5]
	global_load_ushort v136, v[158:159], off offset:2048
	s_mov_b32 s8, 0x30000
	v_add_co_u32_e64 v160, s[8:9], s8, v146
	s_waitcnt vmcnt(0)
	v_lshlrev_b32_e32 v136, 16, v136
	v_mul_f32_e32 v136, v167, v136
	v_addc_co_u32_e64 v161, s[8:9], 0, v147, s[8:9]
	v_cndmask_b32_e64 v158, -v136, v136, s[4:5]
	global_load_ushort v136, v[160:161], off offset:2048
	s_mov_b32 s8, 0x40000
	v_add_co_u32_e64 v160, s[8:9], s8, v146
	s_waitcnt vmcnt(0)
	v_lshlrev_b32_e32 v136, 16, v136
	v_mul_f32_e32 v136, v167, v136
	v_addc_co_u32_e64 v161, s[8:9], 0, v147, s[8:9]
	v_cndmask_b32_e64 v159, -v136, v136, s[4:5]
	global_load_ushort v136, v[160:161], off offset:2048
	s_mov_b32 s8, 0x50000
	v_add_co_u32_e64 v162, s[8:9], s8, v146
	v_add_f32_e32 v176, v127, v159
	s_nop 0
	v_addc_co_u32_e64 v163, s[8:9], 0, v147, s[8:9]
	s_mov_b32 s8, 0x60000
	s_waitcnt vmcnt(0)
	v_lshlrev_b32_e32 v136, 16, v136
	v_mul_f32_e32 v136, v167, v136
	v_cndmask_b32_e64 v160, -v136, v136, s[4:5]
	global_load_ushort v136, v[162:163], off offset:2048
	v_add_co_u32_e64 v162, s[8:9], s8, v146
	s_waitcnt vmcnt(0)
	v_lshlrev_b32_e32 v136, 16, v136
	v_mul_f32_e32 v136, v167, v136
	v_addc_co_u32_e64 v163, s[8:9], 0, v147, s[8:9]
	v_cndmask_b32_e64 v161, -v136, v136, s[4:5]
	global_load_ushort v136, v[162:163], off offset:2048
	s_mov_b32 s8, 0x70000
	v_add_co_u32_e64 v164, s[8:9], s8, v146
	s_waitcnt vmcnt(0)
	v_lshlrev_b32_e32 v136, 16, v136
	v_addc_co_u32_e64 v165, s[8:9], 0, v147, s[8:9]
	v_mul_f32_e32 v136, v167, v136
	s_mov_b32 s8, 0x800000
	v_cndmask_b32_e64 v162, -v136, v136, s[4:5]
	global_load_ushort v136, v[164:165], off offset:2048
	v_add_co_u32_e64 v164, s[8:9], s8, v146
	s_waitcnt vmcnt(0)
	v_lshlrev_b32_e32 v136, 16, v136
	v_addc_co_u32_e64 v165, s[8:9], 0, v147, s[8:9]
	s_mov_b32 s8, 0x810000
	s_nop 0
	v_add_co_u32_e64 v168, s[8:9], s8, v146
	global_load_ushort v165, v[164:165], off offset:2048
	s_nop 0
	v_addc_co_u32_e64 v169, s[8:9], 0, v147, s[8:9]
	s_mov_b32 s8, 0x820000
	global_load_ushort v166, v[168:169], off offset:2048
	v_add_co_u32_e64 v168, s[8:9], s8, v146
	v_mul_f32_e32 v136, v167, v136
	s_nop 0
	v_addc_co_u32_e64 v169, s[8:9], 0, v147, s[8:9]
	s_mov_b32 s8, 0x830000
	s_nop 0
	v_add_co_u32_e64 v170, s[8:9], s8, v146
	global_load_ushort v168, v[168:169], off offset:2048
	s_nop 0
	v_addc_co_u32_e64 v171, s[8:9], 0, v147, s[8:9]
	s_mov_b32 s8, 0x840000
	global_load_ushort v169, v[170:171], off offset:2048
	v_add_co_u32_e64 v170, s[8:9], s8, v146
	v_cndmask_b32_e64 v163, -v136, v136, s[4:5]
	s_nop 0
	v_addc_co_u32_e64 v171, s[8:9], 0, v147, s[8:9]
	s_mov_b32 s8, 0x850000
	s_nop 0
	v_add_co_u32_e64 v172, s[8:9], s8, v146
	global_load_ushort v170, v[170:171], off offset:2048
	s_nop 0
	v_addc_co_u32_e64 v173, s[8:9], 0, v147, s[8:9]
	s_mov_b32 s8, 0x860000
	global_load_ushort v171, v[172:173], off offset:2048
	v_add_co_u32_e64 v172, s[8:9], s8, v146
	v_add_f32_e32 v127, v123, v163
	s_nop 0
	v_addc_co_u32_e64 v173, s[8:9], 0, v147, s[8:9]
	v_add_co_u32_e64 v146, s[8:9], s67, v146
	global_load_ushort v172, v[172:173], off offset:2048
	s_nop 0
	v_addc_co_u32_e64 v147, s[8:9], 0, v147, s[8:9]
	global_load_ushort v173, v[146:147], off offset:2048
	v_or_b32_e32 v146, s57, v148
	s_and_b64 s[8:9], vcc, exec
	s_cselect_b32 s62, 0, 0x80
	s_add_u32 s18, s60, 0x800
	v_ashrrev_i32_e32 v147, 31, v146
	s_addc_u32 s19, s61, 0
	v_lshl_add_u64 v[174:175], s[60:61], 0, v[146:147]
	v_lshlrev_b64 v[182:183], 11, v[174:175]
	v_sub_co_u32_e64 v174, s[8:9], s18, v146
	v_mov_b32_e32 v136, s19
	s_nop 0
	v_subb_co_u32_e64 v175, s[8:9], v136, v147, s[8:9]
	v_lshlrev_b64 v[184:185], 11, v[174:175]
	v_add_f32_e32 v147, v124, v156
	v_add_f32_e32 v174, v125, v157
	v_add_f32_e32 v124, v120, v160
	v_add_f32_e32 v125, v121, v161
	v_add_f32_e32 v175, v126, v158
	v_mul_f32_e32 v120, 0x3cb504f3, v147
	v_mul_f32_e32 v121, 0x3cb504f3, v174
	s_lshl_b32 s0, s0, 9
	v_cvt_pk_bf16_f32 v178, v120, v121
	v_mul_f32_e32 v120, 0x3cb504f3, v175
	v_mul_f32_e32 v121, 0x3cb504f3, v176
	v_add_f32_e32 v126, v122, v162
	s_or_b32 s0, s62, s0
	v_cvt_pk_bf16_f32 v179, v120, v121
	v_mul_f32_e32 v120, 0x3cb504f3, v124
	v_mul_f32_e32 v121, 0x3cb504f3, v125
	v_or_b32_e32 v122, s0, v150
	v_cvt_pk_bf16_f32 v180, v120, v121
	v_mul_f32_e32 v120, 0x3cb504f3, v126
	v_mul_f32_e32 v121, 0x3cb504f3, v127
	v_cvt_pk_bf16_f32 v181, v120, v121
	v_lshl_add_u64 v[120:121], s[10:11], 0, v[182:183]
	v_lshlrev_b32_e32 v136, 1, v122
	v_cndmask_b32_e32 v164, v154, v155, vcc
	v_cmp_lt_i32_e32 vcc, 0, v146
	v_lshl_add_u64 v[122:123], v[120:121], 0, v[136:137]
	v_lshl_add_u64 v[120:121], s[10:11], 0, v[184:185]
	global_store_dwordx4 v[122:123], v[178:181], off
	s_and_saveexec_b64 s[8:9], vcc
	s_cbranch_execz .LBB0_482
	v_mul_f32_e32 v147, v164, v147
	v_mul_f32_e32 v174, v164, v174
	v_mul_f32_e32 v124, v164, v124
	v_mul_f32_e32 v125, v164, v125
	v_cvt_pk_bf16_f32 v174, v147, v174
	v_mul_f32_e32 v147, v164, v175
	v_mul_f32_e32 v175, v164, v176
	v_cvt_pk_bf16_f32 v176, v124, v125
	v_mul_f32_e32 v124, v164, v126
	v_mul_f32_e32 v125, v164, v127
	v_cvt_pk_bf16_f32 v177, v124, v125
	v_lshl_add_u64 v[124:125], v[120:121], 0, v[136:137]
	v_cvt_pk_bf16_f32 v175, v147, v175
	global_store_dwordx4 v[124:125], v[174:177], off
; __device__ __forceinline__ unsigned cvt_pk_bf16(float lo, float hi) { unsigned r; asm("v_cvt_pk_bf16_f32 %0, %1, %2" : "=v"(r) : "v"(lo), "v"(hi)); return r; }
;     __device__ __forceinline__ void operator()(const f32x4 (&acc)[2][2][4][2], const Unit& u, int wr, int wc, int fr, int fq, LAS unsigned char* xs, int wid, int lane) const {
;     ...
;         for (int ai = 0; ai < 2; ++ai)
; #pragma unroll
;             for (int m = 0; m < 4; ++m) {
;                 const int k = k0 + ai * 128 + m * 16 + fr;
; #pragma unroll
;                 for (int bj = 0; bj < 2; ++bj) {
;                     const int col = (2 * u.pn + bj) * 256 + cs * 128 + wc * 32 + 8 * fq;
;                     f32x4 a = acc[ai][bj][m][0], b = acc[ai][bj][m][1];
; #pragma unroll
;                     for (int j = 0; j < 4; ++j) { a[j] += hv[bj][j]; b[j] += hv[bj][4 + j]; }
;                     u32x4 w; w.x = cvt_pk_bf16(a[0] * sc, a[1] * sc); w.y = cvt_pk_bf16(a[2] * sc, a[3] * sc); w.z = cvt_pk_bf16(b[0] * sc, b[1] * sc); w.w = cvt_pk_bf16(b[2] * sc, b[3] * sc);
;                     *(u32x4*)(pq + (tok0 + k) * 1024 + col) = w;
;                     if (k > 0) {
;                         u32x4 w2; w2.x = cvt_pk_bf16(a[0] * scm, a[1] * scm); w2.y = cvt_pk_bf16(a[2] * scm, a[3] * scm); w2.z = cvt_pk_bf16(b[0] * scm, b[1] * scm); w2.w = cvt_pk_bf16(b[2] * scm, b[3] * scm);
;                         *(u32x4*)(pq + (tok0 + S - k) * 1024 + col) = w2;
;                     }
;                 }
.LBB0_482:
	s_or_b64 exec, exec, s[8:9]
	s_waitcnt vmcnt(8)
	v_lshlrev_b32_e32 v124, 16, v165
	s_waitcnt vmcnt(7)
	v_lshlrev_b32_e32 v125, 16, v166
	v_mul_f32_e32 v124, v167, v124
	v_mul_f32_e32 v125, v167, v125
	s_waitcnt vmcnt(6)
	v_lshlrev_b32_e32 v126, 16, v168
	s_waitcnt vmcnt(5)
	v_lshlrev_b32_e32 v127, 16, v169
	v_cndmask_b32_e64 v124, -v124, v124, s[4:5]
	v_cndmask_b32_e64 v125, -v125, v125, s[4:5]
	v_mul_f32_e32 v126, v167, v126
	v_mul_f32_e32 v127, v167, v127
	s_waitcnt vmcnt(4)
	v_lshlrev_b32_e32 v147, 16, v170
	s_waitcnt vmcnt(3)
	v_lshlrev_b32_e32 v165, 16, v171
	v_cndmask_b32_e64 v126, -v126, v126, s[4:5]
	v_cndmask_b32_e64 v127, -v127, v127, s[4:5]
	v_mul_f32_e32 v147, v167, v147
	v_mul_f32_e32 v165, v167, v165
	s_waitcnt vmcnt(2)
	v_lshlrev_b32_e32 v166, 16, v172
	s_waitcnt vmcnt(1)
	v_lshlrev_b32_e32 v168, 16, v173
	v_add_f32_e32 v116, v116, v124
	v_add_f32_e32 v117, v117, v125
	v_cndmask_b32_e64 v147, -v147, v147, s[4:5]
	v_cndmask_b32_e64 v165, -v165, v165, s[4:5]
	v_mul_f32_e32 v166, v167, v166
	v_mul_f32_e32 v167, v167, v168
	v_add_f32_e32 v118, v118, v126
	v_add_f32_e32 v119, v119, v127
	v_mul_f32_e32 v168, 0x3cb504f3, v116
	v_mul_f32_e32 v169, 0x3cb504f3, v117
	v_cndmask_b32_e64 v166, -v166, v166, s[4:5]
	v_add_f32_e32 v112, v112, v147
	v_add_f32_e32 v113, v113, v165
	v_cvt_pk_bf16_f32 v168, v168, v169
	v_mul_f32_e32 v169, 0x3cb504f3, v118
	v_mul_f32_e32 v170, 0x3cb504f3, v119
	v_cndmask_b32_e64 v167, -v167, v167, s[4:5]
	v_add_f32_e32 v114, v114, v166
	v_cvt_pk_bf16_f32 v169, v169, v170
	v_mul_f32_e32 v170, 0x3cb504f3, v112
	v_mul_f32_e32 v171, 0x3cb504f3, v113
	v_add_f32_e32 v115, v115, v167
	v_cvt_pk_bf16_f32 v170, v170, v171
	v_mul_f32_e32 v171, 0x3cb504f3, v114
	v_mul_f32_e32 v172, 0x3cb504f3, v115
	v_cvt_pk_bf16_f32 v171, v171, v172
	global_store_dwordx4 v[122:123], v[168:171], off offset:512
	s_and_saveexec_b64 s[8:9], vcc
	s_cbranch_execz .LBB0_484
	v_mul_f32_e32 v116, v164, v116
	v_mul_f32_e32 v117, v164, v117
	v_cvt_pk_bf16_f32 v116, v116, v117
	v_mul_f32_e32 v117, v164, v118
	v_mul_f32_e32 v118, v164, v119
	v_mul_f32_e32 v112, v164, v112
	v_mul_f32_e32 v113, v164, v113
	v_cvt_pk_bf16_f32 v117, v117, v118
	v_cvt_pk_bf16_f32 v118, v112, v113
	v_mul_f32_e32 v112, v164, v114
	v_mul_f32_e32 v113, v164, v115
	v_cvt_pk_bf16_f32 v119, v112, v113
	v_lshl_add_u64 v[112:113], v[120:121], 0, v[136:137]
	global_store_dwordx4 v[112:113], v[116:119], off offset:512
.LBB0_484:
	s_or_b64 exec, exec, s[8:9]
	v_or_b32_e32 v112, 16, v146
	v_ashrrev_i32_e32 v113, 31, v112
	v_lshl_add_u64 v[114:115], s[60:61], 0, v[112:113]
	v_lshlrev_b64 v[120:121], 11, v[114:115]
	v_mov_b32_e32 v114, s19
	v_sub_co_u32_e32 v112, vcc, s18, v112
	v_add_f32_e32 v115, v111, v159
	s_nop 0
	v_subb_co_u32_e32 v113, vcc, v114, v113, vcc
	v_lshlrev_b64 v[122:123], 11, v[112:113]
	v_add_f32_e32 v112, v108, v156
	v_add_f32_e32 v113, v109, v157
	v_add_f32_e32 v108, v104, v160
	v_add_f32_e32 v109, v105, v161
	v_add_f32_e32 v114, v110, v158
	v_mul_f32_e32 v104, 0x3cb504f3, v112
	v_mul_f32_e32 v105, 0x3cb504f3, v113
	v_cvt_pk_bf16_f32 v116, v104, v105
	v_mul_f32_e32 v104, 0x3cb504f3, v114
	v_mul_f32_e32 v105, 0x3cb504f3, v115
	v_add_f32_e32 v110, v106, v162
	v_add_f32_e32 v111, v107, v163
	v_cvt_pk_bf16_f32 v117, v104, v105
	v_mul_f32_e32 v104, 0x3cb504f3, v108
	v_mul_f32_e32 v105, 0x3cb504f3, v109
	v_cvt_pk_bf16_f32 v118, v104, v105
	v_mul_f32_e32 v104, 0x3cb504f3, v110
	v_mul_f32_e32 v105, 0x3cb504f3, v111
	s_cmp_gt_i32 s57, -1
	v_cvt_pk_bf16_f32 v119, v104, v105
	v_lshl_add_u64 v[104:105], s[10:11], 0, v[120:121]
	s_cselect_b64 s[62:63], -1, 0
	s_cmp_lt_i32 s57, 0
	v_lshl_add_u64 v[106:107], v[104:105], 0, v[136:137]
	v_lshl_add_u64 v[104:105], s[10:11], 0, v[122:123]
	global_store_dwordx4 v[106:107], v[116:119], off
	s_cbranch_scc1 .LBB0_486
	v_mul_f32_e32 v112, v164, v112
	v_mul_f32_e32 v113, v164, v113
	v_cvt_pk_bf16_f32 v112, v112, v113
	v_mul_f32_e32 v113, v164, v114
	v_mul_f32_e32 v114, v164, v115
	v_mul_f32_e32 v108, v164, v108
	v_mul_f32_e32 v109, v164, v109
	v_cvt_pk_bf16_f32 v113, v113, v114
	v_cvt_pk_bf16_f32 v114, v108, v109
	v_mul_f32_e32 v108, v164, v110
	v_mul_f32_e32 v109, v164, v111
	v_cvt_pk_bf16_f32 v115, v108, v109
	v_lshl_add_u64 v[108:109], v[104:105], 0, v[136:137]
	global_store_dwordx4 v[108:109], v[112:115], off
.LBB0_486:
	v_add_f32_e32 v100, v100, v124
	v_add_f32_e32 v101, v101, v125
	v_add_f32_e32 v102, v102, v126
	v_add_f32_e32 v103, v103, v127
	v_mul_f32_e32 v108, 0x3cb504f3, v100
	v_mul_f32_e32 v109, 0x3cb504f3, v101
	v_add_f32_e32 v96, v96, v147
	v_add_f32_e32 v97, v97, v165
	v_cvt_pk_bf16_f32 v108, v108, v109
	v_mul_f32_e32 v109, 0x3cb504f3, v102
	v_mul_f32_e32 v110, 0x3cb504f3, v103
	v_add_f32_e32 v98, v98, v166
	v_add_f32_e32 v99, v99, v167
	v_cvt_pk_bf16_f32 v109, v109, v110
	v_mul_f32_e32 v110, 0x3cb504f3, v96
	v_mul_f32_e32 v111, 0x3cb504f3, v97
	v_cvt_pk_bf16_f32 v110, v110, v111
	v_mul_f32_e32 v111, 0x3cb504f3, v98
	v_mul_f32_e32 v112, 0x3cb504f3, v99
	v_cvt_pk_bf16_f32 v111, v111, v112
	v_cndmask_b32_e64 v112, 0, 1, s[62:63]
	v_cmp_ne_u32_e64 s[8:9], 1, v112
	s_andn2_b64 vcc, exec, s[62:63]
	global_store_dwordx4 v[106:107], v[108:111], off offset:512
	s_cbranch_vccnz .LBB0_488
	v_mul_f32_e32 v100, v164, v100
	v_mul_f32_e32 v101, v164, v101
	v_cvt_pk_bf16_f32 v100, v100, v101
	v_mul_f32_e32 v101, v164, v102
	v_mul_f32_e32 v102, v164, v103
	v_mul_f32_e32 v96, v164, v96
	v_mul_f32_e32 v97, v164, v97
	v_cvt_pk_bf16_f32 v101, v101, v102
	v_cvt_pk_bf16_f32 v102, v96, v97
	v_mul_f32_e32 v96, v164, v98
	v_mul_f32_e32 v97, v164, v99
	v_cvt_pk_bf16_f32 v103, v96, v97
	v_lshl_add_u64 v[96:97], v[104:105], 0, v[136:137]
	global_store_dwordx4 v[96:97], v[100:103], off offset:512
; __device__ __forceinline__ unsigned cvt_pk_bf16(float lo, float hi) { unsigned r; asm("v_cvt_pk_bf16_f32 %0, %1, %2" : "=v"(r) : "v"(lo), "v"(hi)); return r; }
;     __device__ __forceinline__ void operator()(const f32x4 (&acc)[2][2][4][2], const Unit& u, int wr, int wc, int fr, int fq, LAS unsigned char* xs, int wid, int lane) const {
;     ...
;         for (int ai = 0; ai < 2; ++ai)
; #pragma unroll
;             for (int m = 0; m < 4; ++m) {
;                 const int k = k0 + ai * 128 + m * 16 + fr;
; #pragma unroll
;                 for (int bj = 0; bj < 2; ++bj) {
;                     const int col = (2 * u.pn + bj) * 256 + cs * 128 + wc * 32 + 8 * fq;
;                     f32x4 a = acc[ai][bj][m][0], b = acc[ai][bj][m][1];
; #pragma unroll
;                     for (int j = 0; j < 4; ++j) { a[j] += hv[bj][j]; b[j] += hv[bj][4 + j]; }
;                     u32x4 w; w.x = cvt_pk_bf16(a[0] * sc, a[1] * sc); w.y = cvt_pk_bf16(a[2] * sc, a[3] * sc); w.z = cvt_pk_bf16(b[0] * sc, b[1] * sc); w.w = cvt_pk_bf16(b[2] * sc, b[3] * sc);
;                     *(u32x4*)(pq + (tok0 + k) * 1024 + col) = w;
;                     if (k > 0) {
;                         u32x4 w2; w2.x = cvt_pk_bf16(a[0] * scm, a[1] * scm); w2.y = cvt_pk_bf16(a[2] * scm, a[3] * scm); w2.z = cvt_pk_bf16(b[0] * scm, b[1] * scm); w2.w = cvt_pk_bf16(b[2] * scm, b[3] * scm);
;                         *(u32x4*)(pq + (tok0 + S - k) * 1024 + col) = w2;
;                     }
;                 }
.LBB0_488:
	v_or_b32_e32 v96, 32, v146
	v_ashrrev_i32_e32 v97, 31, v96
	v_lshl_add_u64 v[98:99], s[60:61], 0, v[96:97]
	v_lshlrev_b64 v[104:105], 11, v[98:99]
	v_mov_b32_e32 v98, s19
	v_sub_co_u32_e32 v96, vcc, s18, v96
	v_add_f32_e32 v99, v95, v159
	s_nop 0
	v_subb_co_u32_e32 v97, vcc, v98, v97, vcc
	v_lshlrev_b64 v[106:107], 11, v[96:97]
	v_add_f32_e32 v96, v92, v156
	v_add_f32_e32 v97, v93, v157
	v_add_f32_e32 v92, v88, v160
	v_add_f32_e32 v93, v89, v161
	v_add_f32_e32 v98, v94, v158
	v_mul_f32_e32 v88, 0x3cb504f3, v96
	v_mul_f32_e32 v89, 0x3cb504f3, v97
	v_cvt_pk_bf16_f32 v100, v88, v89
	v_mul_f32_e32 v88, 0x3cb504f3, v98
	v_mul_f32_e32 v89, 0x3cb504f3, v99
	v_add_f32_e32 v94, v90, v162
	v_add_f32_e32 v95, v91, v163
	v_cvt_pk_bf16_f32 v101, v88, v89
	v_mul_f32_e32 v88, 0x3cb504f3, v92
	v_mul_f32_e32 v89, 0x3cb504f3, v93
	v_cvt_pk_bf16_f32 v102, v88, v89
	v_mul_f32_e32 v88, 0x3cb504f3, v94
	v_mul_f32_e32 v89, 0x3cb504f3, v95
	v_cvt_pk_bf16_f32 v103, v88, v89
	v_lshl_add_u64 v[88:89], s[10:11], 0, v[104:105]
	v_lshl_add_u64 v[90:91], v[88:89], 0, v[136:137]
	s_and_b64 vcc, exec, s[8:9]
	v_lshl_add_u64 v[88:89], s[10:11], 0, v[106:107]
	global_store_dwordx4 v[90:91], v[100:103], off
	s_cbranch_vccnz .LBB0_490
	v_mul_f32_e32 v96, v164, v96
	v_mul_f32_e32 v97, v164, v97
	v_cvt_pk_bf16_f32 v96, v96, v97
	v_mul_f32_e32 v97, v164, v98
	v_mul_f32_e32 v98, v164, v99
	v_mul_f32_e32 v92, v164, v92
	v_mul_f32_e32 v93, v164, v93
	v_cvt_pk_bf16_f32 v97, v97, v98
	v_cvt_pk_bf16_f32 v98, v92, v93
	v_mul_f32_e32 v92, v164, v94
	v_mul_f32_e32 v93, v164, v95
	v_cvt_pk_bf16_f32 v99, v92, v93
	v_lshl_add_u64 v[92:93], v[88:89], 0, v[136:137]
	global_store_dwordx4 v[92:93], v[96:99], off
.LBB0_490:
	v_add_f32_e32 v84, v84, v124
	v_add_f32_e32 v85, v85, v125
	v_add_f32_e32 v86, v86, v126
	v_add_f32_e32 v87, v87, v127
	v_mul_f32_e32 v92, 0x3cb504f3, v84
	v_mul_f32_e32 v93, 0x3cb504f3, v85
	v_add_f32_e32 v80, v80, v147
	v_add_f32_e32 v81, v81, v165
	v_cvt_pk_bf16_f32 v92, v92, v93
	v_mul_f32_e32 v93, 0x3cb504f3, v86
	v_mul_f32_e32 v94, 0x3cb504f3, v87
	v_add_f32_e32 v82, v82, v166
	v_cvt_pk_bf16_f32 v93, v93, v94
	v_mul_f32_e32 v94, 0x3cb504f3, v80
	v_mul_f32_e32 v95, 0x3cb504f3, v81
	v_add_f32_e32 v83, v83, v167
	v_cvt_pk_bf16_f32 v94, v94, v95
	v_mul_f32_e32 v95, 0x3cb504f3, v82
	s_and_b64 vcc, exec, s[8:9]
	v_mul_f32_e32 v96, 0x3cb504f3, v83
	v_cvt_pk_bf16_f32 v95, v95, v96
	global_store_dwordx4 v[90:91], v[92:95], off offset:512
	s_cbranch_vccnz .LBB0_492
	v_mul_f32_e32 v84, v164, v84
	v_mul_f32_e32 v85, v164, v85
	v_cvt_pk_bf16_f32 v84, v84, v85
	v_mul_f32_e32 v85, v164, v86
	v_mul_f32_e32 v86, v164, v87
	v_mul_f32_e32 v80, v164, v80
	v_mul_f32_e32 v81, v164, v81
	v_cvt_pk_bf16_f32 v85, v85, v86
	v_cvt_pk_bf16_f32 v86, v80, v81
	v_mul_f32_e32 v80, v164, v82
	v_mul_f32_e32 v81, v164, v83
	v_cvt_pk_bf16_f32 v87, v80, v81
	v_lshl_add_u64 v[80:81], v[88:89], 0, v[136:137]
	global_store_dwordx4 v[80:81], v[84:87], off offset:512
.LBB0_492:
	v_or_b32_e32 v80, 48, v146
	v_ashrrev_i32_e32 v81, 31, v80
	v_lshl_add_u64 v[82:83], s[60:61], 0, v[80:81]
	v_lshlrev_b64 v[88:89], 11, v[82:83]
	v_mov_b32_e32 v82, s19
	v_sub_co_u32_e32 v80, vcc, s18, v80
	v_add_f32_e32 v83, v79, v159
	s_nop 0
	v_subb_co_u32_e32 v81, vcc, v82, v81, vcc
	v_lshlrev_b64 v[90:91], 11, v[80:81]
	v_add_f32_e32 v80, v76, v156
	v_add_f32_e32 v81, v77, v157
	v_add_f32_e32 v76, v72, v160
	v_add_f32_e32 v77, v73, v161
	v_add_f32_e32 v82, v78, v158
	v_mul_f32_e32 v72, 0x3cb504f3, v80
	v_mul_f32_e32 v73, 0x3cb504f3, v81
	v_cvt_pk_bf16_f32 v84, v72, v73
	v_mul_f32_e32 v72, 0x3cb504f3, v82
	v_mul_f32_e32 v73, 0x3cb504f3, v83
	v_add_f32_e32 v78, v74, v162
	v_add_f32_e32 v79, v75, v163
	v_cvt_pk_bf16_f32 v85, v72, v73
	v_mul_f32_e32 v72, 0x3cb504f3, v76
	v_mul_f32_e32 v73, 0x3cb504f3, v77
	v_cvt_pk_bf16_f32 v86, v72, v73
	v_mul_f32_e32 v72, 0x3cb504f3, v78
	v_mul_f32_e32 v73, 0x3cb504f3, v79
	v_cvt_pk_bf16_f32 v87, v72, v73
	v_lshl_add_u64 v[72:73], s[10:11], 0, v[88:89]
	v_lshl_add_u64 v[74:75], v[72:73], 0, v[136:137]
	s_and_b64 vcc, exec, s[8:9]
	v_lshl_add_u64 v[72:73], s[10:11], 0, v[90:91]
	global_store_dwordx4 v[74:75], v[84:87], off
	s_cbranch_vccnz .LBB0_494
	v_mul_f32_e32 v80, v164, v80
	v_mul_f32_e32 v81, v164, v81
	v_cvt_pk_bf16_f32 v80, v80, v81
	v_mul_f32_e32 v81, v164, v82
	v_mul_f32_e32 v82, v164, v83
	v_mul_f32_e32 v76, v164, v76
	v_mul_f32_e32 v77, v164, v77
	v_cvt_pk_bf16_f32 v81, v81, v82
	v_cvt_pk_bf16_f32 v82, v76, v77
	v_mul_f32_e32 v76, v164, v78
	v_mul_f32_e32 v77, v164, v79
	v_cvt_pk_bf16_f32 v83, v76, v77
	v_lshl_add_u64 v[76:77], v[72:73], 0, v[136:137]
	global_store_dwordx4 v[76:77], v[80:83], off
.LBB0_494:
	v_add_f32_e32 v68, v68, v124
	v_add_f32_e32 v69, v69, v125
	v_add_f32_e32 v70, v70, v126
	v_add_f32_e32 v71, v71, v127
	v_mul_f32_e32 v76, 0x3cb504f3, v68
	v_mul_f32_e32 v77, 0x3cb504f3, v69
	v_add_f32_e32 v64, v64, v147
	v_add_f32_e32 v65, v65, v165
	v_cvt_pk_bf16_f32 v76, v76, v77
	v_mul_f32_e32 v77, 0x3cb504f3, v70
	v_mul_f32_e32 v78, 0x3cb504f3, v71
	v_add_f32_e32 v66, v66, v166
	v_cvt_pk_bf16_f32 v77, v77, v78
	v_mul_f32_e32 v78, 0x3cb504f3, v64
	v_mul_f32_e32 v79, 0x3cb504f3, v65
	v_add_f32_e32 v67, v67, v167
	v_cvt_pk_bf16_f32 v78, v78, v79
	v_mul_f32_e32 v79, 0x3cb504f3, v66
	s_and_b64 vcc, exec, s[8:9]
	v_mul_f32_e32 v80, 0x3cb504f3, v67
	v_cvt_pk_bf16_f32 v79, v79, v80
	global_store_dwordx4 v[74:75], v[76:79], off offset:512
	s_cbranch_vccnz .LBB0_496
	v_mul_f32_e32 v68, v164, v68
	v_mul_f32_e32 v69, v164, v69
	v_cvt_pk_bf16_f32 v68, v68, v69
	v_mul_f32_e32 v69, v164, v70
	v_mul_f32_e32 v70, v164, v71
	v_mul_f32_e32 v64, v164, v64
	v_mul_f32_e32 v65, v164, v65
	v_cvt_pk_bf16_f32 v69, v69, v70
	v_cvt_pk_bf16_f32 v70, v64, v65
	v_mul_f32_e32 v64, v164, v66
	v_mul_f32_e32 v65, v164, v67
	v_cvt_pk_bf16_f32 v71, v64, v65
	v_lshl_add_u64 v[64:65], v[72:73], 0, v[136:137]
	global_store_dwordx4 v[64:65], v[68:71], off offset:512
; __device__ __forceinline__ unsigned cvt_pk_bf16(float lo, float hi) { unsigned r; asm("v_cvt_pk_bf16_f32 %0, %1, %2" : "=v"(r) : "v"(lo), "v"(hi)); return r; }
;     __device__ __forceinline__ void operator()(const f32x4 (&acc)[2][2][4][2], const Unit& u, int wr, int wc, int fr, int fq, LAS unsigned char* xs, int wid, int lane) const {
;     ...
;         for (int ai = 0; ai < 2; ++ai)
; #pragma unroll
;             for (int m = 0; m < 4; ++m) {
;                 const int k = k0 + ai * 128 + m * 16 + fr;
; #pragma unroll
;                 for (int bj = 0; bj < 2; ++bj) {
;                     const int col = (2 * u.pn + bj) * 256 + cs * 128 + wc * 32 + 8 * fq;
;                     f32x4 a = acc[ai][bj][m][0], b = acc[ai][bj][m][1];
; #pragma unroll
;                     for (int j = 0; j < 4; ++j) { a[j] += hv[bj][j]; b[j] += hv[bj][4 + j]; }
;                     u32x4 w; w.x = cvt_pk_bf16(a[0] * sc, a[1] * sc); w.y = cvt_pk_bf16(a[2] * sc, a[3] * sc); w.z = cvt_pk_bf16(b[0] * sc, b[1] * sc); w.w = cvt_pk_bf16(b[2] * sc, b[3] * sc);
;                     *(u32x4*)(pq + (tok0 + k) * 1024 + col) = w;
;                     if (k > 0) {
;                         u32x4 w2; w2.x = cvt_pk_bf16(a[0] * scm, a[1] * scm); w2.y = cvt_pk_bf16(a[2] * scm, a[3] * scm); w2.z = cvt_pk_bf16(b[0] * scm, b[1] * scm); w2.w = cvt_pk_bf16(b[2] * scm, b[3] * scm);
;                         *(u32x4*)(pq + (tok0 + S - k) * 1024 + col) = w2;
;                     }
;                 }
.LBB0_496:
	v_add_u32_e32 v64, 0x80, v146
	v_ashrrev_i32_e32 v65, 31, v64
	v_lshl_add_u64 v[66:67], s[60:61], 0, v[64:65]
	v_lshlrev_b64 v[72:73], 11, v[66:67]
	v_mov_b32_e32 v66, s19
	v_sub_co_u32_e64 v64, s[8:9], s18, v64
	v_add_f32_e32 v67, v63, v159
	s_nop 0
	v_subb_co_u32_e64 v65, s[8:9], v66, v65, s[8:9]
	v_lshlrev_b64 v[74:75], 11, v[64:65]
	v_add_f32_e32 v64, v60, v156
	v_add_f32_e32 v65, v61, v157
	v_add_f32_e32 v60, v56, v160
	v_add_f32_e32 v61, v57, v161
	v_add_f32_e32 v66, v62, v158
	v_mul_f32_e32 v56, 0x3cb504f3, v64
	v_mul_f32_e32 v57, 0x3cb504f3, v65
	v_cvt_pk_bf16_f32 v68, v56, v57
	v_mul_f32_e32 v56, 0x3cb504f3, v66
	v_mul_f32_e32 v57, 0x3cb504f3, v67
	v_add_f32_e32 v62, v58, v162
	v_add_f32_e32 v63, v59, v163
	v_cvt_pk_bf16_f32 v69, v56, v57
	v_mul_f32_e32 v56, 0x3cb504f3, v60
	v_mul_f32_e32 v57, 0x3cb504f3, v61
	v_cvt_pk_bf16_f32 v70, v56, v57
	v_mul_f32_e32 v56, 0x3cb504f3, v62
	v_mul_f32_e32 v57, 0x3cb504f3, v63
	v_cvt_pk_bf16_f32 v71, v56, v57
	v_lshl_add_u64 v[56:57], s[10:11], 0, v[72:73]
	v_cmp_lt_i32_e32 vcc, s68, v146
	v_lshl_add_u64 v[58:59], v[56:57], 0, v[136:137]
	v_lshl_add_u64 v[56:57], s[10:11], 0, v[74:75]
	global_store_dwordx4 v[58:59], v[68:71], off
	s_and_saveexec_b64 s[8:9], vcc
	s_cbranch_execz .LBB0_498
	v_mul_f32_e32 v64, v164, v64
	v_mul_f32_e32 v65, v164, v65
	v_cvt_pk_bf16_f32 v64, v64, v65
	v_mul_f32_e32 v65, v164, v66
	v_mul_f32_e32 v66, v164, v67
	v_mul_f32_e32 v60, v164, v60
	v_mul_f32_e32 v61, v164, v61
	v_cvt_pk_bf16_f32 v65, v65, v66
	v_cvt_pk_bf16_f32 v66, v60, v61
	v_mul_f32_e32 v60, v164, v62
	v_mul_f32_e32 v61, v164, v63
	v_cvt_pk_bf16_f32 v67, v60, v61
	v_lshl_add_u64 v[60:61], v[56:57], 0, v[136:137]
	global_store_dwordx4 v[60:61], v[64:67], off
.LBB0_498:
	s_or_b64 exec, exec, s[8:9]
	v_add_f32_e32 v52, v52, v124
	v_add_f32_e32 v53, v53, v125
	v_add_f32_e32 v54, v54, v126
	v_add_f32_e32 v55, v55, v127
	v_mul_f32_e32 v60, 0x3cb504f3, v52
	v_mul_f32_e32 v61, 0x3cb504f3, v53
	v_add_f32_e32 v48, v48, v147
	v_add_f32_e32 v49, v49, v165
	v_cvt_pk_bf16_f32 v60, v60, v61
	v_mul_f32_e32 v61, 0x3cb504f3, v54
	v_mul_f32_e32 v62, 0x3cb504f3, v55
	v_add_f32_e32 v50, v50, v166
	v_cvt_pk_bf16_f32 v61, v61, v62
	v_mul_f32_e32 v62, 0x3cb504f3, v48
	v_mul_f32_e32 v63, 0x3cb504f3, v49
	v_add_f32_e32 v51, v51, v167
	v_cvt_pk_bf16_f32 v62, v62, v63
	v_mul_f32_e32 v63, 0x3cb504f3, v50
	v_mul_f32_e32 v64, 0x3cb504f3, v51
	v_cvt_pk_bf16_f32 v63, v63, v64
	global_store_dwordx4 v[58:59], v[60:63], off offset:512
	s_and_saveexec_b64 s[8:9], vcc
	s_cbranch_execz .LBB0_500
	v_mul_f32_e32 v52, v164, v52
	v_mul_f32_e32 v53, v164, v53
	v_cvt_pk_bf16_f32 v52, v52, v53
	v_mul_f32_e32 v53, v164, v54
	v_mul_f32_e32 v54, v164, v55
	v_mul_f32_e32 v48, v164, v48
	v_mul_f32_e32 v49, v164, v49
	v_cvt_pk_bf16_f32 v53, v53, v54
	v_cvt_pk_bf16_f32 v54, v48, v49
	v_mul_f32_e32 v48, v164, v50
	v_mul_f32_e32 v49, v164, v51
	v_cvt_pk_bf16_f32 v55, v48, v49
	v_lshl_add_u64 v[48:49], v[56:57], 0, v[136:137]
	global_store_dwordx4 v[48:49], v[52:55], off offset:512
.LBB0_500:
	s_or_b64 exec, exec, s[8:9]
	v_add_u32_e32 v48, 0x90, v146
	v_ashrrev_i32_e32 v49, 31, v48
	v_lshl_add_u64 v[50:51], s[60:61], 0, v[48:49]
	v_lshlrev_b64 v[56:57], 11, v[50:51]
	v_mov_b32_e32 v50, s19
	v_sub_co_u32_e64 v48, s[8:9], s18, v48
	v_add_f32_e32 v51, v47, v159
	s_nop 0
	v_subb_co_u32_e64 v49, s[8:9], v50, v49, s[8:9]
	v_lshlrev_b64 v[58:59], 11, v[48:49]
	v_add_f32_e32 v48, v44, v156
	v_add_f32_e32 v49, v45, v157
	v_add_f32_e32 v44, v40, v160
	v_add_f32_e32 v45, v41, v161
	v_add_f32_e32 v50, v46, v158
	v_mul_f32_e32 v40, 0x3cb504f3, v48
	v_mul_f32_e32 v41, 0x3cb504f3, v49
	v_cvt_pk_bf16_f32 v52, v40, v41
	v_mul_f32_e32 v40, 0x3cb504f3, v50
	v_mul_f32_e32 v41, 0x3cb504f3, v51
	v_add_f32_e32 v46, v42, v162
	v_add_f32_e32 v47, v43, v163
	v_cvt_pk_bf16_f32 v53, v40, v41
	v_mul_f32_e32 v40, 0x3cb504f3, v44
	v_mul_f32_e32 v41, 0x3cb504f3, v45
	v_cvt_pk_bf16_f32 v54, v40, v41
	v_mul_f32_e32 v40, 0x3cb504f3, v46
	v_mul_f32_e32 v41, 0x3cb504f3, v47
	v_cvt_pk_bf16_f32 v55, v40, v41
	v_lshl_add_u64 v[40:41], s[10:11], 0, v[56:57]
	v_cmp_lt_i32_e32 vcc, s69, v146
	v_lshl_add_u64 v[42:43], v[40:41], 0, v[136:137]
	v_lshl_add_u64 v[40:41], s[10:11], 0, v[58:59]
	global_store_dwordx4 v[42:43], v[52:55], off
	s_and_saveexec_b64 s[8:9], vcc
	s_cbranch_execz .LBB0_502
	v_mul_f32_e32 v48, v164, v48
	v_mul_f32_e32 v49, v164, v49
	v_cvt_pk_bf16_f32 v48, v48, v49
	v_mul_f32_e32 v49, v164, v50
	v_mul_f32_e32 v50, v164, v51
	v_mul_f32_e32 v44, v164, v44
	v_mul_f32_e32 v45, v164, v45
	v_cvt_pk_bf16_f32 v49, v49, v50
	v_cvt_pk_bf16_f32 v50, v44, v45
	v_mul_f32_e32 v44, v164, v46
	v_mul_f32_e32 v45, v164, v47
	v_cvt_pk_bf16_f32 v51, v44, v45
	v_lshl_add_u64 v[44:45], v[40:41], 0, v[136:137]
	global_store_dwordx4 v[44:45], v[48:51], off
.LBB0_502:
	s_or_b64 exec, exec, s[8:9]
	v_add_f32_e32 v36, v36, v124
	v_add_f32_e32 v37, v37, v125
	v_add_f32_e32 v38, v38, v126
	v_add_f32_e32 v39, v39, v127
	v_mul_f32_e32 v44, 0x3cb504f3, v36
	v_mul_f32_e32 v45, 0x3cb504f3, v37
	v_add_f32_e32 v32, v32, v147
	v_add_f32_e32 v33, v33, v165
	v_cvt_pk_bf16_f32 v44, v44, v45
	v_mul_f32_e32 v45, 0x3cb504f3, v38
	v_mul_f32_e32 v46, 0x3cb504f3, v39
	v_add_f32_e32 v34, v34, v166
	v_cvt_pk_bf16_f32 v45, v45, v46
	v_mul_f32_e32 v46, 0x3cb504f3, v32
	v_mul_f32_e32 v47, 0x3cb504f3, v33
	v_add_f32_e32 v35, v35, v167
	v_cvt_pk_bf16_f32 v46, v46, v47
	v_mul_f32_e32 v47, 0x3cb504f3, v34
	v_mul_f32_e32 v48, 0x3cb504f3, v35
	v_cvt_pk_bf16_f32 v47, v47, v48
	global_store_dwordx4 v[42:43], v[44:47], off offset:512
	s_and_saveexec_b64 s[8:9], vcc
	s_cbranch_execz .LBB0_504
	v_mul_f32_e32 v36, v164, v36
	v_mul_f32_e32 v37, v164, v37
	v_cvt_pk_bf16_f32 v36, v36, v37
	v_mul_f32_e32 v37, v164, v38
	v_mul_f32_e32 v38, v164, v39
	v_mul_f32_e32 v32, v164, v32
	v_mul_f32_e32 v33, v164, v33
	v_cvt_pk_bf16_f32 v37, v37, v38
	v_cvt_pk_bf16_f32 v38, v32, v33
	v_mul_f32_e32 v32, v164, v34
	v_mul_f32_e32 v33, v164, v35
	v_cvt_pk_bf16_f32 v39, v32, v33
	v_lshl_add_u64 v[32:33], v[40:41], 0, v[136:137]
	global_store_dwordx4 v[32:33], v[36:39], off offset:512
; __device__ __forceinline__ unsigned cvt_pk_bf16(float lo, float hi) { unsigned r; asm("v_cvt_pk_bf16_f32 %0, %1, %2" : "=v"(r) : "v"(lo), "v"(hi)); return r; }
;     __device__ __forceinline__ void operator()(const f32x4 (&acc)[2][2][4][2], const Unit& u, int wr, int wc, int fr, int fq, LAS unsigned char* xs, int wid, int lane) const {
;     ...
;         for (int ai = 0; ai < 2; ++ai)
; #pragma unroll
;             for (int m = 0; m < 4; ++m) {
;                 const int k = k0 + ai * 128 + m * 16 + fr;
; #pragma unroll
;                 for (int bj = 0; bj < 2; ++bj) {
;                     const int col = (2 * u.pn + bj) * 256 + cs * 128 + wc * 32 + 8 * fq;
;                     f32x4 a = acc[ai][bj][m][0], b = acc[ai][bj][m][1];
; #pragma unroll
;                     for (int j = 0; j < 4; ++j) { a[j] += hv[bj][j]; b[j] += hv[bj][4 + j]; }
;                     u32x4 w; w.x = cvt_pk_bf16(a[0] * sc, a[1] * sc); w.y = cvt_pk_bf16(a[2] * sc, a[3] * sc); w.z = cvt_pk_bf16(b[0] * sc, b[1] * sc); w.w = cvt_pk_bf16(b[2] * sc, b[3] * sc);
;                     *(u32x4*)(pq + (tok0 + k) * 1024 + col) = w;
;                     if (k > 0) {
;                         u32x4 w2; w2.x = cvt_pk_bf16(a[0] * scm, a[1] * scm); w2.y = cvt_pk_bf16(a[2] * scm, a[3] * scm); w2.z = cvt_pk_bf16(b[0] * scm, b[1] * scm); w2.w = cvt_pk_bf16(b[2] * scm, b[3] * scm);
;                         *(u32x4*)(pq + (tok0 + S - k) * 1024 + col) = w2;
;                     }
;                 }
.LBB0_504:
	s_or_b64 exec, exec, s[8:9]
	v_add_u32_e32 v32, 0xa0, v146
	v_ashrrev_i32_e32 v33, 31, v32
	v_lshl_add_u64 v[34:35], s[60:61], 0, v[32:33]
	v_lshlrev_b64 v[40:41], 11, v[34:35]
	v_mov_b32_e32 v34, s19
	v_sub_co_u32_e64 v32, s[8:9], s18, v32
	v_add_f32_e32 v35, v31, v159
	s_nop 0
	v_subb_co_u32_e64 v33, s[8:9], v34, v33, s[8:9]
	v_lshlrev_b64 v[42:43], 11, v[32:33]
	v_add_f32_e32 v32, v28, v156
	v_add_f32_e32 v33, v29, v157
	v_add_f32_e32 v28, v24, v160
	v_add_f32_e32 v29, v25, v161
	v_add_f32_e32 v34, v30, v158
	v_mul_f32_e32 v24, 0x3cb504f3, v32
	v_mul_f32_e32 v25, 0x3cb504f3, v33
	v_cvt_pk_bf16_f32 v36, v24, v25
	v_mul_f32_e32 v24, 0x3cb504f3, v34
	v_mul_f32_e32 v25, 0x3cb504f3, v35
	v_add_f32_e32 v30, v26, v162
	v_add_f32_e32 v31, v27, v163
	v_cvt_pk_bf16_f32 v37, v24, v25
	v_mul_f32_e32 v24, 0x3cb504f3, v28
	v_mul_f32_e32 v25, 0x3cb504f3, v29
	v_cvt_pk_bf16_f32 v38, v24, v25
	v_mul_f32_e32 v24, 0x3cb504f3, v30
	v_mul_f32_e32 v25, 0x3cb504f3, v31
	v_cvt_pk_bf16_f32 v39, v24, v25
	v_lshl_add_u64 v[24:25], s[10:11], 0, v[40:41]
	v_cmp_lt_i32_e32 vcc, s70, v146
	v_lshl_add_u64 v[26:27], v[24:25], 0, v[136:137]
	v_lshl_add_u64 v[24:25], s[10:11], 0, v[42:43]
	global_store_dwordx4 v[26:27], v[36:39], off
	s_and_saveexec_b64 s[8:9], vcc
	s_cbranch_execz .LBB0_506
	v_mul_f32_e32 v32, v164, v32
	v_mul_f32_e32 v33, v164, v33
	v_cvt_pk_bf16_f32 v32, v32, v33
	v_mul_f32_e32 v33, v164, v34
	v_mul_f32_e32 v34, v164, v35
	v_mul_f32_e32 v28, v164, v28
	v_mul_f32_e32 v29, v164, v29
	v_cvt_pk_bf16_f32 v33, v33, v34
	v_cvt_pk_bf16_f32 v34, v28, v29
	v_mul_f32_e32 v28, v164, v30
	v_mul_f32_e32 v29, v164, v31
	v_cvt_pk_bf16_f32 v35, v28, v29
	v_lshl_add_u64 v[28:29], v[24:25], 0, v[136:137]
	global_store_dwordx4 v[28:29], v[32:35], off
.LBB0_506:
	s_or_b64 exec, exec, s[8:9]
	v_add_f32_e32 v20, v20, v124
	v_add_f32_e32 v21, v21, v125
	v_add_f32_e32 v22, v22, v126
	v_add_f32_e32 v23, v23, v127
	v_mul_f32_e32 v28, 0x3cb504f3, v20
	v_mul_f32_e32 v29, 0x3cb504f3, v21
	v_add_f32_e32 v16, v16, v147
	v_add_f32_e32 v17, v17, v165
	v_cvt_pk_bf16_f32 v28, v28, v29
	v_mul_f32_e32 v29, 0x3cb504f3, v22
	v_mul_f32_e32 v30, 0x3cb504f3, v23
	v_add_f32_e32 v18, v18, v166
	v_cvt_pk_bf16_f32 v29, v29, v30
	v_mul_f32_e32 v30, 0x3cb504f3, v16
	v_mul_f32_e32 v31, 0x3cb504f3, v17
	v_add_f32_e32 v19, v19, v167
	v_cvt_pk_bf16_f32 v30, v30, v31
	v_mul_f32_e32 v31, 0x3cb504f3, v18
	v_mul_f32_e32 v32, 0x3cb504f3, v19
	v_cvt_pk_bf16_f32 v31, v31, v32
	global_store_dwordx4 v[26:27], v[28:31], off offset:512
	s_and_saveexec_b64 s[8:9], vcc
	s_cbranch_execz .LBB0_508
	v_mul_f32_e32 v20, v164, v20
	v_mul_f32_e32 v21, v164, v21
	v_cvt_pk_bf16_f32 v20, v20, v21
	v_mul_f32_e32 v21, v164, v22
	v_mul_f32_e32 v22, v164, v23
	v_mul_f32_e32 v16, v164, v16
	v_mul_f32_e32 v17, v164, v17
	v_cvt_pk_bf16_f32 v21, v21, v22
	v_cvt_pk_bf16_f32 v22, v16, v17
	v_mul_f32_e32 v16, v164, v18
	v_mul_f32_e32 v17, v164, v19
	v_cvt_pk_bf16_f32 v23, v16, v17
	v_lshl_add_u64 v[16:17], v[24:25], 0, v[136:137]
	global_store_dwordx4 v[16:17], v[20:23], off offset:512
.LBB0_508:
	s_or_b64 exec, exec, s[8:9]
	v_add_u32_e32 v16, 0xb0, v146
	v_ashrrev_i32_e32 v17, 31, v16
	v_lshl_add_u64 v[18:19], s[60:61], 0, v[16:17]
	v_lshlrev_b64 v[24:25], 11, v[18:19]
	v_mov_b32_e32 v18, s19
	v_sub_co_u32_e64 v16, s[8:9], s18, v16
	v_add_f32_e32 v19, v15, v159
	s_nop 0
	v_subb_co_u32_e64 v17, s[8:9], v18, v17, s[8:9]
	v_lshlrev_b64 v[26:27], 11, v[16:17]
	v_add_f32_e32 v16, v12, v156
	v_add_f32_e32 v17, v13, v157
	v_add_f32_e32 v12, v8, v160
	v_add_f32_e32 v13, v9, v161
	v_add_f32_e32 v18, v14, v158
	v_mul_f32_e32 v8, 0x3cb504f3, v16
	v_mul_f32_e32 v9, 0x3cb504f3, v17
	v_cvt_pk_bf16_f32 v20, v8, v9
	v_mul_f32_e32 v8, 0x3cb504f3, v18
	v_mul_f32_e32 v9, 0x3cb504f3, v19
	v_add_f32_e32 v14, v10, v162
	v_add_f32_e32 v15, v11, v163
	v_cvt_pk_bf16_f32 v21, v8, v9
	v_mul_f32_e32 v8, 0x3cb504f3, v12
	v_mul_f32_e32 v9, 0x3cb504f3, v13
	v_cvt_pk_bf16_f32 v22, v8, v9
	v_mul_f32_e32 v8, 0x3cb504f3, v14
	v_mul_f32_e32 v9, 0x3cb504f3, v15
	v_cvt_pk_bf16_f32 v23, v8, v9
	v_lshl_add_u64 v[8:9], s[10:11], 0, v[24:25]
	v_cmp_lt_i32_e32 vcc, s71, v146
	v_lshl_add_u64 v[10:11], v[8:9], 0, v[136:137]
	v_lshl_add_u64 v[8:9], s[10:11], 0, v[26:27]
	global_store_dwordx4 v[10:11], v[20:23], off
	s_and_saveexec_b64 s[8:9], vcc
	s_cbranch_execz .LBB0_510
	v_mul_f32_e32 v16, v164, v16
	v_mul_f32_e32 v17, v164, v17
	v_cvt_pk_bf16_f32 v16, v16, v17
	v_mul_f32_e32 v17, v164, v18
	v_mul_f32_e32 v18, v164, v19
	v_mul_f32_e32 v12, v164, v12
	v_mul_f32_e32 v13, v164, v13
	v_cvt_pk_bf16_f32 v17, v17, v18
	v_cvt_pk_bf16_f32 v18, v12, v13
	v_mul_f32_e32 v12, v164, v14
	v_mul_f32_e32 v13, v164, v15
	v_cvt_pk_bf16_f32 v19, v12, v13
	v_lshl_add_u64 v[12:13], v[8:9], 0, v[136:137]
	global_store_dwordx4 v[12:13], v[16:19], off
.LBB0_510:
	s_or_b64 exec, exec, s[8:9]
	v_add_f32_e32 v4, v4, v124
	v_add_f32_e32 v5, v5, v125
	v_add_f32_e32 v6, v6, v126
	v_add_f32_e32 v7, v7, v127
	v_mul_f32_e32 v12, 0x3cb504f3, v4
	v_mul_f32_e32 v13, 0x3cb504f3, v5
	v_add_f32_e32 v0, v0, v147
	v_add_f32_e32 v1, v1, v165
	v_cvt_pk_bf16_f32 v12, v12, v13
	v_mul_f32_e32 v13, 0x3cb504f3, v6
	v_mul_f32_e32 v14, 0x3cb504f3, v7
	v_add_f32_e32 v2, v2, v166
	v_cvt_pk_bf16_f32 v13, v13, v14
	v_mul_f32_e32 v14, 0x3cb504f3, v0
	v_mul_f32_e32 v15, 0x3cb504f3, v1
	v_add_f32_e32 v3, v3, v167
	v_cvt_pk_bf16_f32 v14, v14, v15
	v_mul_f32_e32 v15, 0x3cb504f3, v2
	v_mul_f32_e32 v16, 0x3cb504f3, v3
	v_cvt_pk_bf16_f32 v15, v15, v16
	global_store_dwordx4 v[10:11], v[12:15], off offset:512
	s_and_saveexec_b64 s[8:9], vcc
	s_cbranch_execz .LBB0_512
	v_mul_f32_e32 v4, v164, v4
	v_mul_f32_e32 v5, v164, v5
	v_cvt_pk_bf16_f32 v4, v4, v5
	v_mul_f32_e32 v5, v164, v6
	v_mul_f32_e32 v6, v164, v7
	v_mul_f32_e32 v0, v164, v0
	v_mul_f32_e32 v1, v164, v1
	v_cvt_pk_bf16_f32 v5, v5, v6
	v_cvt_pk_bf16_f32 v6, v0, v1
	v_mul_f32_e32 v0, v164, v2
	v_mul_f32_e32 v1, v164, v3
	v_cvt_pk_bf16_f32 v7, v0, v1
	v_lshl_add_u64 v[0:1], v[8:9], 0, v[136:137]
	global_store_dwordx4 v[0:1], v[4:7], off offset:512

; __device__ __forceinline__ unsigned cvt_pk_bf16(float lo, float hi) { unsigned r; asm("v_cvt_pk_bf16_f32 %0, %1, %2" : "=v"(r) : "v"(lo), "v"(hi)); return r; }
;     __device__ __forceinline__ void operator()(const f32x4 (&acc)[2][2][4][2], const Unit& u, int wr, int wc, int fr, int fq, LAS unsigned char* xs, int wid, int lane) const {
;     ...
;         for (int ai = 0; ai < 2; ++ai) {
;             f32x4 xf[4][2][2];
;             if (SRCF32) {
; #pragma unroll
;                 for (int m = 0; m < 4; ++m)
; #pragma unroll
;                     for (int bj = 0; bj < 2; ++bj) { const size_t o = (size_t)(row0 + ai * 128 + m * 16 + fr) * D + col0 + bj * 128; xf[m][bj][0] = *(const f32x4*)(xo + o); xf[m][bj][1] = *(const f32x4*)(xo + o + 4); }
;             }
; #pragma unroll
;             for (int m = 0; m < 4; ++m) {
;                 const size_t row = (size_t)(row0 + ai * 128 + m * 16 + fr);
;                 float ss = 0.f;
; #pragma unroll
;                 for (int bj = 0; bj < 2; ++bj) {
;                     const size_t o = row * D + col0 + bj * 128;
;                     f32x4 x0, x1;
;                     if (SRCF32) { x0 = xf[m][bj][0]; x1 = xf[m][bj][1]; }
;                     else { const u32x4 r = raw[ai][m][bj]; x0 = (f32x4){bf_lo(r.x), bf_hi(r.x), bf_lo(r.y), bf_hi(r.y)}; x1 = (f32x4){bf_lo(r.z), bf_hi(r.z), bf_lo(r.w), bf_hi(r.w)}; }
;                     const f32x4 v0 = x0 + acc[ai][bj][m][0], v1 = x1 + acc[ai][bj][m][1];
;                     if (LAST) { *(f32x4*)(out + o) = v0; *(f32x4*)(out + o + 4) = v1; }
;                     else {
;                         ss += (v0[0] * v0[0] + v0[1] * v0[1]) + (v0[2] * v0[2] + v0[3] * v0[3]) + (v1[0] * v1[0] + v1[1] * v1[1]) + (v1[2] * v1[2] + v1[3] * v1[3]);
;                         u32x4 w; w.x = cvt_pk_bf16(v0[0], v0[1]); w.y = cvt_pk_bf16(v0[2], v0[3]); w.z = cvt_pk_bf16(v1[0], v1[1]); w.w = cvt_pk_bf16(v1[2], v1[3]); *(u32x4*)(xb + o) = w;
;                     }
;                 }
;                 if (!LAST) { ss += __shfl_xor(ss, 16); ss += __shfl_xor(ss, 32);
;                     if (fq == 0) P[(ai * 128 + wr * 64 + m * 16 + fr) * 4 + wc] = ss; }
;             }
.LBB0_622:
	s_lshl_b32 s18, s60, 8
	s_add_i32 s19, s18, s23
	s_cmpk_lt_i32 s19, 0x4000
	v_lshl_or_b32 v192, s46, 8, v206
	s_cselect_b32 s35, s45, s28
	s_cselect_b32 s38, s44, s27
	v_or_b32_e32 v196, s19, v204
	v_mov_b32_e32 v128, s38
	v_mov_b32_e32 v129, s35
	v_ashrrev_i32_e32 v193, 31, v192
	v_ashrrev_i32_e32 v197, 31, v196
	v_lshl_add_u64 v[194:195], v[192:193], 2, v[128:129]
	v_lshlrev_b64 v[128:129], 13, v[196:197]
	v_lshl_add_u64 v[128:129], v[194:195], 0, v[128:129]
	global_load_dwordx4 v[216:219], v[128:129], off
	global_load_dwordx4 v[220:223], v[128:129], off offset:16
	global_load_dwordx4 v[224:227], v[128:129], off offset:512
	global_load_dwordx4 v[228:231], v[128:129], off offset:528
	v_or_b32_e32 v202, 16, v196
	v_or_b32_e32 v200, 32, v196
	v_or_b32_e32 v198, 48, v196
	v_ashrrev_i32_e32 v203, 31, v202
	v_ashrrev_i32_e32 v201, 31, v200
	v_ashrrev_i32_e32 v199, 31, v198
	v_lshlrev_b64 v[128:129], 13, v[202:203]
	v_lshlrev_b64 v[130:131], 13, v[200:201]
	v_lshlrev_b64 v[132:133], 13, v[198:199]
	v_lshl_add_u64 v[128:129], v[194:195], 0, v[128:129]
	v_lshl_add_u64 v[130:131], v[194:195], 0, v[130:131]
	v_lshl_add_u64 v[132:133], v[194:195], 0, v[132:133]
	global_load_dwordx4 v[168:171], v[128:129], off offset:16
	global_load_dwordx4 v[172:175], v[128:129], off
	global_load_dwordx4 v[160:163], v[128:129], off offset:528
	global_load_dwordx4 v[164:167], v[128:129], off offset:512
	global_load_dwordx4 v[152:155], v[130:131], off offset:16
	global_load_dwordx4 v[156:159], v[130:131], off
	global_load_dwordx4 v[144:147], v[130:131], off offset:528
	global_load_dwordx4 v[148:151], v[130:131], off offset:512
	global_load_dwordx4 v[136:139], v[132:133], off offset:16
	global_load_dwordx4 v[140:143], v[132:133], off
	s_nop 0
	global_load_dwordx4 v[128:131], v[132:133], off offset:528
	s_nop 0
	global_load_dwordx4 v[132:135], v[132:133], off offset:512
	v_and_b32_e32 v215, 64, v211
	v_xor_b32_e32 v214, 16, v211
	v_add_u32_e32 v215, 64, v215
	v_xor_b32_e32 v232, 32, v211
	v_cmp_lt_i32_e32 vcc, v214, v215
	s_waitcnt vmcnt(0)
	v_pk_add_f32 v[126:127], v[126:127], v[218:219]
	v_pk_add_f32 v[124:125], v[124:125], v[216:217]
	v_pk_add_f32 v[216:217], v[118:119], v[226:227]
	v_pk_add_f32 v[116:117], v[116:117], v[224:225]
	v_cndmask_b32_e32 v214, v211, v214, vcc
	v_cmp_lt_i32_e32 vcc, v232, v215
	v_pk_add_f32 v[120:121], v[120:121], v[220:221]
	v_pk_add_f32 v[218:219], v[114:115], v[230:231]
	v_pk_add_f32 v[220:221], v[112:113], v[228:229]
	v_mul_f32_e32 v114, v125, v125
	v_mul_f32_e32 v115, v127, v127
	v_cvt_pk_bf16_f32 v112, v124, v125
	v_cvt_pk_bf16_f32 v113, v126, v127
	v_mul_f32_e32 v125, v117, v117
	v_mul_f32_e32 v127, v217, v217
	v_cndmask_b32_e32 v215, v211, v232, vcc
	v_lshlrev_b64 v[232:233], 12, v[196:197]
	v_pk_add_f32 v[122:123], v[122:123], v[222:223]
	v_mul_f32_e32 v118, v121, v121
	v_mul_f32_e32 v197, v221, v221
	v_fmac_f32_e32 v114, v124, v124
	v_fmac_f32_e32 v115, v126, v126
	v_fmac_f32_e32 v125, v116, v116
	v_fmac_f32_e32 v127, v216, v216
	v_mul_f32_e32 v119, v123, v123
	v_mul_f32_e32 v222, v219, v219
	v_fmac_f32_e32 v118, v120, v120
	v_fmac_f32_e32 v197, v220, v220
	v_add_f32_e32 v114, v114, v115
	v_add_f32_e32 v115, v125, v127
	v_fmac_f32_e32 v119, v122, v122
	v_fmac_f32_e32 v222, v218, v218
	v_add_f32_e32 v114, v114, v118
	v_add_f32_e32 v115, v115, v197
	v_add_f32_e32 v114, v119, v114
	v_add_f32_e32 v115, v222, v115
	v_lshlrev_b32_e32 v214, 2, v214
	v_add_f32_e32 v118, v114, v115
	ds_bpermute_b32 v119, v214, v118
	v_lshl_add_u64 v[232:233], s[12:13], 0, v[232:233]
	v_lshl_add_u64 v[232:233], v[192:193], 1, v[232:233]
	v_cvt_pk_bf16_f32 v114, v120, v121
	v_cvt_pk_bf16_f32 v115, v122, v123
	global_store_dwordx4 v[232:233], v[112:115], off
	v_cvt_pk_bf16_f32 v120, v116, v117
	v_cvt_pk_bf16_f32 v121, v216, v217
	v_cvt_pk_bf16_f32 v122, v220, v221
	v_cvt_pk_bf16_f32 v123, v218, v219
	global_store_dwordx4 v[232:233], v[120:123], off offset:256
	s_waitcnt lgkmcnt(0)
	v_add_f32_e32 v112, v118, v119
	v_lshlrev_b32_e32 v118, 2, v215
	ds_bpermute_b32 v113, v118, v112
	s_and_saveexec_b64 s[60:61], s[6:7]
	s_cbranch_execz .LBB0_624
	s_waitcnt lgkmcnt(0)
	v_add_f32_e32 v112, v112, v113
	ds_write_b32 v213, v112
.LBB0_624:
	s_or_b64 exec, exec, s[60:61]
	v_pk_add_f32 v[110:111], v[110:111], v[174:175]
	v_pk_add_f32 v[108:109], v[108:109], v[172:173]
	v_pk_add_f32 v[114:115], v[106:107], v[170:171]
	v_pk_add_f32 v[106:107], v[104:105], v[168:169]
	v_mul_f32_e32 v104, v109, v109
	v_mul_f32_e32 v105, v111, v111
	v_fmac_f32_e32 v104, v108, v108
	v_fmac_f32_e32 v105, v110, v110
	v_add_f32_e32 v104, v104, v105
	v_mul_f32_e32 v105, v107, v107
	v_fmac_f32_e32 v105, v106, v106
	v_add_f32_e32 v104, v104, v105
	v_mul_f32_e32 v105, v115, v115
	v_fmac_f32_e32 v105, v114, v114
	v_pk_add_f32 v[102:103], v[102:103], v[166:167]
	v_pk_add_f32 v[100:101], v[100:101], v[164:165]
	v_add_f32_e32 v116, v105, v104
	v_cvt_pk_bf16_f32 v105, v110, v111
	v_pk_add_f32 v[110:111], v[96:97], v[160:161]
	v_mul_f32_e32 v96, v101, v101
	v_mul_f32_e32 v97, v103, v103
	v_fmac_f32_e32 v96, v100, v100
	v_fmac_f32_e32 v97, v102, v102
	v_add_f32_e32 v96, v96, v97
	v_mul_f32_e32 v97, v111, v111
	v_cvt_pk_bf16_f32 v104, v108, v109
	v_pk_add_f32 v[108:109], v[98:99], v[162:163]
	v_fmac_f32_e32 v97, v110, v110
	v_add_f32_e32 v96, v96, v97
	v_mul_f32_e32 v97, v109, v109
	v_fmac_f32_e32 v97, v108, v108
	v_add_f32_e32 v96, v97, v96
	v_add_f32_e32 v99, v116, v96
	v_cvt_pk_bf16_f32 v106, v106, v107
	v_cvt_pk_bf16_f32 v107, v114, v115
	ds_bpermute_b32 v114, v214, v99
	s_waitcnt lgkmcnt(1)
	v_lshlrev_b64 v[112:113], 12, v[202:203]
	v_lshl_add_u64 v[96:97], s[12:13], 0, v[112:113]
	v_lshl_add_u64 v[112:113], v[192:193], 1, v[96:97]
	global_store_dwordx4 v[112:113], v[104:107], off
	s_waitcnt lgkmcnt(0)
	v_add_f32_e32 v96, v99, v114
	ds_bpermute_b32 v97, v118, v96
	v_cvt_pk_bf16_f32 v98, v100, v101
	v_cvt_pk_bf16_f32 v99, v102, v103
	v_cvt_pk_bf16_f32 v100, v110, v111
	v_cvt_pk_bf16_f32 v101, v108, v109
	global_store_dwordx4 v[112:113], v[98:101], off offset:256
	s_and_saveexec_b64 s[60:61], s[6:7]
	s_cbranch_execz .LBB0_626
	s_waitcnt lgkmcnt(0)
	v_add_f32_e32 v96, v96, v97
	ds_write_b32 v213, v96 offset:256
; __device__ __forceinline__ unsigned cvt_pk_bf16(float lo, float hi) { unsigned r; asm("v_cvt_pk_bf16_f32 %0, %1, %2" : "=v"(r) : "v"(lo), "v"(hi)); return r; }
;     __device__ __forceinline__ void operator()(const f32x4 (&acc)[2][2][4][2], const Unit& u, int wr, int wc, int fr, int fq, LAS unsigned char* xs, int wid, int lane) const {
;     ...
;         for (int ai = 0; ai < 2; ++ai) {
;             f32x4 xf[4][2][2];
;             if (SRCF32) {
; #pragma unroll
;                 for (int m = 0; m < 4; ++m)
; #pragma unroll
;                     for (int bj = 0; bj < 2; ++bj) { const size_t o = (size_t)(row0 + ai * 128 + m * 16 + fr) * D + col0 + bj * 128; xf[m][bj][0] = *(const f32x4*)(xo + o); xf[m][bj][1] = *(const f32x4*)(xo + o + 4); }
;             }
; #pragma unroll
;             for (int m = 0; m < 4; ++m) {
;                 const size_t row = (size_t)(row0 + ai * 128 + m * 16 + fr);
;                 float ss = 0.f;
; #pragma unroll
;                 for (int bj = 0; bj < 2; ++bj) {
;                     const size_t o = row * D + col0 + bj * 128;
;                     f32x4 x0, x1;
;                     if (SRCF32) { x0 = xf[m][bj][0]; x1 = xf[m][bj][1]; }
;                     else { const u32x4 r = raw[ai][m][bj]; x0 = (f32x4){bf_lo(r.x), bf_hi(r.x), bf_lo(r.y), bf_hi(r.y)}; x1 = (f32x4){bf_lo(r.z), bf_hi(r.z), bf_lo(r.w), bf_hi(r.w)}; }
;                     const f32x4 v0 = x0 + acc[ai][bj][m][0], v1 = x1 + acc[ai][bj][m][1];
;                     if (LAST) { *(f32x4*)(out + o) = v0; *(f32x4*)(out + o + 4) = v1; }
;                     else {
;                         ss += (v0[0] * v0[0] + v0[1] * v0[1]) + (v0[2] * v0[2] + v0[3] * v0[3]) + (v1[0] * v1[0] + v1[1] * v1[1]) + (v1[2] * v1[2] + v1[3] * v1[3]);
;                         u32x4 w; w.x = cvt_pk_bf16(v0[0], v0[1]); w.y = cvt_pk_bf16(v0[2], v0[3]); w.z = cvt_pk_bf16(v1[0], v1[1]); w.w = cvt_pk_bf16(v1[2], v1[3]); *(u32x4*)(xb + o) = w;
;                     }
;                 }
;                 if (!LAST) { ss += __shfl_xor(ss, 16); ss += __shfl_xor(ss, 32);
;                     if (fq == 0) P[(ai * 128 + wr * 64 + m * 16 + fr) * 4 + wc] = ss; }
;             }
.LBB0_626:
	s_or_b64 exec, exec, s[60:61]
	v_pk_add_f32 v[94:95], v[94:95], v[158:159]
	v_pk_add_f32 v[92:93], v[92:93], v[156:157]
	v_pk_add_f32 v[98:99], v[90:91], v[154:155]
	v_pk_add_f32 v[90:91], v[88:89], v[152:153]
	v_mul_f32_e32 v88, v93, v93
	v_mul_f32_e32 v89, v95, v95
	v_fmac_f32_e32 v88, v92, v92
	v_fmac_f32_e32 v89, v94, v94
	v_add_f32_e32 v88, v88, v89
	v_mul_f32_e32 v89, v91, v91
	v_fmac_f32_e32 v89, v90, v90
	v_add_f32_e32 v88, v88, v89
	v_mul_f32_e32 v89, v99, v99
	v_fmac_f32_e32 v89, v98, v98
	v_pk_add_f32 v[86:87], v[86:87], v[150:151]
	v_pk_add_f32 v[84:85], v[84:85], v[148:149]
	v_add_f32_e32 v100, v89, v88
	v_cvt_pk_bf16_f32 v89, v94, v95
	v_pk_add_f32 v[94:95], v[80:81], v[144:145]
	v_mul_f32_e32 v80, v85, v85
	v_mul_f32_e32 v81, v87, v87
	v_fmac_f32_e32 v80, v84, v84
	v_fmac_f32_e32 v81, v86, v86
	v_add_f32_e32 v80, v80, v81
	v_mul_f32_e32 v81, v95, v95
	v_cvt_pk_bf16_f32 v88, v92, v93
	v_pk_add_f32 v[92:93], v[82:83], v[146:147]
	v_fmac_f32_e32 v81, v94, v94
	v_add_f32_e32 v80, v80, v81
	v_mul_f32_e32 v81, v93, v93
	v_fmac_f32_e32 v81, v92, v92
	v_add_f32_e32 v80, v81, v80
	v_add_f32_e32 v83, v100, v80
	v_cvt_pk_bf16_f32 v90, v90, v91
	v_cvt_pk_bf16_f32 v91, v98, v99
	ds_bpermute_b32 v98, v214, v83
	s_waitcnt lgkmcnt(1)
	v_lshlrev_b64 v[96:97], 12, v[200:201]
	v_lshl_add_u64 v[80:81], s[12:13], 0, v[96:97]
	v_lshl_add_u64 v[96:97], v[192:193], 1, v[80:81]
	global_store_dwordx4 v[96:97], v[88:91], off
	s_waitcnt lgkmcnt(0)
	v_add_f32_e32 v80, v83, v98
	ds_bpermute_b32 v81, v118, v80
	v_cvt_pk_bf16_f32 v82, v84, v85
	v_cvt_pk_bf16_f32 v83, v86, v87
	v_cvt_pk_bf16_f32 v84, v94, v95
	v_cvt_pk_bf16_f32 v85, v92, v93
	global_store_dwordx4 v[96:97], v[82:85], off offset:256
	s_and_saveexec_b64 s[60:61], s[6:7]
	s_cbranch_execz .LBB0_628
	s_waitcnt lgkmcnt(0)
	v_add_f32_e32 v80, v80, v81
	ds_write_b32 v213, v80 offset:512
.LBB0_628:
	s_or_b64 exec, exec, s[60:61]
	v_pk_add_f32 v[78:79], v[78:79], v[142:143]
	v_pk_add_f32 v[76:77], v[76:77], v[140:141]
	v_pk_add_f32 v[82:83], v[74:75], v[138:139]
	v_pk_add_f32 v[74:75], v[72:73], v[136:137]
	v_mul_f32_e32 v72, v77, v77
	v_mul_f32_e32 v73, v79, v79
	v_fmac_f32_e32 v72, v76, v76
	v_fmac_f32_e32 v73, v78, v78
	v_add_f32_e32 v72, v72, v73
	v_mul_f32_e32 v73, v75, v75
	v_fmac_f32_e32 v73, v74, v74
	v_add_f32_e32 v72, v72, v73
	v_mul_f32_e32 v73, v83, v83
	v_fmac_f32_e32 v73, v82, v82
	v_pk_add_f32 v[70:71], v[70:71], v[134:135]
	v_pk_add_f32 v[68:69], v[68:69], v[132:133]
	v_add_f32_e32 v84, v73, v72
	v_cvt_pk_bf16_f32 v73, v78, v79
	v_pk_add_f32 v[78:79], v[64:65], v[128:129]
	v_mul_f32_e32 v64, v69, v69
	v_mul_f32_e32 v65, v71, v71
	v_fmac_f32_e32 v64, v68, v68
	v_fmac_f32_e32 v65, v70, v70
	v_add_f32_e32 v64, v64, v65
	v_mul_f32_e32 v65, v79, v79
	v_cvt_pk_bf16_f32 v72, v76, v77
	v_pk_add_f32 v[76:77], v[66:67], v[130:131]
	v_fmac_f32_e32 v65, v78, v78
	v_add_f32_e32 v64, v64, v65
	v_mul_f32_e32 v65, v77, v77
	v_fmac_f32_e32 v65, v76, v76
	v_add_f32_e32 v64, v65, v64
	v_add_f32_e32 v67, v84, v64
	v_cvt_pk_bf16_f32 v74, v74, v75
	v_cvt_pk_bf16_f32 v75, v82, v83
	ds_bpermute_b32 v82, v214, v67
	s_waitcnt lgkmcnt(1)
	v_lshlrev_b64 v[80:81], 12, v[198:199]
	v_lshl_add_u64 v[64:65], s[12:13], 0, v[80:81]
	v_lshl_add_u64 v[80:81], v[192:193], 1, v[64:65]
	global_store_dwordx4 v[80:81], v[72:75], off
	s_waitcnt lgkmcnt(0)
	v_add_f32_e32 v64, v67, v82
	ds_bpermute_b32 v65, v118, v64
	v_cvt_pk_bf16_f32 v66, v68, v69
	v_cvt_pk_bf16_f32 v67, v70, v71
	v_cvt_pk_bf16_f32 v68, v78, v79
	v_cvt_pk_bf16_f32 v69, v76, v77
	global_store_dwordx4 v[80:81], v[66:69], off offset:256
	s_and_saveexec_b64 s[60:61], s[6:7]
	s_cbranch_execz .LBB0_630
	s_waitcnt lgkmcnt(0)
	v_add_f32_e32 v64, v64, v65
	ds_write_b32 v213, v64 offset:768
.LBB0_630:
	s_or_b64 exec, exec, s[60:61]
	v_add_u32_e32 v136, 0x80, v196
	v_ashrrev_i32_e32 v137, 31, v136
	s_waitcnt lgkmcnt(0)
	v_lshlrev_b64 v[64:65], 13, v[136:137]
	v_lshl_add_u64 v[64:65], v[194:195], 0, v[64:65]
	global_load_dwordx4 v[120:123], v[64:65], off
	global_load_dwordx4 v[124:127], v[64:65], off offset:16
	global_load_dwordx4 v[128:131], v[64:65], off offset:512
	global_load_dwordx4 v[132:135], v[64:65], off offset:528
	v_add_u32_e32 v116, 0x90, v196
	v_add_u32_e32 v114, 0xa0, v196
	v_add_u32_e32 v112, 0xb0, v196
	v_ashrrev_i32_e32 v117, 31, v116
	v_ashrrev_i32_e32 v115, 31, v114
	v_ashrrev_i32_e32 v113, 31, v112
	v_lshlrev_b64 v[64:65], 13, v[116:117]
	v_lshlrev_b64 v[66:67], 13, v[114:115]
	v_lshlrev_b64 v[68:69], 13, v[112:113]
	v_lshl_add_u64 v[64:65], v[194:195], 0, v[64:65]
	v_lshl_add_u64 v[66:67], v[194:195], 0, v[66:67]
	v_lshl_add_u64 v[68:69], v[194:195], 0, v[68:69]
	global_load_dwordx4 v[104:107], v[64:65], off offset:16
	global_load_dwordx4 v[108:111], v[64:65], off
	global_load_dwordx4 v[96:99], v[64:65], off offset:528
	global_load_dwordx4 v[100:103], v[64:65], off offset:512
	global_load_dwordx4 v[88:91], v[66:67], off offset:16
	global_load_dwordx4 v[92:95], v[66:67], off
	global_load_dwordx4 v[80:83], v[66:67], off offset:528
	global_load_dwordx4 v[84:87], v[66:67], off offset:512
	global_load_dwordx4 v[72:75], v[68:69], off offset:16
	global_load_dwordx4 v[76:79], v[68:69], off
	s_nop 0
	global_load_dwordx4 v[64:67], v[68:69], off offset:528
	s_nop 0
	global_load_dwordx4 v[68:71], v[68:69], off offset:512
	v_lshlrev_b64 v[136:137], 12, v[136:137]
	s_waitcnt vmcnt(15)
	v_pk_add_f32 v[62:63], v[62:63], v[122:123]
	v_pk_add_f32 v[60:61], v[60:61], v[120:121]
	s_waitcnt vmcnt(14)
	v_pk_add_f32 v[58:59], v[58:59], v[126:127]
	v_pk_add_f32 v[56:57], v[56:57], v[124:125]
	s_waitcnt vmcnt(13)
; __device__ __forceinline__ unsigned cvt_pk_bf16(float lo, float hi) { unsigned r; asm("v_cvt_pk_bf16_f32 %0, %1, %2" : "=v"(r) : "v"(lo), "v"(hi)); return r; }
;     __device__ __forceinline__ void operator()(const f32x4 (&acc)[2][2][4][2], const Unit& u, int wr, int wc, int fr, int fq, LAS unsigned char* xs, int wid, int lane) const {
;     ...
;         for (int ai = 0; ai < 2; ++ai) {
;             f32x4 xf[4][2][2];
;             if (SRCF32) {
; #pragma unroll
;                 for (int m = 0; m < 4; ++m)
; #pragma unroll
;                     for (int bj = 0; bj < 2; ++bj) { const size_t o = (size_t)(row0 + ai * 128 + m * 16 + fr) * D + col0 + bj * 128; xf[m][bj][0] = *(const f32x4*)(xo + o); xf[m][bj][1] = *(const f32x4*)(xo + o + 4); }
;             }
; #pragma unroll
;             for (int m = 0; m < 4; ++m) {
;                 const size_t row = (size_t)(row0 + ai * 128 + m * 16 + fr);
;                 float ss = 0.f;
; #pragma unroll
;                 for (int bj = 0; bj < 2; ++bj) {
;                     const size_t o = row * D + col0 + bj * 128;
;                     f32x4 x0, x1;
;                     if (SRCF32) { x0 = xf[m][bj][0]; x1 = xf[m][bj][1]; }
;                     else { const u32x4 r = raw[ai][m][bj]; x0 = (f32x4){bf_lo(r.x), bf_hi(r.x), bf_lo(r.y), bf_hi(r.y)}; x1 = (f32x4){bf_lo(r.z), bf_hi(r.z), bf_lo(r.w), bf_hi(r.w)}; }
;                     const f32x4 v0 = x0 + acc[ai][bj][m][0], v1 = x1 + acc[ai][bj][m][1];
;                     if (LAST) { *(f32x4*)(out + o) = v0; *(f32x4*)(out + o + 4) = v1; }
;                     else {
;                         ss += (v0[0] * v0[0] + v0[1] * v0[1]) + (v0[2] * v0[2] + v0[3] * v0[3]) + (v1[0] * v1[0] + v1[1] * v1[1]) + (v1[2] * v1[2] + v1[3] * v1[3]);
;                         u32x4 w; w.x = cvt_pk_bf16(v0[0], v0[1]); w.y = cvt_pk_bf16(v0[2], v0[3]); w.z = cvt_pk_bf16(v1[0], v1[1]); w.w = cvt_pk_bf16(v1[2], v1[3]); *(u32x4*)(xb + o) = w;
;                     }
;                 }
;                 if (!LAST) { ss += __shfl_xor(ss, 16); ss += __shfl_xor(ss, 32);
;                     if (fq == 0) P[(ai * 128 + wr * 64 + m * 16 + fr) * 4 + wc] = ss; }
;             }
	v_pk_add_f32 v[54:55], v[54:55], v[130:131]
	v_pk_add_f32 v[52:53], v[52:53], v[128:129]
	s_waitcnt vmcnt(12)
	v_pk_add_f32 v[120:121], v[50:51], v[134:135]
	v_pk_add_f32 v[122:123], v[48:49], v[132:133]
	v_mul_f32_e32 v119, v61, v61
	v_mul_f32_e32 v124, v63, v63
	v_mul_f32_e32 v125, v57, v57
	v_mul_f32_e32 v126, v59, v59
	v_cvt_pk_bf16_f32 v50, v56, v57
	v_cvt_pk_bf16_f32 v51, v58, v59
	v_mul_f32_e32 v57, v53, v53
	v_mul_f32_e32 v59, v55, v55
	v_cvt_pk_bf16_f32 v48, v60, v61
	v_mul_f32_e32 v61, v123, v123
	v_fmac_f32_e32 v119, v60, v60
	v_fmac_f32_e32 v124, v62, v62
	v_fmac_f32_e32 v57, v52, v52
	v_fmac_f32_e32 v59, v54, v54
	v_cvt_pk_bf16_f32 v49, v62, v63
	v_mul_f32_e32 v63, v121, v121
	v_fmac_f32_e32 v125, v56, v56
	v_fmac_f32_e32 v61, v122, v122
	v_add_f32_e32 v56, v119, v124
	v_add_f32_e32 v57, v57, v59
	v_fmac_f32_e32 v126, v58, v58
	v_fmac_f32_e32 v63, v120, v120
	v_add_f32_e32 v56, v56, v125
	v_add_f32_e32 v57, v57, v61
	v_add_f32_e32 v56, v126, v56
	v_add_f32_e32 v57, v63, v57
	v_add_f32_e32 v58, v56, v57
	ds_bpermute_b32 v59, v214, v58
	v_lshl_add_u64 v[56:57], s[12:13], 0, v[136:137]
	v_lshl_add_u64 v[56:57], v[192:193], 1, v[56:57]
	global_store_dwordx4 v[56:57], v[48:51], off
	s_waitcnt lgkmcnt(0)
	s_nop 0
	v_add_f32_e32 v48, v58, v59
	ds_bpermute_b32 v49, v118, v48
	v_cvt_pk_bf16_f32 v50, v52, v53
	v_cvt_pk_bf16_f32 v51, v54, v55
	v_cvt_pk_bf16_f32 v52, v122, v123
	v_cvt_pk_bf16_f32 v53, v120, v121
	global_store_dwordx4 v[56:57], v[50:53], off offset:256
	s_and_saveexec_b64 s[60:61], s[6:7]
	s_cbranch_execz .LBB0_632
	s_waitcnt lgkmcnt(0)
	v_add_f32_e32 v48, v48, v49
	ds_write_b32 v213, v48 offset:2048
.LBB0_632:
	s_or_b64 exec, exec, s[60:61]
	s_waitcnt vmcnt(12)
	v_pk_add_f32 v[46:47], v[46:47], v[110:111]
	v_pk_add_f32 v[44:45], v[44:45], v[108:109]
	v_pk_add_f32 v[50:51], v[42:43], v[106:107]
	v_pk_add_f32 v[42:43], v[40:41], v[104:105]
	v_mul_f32_e32 v40, v45, v45
	v_mul_f32_e32 v41, v47, v47
	v_fmac_f32_e32 v40, v44, v44
	v_fmac_f32_e32 v41, v46, v46
	v_add_f32_e32 v40, v40, v41
	v_mul_f32_e32 v41, v43, v43
	v_fmac_f32_e32 v41, v42, v42
	v_add_f32_e32 v40, v40, v41
	v_mul_f32_e32 v41, v51, v51
	v_fmac_f32_e32 v41, v50, v50
	s_waitcnt vmcnt(10)
	v_pk_add_f32 v[38:39], v[38:39], v[102:103]
	v_pk_add_f32 v[36:37], v[36:37], v[100:101]
	v_add_f32_e32 v52, v41, v40
	v_cvt_pk_bf16_f32 v41, v46, v47
	v_pk_add_f32 v[46:47], v[32:33], v[96:97]
	v_mul_f32_e32 v32, v37, v37
	v_mul_f32_e32 v33, v39, v39
	v_fmac_f32_e32 v32, v36, v36
	v_fmac_f32_e32 v33, v38, v38
	v_add_f32_e32 v32, v32, v33
	v_mul_f32_e32 v33, v47, v47
	v_cvt_pk_bf16_f32 v40, v44, v45
	v_pk_add_f32 v[44:45], v[34:35], v[98:99]
	v_fmac_f32_e32 v33, v46, v46
	v_add_f32_e32 v32, v32, v33
	v_mul_f32_e32 v33, v45, v45
	v_fmac_f32_e32 v33, v44, v44
	v_add_f32_e32 v32, v33, v32
	v_add_f32_e32 v35, v52, v32
	v_cvt_pk_bf16_f32 v42, v42, v43
	v_cvt_pk_bf16_f32 v43, v50, v51
	ds_bpermute_b32 v50, v214, v35
	s_waitcnt lgkmcnt(1)
	v_lshlrev_b64 v[48:49], 12, v[116:117]
	v_lshl_add_u64 v[32:33], s[12:13], 0, v[48:49]
	v_lshl_add_u64 v[48:49], v[192:193], 1, v[32:33]
	global_store_dwordx4 v[48:49], v[40:43], off
	s_waitcnt lgkmcnt(0)
	v_add_f32_e32 v32, v35, v50
	ds_bpermute_b32 v33, v118, v32
	v_cvt_pk_bf16_f32 v34, v36, v37
	v_cvt_pk_bf16_f32 v35, v38, v39
	v_cvt_pk_bf16_f32 v36, v46, v47
	v_cvt_pk_bf16_f32 v37, v44, v45
	global_store_dwordx4 v[48:49], v[34:37], off offset:256
	s_and_saveexec_b64 s[60:61], s[6:7]
	s_cbranch_execz .LBB0_634
	s_waitcnt lgkmcnt(0)
	v_add_f32_e32 v32, v32, v33
	ds_write_b32 v213, v32 offset:2304
; __device__ __forceinline__ unsigned cvt_pk_bf16(float lo, float hi) { unsigned r; asm("v_cvt_pk_bf16_f32 %0, %1, %2" : "=v"(r) : "v"(lo), "v"(hi)); return r; }
;     __device__ __forceinline__ void operator()(const f32x4 (&acc)[2][2][4][2], const Unit& u, int wr, int wc, int fr, int fq, LAS unsigned char* xs, int wid, int lane) const {
;     ...
;         for (int ai = 0; ai < 2; ++ai) {
;             f32x4 xf[4][2][2];
;             if (SRCF32) {
; #pragma unroll
;                 for (int m = 0; m < 4; ++m)
; #pragma unroll
;                     for (int bj = 0; bj < 2; ++bj) { const size_t o = (size_t)(row0 + ai * 128 + m * 16 + fr) * D + col0 + bj * 128; xf[m][bj][0] = *(const f32x4*)(xo + o); xf[m][bj][1] = *(const f32x4*)(xo + o + 4); }
;             }
; #pragma unroll
;             for (int m = 0; m < 4; ++m) {
;                 const size_t row = (size_t)(row0 + ai * 128 + m * 16 + fr);
;                 float ss = 0.f;
; #pragma unroll
;                 for (int bj = 0; bj < 2; ++bj) {
;                     const size_t o = row * D + col0 + bj * 128;
;                     f32x4 x0, x1;
;                     if (SRCF32) { x0 = xf[m][bj][0]; x1 = xf[m][bj][1]; }
;                     else { const u32x4 r = raw[ai][m][bj]; x0 = (f32x4){bf_lo(r.x), bf_hi(r.x), bf_lo(r.y), bf_hi(r.y)}; x1 = (f32x4){bf_lo(r.z), bf_hi(r.z), bf_lo(r.w), bf_hi(r.w)}; }
;                     const f32x4 v0 = x0 + acc[ai][bj][m][0], v1 = x1 + acc[ai][bj][m][1];
;                     if (LAST) { *(f32x4*)(out + o) = v0; *(f32x4*)(out + o + 4) = v1; }
;                     else {
;                         ss += (v0[0] * v0[0] + v0[1] * v0[1]) + (v0[2] * v0[2] + v0[3] * v0[3]) + (v1[0] * v1[0] + v1[1] * v1[1]) + (v1[2] * v1[2] + v1[3] * v1[3]);
;                         u32x4 w; w.x = cvt_pk_bf16(v0[0], v0[1]); w.y = cvt_pk_bf16(v0[2], v0[3]); w.z = cvt_pk_bf16(v1[0], v1[1]); w.w = cvt_pk_bf16(v1[2], v1[3]); *(u32x4*)(xb + o) = w;
;                     }
;                 }
;                 if (!LAST) { ss += __shfl_xor(ss, 16); ss += __shfl_xor(ss, 32);
;                     if (fq == 0) P[(ai * 128 + wr * 64 + m * 16 + fr) * 4 + wc] = ss; }
;             }
.LBB0_634:
	s_or_b64 exec, exec, s[60:61]
	s_waitcnt vmcnt(10)
	v_pk_add_f32 v[30:31], v[30:31], v[94:95]
	v_pk_add_f32 v[28:29], v[28:29], v[92:93]
	v_pk_add_f32 v[34:35], v[26:27], v[90:91]
	v_pk_add_f32 v[26:27], v[24:25], v[88:89]
	v_mul_f32_e32 v24, v29, v29
	v_mul_f32_e32 v25, v31, v31
	v_fmac_f32_e32 v24, v28, v28
	v_fmac_f32_e32 v25, v30, v30
	v_add_f32_e32 v24, v24, v25
	v_mul_f32_e32 v25, v27, v27
	v_fmac_f32_e32 v25, v26, v26
	v_add_f32_e32 v24, v24, v25
	v_mul_f32_e32 v25, v35, v35
	v_fmac_f32_e32 v25, v34, v34
	s_waitcnt vmcnt(8)
	v_pk_add_f32 v[22:23], v[22:23], v[86:87]
	v_pk_add_f32 v[20:21], v[20:21], v[84:85]
	v_add_f32_e32 v36, v25, v24
	v_cvt_pk_bf16_f32 v25, v30, v31
	v_pk_add_f32 v[30:31], v[16:17], v[80:81]
	v_mul_f32_e32 v16, v21, v21
	v_mul_f32_e32 v17, v23, v23
	v_fmac_f32_e32 v16, v20, v20
	v_fmac_f32_e32 v17, v22, v22
	v_add_f32_e32 v16, v16, v17
	v_mul_f32_e32 v17, v31, v31
	v_cvt_pk_bf16_f32 v24, v28, v29
	v_pk_add_f32 v[28:29], v[18:19], v[82:83]
	v_fmac_f32_e32 v17, v30, v30
	v_add_f32_e32 v16, v16, v17
	v_mul_f32_e32 v17, v29, v29
	v_fmac_f32_e32 v17, v28, v28
	v_add_f32_e32 v16, v17, v16
	v_add_f32_e32 v19, v36, v16
	v_cvt_pk_bf16_f32 v26, v26, v27
	v_cvt_pk_bf16_f32 v27, v34, v35
	ds_bpermute_b32 v34, v214, v19
	s_waitcnt lgkmcnt(1)
	v_lshlrev_b64 v[32:33], 12, v[114:115]
	v_lshl_add_u64 v[16:17], s[12:13], 0, v[32:33]
	v_lshl_add_u64 v[32:33], v[192:193], 1, v[16:17]
	global_store_dwordx4 v[32:33], v[24:27], off
	s_waitcnt lgkmcnt(0)
	v_add_f32_e32 v16, v19, v34
	ds_bpermute_b32 v17, v118, v16
	v_cvt_pk_bf16_f32 v18, v20, v21
	v_cvt_pk_bf16_f32 v19, v22, v23
	v_cvt_pk_bf16_f32 v20, v30, v31
	v_cvt_pk_bf16_f32 v21, v28, v29
	global_store_dwordx4 v[32:33], v[18:21], off offset:256
	s_and_saveexec_b64 s[60:61], s[6:7]
	s_cbranch_execz .LBB0_636
	s_waitcnt lgkmcnt(0)
	v_add_f32_e32 v16, v16, v17
	ds_write_b32 v213, v16 offset:2560
.LBB0_636:
	s_or_b64 exec, exec, s[60:61]
	s_waitcnt vmcnt(8)
	v_pk_add_f32 v[14:15], v[14:15], v[78:79]
	v_pk_add_f32 v[12:13], v[12:13], v[76:77]
	v_pk_add_f32 v[18:19], v[10:11], v[74:75]
	v_pk_add_f32 v[10:11], v[8:9], v[72:73]
	v_mul_f32_e32 v8, v13, v13
	v_mul_f32_e32 v9, v15, v15
	v_fmac_f32_e32 v8, v12, v12
	v_fmac_f32_e32 v9, v14, v14
	v_add_f32_e32 v8, v8, v9
	v_mul_f32_e32 v9, v11, v11
	v_fmac_f32_e32 v9, v10, v10
	v_add_f32_e32 v8, v8, v9
	v_mul_f32_e32 v9, v19, v19
	v_fmac_f32_e32 v9, v18, v18
	s_waitcnt vmcnt(6)
	v_pk_add_f32 v[6:7], v[6:7], v[70:71]
	v_pk_add_f32 v[4:5], v[4:5], v[68:69]
	v_add_f32_e32 v20, v9, v8
	v_cvt_pk_bf16_f32 v9, v14, v15
	v_pk_add_f32 v[14:15], v[0:1], v[64:65]
	v_mul_f32_e32 v0, v5, v5
	v_mul_f32_e32 v1, v7, v7
	v_fmac_f32_e32 v0, v4, v4
	v_fmac_f32_e32 v1, v6, v6
	v_add_f32_e32 v0, v0, v1
	v_mul_f32_e32 v1, v15, v15
	v_cvt_pk_bf16_f32 v8, v12, v13
	v_pk_add_f32 v[12:13], v[2:3], v[66:67]
	v_fmac_f32_e32 v1, v14, v14
	v_add_f32_e32 v0, v0, v1
	v_mul_f32_e32 v1, v13, v13
	v_fmac_f32_e32 v1, v12, v12
	v_add_f32_e32 v0, v1, v0
	v_add_f32_e32 v3, v20, v0
	v_cvt_pk_bf16_f32 v10, v10, v11
	v_cvt_pk_bf16_f32 v11, v18, v19
	ds_bpermute_b32 v18, v214, v3
	s_waitcnt lgkmcnt(1)
	v_lshlrev_b64 v[16:17], 12, v[112:113]
	v_lshl_add_u64 v[0:1], s[12:13], 0, v[16:17]
	v_lshl_add_u64 v[16:17], v[192:193], 1, v[0:1]
	global_store_dwordx4 v[16:17], v[8:11], off
	s_waitcnt lgkmcnt(0)
	v_add_f32_e32 v0, v3, v18
	ds_bpermute_b32 v1, v118, v0
	v_cvt_pk_bf16_f32 v2, v4, v5
	v_cvt_pk_bf16_f32 v3, v6, v7
	v_cvt_pk_bf16_f32 v4, v14, v15
	v_cvt_pk_bf16_f32 v5, v12, v13
	global_store_dwordx4 v[16:17], v[2:5], off offset:256
	s_and_saveexec_b64 s[60:61], s[6:7]
	s_cbranch_execz .LBB0_638
	s_waitcnt lgkmcnt(0)
	v_add_f32_e32 v0, v0, v1
	ds_write_b32 v213, v0 offset:2816

; #define LAS __attribute__((address_space(3)))
; __device__ __forceinline__ unsigned cvt_pk_bf16(float lo, float hi) { unsigned r; asm("v_cvt_pk_bf16_f32 %0, %1, %2" : "=v"(r) : "v"(lo), "v"(hi)); return r; }
; #define LDS_WAIT() asm volatile("s_waitcnt lgkmcnt(0)" ::: "memory")
; __device__ __forceinline__ void tstore_sub(const f32x4 (&v)[4][2], bf16_t* dst  , LAS unsigned char* x, int fr, int fq, int lane) {
; #pragma unroll
;     for (int m = 0; m < 4; ++m)
; #pragma unroll
;         for (int n = 0; n < 2; ++n)
; #pragma unroll
;             for (int j = 0; j < 4; ++j) {
;                 const int ch = 8 * fq + 4 * n + j, tok = 16 * m + fr;
;                 const unsigned b = cvt_pk_bf16(v[m][n][j], 0.f);
;                 *(LAS unsigned short*)(x + ch * 128 + ((((tok >> 3) ^ fq) << 4) | ((tok & 7) << 1))) = (unsigned short)b;
;             }
;     LDS_WAIT();
; #pragma unroll
;     for (int i = 0; i < 4; ++i) {
;         const int q = lane + 64 * i, ch = q >> 3, tc = q & 7;
;         const u32x4 o = *(const LAS u32x4*)(x + ch * 128 + ((tc ^ ((ch >> 3) & 3)) << 4));
;         *(u32x4*)(dst + (size_t)ch * T + tc * 8) = o;
;     }
;     LDS_WAIT();
; }
;     __device__ __forceinline__ void operator()(const f32x4 (&acc)[2][2][4][2], const Unit& u, int wr, int wc, int fr, int fq, LAS unsigned char* xs, int wid, int lane) const {
;     ...
;                     if (ODD) {
;                         float* vss = (float*)(ws + OFF_VSS);
; #pragma unroll
;                         for (int m = 0; m < 4; ++m) {
;                             float s = 0.f;
; #pragma unroll
;                             for (int n = 0; n < 2; ++n) s += (v[m][n][0] * v[m][n][0] + v[m][n][1] * v[m][n][1]) + (v[m][n][2] * v[m][n][2] + v[m][n][3] * v[m][n][3]);
;                             s += __shfl_xor(s, 16); s += __shfl_xor(s, 32);
;                             if (fq == 0) vss[(size_t)(row0 + ai * 128 + m * 16 + fr) * 32 + (2 * (pn - 24) + bj) * 4 + wc] = s;
;                         }
.LBB0_716:
	s_or_b64 exec, exec, s[72:73]
	v_cvt_pk_bf16_f32 v159, v184, v137
	ds_write_b16 v238, v159
	v_cvt_pk_bf16_f32 v159, v185, v137
	ds_write_b16 v238, v159 offset:128
	v_cvt_pk_bf16_f32 v159, v182, v137
	ds_write_b16 v238, v159 offset:256
	v_cvt_pk_bf16_f32 v159, v183, v137
	ds_write_b16 v238, v159 offset:384
	v_cvt_pk_bf16_f32 v159, v180, v137
	ds_write_b16 v238, v159 offset:512
	v_cvt_pk_bf16_f32 v159, v181, v137
	ds_write_b16 v238, v159 offset:640
	v_cvt_pk_bf16_f32 v159, v178, v137
	ds_write_b16 v238, v159 offset:768
	v_cvt_pk_bf16_f32 v159, v179, v137
	ds_write_b16 v238, v159 offset:896
	v_cvt_pk_bf16_f32 v159, v192, v137
	ds_write_b16 v239, v159
	v_cvt_pk_bf16_f32 v159, v193, v137
	ds_write_b16 v239, v159 offset:128
	v_cvt_pk_bf16_f32 v159, v190, v137
	ds_write_b16 v239, v159 offset:256
	v_cvt_pk_bf16_f32 v159, v191, v137
	ds_write_b16 v239, v159 offset:384
	v_cvt_pk_bf16_f32 v159, v188, v137
	ds_write_b16 v239, v159 offset:512
	v_cvt_pk_bf16_f32 v159, v189, v137
	ds_write_b16 v239, v159 offset:640
	v_cvt_pk_bf16_f32 v159, v186, v137
	ds_write_b16 v239, v159 offset:768
	v_cvt_pk_bf16_f32 v159, v187, v137
	ds_write_b16 v239, v159 offset:896
	v_cvt_pk_bf16_f32 v159, v206, v137
	ds_write_b16 v240, v159
	v_cvt_pk_bf16_f32 v159, v207, v137
	ds_write_b16 v240, v159 offset:128
	v_cvt_pk_bf16_f32 v159, v204, v137
	ds_write_b16 v240, v159 offset:256
	v_cvt_pk_bf16_f32 v159, v205, v137
	ds_write_b16 v240, v159 offset:384
	v_cvt_pk_bf16_f32 v159, v202, v137
	ds_write_b16 v240, v159 offset:512
	v_cvt_pk_bf16_f32 v159, v203, v137
	ds_write_b16 v240, v159 offset:640
	v_cvt_pk_bf16_f32 v159, v200, v137
	ds_write_b16 v240, v159 offset:768
	v_cvt_pk_bf16_f32 v159, v201, v137
	ds_write_b16 v240, v159 offset:896
	v_cvt_pk_bf16_f32 v159, v214, v137
	ds_write_b16 v241, v159
	v_cvt_pk_bf16_f32 v159, v215, v137
	ds_write_b16 v241, v159 offset:128
	v_cvt_pk_bf16_f32 v159, v212, v137
	ds_write_b16 v241, v159 offset:256
	v_cvt_pk_bf16_f32 v159, v213, v137
	ds_write_b16 v241, v159 offset:384
	v_cvt_pk_bf16_f32 v159, v210, v137
	ds_write_b16 v241, v159 offset:512
	v_cvt_pk_bf16_f32 v159, v211, v137
	ds_write_b16 v241, v159 offset:640
	v_cvt_pk_bf16_f32 v159, v208, v137
	s_ashr_i32 s69, s68, 31
	ds_write_b16 v241, v159 offset:768
	v_cvt_pk_bf16_f32 v159, v209, v137
	ds_write_b16 v241, v159 offset:896
	s_lshl_b64 s[0:1], s[68:69], 1
	s_waitcnt lgkmcnt(0)
	s_add_u32 s0, s70, s0
	ds_read_b128 v[182:185], v242
	ds_read_b128 v[190:193], v243
	s_addc_u32 s1, s71, s1
	v_lshl_add_u64 v[176:177], s[0:1], 0, v[136:137]
	v_lshl_add_u64 v[212:213], v[176:177], 0, s[48:49]
	v_lshlrev_b32_e32 v180, 1, v138
	v_mov_b32_e32 v181, v137
	ds_read_b128 v[200:203], v244
	ds_read_b128 v[208:211], v245
	v_lshl_add_u64 v[186:187], v[212:213], 0, v[180:181]
	v_mov_b32_e32 v175, v174
	s_waitcnt lgkmcnt(3)
	global_store_dwordx4 v[186:187], v[182:185], off
	v_lshlrev_b32_e32 v178, 1, v142
	v_mov_b32_e32 v179, v137
	v_lshlrev_b32_e32 v182, 1, v140
	v_mov_b32_e32 v183, v137
	v_mov_b32_e32 v184, v174
	v_mov_b32_e32 v185, v174
	v_lshl_add_u64 v[188:189], v[212:213], 0, v[182:183]
	v_pk_mul_f32 v[204:205], v[122:123], v[184:185]
	v_pk_mul_f32 v[206:207], v[120:121], v[174:175]
	s_waitcnt lgkmcnt(2)
	global_store_dwordx4 v[188:189], v[190:193], off
	v_mul_f32_e32 v159, v207, v207
	v_mul_f32_e32 v161, v205, v205
	v_lshl_add_u64 v[190:191], v[212:213], 0, v[178:179]
	s_waitcnt lgkmcnt(1)
	global_store_dwordx4 v[190:191], v[200:203], off
	v_fmac_f32_e32 v159, v206, v206
	v_fmac_f32_e32 v161, v204, v204
	v_pk_mul_f32 v[200:201], v[114:115], v[184:185]
	v_pk_mul_f32 v[202:203], v[112:113], v[174:175]
	v_add_f32_e32 v159, v159, v161
	v_mul_f32_e32 v161, v203, v203
	v_mul_f32_e32 v165, v201, v201
	v_fmac_f32_e32 v161, v202, v202
	v_fmac_f32_e32 v165, v200, v200
	v_add_f32_e32 v161, v161, v165
	v_add_f32_e32 v159, v159, v161
	ds_bpermute_b32 v161, v151, v159
	v_lshlrev_b32_e32 v184, 1, v144
	v_mov_b32_e32 v185, v137
	v_lshl_add_u64 v[192:193], v[212:213], 0, v[184:185]
	s_waitcnt lgkmcnt(1)
	global_store_dwordx4 v[192:193], v[208:211], off
	s_waitcnt lgkmcnt(0)
	v_add_f32_e32 v159, v159, v161
	ds_bpermute_b32 v161, v246, v159
	s_waitcnt lgkmcnt(0)
	s_and_saveexec_b64 s[72:73], s[8:9]
	s_cbranch_execz .LBB0_718
	v_lshlrev_b64 v[208:209], 7, v[162:163]
	v_lshl_add_u64 v[208:209], s[66:67], 0, v[208:209]
	s_waitcnt lgkmcnt(0)
	v_add_f32_e32 v159, v159, v161
	global_store_dword v[208:209], v159, off offset:-752

; #define LAS __attribute__((address_space(3)))
; __device__ __forceinline__ unsigned cvt_pk_bf16(float lo, float hi) { unsigned r; asm("v_cvt_pk_bf16_f32 %0, %1, %2" : "=v"(r) : "v"(lo), "v"(hi)); return r; }
; #define LDS_WAIT() asm volatile("s_waitcnt lgkmcnt(0)" ::: "memory")
; __device__ __forceinline__ void tstore_sub(const f32x4 (&v)[4][2], bf16_t* dst  , LAS unsigned char* x, int fr, int fq, int lane) {
; #pragma unroll
;     for (int m = 0; m < 4; ++m)
; #pragma unroll
;         for (int n = 0; n < 2; ++n)
; #pragma unroll
;             for (int j = 0; j < 4; ++j) {
;                 const int ch = 8 * fq + 4 * n + j, tok = 16 * m + fr;
;                 const unsigned b = cvt_pk_bf16(v[m][n][j], 0.f);
;                 *(LAS unsigned short*)(x + ch * 128 + ((((tok >> 3) ^ fq) << 4) | ((tok & 7) << 1))) = (unsigned short)b;
;             }
;     LDS_WAIT();
; #pragma unroll
;     for (int i = 0; i < 4; ++i) {
;         const int q = lane + 64 * i, ch = q >> 3, tc = q & 7;
;         const u32x4 o = *(const LAS u32x4*)(x + ch * 128 + ((tc ^ ((ch >> 3) & 3)) << 4));
;         *(u32x4*)(dst + (size_t)ch * T + tc * 8) = o;
;     }
;     LDS_WAIT();
; }
;     __device__ __forceinline__ void operator()(const f32x4 (&acc)[2][2][4][2], const Unit& u, int wr, int wc, int fr, int fq, LAS unsigned char* xs, int wid, int lane) const {
;     ...
;                     if (ODD) {
;                         float* vss = (float*)(ws + OFF_VSS);
; #pragma unroll
;                         for (int m = 0; m < 4; ++m) {
;                             float s = 0.f;
; #pragma unroll
;                             for (int n = 0; n < 2; ++n) s += (v[m][n][0] * v[m][n][0] + v[m][n][1] * v[m][n][1]) + (v[m][n][2] * v[m][n][2] + v[m][n][3] * v[m][n][3]);
;                             s += __shfl_xor(s, 16); s += __shfl_xor(s, 32);
;                             if (fq == 0) vss[(size_t)(row0 + ai * 128 + m * 16 + fr) * 32 + (2 * (pn - 24) + bj) * 4 + wc] = s;
;                         }
.LBB0_724:
	s_or_b64 exec, exec, s[72:73]
	v_cvt_pk_bf16_f32 v159, v206, v137
	ds_write_b16 v238, v159
	v_cvt_pk_bf16_f32 v159, v207, v137
	ds_write_b16 v238, v159 offset:128
	v_cvt_pk_bf16_f32 v159, v204, v137
	ds_write_b16 v238, v159 offset:256
	v_cvt_pk_bf16_f32 v159, v205, v137
	ds_write_b16 v238, v159 offset:384
	v_cvt_pk_bf16_f32 v159, v202, v137
	ds_write_b16 v238, v159 offset:512
	v_cvt_pk_bf16_f32 v159, v203, v137
	ds_write_b16 v238, v159 offset:640
	v_cvt_pk_bf16_f32 v159, v200, v137
	ds_write_b16 v238, v159 offset:768
	v_cvt_pk_bf16_f32 v159, v201, v137
	ds_write_b16 v238, v159 offset:896
	v_cvt_pk_bf16_f32 v159, v214, v137
	ds_write_b16 v239, v159
	v_cvt_pk_bf16_f32 v159, v215, v137
	ds_write_b16 v239, v159 offset:128
	v_cvt_pk_bf16_f32 v159, v212, v137
	ds_write_b16 v239, v159 offset:256
	v_cvt_pk_bf16_f32 v159, v213, v137
	ds_write_b16 v239, v159 offset:384
	v_cvt_pk_bf16_f32 v159, v210, v137
	ds_write_b16 v239, v159 offset:512
	v_cvt_pk_bf16_f32 v159, v211, v137
	ds_write_b16 v239, v159 offset:640
	v_cvt_pk_bf16_f32 v159, v208, v137
	ds_write_b16 v239, v159 offset:768
	v_cvt_pk_bf16_f32 v159, v209, v137
	ds_write_b16 v239, v159 offset:896
	v_cvt_pk_bf16_f32 v159, v220, v137
	ds_write_b16 v240, v159
	v_cvt_pk_bf16_f32 v159, v221, v137
	ds_write_b16 v240, v159 offset:128
	v_cvt_pk_bf16_f32 v159, v218, v137
	ds_write_b16 v240, v159 offset:256
	v_cvt_pk_bf16_f32 v159, v219, v137
	ds_write_b16 v240, v159 offset:384
	v_cvt_pk_bf16_f32 v159, v216, v137
	ds_write_b16 v240, v159 offset:512
	v_cvt_pk_bf16_f32 v159, v217, v137
	ds_write_b16 v240, v159 offset:640
	v_cvt_pk_bf16_f32 v159, v198, v137
	ds_write_b16 v240, v159 offset:768
	v_cvt_pk_bf16_f32 v159, v199, v137
	ds_write_b16 v240, v159 offset:896
	v_cvt_pk_bf16_f32 v159, v226, v137
	ds_write_b16 v241, v159
	v_cvt_pk_bf16_f32 v159, v227, v137
	ds_write_b16 v241, v159 offset:128
	v_cvt_pk_bf16_f32 v159, v224, v137
	ds_write_b16 v241, v159 offset:256
	v_cvt_pk_bf16_f32 v159, v225, v137
	ds_write_b16 v241, v159 offset:384
	v_cvt_pk_bf16_f32 v159, v222, v137
	ds_write_b16 v241, v159 offset:512
	v_cvt_pk_bf16_f32 v159, v223, v137
	ds_write_b16 v241, v159 offset:640
	v_cvt_pk_bf16_f32 v159, v196, v137
	ds_write_b16 v241, v159 offset:768
	v_cvt_pk_bf16_f32 v159, v197, v137
	ds_write_b16 v241, v159 offset:896
	s_waitcnt lgkmcnt(0)
	ds_read_b128 v[194:197], v242
	ds_read_b128 v[198:201], v243
	s_lshl_b32 s72, s34, 1
	s_mov_b32 s73, s49
	v_lshl_add_u64 v[210:211], v[176:177], 0, s[72:73]
	v_mov_b32_e32 v181, v137
	v_pk_mul_f32 v[206:207], v[62:63], v[166:167] op_sel_hi:[1,0]
	v_pk_mul_f32 v[208:209], v[60:61], v[166:167] op_sel_hi:[1,0]
	v_lshl_add_u64 v[202:203], v[210:211], 0, v[180:181]
	v_mul_f32_e32 v159, v209, v209
	s_waitcnt lgkmcnt(14)
	v_mul_f32_e32 v161, v207, v207
	s_waitcnt lgkmcnt(1)
	global_store_dwordx4 v[202:203], v[194:197], off
	v_pk_mul_f32 v[202:203], v[54:55], v[166:167] op_sel_hi:[1,0]
	v_pk_mul_f32 v[204:205], v[52:53], v[166:167] op_sel_hi:[1,0]
	v_fmac_f32_e32 v159, v208, v208
	v_fmac_f32_e32 v161, v206, v206
	v_add_f32_e32 v159, v159, v161
	v_mul_f32_e32 v161, v205, v205
	v_mul_f32_e32 v163, v203, v203
	v_fmac_f32_e32 v161, v204, v204
	v_fmac_f32_e32 v163, v202, v202
	v_add_f32_e32 v161, v161, v163
	v_mov_b32_e32 v183, v137
	v_add_f32_e32 v159, v159, v161
	v_lshl_add_u64 v[194:195], v[210:211], 0, v[182:183]
	ds_bpermute_b32 v161, v151, v159
	s_waitcnt lgkmcnt(1)
	global_store_dwordx4 v[194:195], v[198:201], off
	ds_read_b128 v[194:197], v244
	ds_read_b128 v[198:201], v245
	v_mov_b32_e32 v179, v137
	v_lshl_add_u64 v[212:213], v[210:211], 0, v[178:179]
	v_mov_b32_e32 v185, v137
	s_waitcnt lgkmcnt(2)
	v_add_f32_e32 v159, v159, v161
	s_waitcnt lgkmcnt(1)
	global_store_dwordx4 v[212:213], v[194:197], off
	ds_bpermute_b32 v161, v246, v159
	s_nop 0
	v_lshl_add_u64 v[194:195], v[210:211], 0, v[184:185]
	s_waitcnt lgkmcnt(1)
	global_store_dwordx4 v[194:195], v[198:201], off
	s_waitcnt lgkmcnt(0)
	s_nop 1
	v_add_u32_e32 v200, 0x80, v162
	v_ashrrev_i32_e32 v201, 31, v200
	s_and_saveexec_b64 s[74:75], s[8:9]
	s_cbranch_execz .LBB0_726
	v_lshlrev_b64 v[194:195], 7, v[200:201]
	v_lshl_add_u64 v[194:195], s[66:67], 0, v[194:195]
	s_waitcnt lgkmcnt(0)
	v_add_f32_e32 v159, v159, v161
	global_store_dword v[194:195], v159, off offset:-768

; #define LAS __attribute__((address_space(3)))
; __device__ __forceinline__ unsigned cvt_pk_bf16(float lo, float hi) { unsigned r; asm("v_cvt_pk_bf16_f32 %0, %1, %2" : "=v"(r) : "v"(lo), "v"(hi)); return r; }
; #define LDS_WAIT() asm volatile("s_waitcnt lgkmcnt(0)" ::: "memory")
; __device__ __forceinline__ void tstore_sub(const f32x4 (&v)[4][2], bf16_t* dst  , LAS unsigned char* x, int fr, int fq, int lane) {
; #pragma unroll
;     for (int m = 0; m < 4; ++m)
; #pragma unroll
;         for (int n = 0; n < 2; ++n)
; #pragma unroll
;             for (int j = 0; j < 4; ++j) {
;                 const int ch = 8 * fq + 4 * n + j, tok = 16 * m + fr;
;                 const unsigned b = cvt_pk_bf16(v[m][n][j], 0.f);
;                 *(LAS unsigned short*)(x + ch * 128 + ((((tok >> 3) ^ fq) << 4) | ((tok & 7) << 1))) = (unsigned short)b;
;             }
;     LDS_WAIT();
; #pragma unroll
;     for (int i = 0; i < 4; ++i) {
;         const int q = lane + 64 * i, ch = q >> 3, tc = q & 7;
;         const u32x4 o = *(const LAS u32x4*)(x + ch * 128 + ((tc ^ ((ch >> 3) & 3)) << 4));
;         *(u32x4*)(dst + (size_t)ch * T + tc * 8) = o;
;     }
;     LDS_WAIT();
; }
;     __device__ __forceinline__ void operator()(const f32x4 (&acc)[2][2][4][2], const Unit& u, int wr, int wc, int fr, int fq, LAS unsigned char* xs, int wid, int lane) const {
;     ...
;                     if (ODD) {
;                         float* vss = (float*)(ws + OFF_VSS);
; #pragma unroll
;                         for (int m = 0; m < 4; ++m) {
;                             float s = 0.f;
; #pragma unroll
;                             for (int n = 0; n < 2; ++n) s += (v[m][n][0] * v[m][n][0] + v[m][n][1] * v[m][n][1]) + (v[m][n][2] * v[m][n][2] + v[m][n][3] * v[m][n][3]);
;                             s += __shfl_xor(s, 16); s += __shfl_xor(s, 32);
;                             if (fq == 0) vss[(size_t)(row0 + ai * 128 + m * 16 + fr) * 32 + (2 * (pn - 24) + bj) * 4 + wc] = s;
;                         }
.LBB0_732:
	s_or_b64 exec, exec, s[74:75]
	v_cvt_pk_bf16_f32 v159, v208, v137
	ds_write_b16 v238, v159
	v_cvt_pk_bf16_f32 v159, v209, v137
	ds_write_b16 v238, v159 offset:128
	v_cvt_pk_bf16_f32 v159, v206, v137
	ds_write_b16 v238, v159 offset:256
	v_cvt_pk_bf16_f32 v159, v207, v137
	ds_write_b16 v238, v159 offset:384
	v_cvt_pk_bf16_f32 v159, v204, v137
	ds_write_b16 v238, v159 offset:512
	v_cvt_pk_bf16_f32 v159, v205, v137
	ds_write_b16 v238, v159 offset:640
	v_cvt_pk_bf16_f32 v159, v202, v137
	ds_write_b16 v238, v159 offset:768
	v_cvt_pk_bf16_f32 v159, v203, v137
	ds_write_b16 v238, v159 offset:896
	v_cvt_pk_bf16_f32 v159, v216, v137
	ds_write_b16 v239, v159
	v_cvt_pk_bf16_f32 v159, v217, v137
	ds_write_b16 v239, v159 offset:128
	v_cvt_pk_bf16_f32 v159, v214, v137
	ds_write_b16 v239, v159 offset:256
	v_cvt_pk_bf16_f32 v159, v215, v137
	ds_write_b16 v239, v159 offset:384
	v_cvt_pk_bf16_f32 v159, v212, v137
	ds_write_b16 v239, v159 offset:512
	v_cvt_pk_bf16_f32 v159, v213, v137
	ds_write_b16 v239, v159 offset:640
	v_cvt_pk_bf16_f32 v159, v210, v137
	ds_write_b16 v239, v159 offset:768
	v_cvt_pk_bf16_f32 v159, v211, v137
	ds_write_b16 v239, v159 offset:896
	v_cvt_pk_bf16_f32 v159, v224, v137
	ds_write_b16 v240, v159
	v_cvt_pk_bf16_f32 v159, v225, v137
	ds_write_b16 v240, v159 offset:128
	v_cvt_pk_bf16_f32 v159, v222, v137
	ds_write_b16 v240, v159 offset:256
	v_cvt_pk_bf16_f32 v159, v223, v137
	ds_write_b16 v240, v159 offset:384
	v_cvt_pk_bf16_f32 v159, v220, v137
	ds_write_b16 v240, v159 offset:512
	v_cvt_pk_bf16_f32 v159, v221, v137
	ds_write_b16 v240, v159 offset:640
	v_cvt_pk_bf16_f32 v159, v218, v137
	ds_write_b16 v240, v159 offset:768
	v_cvt_pk_bf16_f32 v159, v219, v137
	ds_write_b16 v240, v159 offset:896
	v_cvt_pk_bf16_f32 v159, v232, v137
	ds_write_b16 v241, v159
	v_cvt_pk_bf16_f32 v159, v233, v137
	ds_write_b16 v241, v159 offset:128
	v_cvt_pk_bf16_f32 v159, v230, v137
	ds_write_b16 v241, v159 offset:256
	v_cvt_pk_bf16_f32 v159, v231, v137
	ds_write_b16 v241, v159 offset:384
	v_cvt_pk_bf16_f32 v159, v228, v137
	ds_write_b16 v241, v159 offset:512
	v_cvt_pk_bf16_f32 v159, v229, v137
	v_mov_b32_e32 v167, v166
	ds_write_b16 v241, v159 offset:640
	v_cvt_pk_bf16_f32 v159, v226, v137
	v_mov_b32_e32 v202, v166
	v_mov_b32_e32 v203, v166
	ds_write_b16 v241, v159 offset:768
	v_cvt_pk_bf16_f32 v159, v227, v137
	v_pk_mul_f32 v[206:207], v[58:59], v[202:203]
	v_pk_mul_f32 v[208:209], v[56:57], v[166:167]
	ds_write_b16 v241, v159 offset:896
	v_mul_f32_e32 v159, v209, v209
	s_waitcnt lgkmcnt(14)
	v_mul_f32_e32 v161, v207, v207
	v_pk_mul_f32 v[202:203], v[50:51], v[202:203]
	v_pk_mul_f32 v[204:205], v[48:49], v[166:167]
	v_fmac_f32_e32 v159, v208, v208
	v_fmac_f32_e32 v161, v206, v206
	v_add_f32_e32 v159, v159, v161
	v_mul_f32_e32 v161, v205, v205
	v_mul_f32_e32 v163, v203, v203
	v_fmac_f32_e32 v161, v204, v204
	v_fmac_f32_e32 v163, v202, v202
	v_add_f32_e32 v161, v161, v163
	v_add_f32_e32 v159, v159, v161
	ds_bpermute_b32 v161, v151, v159
	s_waitcnt lgkmcnt(0)
	ds_read_b128 v[210:213], v242
	ds_read_b128 v[214:217], v243
	ds_read_b128 v[218:221], v244
	ds_read_b128 v[222:225], v245
	s_waitcnt lgkmcnt(3)
	global_store_dwordx4 v[186:187], v[210:213], off offset:256
	s_waitcnt lgkmcnt(2)
	global_store_dwordx4 v[188:189], v[214:217], off offset:256
	s_waitcnt lgkmcnt(1)
	global_store_dwordx4 v[190:191], v[218:221], off offset:256
	s_waitcnt lgkmcnt(0)
	global_store_dwordx4 v[192:193], v[222:225], off offset:256
	v_add_f32_e32 v159, v159, v161
	ds_bpermute_b32 v161, v246, v159
	s_waitcnt lgkmcnt(0)
	s_and_saveexec_b64 s[74:75], s[8:9]
	s_cbranch_execz .LBB0_734
	v_lshlrev_b64 v[186:187], 7, v[200:201]
	v_lshl_add_u64 v[186:187], s[66:67], 0, v[186:187]
	s_waitcnt lgkmcnt(0)
	v_add_f32_e32 v159, v159, v161
	global_store_dword v[186:187], v159, off offset:-752

; #define LAS __attribute__((address_space(3)))
; __device__ __forceinline__ unsigned cvt_pk_bf16(float lo, float hi) { unsigned r; asm("v_cvt_pk_bf16_f32 %0, %1, %2" : "=v"(r) : "v"(lo), "v"(hi)); return r; }
; __device__ __forceinline__ float silu_f(float x) { return x * __builtin_amdgcn_rcpf(1.f + __builtin_amdgcn_exp2f(-LOG2E * x)); }
; #define LDS_WAIT() asm volatile("s_waitcnt lgkmcnt(0)" ::: "memory")
; __device__ __forceinline__ void tstore_sub(const f32x4 (&v)[4][2], bf16_t* dst  , LAS unsigned char* x, int fr, int fq, int lane) {
; #pragma unroll
;     for (int m = 0; m < 4; ++m)
; #pragma unroll
;         for (int n = 0; n < 2; ++n)
; #pragma unroll
;             for (int j = 0; j < 4; ++j) {
;                 const int ch = 8 * fq + 4 * n + j, tok = 16 * m + fr;
;                 const unsigned b = cvt_pk_bf16(v[m][n][j], 0.f);
;                 *(LAS unsigned short*)(x + ch * 128 + ((((tok >> 3) ^ fq) << 4) | ((tok & 7) << 1))) = (unsigned short)b;
;             }
;     LDS_WAIT();
; #pragma unroll
;     for (int i = 0; i < 4; ++i) {
;         const int q = lane + 64 * i, ch = q >> 3, tc = q & 7;
;         const u32x4 o = *(const LAS u32x4*)(x + ch * 128 + ((tc ^ ((ch >> 3) & 3)) << 4));
;         *(u32x4*)(dst + (size_t)ch * T + tc * 8) = o;
;     }
;     LDS_WAIT();
; }
;     __device__ __forceinline__ void operator()(const f32x4 (&acc)[2][2][4][2], const Unit& u, int wr, int wc, int fr, int fq, LAS unsigned char* xs, int wid, int lane) const {
;     ...
;         } else if (mode == 1 || mode == 2) {
; #pragma unroll
;             for (int ai = 0; ai < 2; ++ai)
; #pragma unroll
;                 for (int m = 0; m < 4; ++m) {
;                     const float r = rs[ai][m];
;                     bf16_t* rowp = base + (size_t)(row0 + ai * 128 + m * 16 + fr) * ldc + wc * 32 + 8 * fq;
;                     float o[8];
; #pragma unroll
;                     for (int n = 0; n < 2; ++n)
; #pragma unroll
;                         for (int j = 0; j < 4; ++j) { const float a = acc[ai][0][m][n][j] * r, b = acc[ai][1][m][n][j] * r; o[4 * n + j] = (mode == 1) ? a * b : a * silu_f(b); }
;                     u32x4 w; w.x = cvt_pk_bf16(o[0], o[1]); w.y = cvt_pk_bf16(o[2], o[3]); w.z = cvt_pk_bf16(o[4], o[5]); w.w = cvt_pk_bf16(o[6], o[7]);
;                     *(u32x4*)rowp = w;
;                     __builtin_amdgcn_sched_barrier(0);
;                 }
.LBB0_740:
	s_or_b64 exec, exec, s[74:75]
	v_cvt_pk_bf16_f32 v151, v208, v137
	ds_write_b16 v238, v151
	v_cvt_pk_bf16_f32 v151, v209, v137
	ds_write_b16 v238, v151 offset:128
	v_cvt_pk_bf16_f32 v151, v206, v137
	ds_write_b16 v238, v151 offset:256
	v_cvt_pk_bf16_f32 v151, v207, v137
	ds_write_b16 v238, v151 offset:384
	v_cvt_pk_bf16_f32 v151, v204, v137
	ds_write_b16 v238, v151 offset:512
	v_cvt_pk_bf16_f32 v151, v205, v137
	ds_write_b16 v238, v151 offset:640
	v_cvt_pk_bf16_f32 v151, v202, v137
	ds_write_b16 v238, v151 offset:768
	v_cvt_pk_bf16_f32 v151, v203, v137
	ds_write_b16 v238, v151 offset:896
	v_cvt_pk_bf16_f32 v151, v192, v137
	ds_write_b16 v239, v151
	v_cvt_pk_bf16_f32 v151, v193, v137
	ds_write_b16 v239, v151 offset:128
	v_cvt_pk_bf16_f32 v151, v190, v137
	ds_write_b16 v239, v151 offset:256
	v_cvt_pk_bf16_f32 v151, v191, v137
	ds_write_b16 v239, v151 offset:384
	v_cvt_pk_bf16_f32 v151, v188, v137
	ds_write_b16 v239, v151 offset:512
	v_cvt_pk_bf16_f32 v151, v189, v137
	ds_write_b16 v239, v151 offset:640
	v_cvt_pk_bf16_f32 v151, v186, v137
	ds_write_b16 v239, v151 offset:768
	v_cvt_pk_bf16_f32 v151, v187, v137
	ds_write_b16 v239, v151 offset:896
	v_cvt_pk_bf16_f32 v151, v212, v137
	ds_write_b16 v240, v151
	v_cvt_pk_bf16_f32 v151, v213, v137
	ds_write_b16 v240, v151 offset:128
	v_cvt_pk_bf16_f32 v151, v210, v137
	ds_write_b16 v240, v151 offset:256
	v_cvt_pk_bf16_f32 v151, v211, v137
	ds_write_b16 v240, v151 offset:384
	v_cvt_pk_bf16_f32 v151, v200, v137
	ds_write_b16 v240, v151 offset:512
	v_cvt_pk_bf16_f32 v151, v201, v137
	ds_write_b16 v240, v151 offset:640
	v_cvt_pk_bf16_f32 v151, v198, v137
	ds_write_b16 v240, v151 offset:768
	v_cvt_pk_bf16_f32 v151, v199, v137
	ds_write_b16 v240, v151 offset:896
	v_cvt_pk_bf16_f32 v151, v218, v137
	ds_write_b16 v241, v151
	v_cvt_pk_bf16_f32 v151, v219, v137
	ds_write_b16 v241, v151 offset:128
	v_cvt_pk_bf16_f32 v151, v216, v137
	ds_write_b16 v241, v151 offset:256
	v_cvt_pk_bf16_f32 v151, v217, v137
	ds_write_b16 v241, v151 offset:384
	v_cvt_pk_bf16_f32 v151, v214, v137
	ds_write_b16 v241, v151 offset:512
	v_cvt_pk_bf16_f32 v151, v215, v137
	ds_write_b16 v241, v151 offset:640
	v_cvt_pk_bf16_f32 v151, v196, v137
	ds_write_b16 v241, v151 offset:768
	v_cvt_pk_bf16_f32 v151, v197, v137
	ds_write_b16 v241, v151 offset:896
	s_waitcnt lgkmcnt(0)
	ds_read_b128 v[186:189], v242
	ds_read_b128 v[190:193], v243
	s_mov_b32 s73, s49
	v_lshl_add_u64 v[176:177], v[176:177], 0, s[72:73]
	s_mov_b64 s[0:1], 0x100
	v_lshl_add_u64 v[176:177], v[176:177], 0, s[0:1]
	v_mov_b32_e32 v181, v137
	v_lshl_add_u64 v[180:181], v[176:177], 0, v[180:181]
	v_mov_b32_e32 v183, v137
	s_waitcnt lgkmcnt(1)
	global_store_dwordx4 v[180:181], v[186:189], off
	v_mov_b32_e32 v179, v137
	v_mov_b32_e32 v185, v137
	v_lshl_add_u64 v[186:187], v[176:177], 0, v[182:183]
	ds_read_b128 v[180:183], v244
	s_waitcnt lgkmcnt(1)
	global_store_dwordx4 v[186:187], v[190:193], off
	ds_read_b128 v[186:189], v245
	v_lshl_add_u64 v[178:179], v[176:177], 0, v[178:179]
	v_lshl_add_u64 v[176:177], v[176:177], 0, v[184:185]
	s_waitcnt lgkmcnt(1)
	global_store_dwordx4 v[178:179], v[180:183], off
	s_waitcnt lgkmcnt(0)
	global_store_dwordx4 v[176:177], v[186:189], off
	s_waitcnt lgkmcnt(0)
	s_branch .LBB0_707
.LBB0_741:
	s_waitcnt lgkmcnt(7)
	v_mul_f32_e32 v120, v120, v174
	v_mul_f32_e32 v159, 0xbfb8aa3b, v120
	s_add_u32 s0, s70, s89
	v_exp_f32_e32 v159, v159
	s_addc_u32 s1, s71, 0
	v_mov_b32_e32 v151, v137
	v_lshl_add_u64 v[176:177], s[0:1], 0, v[150:151]
	s_ashr_i32 s0, s68, 31
	v_mul_lo_u32 v151, s65, v162
	s_mul_i32 s0, s64, s0
	v_mad_u64_u32 v[178:179], s[18:19], s64, v162, 0
	v_add3_u32 v179, v179, s0, v151
	v_add_f32_e32 v151, 1.0, v159
	v_rcp_f32_e32 v151, v151
	v_mul_f32_e32 v121, v121, v174
	v_mul_f32_e32 v159, 0xbfb8aa3b, v121
	v_exp_f32_e32 v159, v159
	v_mul_f32_e32 v151, v120, v151
	v_mul_f32_e32 v124, v124, v174
	v_cndmask_b32_e64 v120, v151, v120, s[12:13]
	v_mul_f32_e32 v120, v124, v120
	v_add_f32_e32 v124, 1.0, v159
	v_mul_f32_e32 v122, v122, v174
	v_rcp_f32_e32 v124, v124
	v_mul_f32_e32 v151, 0xbfb8aa3b, v122
	v_exp_f32_e32 v151, v151
	v_mul_f32_e32 v123, v123, v174
	v_mul_f32_e32 v124, v121, v124
	v_cndmask_b32_e64 v121, v124, v121, s[12:13]
	v_add_f32_e32 v124, 1.0, v151
	v_mul_f32_e32 v151, 0xbfb8aa3b, v123
	v_exp_f32_e32 v151, v151
	v_mul_f32_e32 v125, v125, v174
	v_rcp_f32_e32 v124, v124
	v_mul_f32_e32 v121, v125, v121
	v_mul_f32_e32 v125, v126, v174
	v_add_f32_e32 v126, 1.0, v151
	v_rcp_f32_e32 v126, v126
	v_mul_f32_e32 v124, v122, v124
	v_cndmask_b32_e64 v122, v124, v122, s[12:13]
	v_mul_f32_e32 v112, v112, v174
	v_mul_f32_e32 v122, v125, v122
	v_mul_f32_e32 v125, v123, v126
	v_mul_f32_e32 v126, 0xbfb8aa3b, v112
	v_exp_f32_e32 v126, v126
	v_mul_f32_e32 v124, v127, v174
	v_cndmask_b32_e64 v123, v125, v123, s[12:13]
	v_mul_f32_e32 v123, v124, v123
	v_add_f32_e32 v124, 1.0, v126
	v_rcp_f32_e32 v124, v124
	v_mul_f32_e32 v113, v113, v174
	v_mul_f32_e32 v125, 0xbfb8aa3b, v113
	v_exp_f32_e32 v125, v125
	v_mul_f32_e32 v124, v112, v124
	v_mul_f32_e32 v116, v116, v174
	v_cndmask_b32_e64 v112, v124, v112, s[12:13]
	v_mul_f32_e32 v124, v116, v112
	v_add_f32_e32 v112, 1.0, v125
	v_mul_f32_e32 v114, v114, v174
	v_rcp_f32_e32 v112, v112
	v_mul_f32_e32 v116, 0xbfb8aa3b, v114
	v_exp_f32_e32 v116, v116
	v_mul_f32_e32 v115, v115, v174
	v_mul_f32_e32 v112, v113, v112
	v_cndmask_b32_e64 v112, v112, v113, s[12:13]
	v_add_f32_e32 v113, 1.0, v116
	v_mul_f32_e32 v116, 0xbfb8aa3b, v115
	v_exp_f32_e32 v116, v116
	v_rcp_f32_e32 v113, v113
	v_mul_f32_e32 v117, v117, v174
	v_mul_f32_e32 v125, v117, v112
	v_add_f32_e32 v116, 1.0, v116
	v_rcp_f32_e32 v116, v116
	v_mul_f32_e32 v113, v114, v113
	v_mul_f32_e32 v112, v118, v174
	v_cndmask_b32_e64 v113, v113, v114, s[12:13]
	v_mul_f32_e32 v118, v112, v113
	v_mul_f32_e32 v113, v115, v116
	v_mul_f32_e32 v112, v119, v174
	v_cndmask_b32_e64 v113, v113, v115, s[12:13]
	v_mul_f32_e32 v115, v112, v113
	v_lshl_add_u64 v[116:117], v[178:179], 1, v[176:177]
	v_cvt_pk_bf16_f32 v112, v120, v121
	v_cvt_pk_bf16_f32 v113, v122, v123
	v_cvt_pk_bf16_f32 v114, v124, v125
	v_cvt_pk_bf16_f32 v115, v118, v115
	global_store_dwordx4 v[116:117], v[112:115], off
	s_waitcnt lgkmcnt(6)
; __device__ __forceinline__ unsigned cvt_pk_bf16(float lo, float hi) { unsigned r; asm("v_cvt_pk_bf16_f32 %0, %1, %2" : "=v"(r) : "v"(lo), "v"(hi)); return r; }
; __device__ __forceinline__ float silu_f(float x) { return x * __builtin_amdgcn_rcpf(1.f + __builtin_amdgcn_exp2f(-LOG2E * x)); }
;     __device__ __forceinline__ void operator()(const f32x4 (&acc)[2][2][4][2], const Unit& u, int wr, int wc, int fr, int fq, LAS unsigned char* xs, int wid, int lane) const {
;     ...
;         } else if (mode == 1 || mode == 2) {
; #pragma unroll
;             for (int ai = 0; ai < 2; ++ai)
; #pragma unroll
;                 for (int m = 0; m < 4; ++m) {
;                     const float r = rs[ai][m];
;                     bf16_t* rowp = base + (size_t)(row0 + ai * 128 + m * 16 + fr) * ldc + wc * 32 + 8 * fq;
;                     float o[8];
; #pragma unroll
;                     for (int n = 0; n < 2; ++n)
; #pragma unroll
;                         for (int j = 0; j < 4; ++j) { const float a = acc[ai][0][m][n][j] * r, b = acc[ai][1][m][n][j] * r; o[4 * n + j] = (mode == 1) ? a * b : a * silu_f(b); }
;                     u32x4 w; w.x = cvt_pk_bf16(o[0], o[1]); w.y = cvt_pk_bf16(o[2], o[3]); w.z = cvt_pk_bf16(o[4], o[5]); w.w = cvt_pk_bf16(o[6], o[7]);
;                     *(u32x4*)rowp = w;
;                     __builtin_amdgcn_sched_barrier(0);
;                 }
	v_mul_f32_e32 v104, v104, v172
	v_mul_f32_e32 v113, 0xbfb8aa3b, v104
	v_exp_f32_e32 v115, v113
	v_or_b32_e32 v112, 16, v162
	v_mul_lo_u32 v114, s65, v112
	v_mad_u64_u32 v[112:113], s[18:19], s64, v112, 0
	v_add3_u32 v113, v113, s0, v114
	v_add_f32_e32 v114, 1.0, v115
	v_rcp_f32_e32 v114, v114
	v_mul_f32_e32 v105, v105, v172
	v_mul_f32_e32 v115, 0xbfb8aa3b, v105
	v_exp_f32_e32 v115, v115
	v_mul_f32_e32 v114, v104, v114
	v_mul_f32_e32 v108, v108, v172
	v_cndmask_b32_e64 v104, v114, v104, s[12:13]
	v_mul_f32_e32 v104, v108, v104
	v_add_f32_e32 v108, 1.0, v115
	v_mul_f32_e32 v106, v106, v172
	v_rcp_f32_e32 v108, v108
	v_mul_f32_e32 v114, 0xbfb8aa3b, v106
	v_exp_f32_e32 v114, v114
	v_mul_f32_e32 v107, v107, v172
	v_mul_f32_e32 v108, v105, v108
	v_cndmask_b32_e64 v105, v108, v105, s[12:13]
	v_add_f32_e32 v108, 1.0, v114
	v_mul_f32_e32 v114, 0xbfb8aa3b, v107
	v_exp_f32_e32 v114, v114
	v_mul_f32_e32 v109, v109, v172
	v_rcp_f32_e32 v108, v108
	v_mul_f32_e32 v105, v109, v105
	v_mul_f32_e32 v109, v110, v172
	v_add_f32_e32 v110, 1.0, v114
	v_rcp_f32_e32 v110, v110
	v_mul_f32_e32 v108, v106, v108
	v_cndmask_b32_e64 v106, v108, v106, s[12:13]
	v_mul_f32_e32 v96, v96, v172
	v_mul_f32_e32 v106, v109, v106
	v_mul_f32_e32 v109, v107, v110
	v_mul_f32_e32 v110, 0xbfb8aa3b, v96
	v_exp_f32_e32 v110, v110
	v_mul_f32_e32 v108, v111, v172
	v_cndmask_b32_e64 v107, v109, v107, s[12:13]
	v_mul_f32_e32 v107, v108, v107
	v_add_f32_e32 v108, 1.0, v110
	v_rcp_f32_e32 v108, v108
	v_mul_f32_e32 v97, v97, v172
	v_mul_f32_e32 v109, 0xbfb8aa3b, v97
	v_exp_f32_e32 v109, v109
	v_mul_f32_e32 v108, v96, v108
	v_mul_f32_e32 v100, v100, v172
	v_cndmask_b32_e64 v96, v108, v96, s[12:13]
	v_mul_f32_e32 v108, v100, v96
	v_add_f32_e32 v96, 1.0, v109
	v_mul_f32_e32 v98, v98, v172
	v_rcp_f32_e32 v96, v96
	v_mul_f32_e32 v100, 0xbfb8aa3b, v98
	v_exp_f32_e32 v100, v100
	v_mul_f32_e32 v99, v99, v172
	v_mul_f32_e32 v96, v97, v96
	v_cndmask_b32_e64 v96, v96, v97, s[12:13]
	v_add_f32_e32 v97, 1.0, v100
	v_mul_f32_e32 v100, 0xbfb8aa3b, v99
	v_exp_f32_e32 v100, v100
	v_rcp_f32_e32 v97, v97
	v_mul_f32_e32 v101, v101, v172
	v_mul_f32_e32 v109, v101, v96
	v_add_f32_e32 v100, 1.0, v100
	v_rcp_f32_e32 v100, v100
	v_mul_f32_e32 v97, v98, v97
	v_mul_f32_e32 v96, v102, v172
	v_cndmask_b32_e64 v97, v97, v98, s[12:13]
	v_mul_f32_e32 v102, v96, v97
	v_mul_f32_e32 v97, v99, v100
	v_mul_f32_e32 v96, v103, v172
	v_cndmask_b32_e64 v97, v97, v99, s[12:13]
	v_mul_f32_e32 v99, v96, v97
	v_lshl_add_u64 v[100:101], v[112:113], 1, v[176:177]
	v_cvt_pk_bf16_f32 v96, v104, v105
	v_cvt_pk_bf16_f32 v97, v106, v107
	v_cvt_pk_bf16_f32 v98, v108, v109
	v_cvt_pk_bf16_f32 v99, v102, v99
	global_store_dwordx4 v[100:101], v[96:99], off
	s_waitcnt lgkmcnt(5)
	v_mul_f32_e32 v88, v88, v170
	v_mul_f32_e32 v97, 0xbfb8aa3b, v88
	v_exp_f32_e32 v99, v97
	v_or_b32_e32 v96, 32, v162
	v_mul_lo_u32 v98, s65, v96
	v_mad_u64_u32 v[96:97], s[18:19], s64, v96, 0
	v_add3_u32 v97, v97, s0, v98
	v_add_f32_e32 v98, 1.0, v99
	v_rcp_f32_e32 v98, v98
	v_mul_f32_e32 v89, v89, v170
	v_mul_f32_e32 v99, 0xbfb8aa3b, v89
	v_exp_f32_e32 v99, v99
	v_mul_f32_e32 v98, v88, v98
	v_mul_f32_e32 v92, v92, v170
	v_cndmask_b32_e64 v88, v98, v88, s[12:13]
	v_mul_f32_e32 v88, v92, v88
	v_add_f32_e32 v92, 1.0, v99
	v_mul_f32_e32 v90, v90, v170
	v_rcp_f32_e32 v92, v92
	v_mul_f32_e32 v98, 0xbfb8aa3b, v90
	v_exp_f32_e32 v98, v98
	v_mul_f32_e32 v91, v91, v170
	v_mul_f32_e32 v92, v89, v92
	v_cndmask_b32_e64 v89, v92, v89, s[12:13]
	v_add_f32_e32 v92, 1.0, v98
	v_mul_f32_e32 v98, 0xbfb8aa3b, v91
	v_exp_f32_e32 v98, v98
	v_mul_f32_e32 v93, v93, v170
	v_rcp_f32_e32 v92, v92
	v_mul_f32_e32 v89, v93, v89
	v_mul_f32_e32 v93, v94, v170
	v_add_f32_e32 v94, 1.0, v98
	v_rcp_f32_e32 v94, v94
	v_mul_f32_e32 v92, v90, v92
	v_cndmask_b32_e64 v90, v92, v90, s[12:13]
	v_mul_f32_e32 v80, v80, v170
	v_mul_f32_e32 v90, v93, v90
	v_mul_f32_e32 v93, v91, v94
	v_mul_f32_e32 v94, 0xbfb8aa3b, v80
	v_exp_f32_e32 v94, v94
	v_mul_f32_e32 v92, v95, v170
	v_cndmask_b32_e64 v91, v93, v91, s[12:13]
	v_mul_f32_e32 v91, v92, v91
	v_add_f32_e32 v92, 1.0, v94
	v_rcp_f32_e32 v92, v92
	v_mul_f32_e32 v81, v81, v170
	v_mul_f32_e32 v93, 0xbfb8aa3b, v81
	v_exp_f32_e32 v93, v93
	v_mul_f32_e32 v92, v80, v92
	v_mul_f32_e32 v84, v84, v170
	v_cndmask_b32_e64 v80, v92, v80, s[12:13]
	v_mul_f32_e32 v92, v84, v80
	v_add_f32_e32 v80, 1.0, v93
	v_mul_f32_e32 v82, v82, v170
	v_rcp_f32_e32 v80, v80
	v_mul_f32_e32 v84, 0xbfb8aa3b, v82
	v_exp_f32_e32 v84, v84
	v_mul_f32_e32 v83, v83, v170
	v_mul_f32_e32 v80, v81, v80
	v_cndmask_b32_e64 v80, v80, v81, s[12:13]
	v_add_f32_e32 v81, 1.0, v84
	v_mul_f32_e32 v84, 0xbfb8aa3b, v83
	v_exp_f32_e32 v84, v84
	v_rcp_f32_e32 v81, v81
	v_mul_f32_e32 v85, v85, v170
	v_mul_f32_e32 v93, v85, v80
	v_add_f32_e32 v84, 1.0, v84
	v_rcp_f32_e32 v84, v84
	v_mul_f32_e32 v81, v82, v81
	v_mul_f32_e32 v80, v86, v170
	v_cndmask_b32_e64 v81, v81, v82, s[12:13]
	v_mul_f32_e32 v86, v80, v81
	v_mul_f32_e32 v81, v83, v84
	v_mul_f32_e32 v80, v87, v170
	v_cndmask_b32_e64 v81, v81, v83, s[12:13]
	v_mul_f32_e32 v83, v80, v81
	v_lshl_add_u64 v[84:85], v[96:97], 1, v[176:177]
	v_cvt_pk_bf16_f32 v80, v88, v89
	v_cvt_pk_bf16_f32 v81, v90, v91
	v_cvt_pk_bf16_f32 v82, v92, v93
	v_cvt_pk_bf16_f32 v83, v86, v83
	global_store_dwordx4 v[84:85], v[80:83], off
	s_waitcnt lgkmcnt(4)
; __device__ __forceinline__ unsigned cvt_pk_bf16(float lo, float hi) { unsigned r; asm("v_cvt_pk_bf16_f32 %0, %1, %2" : "=v"(r) : "v"(lo), "v"(hi)); return r; }
; __device__ __forceinline__ float silu_f(float x) { return x * __builtin_amdgcn_rcpf(1.f + __builtin_amdgcn_exp2f(-LOG2E * x)); }
;     __device__ __forceinline__ void operator()(const f32x4 (&acc)[2][2][4][2], const Unit& u, int wr, int wc, int fr, int fq, LAS unsigned char* xs, int wid, int lane) const {
;     ...
;         } else if (mode == 1 || mode == 2) {
; #pragma unroll
;             for (int ai = 0; ai < 2; ++ai)
; #pragma unroll
;                 for (int m = 0; m < 4; ++m) {
;                     const float r = rs[ai][m];
;                     bf16_t* rowp = base + (size_t)(row0 + ai * 128 + m * 16 + fr) * ldc + wc * 32 + 8 * fq;
;                     float o[8];
; #pragma unroll
;                     for (int n = 0; n < 2; ++n)
; #pragma unroll
;                         for (int j = 0; j < 4; ++j) { const float a = acc[ai][0][m][n][j] * r, b = acc[ai][1][m][n][j] * r; o[4 * n + j] = (mode == 1) ? a * b : a * silu_f(b); }
;                     u32x4 w; w.x = cvt_pk_bf16(o[0], o[1]); w.y = cvt_pk_bf16(o[2], o[3]); w.z = cvt_pk_bf16(o[4], o[5]); w.w = cvt_pk_bf16(o[6], o[7]);
;                     *(u32x4*)rowp = w;
;                     __builtin_amdgcn_sched_barrier(0);
;                 }
	v_mul_f32_e32 v72, v72, v168
	v_mul_f32_e32 v81, 0xbfb8aa3b, v72
	v_exp_f32_e32 v83, v81
	v_or_b32_e32 v80, 48, v162
	v_mul_lo_u32 v82, s65, v80
	v_mad_u64_u32 v[80:81], s[18:19], s64, v80, 0
	v_add3_u32 v81, v81, s0, v82
	v_add_f32_e32 v82, 1.0, v83
	v_rcp_f32_e32 v82, v82
	v_mul_f32_e32 v73, v73, v168
	v_mul_f32_e32 v83, 0xbfb8aa3b, v73
	v_exp_f32_e32 v83, v83
	v_mul_f32_e32 v82, v72, v82
	v_mul_f32_e32 v76, v76, v168
	v_cndmask_b32_e64 v72, v82, v72, s[12:13]
	v_mul_f32_e32 v72, v76, v72
	v_add_f32_e32 v76, 1.0, v83
	v_mul_f32_e32 v74, v74, v168
	v_rcp_f32_e32 v76, v76
	v_mul_f32_e32 v82, 0xbfb8aa3b, v74
	v_exp_f32_e32 v82, v82
	v_mul_f32_e32 v75, v75, v168
	v_mul_f32_e32 v76, v73, v76
	v_cndmask_b32_e64 v73, v76, v73, s[12:13]
	v_add_f32_e32 v76, 1.0, v82
	v_mul_f32_e32 v82, 0xbfb8aa3b, v75
	v_exp_f32_e32 v82, v82
	v_mul_f32_e32 v77, v77, v168
	v_rcp_f32_e32 v76, v76
	v_mul_f32_e32 v73, v77, v73
	v_mul_f32_e32 v77, v78, v168
	v_add_f32_e32 v78, 1.0, v82
	v_rcp_f32_e32 v78, v78
	v_mul_f32_e32 v76, v74, v76
	v_cndmask_b32_e64 v74, v76, v74, s[12:13]
	v_mul_f32_e32 v64, v64, v168
	v_mul_f32_e32 v74, v77, v74
	v_mul_f32_e32 v77, v75, v78
	v_mul_f32_e32 v78, 0xbfb8aa3b, v64
	v_exp_f32_e32 v78, v78
	v_mul_f32_e32 v76, v79, v168
	v_cndmask_b32_e64 v75, v77, v75, s[12:13]
	v_mul_f32_e32 v75, v76, v75
	v_add_f32_e32 v76, 1.0, v78
	v_rcp_f32_e32 v76, v76
	v_mul_f32_e32 v65, v65, v168
	v_mul_f32_e32 v77, 0xbfb8aa3b, v65
	v_exp_f32_e32 v77, v77
	v_mul_f32_e32 v76, v64, v76
	v_mul_f32_e32 v68, v68, v168
	v_cndmask_b32_e64 v64, v76, v64, s[12:13]
	v_mul_f32_e32 v76, v68, v64
	v_add_f32_e32 v64, 1.0, v77
	v_mul_f32_e32 v66, v66, v168
	v_rcp_f32_e32 v64, v64
	v_mul_f32_e32 v68, 0xbfb8aa3b, v66
	v_exp_f32_e32 v68, v68
	v_mul_f32_e32 v67, v67, v168
	v_mul_f32_e32 v64, v65, v64
	v_cndmask_b32_e64 v64, v64, v65, s[12:13]
	v_add_f32_e32 v65, 1.0, v68
	v_mul_f32_e32 v68, 0xbfb8aa3b, v67
	v_exp_f32_e32 v68, v68
	v_rcp_f32_e32 v65, v65
	v_mul_f32_e32 v69, v69, v168
	v_mul_f32_e32 v77, v69, v64
	v_add_f32_e32 v68, 1.0, v68
	v_rcp_f32_e32 v68, v68
	v_mul_f32_e32 v65, v66, v65
	v_mul_f32_e32 v64, v70, v168
	v_cndmask_b32_e64 v65, v65, v66, s[12:13]
	v_mul_f32_e32 v70, v64, v65
	v_mul_f32_e32 v65, v67, v68
	v_mul_f32_e32 v64, v71, v168
	v_cndmask_b32_e64 v65, v65, v67, s[12:13]
	v_mul_f32_e32 v67, v64, v65
	v_lshl_add_u64 v[68:69], v[80:81], 1, v[176:177]
	v_cvt_pk_bf16_f32 v64, v72, v73
	v_cvt_pk_bf16_f32 v65, v74, v75
	v_cvt_pk_bf16_f32 v66, v76, v77
	v_cvt_pk_bf16_f32 v67, v70, v67
	global_store_dwordx4 v[68:69], v[64:67], off
	s_nop 1
	v_add_u32_e32 v64, 0x80, v162
	v_ashrrev_i32_e32 v65, 31, v64
	s_waitcnt lgkmcnt(3)
	v_mul_f32_e32 v56, v56, v166
	v_mul_lo_u32 v66, s64, v65
	v_mul_f32_e32 v65, 0xbfb8aa3b, v56
	v_exp_f32_e32 v68, v65
	v_mul_lo_u32 v67, s65, v64
	v_mad_u64_u32 v[64:65], s[0:1], s64, v64, 0
	v_add3_u32 v65, v65, v66, v67
	v_add_f32_e32 v66, 1.0, v68
	v_rcp_f32_e32 v66, v66
	v_mul_f32_e32 v57, v57, v166
	v_mul_f32_e32 v67, 0xbfb8aa3b, v57
	v_exp_f32_e32 v67, v67
	v_mul_f32_e32 v66, v56, v66
	v_mul_f32_e32 v60, v60, v166
	v_cndmask_b32_e64 v56, v66, v56, s[12:13]
	v_mul_f32_e32 v56, v60, v56
	v_add_f32_e32 v60, 1.0, v67
	v_mul_f32_e32 v58, v58, v166
	v_rcp_f32_e32 v60, v60
	v_mul_f32_e32 v66, 0xbfb8aa3b, v58
	v_exp_f32_e32 v66, v66
	v_mul_f32_e32 v59, v59, v166
	v_mul_f32_e32 v60, v57, v60
	v_cndmask_b32_e64 v57, v60, v57, s[12:13]
	v_add_f32_e32 v60, 1.0, v66
	v_mul_f32_e32 v66, 0xbfb8aa3b, v59
	v_exp_f32_e32 v66, v66
	v_mul_f32_e32 v61, v61, v166
	v_rcp_f32_e32 v60, v60
	v_mul_f32_e32 v57, v61, v57
	v_mul_f32_e32 v61, v62, v166
	v_add_f32_e32 v62, 1.0, v66
	v_rcp_f32_e32 v62, v62
	v_mul_f32_e32 v60, v58, v60
	v_cndmask_b32_e64 v58, v60, v58, s[12:13]
	v_mul_f32_e32 v48, v48, v166
	v_mul_f32_e32 v58, v61, v58
	v_mul_f32_e32 v61, v59, v62
	v_mul_f32_e32 v62, 0xbfb8aa3b, v48
	v_exp_f32_e32 v62, v62
	v_mul_f32_e32 v60, v63, v166
	v_cndmask_b32_e64 v59, v61, v59, s[12:13]
	v_mul_f32_e32 v59, v60, v59
	v_add_f32_e32 v60, 1.0, v62
	v_rcp_f32_e32 v60, v60
	v_mul_f32_e32 v49, v49, v166
	v_mul_f32_e32 v61, 0xbfb8aa3b, v49
	v_exp_f32_e32 v61, v61
	v_mul_f32_e32 v60, v48, v60
	v_mul_f32_e32 v52, v52, v166
	v_cndmask_b32_e64 v48, v60, v48, s[12:13]
	v_mul_f32_e32 v60, v52, v48
	v_add_f32_e32 v48, 1.0, v61
	v_mul_f32_e32 v50, v50, v166
	v_rcp_f32_e32 v48, v48
	v_mul_f32_e32 v52, 0xbfb8aa3b, v50
	v_exp_f32_e32 v52, v52
	v_mul_f32_e32 v51, v51, v166
	v_mul_f32_e32 v48, v49, v48
	v_cndmask_b32_e64 v48, v48, v49, s[12:13]
	v_add_f32_e32 v49, 1.0, v52
	v_mul_f32_e32 v52, 0xbfb8aa3b, v51
	v_exp_f32_e32 v52, v52
	v_rcp_f32_e32 v49, v49
	v_mul_f32_e32 v53, v53, v166
	v_mul_f32_e32 v61, v53, v48
	v_add_f32_e32 v52, 1.0, v52
	v_rcp_f32_e32 v52, v52
	v_mul_f32_e32 v49, v50, v49
	v_mul_f32_e32 v48, v54, v166
	v_cndmask_b32_e64 v49, v49, v50, s[12:13]
	v_mul_f32_e32 v54, v48, v49
	v_mul_f32_e32 v49, v51, v52
	v_mul_f32_e32 v48, v55, v166
	v_cndmask_b32_e64 v49, v49, v51, s[12:13]
	v_mul_f32_e32 v51, v48, v49
	v_lshl_add_u64 v[52:53], v[64:65], 1, v[176:177]
	v_cvt_pk_bf16_f32 v48, v56, v57
	v_cvt_pk_bf16_f32 v49, v58, v59
	v_cvt_pk_bf16_f32 v50, v60, v61
	v_cvt_pk_bf16_f32 v51, v54, v51
	global_store_dwordx4 v[52:53], v[48:51], off
	s_nop 1
	v_add_u32_e32 v48, 0x90, v162
	v_ashrrev_i32_e32 v49, 31, v48
	s_waitcnt lgkmcnt(2)
; __device__ __forceinline__ unsigned cvt_pk_bf16(float lo, float hi) { unsigned r; asm("v_cvt_pk_bf16_f32 %0, %1, %2" : "=v"(r) : "v"(lo), "v"(hi)); return r; }
; __device__ __forceinline__ float silu_f(float x) { return x * __builtin_amdgcn_rcpf(1.f + __builtin_amdgcn_exp2f(-LOG2E * x)); }
;     __device__ __forceinline__ void operator()(const f32x4 (&acc)[2][2][4][2], const Unit& u, int wr, int wc, int fr, int fq, LAS unsigned char* xs, int wid, int lane) const {
;     ...
;         } else if (mode == 1 || mode == 2) {
; #pragma unroll
;             for (int ai = 0; ai < 2; ++ai)
; #pragma unroll
;                 for (int m = 0; m < 4; ++m) {
;                     const float r = rs[ai][m];
;                     bf16_t* rowp = base + (size_t)(row0 + ai * 128 + m * 16 + fr) * ldc + wc * 32 + 8 * fq;
;                     float o[8];
; #pragma unroll
;                     for (int n = 0; n < 2; ++n)
; #pragma unroll
;                         for (int j = 0; j < 4; ++j) { const float a = acc[ai][0][m][n][j] * r, b = acc[ai][1][m][n][j] * r; o[4 * n + j] = (mode == 1) ? a * b : a * silu_f(b); }
;                     u32x4 w; w.x = cvt_pk_bf16(o[0], o[1]); w.y = cvt_pk_bf16(o[2], o[3]); w.z = cvt_pk_bf16(o[4], o[5]); w.w = cvt_pk_bf16(o[6], o[7]);
;                     *(u32x4*)rowp = w;
;                     __builtin_amdgcn_sched_barrier(0);
;                 }
	v_mul_f32_e32 v40, v40, v164
	v_mul_lo_u32 v50, s64, v49
	v_mul_f32_e32 v49, 0xbfb8aa3b, v40
	v_exp_f32_e32 v52, v49
	v_mul_lo_u32 v51, s65, v48
	v_mad_u64_u32 v[48:49], s[0:1], s64, v48, 0
	v_add3_u32 v49, v49, v50, v51
	v_add_f32_e32 v50, 1.0, v52
	v_rcp_f32_e32 v50, v50
	v_mul_f32_e32 v41, v41, v164
	v_mul_f32_e32 v51, 0xbfb8aa3b, v41
	v_exp_f32_e32 v51, v51
	v_mul_f32_e32 v50, v40, v50
	v_mul_f32_e32 v44, v44, v164
	v_cndmask_b32_e64 v40, v50, v40, s[12:13]
	v_mul_f32_e32 v40, v44, v40
	v_add_f32_e32 v44, 1.0, v51
	v_mul_f32_e32 v42, v42, v164
	v_rcp_f32_e32 v44, v44
	v_mul_f32_e32 v50, 0xbfb8aa3b, v42
	v_exp_f32_e32 v50, v50
	v_mul_f32_e32 v43, v43, v164
	v_mul_f32_e32 v44, v41, v44
	v_cndmask_b32_e64 v41, v44, v41, s[12:13]
	v_add_f32_e32 v44, 1.0, v50
	v_mul_f32_e32 v50, 0xbfb8aa3b, v43
	v_exp_f32_e32 v50, v50
	v_mul_f32_e32 v45, v45, v164
	v_rcp_f32_e32 v44, v44
	v_mul_f32_e32 v41, v45, v41
	v_mul_f32_e32 v45, v46, v164
	v_add_f32_e32 v46, 1.0, v50
	v_rcp_f32_e32 v46, v46
	v_mul_f32_e32 v44, v42, v44
	v_cndmask_b32_e64 v42, v44, v42, s[12:13]
	v_mul_f32_e32 v32, v32, v164
	v_mul_f32_e32 v42, v45, v42
	v_mul_f32_e32 v45, v43, v46
	v_mul_f32_e32 v46, 0xbfb8aa3b, v32
	v_exp_f32_e32 v46, v46
	v_mul_f32_e32 v44, v47, v164
	v_cndmask_b32_e64 v43, v45, v43, s[12:13]
	v_mul_f32_e32 v43, v44, v43
	v_add_f32_e32 v44, 1.0, v46
	v_rcp_f32_e32 v44, v44
	v_mul_f32_e32 v33, v33, v164
	v_mul_f32_e32 v45, 0xbfb8aa3b, v33
	v_exp_f32_e32 v45, v45
	v_mul_f32_e32 v44, v32, v44
	v_mul_f32_e32 v36, v36, v164
	v_cndmask_b32_e64 v32, v44, v32, s[12:13]
	v_mul_f32_e32 v44, v36, v32
	v_add_f32_e32 v32, 1.0, v45
	v_mul_f32_e32 v34, v34, v164
	v_rcp_f32_e32 v32, v32
	v_mul_f32_e32 v36, 0xbfb8aa3b, v34
	v_exp_f32_e32 v36, v36
	v_mul_f32_e32 v35, v35, v164
	v_mul_f32_e32 v32, v33, v32
	v_cndmask_b32_e64 v32, v32, v33, s[12:13]
	v_add_f32_e32 v33, 1.0, v36
	v_mul_f32_e32 v36, 0xbfb8aa3b, v35
	v_exp_f32_e32 v36, v36
	v_rcp_f32_e32 v33, v33
	v_mul_f32_e32 v37, v37, v164
	v_mul_f32_e32 v45, v37, v32
	v_add_f32_e32 v36, 1.0, v36
	v_rcp_f32_e32 v36, v36
	v_mul_f32_e32 v33, v34, v33
	v_mul_f32_e32 v32, v38, v164
	v_cndmask_b32_e64 v33, v33, v34, s[12:13]
	v_mul_f32_e32 v38, v32, v33
	v_mul_f32_e32 v33, v35, v36
	v_mul_f32_e32 v32, v39, v164
	v_cndmask_b32_e64 v33, v33, v35, s[12:13]
	v_mul_f32_e32 v35, v32, v33
	v_lshl_add_u64 v[36:37], v[48:49], 1, v[176:177]
	v_cvt_pk_bf16_f32 v32, v40, v41
	v_cvt_pk_bf16_f32 v33, v42, v43
	v_cvt_pk_bf16_f32 v34, v44, v45
	v_cvt_pk_bf16_f32 v35, v38, v35
	global_store_dwordx4 v[36:37], v[32:35], off
	s_nop 1
	v_add_u32_e32 v32, 0xa0, v162
	v_ashrrev_i32_e32 v33, 31, v32
	s_waitcnt lgkmcnt(1)
; __device__ __forceinline__ unsigned cvt_pk_bf16(float lo, float hi) { unsigned r; asm("v_cvt_pk_bf16_f32 %0, %1, %2" : "=v"(r) : "v"(lo), "v"(hi)); return r; }
; __device__ __forceinline__ float silu_f(float x) { return x * __builtin_amdgcn_rcpf(1.f + __builtin_amdgcn_exp2f(-LOG2E * x)); }
;     __device__ __forceinline__ void operator()(const f32x4 (&acc)[2][2][4][2], const Unit& u, int wr, int wc, int fr, int fq, LAS unsigned char* xs, int wid, int lane) const {
;     ...
;         } else if (mode == 1 || mode == 2) {
; #pragma unroll
;             for (int ai = 0; ai < 2; ++ai)
; #pragma unroll
;                 for (int m = 0; m < 4; ++m) {
;                     const float r = rs[ai][m];
;                     bf16_t* rowp = base + (size_t)(row0 + ai * 128 + m * 16 + fr) * ldc + wc * 32 + 8 * fq;
;                     float o[8];
; #pragma unroll
;                     for (int n = 0; n < 2; ++n)
; #pragma unroll
;                         for (int j = 0; j < 4; ++j) { const float a = acc[ai][0][m][n][j] * r, b = acc[ai][1][m][n][j] * r; o[4 * n + j] = (mode == 1) ? a * b : a * silu_f(b); }
;                     u32x4 w; w.x = cvt_pk_bf16(o[0], o[1]); w.y = cvt_pk_bf16(o[2], o[3]); w.z = cvt_pk_bf16(o[4], o[5]); w.w = cvt_pk_bf16(o[6], o[7]);
;                     *(u32x4*)rowp = w;
;                     __builtin_amdgcn_sched_barrier(0);
;                 }
	v_mul_f32_e32 v24, v24, v160
	v_mul_lo_u32 v34, s64, v33
	v_mul_f32_e32 v33, 0xbfb8aa3b, v24
	v_exp_f32_e32 v36, v33
	v_mul_lo_u32 v35, s65, v32
	v_mad_u64_u32 v[32:33], s[0:1], s64, v32, 0
	v_add3_u32 v33, v33, v34, v35
	v_add_f32_e32 v34, 1.0, v36
	v_rcp_f32_e32 v34, v34
	v_mul_f32_e32 v25, v25, v160
	v_mul_f32_e32 v35, 0xbfb8aa3b, v25
	v_exp_f32_e32 v35, v35
	v_mul_f32_e32 v34, v24, v34
	v_mul_f32_e32 v28, v28, v160
	v_cndmask_b32_e64 v24, v34, v24, s[12:13]
	v_mul_f32_e32 v24, v28, v24
	v_add_f32_e32 v28, 1.0, v35
	v_mul_f32_e32 v26, v26, v160
	v_rcp_f32_e32 v28, v28
	v_mul_f32_e32 v34, 0xbfb8aa3b, v26
	v_exp_f32_e32 v34, v34
	v_mul_f32_e32 v27, v27, v160
	v_mul_f32_e32 v28, v25, v28
	v_cndmask_b32_e64 v25, v28, v25, s[12:13]
	v_add_f32_e32 v28, 1.0, v34
	v_mul_f32_e32 v34, 0xbfb8aa3b, v27
	v_exp_f32_e32 v34, v34
	v_mul_f32_e32 v29, v29, v160
	v_rcp_f32_e32 v28, v28
	v_mul_f32_e32 v25, v29, v25
	v_mul_f32_e32 v29, v30, v160
	v_add_f32_e32 v30, 1.0, v34
	v_rcp_f32_e32 v30, v30
	v_mul_f32_e32 v28, v26, v28
	v_cndmask_b32_e64 v26, v28, v26, s[12:13]
	v_mul_f32_e32 v16, v16, v160
	v_mul_f32_e32 v26, v29, v26
	v_mul_f32_e32 v29, v27, v30
	v_mul_f32_e32 v30, 0xbfb8aa3b, v16
	v_exp_f32_e32 v30, v30
	v_mul_f32_e32 v28, v31, v160
	v_cndmask_b32_e64 v27, v29, v27, s[12:13]
	v_mul_f32_e32 v27, v28, v27
	v_add_f32_e32 v28, 1.0, v30
	v_rcp_f32_e32 v28, v28
	v_mul_f32_e32 v17, v17, v160
	v_mul_f32_e32 v29, 0xbfb8aa3b, v17
	v_exp_f32_e32 v29, v29
	v_mul_f32_e32 v28, v16, v28
	v_mul_f32_e32 v20, v20, v160
	v_cndmask_b32_e64 v16, v28, v16, s[12:13]
	v_mul_f32_e32 v28, v20, v16
	v_add_f32_e32 v16, 1.0, v29
	v_mul_f32_e32 v18, v18, v160
	v_rcp_f32_e32 v16, v16
	v_mul_f32_e32 v20, 0xbfb8aa3b, v18
	v_exp_f32_e32 v20, v20
	v_mul_f32_e32 v19, v19, v160
	v_mul_f32_e32 v16, v17, v16
	v_cndmask_b32_e64 v16, v16, v17, s[12:13]
	v_add_f32_e32 v17, 1.0, v20
	v_mul_f32_e32 v20, 0xbfb8aa3b, v19
	v_exp_f32_e32 v20, v20
	v_rcp_f32_e32 v17, v17
	v_mul_f32_e32 v21, v21, v160
	v_mul_f32_e32 v29, v21, v16
	v_add_f32_e32 v20, 1.0, v20
	v_rcp_f32_e32 v20, v20
	v_mul_f32_e32 v17, v18, v17
	v_mul_f32_e32 v16, v22, v160
	v_cndmask_b32_e64 v17, v17, v18, s[12:13]
	v_mul_f32_e32 v22, v16, v17
	v_mul_f32_e32 v17, v19, v20
	v_mul_f32_e32 v16, v23, v160
	v_cndmask_b32_e64 v17, v17, v19, s[12:13]
	v_mul_f32_e32 v19, v16, v17
	v_lshl_add_u64 v[20:21], v[32:33], 1, v[176:177]
	v_cvt_pk_bf16_f32 v16, v24, v25
	v_cvt_pk_bf16_f32 v17, v26, v27
	v_cvt_pk_bf16_f32 v18, v28, v29
	v_cvt_pk_bf16_f32 v19, v22, v19
	global_store_dwordx4 v[20:21], v[16:19], off
	s_nop 1
	v_add_u32_e32 v16, 0xb0, v162
	v_ashrrev_i32_e32 v17, 31, v16
	s_waitcnt lgkmcnt(0)
	v_mul_f32_e32 v8, v8, v158
	v_mul_lo_u32 v18, s64, v17
	v_mul_f32_e32 v17, 0xbfb8aa3b, v8
	v_exp_f32_e32 v20, v17
	v_mul_lo_u32 v19, s65, v16
	v_mad_u64_u32 v[16:17], s[0:1], s64, v16, 0
	v_add3_u32 v17, v17, v18, v19
	v_add_f32_e32 v18, 1.0, v20
	v_rcp_f32_e32 v18, v18
	v_mul_f32_e32 v9, v9, v158
	v_mul_f32_e32 v19, 0xbfb8aa3b, v9
	v_exp_f32_e32 v19, v19
	v_mul_f32_e32 v18, v8, v18
	v_mul_f32_e32 v12, v12, v158
	v_cndmask_b32_e64 v8, v18, v8, s[12:13]
	v_mul_f32_e32 v8, v12, v8
	v_add_f32_e32 v12, 1.0, v19
	v_mul_f32_e32 v10, v10, v158
	v_rcp_f32_e32 v12, v12
	v_mul_f32_e32 v18, 0xbfb8aa3b, v10
	v_exp_f32_e32 v18, v18
	v_mul_f32_e32 v11, v11, v158
	v_mul_f32_e32 v12, v9, v12
	v_cndmask_b32_e64 v9, v12, v9, s[12:13]
	v_add_f32_e32 v12, 1.0, v18
	v_mul_f32_e32 v18, 0xbfb8aa3b, v11
	v_exp_f32_e32 v18, v18
	v_mul_f32_e32 v13, v13, v158
	v_rcp_f32_e32 v12, v12
	v_mul_f32_e32 v9, v13, v9
	v_mul_f32_e32 v13, v14, v158
	v_add_f32_e32 v14, 1.0, v18
	v_rcp_f32_e32 v14, v14
	v_mul_f32_e32 v12, v10, v12
	v_cndmask_b32_e64 v10, v12, v10, s[12:13]
	v_mul_f32_e32 v0, v0, v158
	v_mul_f32_e32 v10, v13, v10
	v_mul_f32_e32 v13, v11, v14
	v_mul_f32_e32 v14, 0xbfb8aa3b, v0
	v_exp_f32_e32 v14, v14
	v_mul_f32_e32 v12, v15, v158
	v_cndmask_b32_e64 v11, v13, v11, s[12:13]
	v_mul_f32_e32 v11, v12, v11
	v_add_f32_e32 v12, 1.0, v14
	v_rcp_f32_e32 v12, v12
	v_mul_f32_e32 v1, v1, v158
	v_mul_f32_e32 v13, 0xbfb8aa3b, v1
	v_exp_f32_e32 v13, v13
	v_mul_f32_e32 v12, v0, v12
	v_mul_f32_e32 v4, v4, v158
	v_cndmask_b32_e64 v0, v12, v0, s[12:13]
	v_mul_f32_e32 v12, v4, v0
	v_add_f32_e32 v0, 1.0, v13
	v_mul_f32_e32 v2, v2, v158
	v_rcp_f32_e32 v0, v0
	v_mul_f32_e32 v4, 0xbfb8aa3b, v2
	v_exp_f32_e32 v4, v4
	v_mul_f32_e32 v3, v3, v158
	v_mul_f32_e32 v0, v1, v0
	v_cndmask_b32_e64 v0, v0, v1, s[12:13]
	v_add_f32_e32 v1, 1.0, v4
	v_mul_f32_e32 v4, 0xbfb8aa3b, v3
	v_exp_f32_e32 v4, v4
	v_rcp_f32_e32 v1, v1
	v_mul_f32_e32 v5, v5, v158
	v_mul_f32_e32 v13, v5, v0
	v_add_f32_e32 v4, 1.0, v4
	v_rcp_f32_e32 v4, v4
	v_mul_f32_e32 v1, v2, v1
	v_mul_f32_e32 v0, v6, v158
	v_cndmask_b32_e64 v1, v1, v2, s[12:13]
	v_mul_f32_e32 v6, v0, v1
	v_mul_f32_e32 v1, v3, v4
	v_mul_f32_e32 v0, v7, v158
	v_cndmask_b32_e64 v1, v1, v3, s[12:13]
	v_mul_f32_e32 v3, v0, v1
	v_lshl_add_u64 v[4:5], v[16:17], 1, v[176:177]
	v_cvt_pk_bf16_f32 v0, v8, v9
	v_cvt_pk_bf16_f32 v1, v10, v11
	v_cvt_pk_bf16_f32 v2, v12, v13
	v_cvt_pk_bf16_f32 v3, v6, v3
	global_store_dwordx4 v[4:5], v[0:3], off
	s_andn2_b64 vcc, exec, s[10:11]
	s_mov_b64 s[10:11], -1
	s_cbranch_vccnz .LBB0_691

;     __device__ __forceinline__ void operator()(const f32x4 (&acc)[2][2][4][2], const Unit& u, int wr, int wc, int fr, int fq, LAS unsigned char* xs, int wid, int lane) const {
;     ...
;         if (!SRCF32) {
; #pragma unroll
;             for (int ai = 0; ai < 2; ++ai)
; #pragma unroll
;                 for (int m = 0; m < 4; ++m)
; #pragma unroll
;                     for (int bj = 0; bj < 2; ++bj) raw[ai][m][bj] = *(const u32x4*)(xb + (size_t)(row0 + ai * 128 + m * 16 + fr) * D + col0 + bj * 128);
;         }
; #pragma unroll
;         for (int ai = 0; ai < 2; ++ai) {
;             f32x4 xf[4][2][2];
;             if (SRCF32) {
; #pragma unroll
;                 for (int m = 0; m < 4; ++m)
; #pragma unroll
;                     for (int bj = 0; bj < 2; ++bj) { const size_t o = (size_t)(row0 + ai * 128 + m * 16 + fr) * D + col0 + bj * 128; xf[m][bj][0] = *(const f32x4*)(xo + o); xf[m][bj][1] = *(const f32x4*)(xo + o + 4); }
;             }
; #pragma unroll
;             for (int m = 0; m < 4; ++m) {
;                 const size_t row = (size_t)(row0 + ai * 128 + m * 16 + fr);
;                 float ss = 0.f;
; #pragma unroll
;                 for (int bj = 0; bj < 2; ++bj) {
;                     const size_t o = row * D + col0 + bj * 128;
;                     f32x4 x0, x1;
;                     if (SRCF32) { x0 = xf[m][bj][0]; x1 = xf[m][bj][1]; }
;                     else { const u32x4 r = raw[ai][m][bj]; x0 = (f32x4){bf_lo(r.x), bf_hi(r.x), bf_lo(r.y), bf_hi(r.y)}; x1 = (f32x4){bf_lo(r.z), bf_hi(r.z), bf_lo(r.w), bf_hi(r.w)}; }
;                     const f32x4 v0 = x0 + acc[ai][bj][m][0], v1 = x1 + acc[ai][bj][m][1];
;                     if (LAST) { *(f32x4*)(out + o) = v0; *(f32x4*)(out + o + 4) = v1; }
;                     else {
;                         ss += (v0[0] * v0[0] + v0[1] * v0[1]) + (v0[2] * v0[2] + v0[3] * v0[3]) + (v1[0] * v1[0] + v1[1] * v1[1]) + (v1[2] * v1[2] + v1[3] * v1[3]);
;                         u32x4 w; w.x = cvt_pk_bf16(v0[0], v0[1]); w.y = cvt_pk_bf16(v0[2], v0[3]); w.z = cvt_pk_bf16(v1[0], v1[1]); w.w = cvt_pk_bf16(v1[2], v1[3]); *(u32x4*)(xb + o) = w;
;                     }
;                 }
;                 if (!LAST) { ss += __shfl_xor(ss, 16); ss += __shfl_xor(ss, 32);
;                     if (fq == 0) P[(ai * 128 + wr * 64 + m * 16 + fr) * 4 + wc] = ss; }
.LBB0_892:
	s_lshl_b32 s18, s64, 8
	v_lshl_or_b32 v200, s48, 8, v218
	v_add_u32_e32 v104, s18, v216
	v_ashrrev_i32_e32 v201, 31, v200
	v_lshlrev_b64 v[234:235], 1, v[200:201]
	v_ashrrev_i32_e32 v105, 31, v104
	v_lshl_add_u64 v[106:107], s[42:43], 0, v[234:235]
	v_lshlrev_b64 v[236:237], 12, v[104:105]
	v_lshl_add_u64 v[112:113], v[106:107], 0, v[236:237]
	global_load_dwordx4 v[226:229], v[112:113], off
	global_load_dwordx4 v[230:233], v[112:113], off offset:256
	v_or_b32_e32 v112, 16, v104
	v_or_b32_e32 v114, 32, v104
	v_or_b32_e32 v124, 48, v104
	v_add_u32_e32 v126, 0x80, v104
	v_add_u32_e32 v140, 0x90, v104
	v_add_u32_e32 v142, 0xa0, v104
	v_add_u32_e32 v104, 0xb0, v104
	v_ashrrev_i32_e32 v113, 31, v112
	v_ashrrev_i32_e32 v115, 31, v114
	v_ashrrev_i32_e32 v125, 31, v124
	v_ashrrev_i32_e32 v127, 31, v126
	v_ashrrev_i32_e32 v141, 31, v140
	v_ashrrev_i32_e32 v143, 31, v142
	v_ashrrev_i32_e32 v105, 31, v104
	v_lshlrev_b64 v[214:215], 12, v[112:113]
	v_lshlrev_b64 v[212:213], 12, v[114:115]
	v_lshlrev_b64 v[210:211], 12, v[124:125]
	v_lshlrev_b64 v[208:209], 12, v[126:127]
	v_lshlrev_b64 v[206:207], 12, v[140:141]
	v_lshlrev_b64 v[204:205], 12, v[142:143]
	v_lshlrev_b64 v[202:203], 12, v[104:105]
	v_lshl_add_u64 v[104:105], v[106:107], 0, v[214:215]
	v_lshl_add_u64 v[112:113], v[106:107], 0, v[212:213]
	v_lshl_add_u64 v[114:115], v[106:107], 0, v[210:211]
	v_lshl_add_u64 v[124:125], v[106:107], 0, v[208:209]
	v_lshl_add_u64 v[126:127], v[106:107], 0, v[206:207]
	v_lshl_add_u64 v[238:239], v[106:107], 0, v[204:205]
	v_lshl_add_u64 v[106:107], v[106:107], 0, v[202:203]
	global_load_dwordx4 v[180:183], v[104:105], off
	global_load_dwordx4 v[176:179], v[104:105], off offset:256
	global_load_dwordx4 v[172:175], v[112:113], off
	global_load_dwordx4 v[168:171], v[112:113], off offset:256
	global_load_dwordx4 v[164:167], v[114:115], off
	global_load_dwordx4 v[160:163], v[114:115], off offset:256
	global_load_dwordx4 v[156:159], v[124:125], off
	global_load_dwordx4 v[152:155], v[124:125], off offset:256
	global_load_dwordx4 v[148:151], v[126:127], off
	global_load_dwordx4 v[144:147], v[126:127], off offset:256
	global_load_dwordx4 v[140:143], v[238:239], off
	s_nop 0
	global_load_dwordx4 v[124:127], v[238:239], off offset:256
	global_load_dwordx4 v[112:115], v[106:107], off
	s_nop 0
	global_load_dwordx4 v[104:107], v[106:107], off offset:256
	s_waitcnt vmcnt(0)
	v_lshlrev_b32_e32 v238, 16, v226
	v_and_b32_e32 v239, 0xffff0000, v226
	v_lshlrev_b32_e32 v226, 16, v227
	v_and_b32_e32 v227, 0xffff0000, v227
	v_lshlrev_b32_e32 v240, 16, v228
	v_and_b32_e32 v241, 0xffff0000, v228
	v_lshlrev_b32_e32 v242, 16, v230
	v_and_b32_e32 v243, 0xffff0000, v230
	v_lshlrev_b32_e32 v230, 16, v231
	v_and_b32_e32 v231, 0xffff0000, v231
	v_lshlrev_b32_e32 v244, 16, v232
	v_and_b32_e32 v245, 0xffff0000, v232
	v_lshlrev_b32_e32 v232, 16, v233
	v_and_b32_e32 v233, 0xffff0000, v233
	v_pk_add_f32 v[138:139], v[138:139], v[226:227]
	v_pk_add_f32 v[136:137], v[136:137], v[238:239]
	v_pk_add_f32 v[132:133], v[132:133], v[240:241]
	v_pk_add_f32 v[226:227], v[130:131], v[230:231]
	v_pk_add_f32 v[230:231], v[122:123], v[232:233]
	v_pk_add_f32 v[232:233], v[120:121], v[244:245]
	v_mul_f32_e32 v120, v137, v137
	v_mul_f32_e32 v121, v139, v139
	v_lshlrev_b32_e32 v228, 16, v229
	v_and_b32_e32 v229, 0xffff0000, v229
	v_mul_f32_e32 v122, v133, v133
	v_fmac_f32_e32 v120, v136, v136
	v_fmac_f32_e32 v121, v138, v138
	v_pk_add_f32 v[134:135], v[134:135], v[228:229]
	v_pk_add_f32 v[228:229], v[128:129], v[242:243]
	v_fmac_f32_e32 v122, v132, v132
	v_add_f32_e32 v120, v120, v121
	v_add_f32_e32 v120, v122, v120
	v_mul_f32_e32 v121, v229, v229
	v_mul_f32_e32 v122, v227, v227
	v_fmac_f32_e32 v121, v228, v228
	v_fmac_f32_e32 v122, v226, v226
	v_add_f32_e32 v121, v121, v122
	v_mul_f32_e32 v122, v233, v233
	v_fmac_f32_e32 v122, v232, v232
	v_mul_f32_e32 v123, v135, v135
	v_add_f32_e32 v121, v122, v121
	v_mul_f32_e32 v122, v231, v231
	v_fmac_f32_e32 v123, v134, v134
	v_fmac_f32_e32 v122, v230, v230
	v_add_f32_e32 v120, v123, v120
	v_add_f32_e32 v121, v122, v121
	v_and_b32_e32 v122, 64, v223
	v_cvt_pk_bf16_f32 v131, v134, v135
	v_add_f32_e32 v121, v120, v121
	v_xor_b32_e32 v120, 16, v223
	v_add_u32_e32 v134, 64, v122
	v_cmp_lt_i32_e32 vcc, v120, v134
	v_lshl_add_u64 v[122:123], s[42:43], 0, v[236:237]
	v_cvt_pk_bf16_f32 v130, v132, v133
	v_lshl_add_u64 v[132:133], v[122:123], 0, v[234:235]
	v_cndmask_b32_e32 v120, v223, v120, vcc
	v_lshlrev_b32_e32 v120, 2, v120
	ds_bpermute_b32 v135, v120, v121
	v_cvt_pk_bf16_f32 v128, v136, v137
	v_cvt_pk_bf16_f32 v129, v138, v139
	global_store_dwordx4 v[132:133], v[128:131], off
	s_waitcnt lgkmcnt(0)
	v_add_f32_e32 v122, v121, v135
	v_xor_b32_e32 v121, 32, v223
	v_cmp_lt_i32_e32 vcc, v121, v134
	v_cvt_pk_bf16_f32 v128, v228, v229
	v_cvt_pk_bf16_f32 v129, v226, v227
	v_cvt_pk_bf16_f32 v130, v232, v233
	v_cvt_pk_bf16_f32 v131, v230, v231
	global_store_dwordx4 v[132:133], v[128:131], off offset:256
	s_nop 0
	v_cndmask_b32_e32 v121, v223, v121, vcc
	v_lshlrev_b32_e32 v121, 2, v121
	ds_bpermute_b32 v123, v121, v122
	s_and_saveexec_b64 s[64:65], s[8:9]
	s_cbranch_execz .LBB0_894
	s_waitcnt lgkmcnt(0)
	v_add_f32_e32 v122, v122, v123
	ds_write_b32 v225, v122
; __device__ __forceinline__ unsigned cvt_pk_bf16(float lo, float hi) { unsigned r; asm("v_cvt_pk_bf16_f32 %0, %1, %2" : "=v"(r) : "v"(lo), "v"(hi)); return r; }
;     __device__ __forceinline__ void operator()(const f32x4 (&acc)[2][2][4][2], const Unit& u, int wr, int wc, int fr, int fq, LAS unsigned char* xs, int wid, int lane) const {
;     ...
; #pragma unroll
;             for (int m = 0; m < 4; ++m) {
;                 const size_t row = (size_t)(row0 + ai * 128 + m * 16 + fr);
;                 float ss = 0.f;
; #pragma unroll
;                 for (int bj = 0; bj < 2; ++bj) {
;                     const size_t o = row * D + col0 + bj * 128;
;                     f32x4 x0, x1;
;                     if (SRCF32) { x0 = xf[m][bj][0]; x1 = xf[m][bj][1]; }
;                     else { const u32x4 r = raw[ai][m][bj]; x0 = (f32x4){bf_lo(r.x), bf_hi(r.x), bf_lo(r.y), bf_hi(r.y)}; x1 = (f32x4){bf_lo(r.z), bf_hi(r.z), bf_lo(r.w), bf_hi(r.w)}; }
;                     const f32x4 v0 = x0 + acc[ai][bj][m][0], v1 = x1 + acc[ai][bj][m][1];
;                     if (LAST) { *(f32x4*)(out + o) = v0; *(f32x4*)(out + o + 4) = v1; }
;                     else {
;                         ss += (v0[0] * v0[0] + v0[1] * v0[1]) + (v0[2] * v0[2] + v0[3] * v0[3]) + (v1[0] * v1[0] + v1[1] * v1[1]) + (v1[2] * v1[2] + v1[3] * v1[3]);
;                         u32x4 w; w.x = cvt_pk_bf16(v0[0], v0[1]); w.y = cvt_pk_bf16(v0[2], v0[3]); w.z = cvt_pk_bf16(v1[0], v1[1]); w.w = cvt_pk_bf16(v1[2], v1[3]); *(u32x4*)(xb + o) = w;
;                     }
;                 }
;                 if (!LAST) { ss += __shfl_xor(ss, 16); ss += __shfl_xor(ss, 32);
;                     if (fq == 0) P[(ai * 128 + wr * 64 + m * 16 + fr) * 4 + wc] = ss; }
.LBB0_894:
	s_or_b64 exec, exec, s[64:65]
	v_lshlrev_b32_e32 v122, 16, v180
	s_waitcnt lgkmcnt(0)
	v_and_b32_e32 v123, 0xffff0000, v180
	v_lshlrev_b32_e32 v128, 16, v181
	v_and_b32_e32 v129, 0xffff0000, v181
	v_lshlrev_b32_e32 v130, 16, v182
	v_and_b32_e32 v131, 0xffff0000, v182
	v_lshlrev_b32_e32 v132, 16, v183
	v_and_b32_e32 v133, 0xffff0000, v183
	v_pk_add_f32 v[118:119], v[118:119], v[128:129]
	v_pk_add_f32 v[116:117], v[116:117], v[122:123]
	v_pk_add_f32 v[122:123], v[110:111], v[132:133]
	v_pk_add_f32 v[110:111], v[108:109], v[130:131]
	v_mul_f32_e32 v108, v117, v117
	v_mul_f32_e32 v109, v119, v119
	v_fmac_f32_e32 v108, v116, v116
	v_fmac_f32_e32 v109, v118, v118
	v_add_f32_e32 v108, v108, v109
	v_mul_f32_e32 v109, v111, v111
	v_fmac_f32_e32 v109, v110, v110
	v_add_f32_e32 v108, v109, v108
	v_mul_f32_e32 v109, v123, v123
	v_fmac_f32_e32 v109, v122, v122
	v_add_f32_e32 v130, v109, v108
	v_cvt_pk_bf16_f32 v108, v116, v117
	v_cvt_pk_bf16_f32 v109, v118, v119
	v_lshlrev_b32_e32 v116, 16, v176
	v_and_b32_e32 v117, 0xffff0000, v176
	v_lshlrev_b32_e32 v118, 16, v177
	v_and_b32_e32 v119, 0xffff0000, v177
	v_cvt_pk_bf16_f32 v110, v110, v111
	v_cvt_pk_bf16_f32 v111, v122, v123
	v_lshlrev_b32_e32 v122, 16, v178
	v_and_b32_e32 v123, 0xffff0000, v178
	v_pk_add_f32 v[102:103], v[102:103], v[118:119]
	v_pk_add_f32 v[100:101], v[100:101], v[116:117]
	v_pk_add_f32 v[118:119], v[96:97], v[122:123]
	v_mul_f32_e32 v96, v101, v101
	v_mul_f32_e32 v97, v103, v103
	v_fmac_f32_e32 v96, v100, v100
	v_fmac_f32_e32 v97, v102, v102
	v_lshlrev_b32_e32 v128, 16, v179
	v_and_b32_e32 v129, 0xffff0000, v179
	v_add_f32_e32 v96, v96, v97
	v_mul_f32_e32 v97, v119, v119
	v_pk_add_f32 v[116:117], v[98:99], v[128:129]
	v_fmac_f32_e32 v97, v118, v118
	v_add_f32_e32 v96, v97, v96
	v_mul_f32_e32 v97, v117, v117
	v_fmac_f32_e32 v97, v116, v116
	v_add_f32_e32 v96, v97, v96
	v_add_f32_e32 v99, v130, v96
	ds_bpermute_b32 v128, v120, v99
	v_lshl_add_u64 v[96:97], s[42:43], 0, v[214:215]
	v_lshl_add_u64 v[122:123], v[200:201], 1, v[96:97]
	global_store_dwordx4 v[122:123], v[108:111], off
	v_cvt_pk_bf16_f32 v98, v100, v101
	s_waitcnt lgkmcnt(0)
	v_add_f32_e32 v96, v99, v128
	ds_bpermute_b32 v97, v121, v96
	v_cvt_pk_bf16_f32 v99, v102, v103
	v_cvt_pk_bf16_f32 v100, v118, v119
	v_cvt_pk_bf16_f32 v101, v116, v117
	global_store_dwordx4 v[122:123], v[98:101], off offset:256
	s_and_saveexec_b64 s[64:65], s[8:9]
	s_cbranch_execz .LBB0_896
	s_waitcnt lgkmcnt(0)
	v_add_f32_e32 v96, v96, v97
	ds_write_b32 v225, v96 offset:256
.LBB0_896:
	s_or_b64 exec, exec, s[64:65]
	v_lshlrev_b32_e32 v96, 16, v172
	s_waitcnt lgkmcnt(0)
	v_and_b32_e32 v97, 0xffff0000, v172
	v_lshlrev_b32_e32 v98, 16, v173
	v_and_b32_e32 v99, 0xffff0000, v173
	v_lshlrev_b32_e32 v100, 16, v174
	v_and_b32_e32 v101, 0xffff0000, v174
	v_lshlrev_b32_e32 v102, 16, v175
	v_and_b32_e32 v103, 0xffff0000, v175
	v_pk_add_f32 v[94:95], v[94:95], v[98:99]
	v_pk_add_f32 v[92:93], v[92:93], v[96:97]
	v_pk_add_f32 v[96:97], v[90:91], v[102:103]
	v_pk_add_f32 v[90:91], v[88:89], v[100:101]
	v_mul_f32_e32 v88, v93, v93
	v_mul_f32_e32 v89, v95, v95
	v_fmac_f32_e32 v88, v92, v92
	v_fmac_f32_e32 v89, v94, v94
	v_add_f32_e32 v88, v88, v89
	v_mul_f32_e32 v89, v91, v91
	v_fmac_f32_e32 v89, v90, v90
	v_add_f32_e32 v88, v89, v88
	v_mul_f32_e32 v89, v97, v97
	v_fmac_f32_e32 v89, v96, v96
	v_add_f32_e32 v100, v89, v88
	v_cvt_pk_bf16_f32 v88, v92, v93
	v_cvt_pk_bf16_f32 v89, v94, v95
	v_lshlrev_b32_e32 v92, 16, v168
	v_and_b32_e32 v93, 0xffff0000, v168
	v_lshlrev_b32_e32 v94, 16, v169
	v_and_b32_e32 v95, 0xffff0000, v169
	v_cvt_pk_bf16_f32 v90, v90, v91
	v_cvt_pk_bf16_f32 v91, v96, v97
	v_lshlrev_b32_e32 v96, 16, v170
	v_and_b32_e32 v97, 0xffff0000, v170
	v_pk_add_f32 v[86:87], v[86:87], v[94:95]
	v_pk_add_f32 v[84:85], v[84:85], v[92:93]
	v_pk_add_f32 v[94:95], v[80:81], v[96:97]
	v_mul_f32_e32 v80, v85, v85
	v_mul_f32_e32 v81, v87, v87
	v_fmac_f32_e32 v80, v84, v84
	v_fmac_f32_e32 v81, v86, v86
	v_lshlrev_b32_e32 v98, 16, v171
	v_and_b32_e32 v99, 0xffff0000, v171
	v_add_f32_e32 v80, v80, v81
	v_mul_f32_e32 v81, v95, v95
	v_pk_add_f32 v[92:93], v[82:83], v[98:99]
	v_fmac_f32_e32 v81, v94, v94
	v_add_f32_e32 v80, v81, v80
	v_mul_f32_e32 v81, v93, v93
	v_fmac_f32_e32 v81, v92, v92
	v_add_f32_e32 v80, v81, v80
	v_add_f32_e32 v83, v100, v80
	ds_bpermute_b32 v98, v120, v83
	v_lshl_add_u64 v[80:81], s[42:43], 0, v[212:213]
	v_lshl_add_u64 v[96:97], v[200:201], 1, v[80:81]
	global_store_dwordx4 v[96:97], v[88:91], off
	v_cvt_pk_bf16_f32 v82, v84, v85
	s_waitcnt lgkmcnt(0)
	v_add_f32_e32 v80, v83, v98
	ds_bpermute_b32 v81, v121, v80
	v_cvt_pk_bf16_f32 v83, v86, v87
	v_cvt_pk_bf16_f32 v84, v94, v95
	v_cvt_pk_bf16_f32 v85, v92, v93
	global_store_dwordx4 v[96:97], v[82:85], off offset:256
	s_and_saveexec_b64 s[64:65], s[8:9]
	s_cbranch_execz .LBB0_898
	s_waitcnt lgkmcnt(0)
	v_add_f32_e32 v80, v80, v81
	ds_write_b32 v225, v80 offset:512
; __device__ __forceinline__ unsigned cvt_pk_bf16(float lo, float hi) { unsigned r; asm("v_cvt_pk_bf16_f32 %0, %1, %2" : "=v"(r) : "v"(lo), "v"(hi)); return r; }
;     __device__ __forceinline__ void operator()(const f32x4 (&acc)[2][2][4][2], const Unit& u, int wr, int wc, int fr, int fq, LAS unsigned char* xs, int wid, int lane) const {
;     ...
; #pragma unroll
;             for (int m = 0; m < 4; ++m) {
;                 const size_t row = (size_t)(row0 + ai * 128 + m * 16 + fr);
;                 float ss = 0.f;
; #pragma unroll
;                 for (int bj = 0; bj < 2; ++bj) {
;                     const size_t o = row * D + col0 + bj * 128;
;                     f32x4 x0, x1;
;                     if (SRCF32) { x0 = xf[m][bj][0]; x1 = xf[m][bj][1]; }
;                     else { const u32x4 r = raw[ai][m][bj]; x0 = (f32x4){bf_lo(r.x), bf_hi(r.x), bf_lo(r.y), bf_hi(r.y)}; x1 = (f32x4){bf_lo(r.z), bf_hi(r.z), bf_lo(r.w), bf_hi(r.w)}; }
;                     const f32x4 v0 = x0 + acc[ai][bj][m][0], v1 = x1 + acc[ai][bj][m][1];
;                     if (LAST) { *(f32x4*)(out + o) = v0; *(f32x4*)(out + o + 4) = v1; }
;                     else {
;                         ss += (v0[0] * v0[0] + v0[1] * v0[1]) + (v0[2] * v0[2] + v0[3] * v0[3]) + (v1[0] * v1[0] + v1[1] * v1[1]) + (v1[2] * v1[2] + v1[3] * v1[3]);
;                         u32x4 w; w.x = cvt_pk_bf16(v0[0], v0[1]); w.y = cvt_pk_bf16(v0[2], v0[3]); w.z = cvt_pk_bf16(v1[0], v1[1]); w.w = cvt_pk_bf16(v1[2], v1[3]); *(u32x4*)(xb + o) = w;
;                     }
;                 }
;                 if (!LAST) { ss += __shfl_xor(ss, 16); ss += __shfl_xor(ss, 32);
;                     if (fq == 0) P[(ai * 128 + wr * 64 + m * 16 + fr) * 4 + wc] = ss; }
.LBB0_898:
	s_or_b64 exec, exec, s[64:65]
	v_lshlrev_b32_e32 v80, 16, v164
	s_waitcnt lgkmcnt(0)
	v_and_b32_e32 v81, 0xffff0000, v164
	v_lshlrev_b32_e32 v82, 16, v165
	v_and_b32_e32 v83, 0xffff0000, v165
	v_lshlrev_b32_e32 v84, 16, v166
	v_and_b32_e32 v85, 0xffff0000, v166
	v_lshlrev_b32_e32 v86, 16, v167
	v_and_b32_e32 v87, 0xffff0000, v167
	v_pk_add_f32 v[78:79], v[78:79], v[82:83]
	v_pk_add_f32 v[76:77], v[76:77], v[80:81]
	v_pk_add_f32 v[80:81], v[74:75], v[86:87]
	v_pk_add_f32 v[74:75], v[72:73], v[84:85]
	v_mul_f32_e32 v72, v77, v77
	v_mul_f32_e32 v73, v79, v79
	v_fmac_f32_e32 v72, v76, v76
	v_fmac_f32_e32 v73, v78, v78
	v_add_f32_e32 v72, v72, v73
	v_mul_f32_e32 v73, v75, v75
	v_fmac_f32_e32 v73, v74, v74
	v_add_f32_e32 v72, v73, v72
	v_mul_f32_e32 v73, v81, v81
	v_fmac_f32_e32 v73, v80, v80
	v_add_f32_e32 v84, v73, v72
	v_cvt_pk_bf16_f32 v72, v76, v77
	v_cvt_pk_bf16_f32 v73, v78, v79
	v_lshlrev_b32_e32 v76, 16, v160
	v_and_b32_e32 v77, 0xffff0000, v160
	v_lshlrev_b32_e32 v78, 16, v161
	v_and_b32_e32 v79, 0xffff0000, v161
	v_cvt_pk_bf16_f32 v74, v74, v75
	v_cvt_pk_bf16_f32 v75, v80, v81
	v_lshlrev_b32_e32 v80, 16, v162
	v_and_b32_e32 v81, 0xffff0000, v162
	v_pk_add_f32 v[70:71], v[70:71], v[78:79]
	v_pk_add_f32 v[68:69], v[68:69], v[76:77]
	v_pk_add_f32 v[78:79], v[64:65], v[80:81]
	v_mul_f32_e32 v64, v69, v69
	v_mul_f32_e32 v65, v71, v71
	v_fmac_f32_e32 v64, v68, v68
	v_fmac_f32_e32 v65, v70, v70
	v_lshlrev_b32_e32 v82, 16, v163
	v_and_b32_e32 v83, 0xffff0000, v163
	v_add_f32_e32 v64, v64, v65
	v_mul_f32_e32 v65, v79, v79
	v_pk_add_f32 v[76:77], v[66:67], v[82:83]
	v_fmac_f32_e32 v65, v78, v78
	v_add_f32_e32 v64, v65, v64
	v_mul_f32_e32 v65, v77, v77
	v_fmac_f32_e32 v65, v76, v76
	v_add_f32_e32 v64, v65, v64
	v_add_f32_e32 v67, v84, v64
	ds_bpermute_b32 v82, v120, v67
	v_lshl_add_u64 v[64:65], s[42:43], 0, v[210:211]
	v_lshl_add_u64 v[80:81], v[200:201], 1, v[64:65]
	global_store_dwordx4 v[80:81], v[72:75], off
	v_cvt_pk_bf16_f32 v66, v68, v69
	s_waitcnt lgkmcnt(0)
	v_add_f32_e32 v64, v67, v82
	ds_bpermute_b32 v65, v121, v64
	v_cvt_pk_bf16_f32 v67, v70, v71
	v_cvt_pk_bf16_f32 v68, v78, v79
	v_cvt_pk_bf16_f32 v69, v76, v77
	global_store_dwordx4 v[80:81], v[66:69], off offset:256
	s_and_saveexec_b64 s[64:65], s[8:9]
	s_cbranch_execz .LBB0_900
	s_waitcnt lgkmcnt(0)
	v_add_f32_e32 v64, v64, v65
	ds_write_b32 v225, v64 offset:768
.LBB0_900:
	s_or_b64 exec, exec, s[64:65]
	v_lshlrev_b32_e32 v64, 16, v156
	s_waitcnt lgkmcnt(0)
	v_and_b32_e32 v65, 0xffff0000, v156
	v_lshlrev_b32_e32 v66, 16, v157
	v_and_b32_e32 v67, 0xffff0000, v157
	v_lshlrev_b32_e32 v68, 16, v158
	v_and_b32_e32 v69, 0xffff0000, v158
	v_lshlrev_b32_e32 v70, 16, v159
	v_and_b32_e32 v71, 0xffff0000, v159
	v_pk_add_f32 v[62:63], v[62:63], v[66:67]
	v_pk_add_f32 v[60:61], v[60:61], v[64:65]
	v_pk_add_f32 v[64:65], v[58:59], v[70:71]
	v_pk_add_f32 v[58:59], v[56:57], v[68:69]
	v_mul_f32_e32 v56, v61, v61
	v_mul_f32_e32 v57, v63, v63
	v_fmac_f32_e32 v56, v60, v60
	v_fmac_f32_e32 v57, v62, v62
	v_add_f32_e32 v56, v56, v57
	v_mul_f32_e32 v57, v59, v59
	v_fmac_f32_e32 v57, v58, v58
	v_add_f32_e32 v56, v57, v56
	v_mul_f32_e32 v57, v65, v65
	v_fmac_f32_e32 v57, v64, v64
	v_add_f32_e32 v68, v57, v56
	v_cvt_pk_bf16_f32 v56, v60, v61
	v_cvt_pk_bf16_f32 v57, v62, v63
	v_lshlrev_b32_e32 v60, 16, v152
	v_and_b32_e32 v61, 0xffff0000, v152
	v_lshlrev_b32_e32 v62, 16, v153
	v_and_b32_e32 v63, 0xffff0000, v153
	v_cvt_pk_bf16_f32 v58, v58, v59
	v_cvt_pk_bf16_f32 v59, v64, v65
	v_lshlrev_b32_e32 v64, 16, v154
	v_and_b32_e32 v65, 0xffff0000, v154
	v_pk_add_f32 v[54:55], v[54:55], v[62:63]
	v_pk_add_f32 v[52:53], v[52:53], v[60:61]
	v_pk_add_f32 v[62:63], v[48:49], v[64:65]
	v_mul_f32_e32 v48, v53, v53
	v_mul_f32_e32 v49, v55, v55
	v_fmac_f32_e32 v48, v52, v52
	v_fmac_f32_e32 v49, v54, v54
	v_lshlrev_b32_e32 v66, 16, v155
	v_and_b32_e32 v67, 0xffff0000, v155
	v_add_f32_e32 v48, v48, v49
	v_mul_f32_e32 v49, v63, v63
	v_pk_add_f32 v[60:61], v[50:51], v[66:67]
	v_fmac_f32_e32 v49, v62, v62
	v_add_f32_e32 v48, v49, v48
	v_mul_f32_e32 v49, v61, v61
	v_fmac_f32_e32 v49, v60, v60
	v_add_f32_e32 v48, v49, v48
	v_add_f32_e32 v51, v68, v48
	ds_bpermute_b32 v66, v120, v51
	v_lshl_add_u64 v[48:49], s[42:43], 0, v[208:209]
	v_lshl_add_u64 v[64:65], v[200:201], 1, v[48:49]
	global_store_dwordx4 v[64:65], v[56:59], off
	v_cvt_pk_bf16_f32 v50, v52, v53
	s_waitcnt lgkmcnt(0)
	v_add_f32_e32 v48, v51, v66
	ds_bpermute_b32 v49, v121, v48
	v_cvt_pk_bf16_f32 v51, v54, v55
	v_cvt_pk_bf16_f32 v52, v62, v63
	v_cvt_pk_bf16_f32 v53, v60, v61
	global_store_dwordx4 v[64:65], v[50:53], off offset:256
	s_and_saveexec_b64 s[64:65], s[8:9]
	s_cbranch_execz .LBB0_902
	s_waitcnt lgkmcnt(0)
	v_add_f32_e32 v48, v48, v49
	ds_write_b32 v225, v48 offset:2048
; __device__ __forceinline__ unsigned cvt_pk_bf16(float lo, float hi) { unsigned r; asm("v_cvt_pk_bf16_f32 %0, %1, %2" : "=v"(r) : "v"(lo), "v"(hi)); return r; }
;     __device__ __forceinline__ void operator()(const f32x4 (&acc)[2][2][4][2], const Unit& u, int wr, int wc, int fr, int fq, LAS unsigned char* xs, int wid, int lane) const {
;     ...
; #pragma unroll
;             for (int m = 0; m < 4; ++m) {
;                 const size_t row = (size_t)(row0 + ai * 128 + m * 16 + fr);
;                 float ss = 0.f;
; #pragma unroll
;                 for (int bj = 0; bj < 2; ++bj) {
;                     const size_t o = row * D + col0 + bj * 128;
;                     f32x4 x0, x1;
;                     if (SRCF32) { x0 = xf[m][bj][0]; x1 = xf[m][bj][1]; }
;                     else { const u32x4 r = raw[ai][m][bj]; x0 = (f32x4){bf_lo(r.x), bf_hi(r.x), bf_lo(r.y), bf_hi(r.y)}; x1 = (f32x4){bf_lo(r.z), bf_hi(r.z), bf_lo(r.w), bf_hi(r.w)}; }
;                     const f32x4 v0 = x0 + acc[ai][bj][m][0], v1 = x1 + acc[ai][bj][m][1];
;                     if (LAST) { *(f32x4*)(out + o) = v0; *(f32x4*)(out + o + 4) = v1; }
;                     else {
;                         ss += (v0[0] * v0[0] + v0[1] * v0[1]) + (v0[2] * v0[2] + v0[3] * v0[3]) + (v1[0] * v1[0] + v1[1] * v1[1]) + (v1[2] * v1[2] + v1[3] * v1[3]);
;                         u32x4 w; w.x = cvt_pk_bf16(v0[0], v0[1]); w.y = cvt_pk_bf16(v0[2], v0[3]); w.z = cvt_pk_bf16(v1[0], v1[1]); w.w = cvt_pk_bf16(v1[2], v1[3]); *(u32x4*)(xb + o) = w;
;                     }
;                 }
;                 if (!LAST) { ss += __shfl_xor(ss, 16); ss += __shfl_xor(ss, 32);
;                     if (fq == 0) P[(ai * 128 + wr * 64 + m * 16 + fr) * 4 + wc] = ss; }
.LBB0_902:
	s_or_b64 exec, exec, s[64:65]
	v_lshlrev_b32_e32 v48, 16, v148
	s_waitcnt lgkmcnt(0)
	v_and_b32_e32 v49, 0xffff0000, v148
	v_lshlrev_b32_e32 v50, 16, v149
	v_and_b32_e32 v51, 0xffff0000, v149
	v_lshlrev_b32_e32 v52, 16, v150
	v_and_b32_e32 v53, 0xffff0000, v150
	v_lshlrev_b32_e32 v54, 16, v151
	v_and_b32_e32 v55, 0xffff0000, v151
	v_pk_add_f32 v[46:47], v[46:47], v[50:51]
	v_pk_add_f32 v[44:45], v[44:45], v[48:49]
	v_pk_add_f32 v[48:49], v[42:43], v[54:55]
	v_pk_add_f32 v[42:43], v[40:41], v[52:53]
	v_mul_f32_e32 v40, v45, v45
	v_mul_f32_e32 v41, v47, v47
	v_fmac_f32_e32 v40, v44, v44
	v_fmac_f32_e32 v41, v46, v46
	v_add_f32_e32 v40, v40, v41
	v_mul_f32_e32 v41, v43, v43
	v_fmac_f32_e32 v41, v42, v42
	v_add_f32_e32 v40, v41, v40
	v_mul_f32_e32 v41, v49, v49
	v_fmac_f32_e32 v41, v48, v48
	v_add_f32_e32 v52, v41, v40
	v_cvt_pk_bf16_f32 v40, v44, v45
	v_cvt_pk_bf16_f32 v41, v46, v47
	v_lshlrev_b32_e32 v44, 16, v144
	v_and_b32_e32 v45, 0xffff0000, v144
	v_lshlrev_b32_e32 v46, 16, v145
	v_and_b32_e32 v47, 0xffff0000, v145
	v_cvt_pk_bf16_f32 v42, v42, v43
	v_cvt_pk_bf16_f32 v43, v48, v49
	v_lshlrev_b32_e32 v48, 16, v146
	v_and_b32_e32 v49, 0xffff0000, v146
	v_pk_add_f32 v[38:39], v[38:39], v[46:47]
	v_pk_add_f32 v[36:37], v[36:37], v[44:45]
	v_pk_add_f32 v[46:47], v[32:33], v[48:49]
	v_mul_f32_e32 v32, v37, v37
	v_mul_f32_e32 v33, v39, v39
	v_fmac_f32_e32 v32, v36, v36
	v_fmac_f32_e32 v33, v38, v38
	v_lshlrev_b32_e32 v50, 16, v147
	v_and_b32_e32 v51, 0xffff0000, v147
	v_add_f32_e32 v32, v32, v33
	v_mul_f32_e32 v33, v47, v47
	v_pk_add_f32 v[44:45], v[34:35], v[50:51]
	v_fmac_f32_e32 v33, v46, v46
	v_add_f32_e32 v32, v33, v32
	v_mul_f32_e32 v33, v45, v45
	v_fmac_f32_e32 v33, v44, v44
	v_add_f32_e32 v32, v33, v32
	v_add_f32_e32 v35, v52, v32
	ds_bpermute_b32 v50, v120, v35
	v_lshl_add_u64 v[32:33], s[42:43], 0, v[206:207]
	v_lshl_add_u64 v[48:49], v[200:201], 1, v[32:33]
	global_store_dwordx4 v[48:49], v[40:43], off
	v_cvt_pk_bf16_f32 v34, v36, v37
	s_waitcnt lgkmcnt(0)
	v_add_f32_e32 v32, v35, v50
	ds_bpermute_b32 v33, v121, v32
	v_cvt_pk_bf16_f32 v35, v38, v39
	v_cvt_pk_bf16_f32 v36, v46, v47
	v_cvt_pk_bf16_f32 v37, v44, v45
	global_store_dwordx4 v[48:49], v[34:37], off offset:256
	s_and_saveexec_b64 s[64:65], s[8:9]
	s_cbranch_execz .LBB0_904
	s_waitcnt lgkmcnt(0)
	v_add_f32_e32 v32, v32, v33
	ds_write_b32 v225, v32 offset:2304
.LBB0_904:
	s_or_b64 exec, exec, s[64:65]
	v_lshlrev_b32_e32 v32, 16, v140
	s_waitcnt lgkmcnt(0)
	v_and_b32_e32 v33, 0xffff0000, v140
	v_lshlrev_b32_e32 v34, 16, v141
	v_and_b32_e32 v35, 0xffff0000, v141
	v_lshlrev_b32_e32 v36, 16, v142
	v_and_b32_e32 v37, 0xffff0000, v142
	v_lshlrev_b32_e32 v38, 16, v143
	v_and_b32_e32 v39, 0xffff0000, v143
	v_pk_add_f32 v[30:31], v[30:31], v[34:35]
	v_pk_add_f32 v[28:29], v[28:29], v[32:33]
	v_pk_add_f32 v[32:33], v[26:27], v[38:39]
	v_pk_add_f32 v[26:27], v[24:25], v[36:37]
	v_mul_f32_e32 v24, v29, v29
	v_mul_f32_e32 v25, v31, v31
	v_fmac_f32_e32 v24, v28, v28
	v_fmac_f32_e32 v25, v30, v30
	v_add_f32_e32 v24, v24, v25
	v_mul_f32_e32 v25, v27, v27
	v_fmac_f32_e32 v25, v26, v26
	v_add_f32_e32 v24, v25, v24
	v_mul_f32_e32 v25, v33, v33
	v_fmac_f32_e32 v25, v32, v32
	v_add_f32_e32 v36, v25, v24
	v_cvt_pk_bf16_f32 v24, v28, v29
	v_cvt_pk_bf16_f32 v25, v30, v31
	v_lshlrev_b32_e32 v28, 16, v124
	v_and_b32_e32 v29, 0xffff0000, v124
	v_lshlrev_b32_e32 v30, 16, v125
	v_and_b32_e32 v31, 0xffff0000, v125
	v_cvt_pk_bf16_f32 v26, v26, v27
	v_cvt_pk_bf16_f32 v27, v32, v33
	v_lshlrev_b32_e32 v32, 16, v126
	v_and_b32_e32 v33, 0xffff0000, v126
	v_pk_add_f32 v[22:23], v[22:23], v[30:31]
	v_pk_add_f32 v[20:21], v[20:21], v[28:29]
	v_pk_add_f32 v[30:31], v[16:17], v[32:33]
	v_mul_f32_e32 v16, v21, v21
	v_mul_f32_e32 v17, v23, v23
	v_fmac_f32_e32 v16, v20, v20
	v_fmac_f32_e32 v17, v22, v22
	v_lshlrev_b32_e32 v34, 16, v127
	v_and_b32_e32 v35, 0xffff0000, v127
	v_add_f32_e32 v16, v16, v17
	v_mul_f32_e32 v17, v31, v31
	v_pk_add_f32 v[28:29], v[18:19], v[34:35]
	v_fmac_f32_e32 v17, v30, v30
	v_add_f32_e32 v16, v17, v16
	v_mul_f32_e32 v17, v29, v29
	v_fmac_f32_e32 v17, v28, v28
	v_add_f32_e32 v16, v17, v16
	v_add_f32_e32 v19, v36, v16
	ds_bpermute_b32 v34, v120, v19
	v_lshl_add_u64 v[16:17], s[42:43], 0, v[204:205]
	v_lshl_add_u64 v[32:33], v[200:201], 1, v[16:17]
	global_store_dwordx4 v[32:33], v[24:27], off
	v_cvt_pk_bf16_f32 v18, v20, v21
	s_waitcnt lgkmcnt(0)
	v_add_f32_e32 v16, v19, v34
	ds_bpermute_b32 v17, v121, v16
	v_cvt_pk_bf16_f32 v19, v22, v23
	v_cvt_pk_bf16_f32 v20, v30, v31
	v_cvt_pk_bf16_f32 v21, v28, v29
	global_store_dwordx4 v[32:33], v[18:21], off offset:256
	s_and_saveexec_b64 s[64:65], s[8:9]
	s_cbranch_execz .LBB0_906
	s_waitcnt lgkmcnt(0)
	v_add_f32_e32 v16, v16, v17
	ds_write_b32 v225, v16 offset:2560
.LBB0_906:
	s_or_b64 exec, exec, s[64:65]
	v_lshlrev_b32_e32 v16, 16, v112
	s_waitcnt lgkmcnt(0)
	v_and_b32_e32 v17, 0xffff0000, v112
	v_lshlrev_b32_e32 v18, 16, v113
	v_and_b32_e32 v19, 0xffff0000, v113
	v_lshlrev_b32_e32 v20, 16, v114
	v_and_b32_e32 v21, 0xffff0000, v114
	v_lshlrev_b32_e32 v22, 16, v115
	v_and_b32_e32 v23, 0xffff0000, v115
	v_pk_add_f32 v[14:15], v[14:15], v[18:19]
	v_pk_add_f32 v[12:13], v[12:13], v[16:17]
	v_pk_add_f32 v[16:17], v[10:11], v[22:23]
	v_pk_add_f32 v[10:11], v[8:9], v[20:21]
	v_mul_f32_e32 v8, v13, v13
	v_mul_f32_e32 v9, v15, v15
	v_fmac_f32_e32 v8, v12, v12
	v_fmac_f32_e32 v9, v14, v14
	v_add_f32_e32 v8, v8, v9
	v_mul_f32_e32 v9, v11, v11
	v_fmac_f32_e32 v9, v10, v10
	v_add_f32_e32 v8, v9, v8
	v_mul_f32_e32 v9, v17, v17
	v_fmac_f32_e32 v9, v16, v16
	v_add_f32_e32 v20, v9, v8
	v_cvt_pk_bf16_f32 v8, v12, v13
	v_cvt_pk_bf16_f32 v9, v14, v15
	v_lshlrev_b32_e32 v12, 16, v104
	v_and_b32_e32 v13, 0xffff0000, v104
	v_lshlrev_b32_e32 v14, 16, v105
	v_and_b32_e32 v15, 0xffff0000, v105
	v_cvt_pk_bf16_f32 v10, v10, v11
	v_cvt_pk_bf16_f32 v11, v16, v17
	v_lshlrev_b32_e32 v16, 16, v106
	v_and_b32_e32 v17, 0xffff0000, v106
	v_pk_add_f32 v[6:7], v[6:7], v[14:15]
	v_pk_add_f32 v[4:5], v[4:5], v[12:13]
	v_pk_add_f32 v[14:15], v[0:1], v[16:17]
	v_mul_f32_e32 v0, v5, v5
	v_mul_f32_e32 v1, v7, v7
	v_fmac_f32_e32 v0, v4, v4
	v_fmac_f32_e32 v1, v6, v6
	v_lshlrev_b32_e32 v18, 16, v107
	v_and_b32_e32 v19, 0xffff0000, v107
	v_add_f32_e32 v0, v0, v1
	v_mul_f32_e32 v1, v15, v15
	v_pk_add_f32 v[12:13], v[2:3], v[18:19]
	v_fmac_f32_e32 v1, v14, v14
	v_add_f32_e32 v0, v1, v0
	v_mul_f32_e32 v1, v13, v13
	v_fmac_f32_e32 v1, v12, v12
	v_add_f32_e32 v0, v1, v0
	v_add_f32_e32 v3, v20, v0
	ds_bpermute_b32 v18, v120, v3
	v_lshl_add_u64 v[0:1], s[42:43], 0, v[202:203]
	v_lshl_add_u64 v[16:17], v[200:201], 1, v[0:1]
	global_store_dwordx4 v[16:17], v[8:11], off
	v_cvt_pk_bf16_f32 v2, v4, v5
	s_waitcnt lgkmcnt(0)
	v_add_f32_e32 v0, v3, v18
	ds_bpermute_b32 v1, v121, v0
	v_cvt_pk_bf16_f32 v3, v6, v7
	v_cvt_pk_bf16_f32 v4, v14, v15
	v_cvt_pk_bf16_f32 v5, v12, v13
	global_store_dwordx4 v[16:17], v[2:5], off offset:256
	s_and_saveexec_b64 s[64:65], s[8:9]
	s_cbranch_execz .LBB0_908
	s_waitcnt lgkmcnt(0)
	v_add_f32_e32 v0, v0, v1
	ds_write_b32 v225, v0 offset:2816

; #define LAS __attribute__((address_space(3)))
; __device__ __forceinline__ unsigned cvt_pk_bf16(float lo, float hi) { unsigned r; asm("v_cvt_pk_bf16_f32 %0, %1, %2" : "=v"(r) : "v"(lo), "v"(hi)); return r; }
; __device__ __forceinline__ void tstore_sub(const f32x4 (&v)[4][2], bf16_t* dst  , LAS unsigned char* x, int fr, int fq, int lane) {
; #pragma unroll
;     for (int m = 0; m < 4; ++m)
; #pragma unroll
;         for (int n = 0; n < 2; ++n)
; #pragma unroll
;             for (int j = 0; j < 4; ++j) {
;                 const int ch = 8 * fq + 4 * n + j, tok = 16 * m + fr;
;                 const unsigned b = cvt_pk_bf16(v[m][n][j], 0.f);
;                 *(LAS unsigned short*)(x + ch * 128 + ((((tok >> 3) ^ fq) << 4) | ((tok & 7) << 1))) = (unsigned short)b;
;             }
;     LDS_WAIT();
; #pragma unroll
;     for (int i = 0; i < 4; ++i) {
;         const int q = lane + 64 * i, ch = q >> 3, tc = q & 7;
;         const u32x4 o = *(const LAS u32x4*)(x + ch * 128 + ((tc ^ ((ch >> 3) & 3)) << 4));
;         *(u32x4*)(dst + (size_t)ch * T + tc * 8) = o;
;     }
;     LDS_WAIT();
; }
;     __device__ __forceinline__ void operator()(const f32x4 (&acc)[2][2][4][2], const Unit& u, int wr, int wc, int fr, int fq, LAS unsigned char* xs, int wid, int lane) const {
;     ...
; #pragma unroll
;             for (int ai = 0; ai < 2; ++ai)
; #pragma unroll
;                 for (int bj = 0; bj < 2; ++bj) {
;                     f32x4 v[4][2];
; #pragma unroll
;                     for (int m = 0; m < 4; ++m) { v[m][0] = acc[ai][bj][m][0] * rs[ai][m]; v[m][1] = acc[ai][bj][m][1] * rs[ai][m]; }
;                     if (ODD) {
;                         float* vss = (float*)(ws + OFF_VSS);
; #pragma unroll
;                         for (int m = 0; m < 4; ++m) {
;                             float s = 0.f;
; #pragma unroll
;                             for (int n = 0; n < 2; ++n) s += (v[m][n][0] * v[m][n][0] + v[m][n][1] * v[m][n][1]) + (v[m][n][2] * v[m][n][2] + v[m][n][3] * v[m][n][3]);
;                             s += __shfl_xor(s, 16); s += __shfl_xor(s, 32);
;                             if (fq == 0) vss[(size_t)(row0 + ai * 128 + m * 16 + fr) * 32 + (2 * (pn - 24) + bj) * 4 + wc] = s;
;                         }
;                     }
;                     tstore_sub(v, base + (size_t)(bj * 128 + wc * 32) * T + row0 + ai * 128, x, fr, fq, lane);
.LBB0_984:
	s_waitcnt lgkmcnt(7)
	v_pk_mul_f32 v[176:177], v[124:125], v[172:173] op_sel_hi:[1,0]
	v_pk_mul_f32 v[174:175], v[126:127], v[172:173] op_sel_hi:[1,0]
	v_cvt_pk_bf16_f32 v143, v176, v137
	ds_write_b16 v167, v143
	v_cvt_pk_bf16_f32 v143, v177, v137
	ds_write_b16 v167, v143 offset:128
	v_cvt_pk_bf16_f32 v143, v174, v137
	ds_write_b16 v167, v143 offset:256
	v_cvt_pk_bf16_f32 v143, v175, v137
	v_pk_mul_f32 v[180:181], v[120:121], v[172:173] op_sel_hi:[1,0]
	ds_write_b16 v167, v143 offset:384
	v_cvt_pk_bf16_f32 v143, v180, v137
	ds_write_b16 v167, v143 offset:512
	v_cvt_pk_bf16_f32 v143, v181, v137
	v_pk_mul_f32 v[178:179], v[122:123], v[172:173] op_sel_hi:[1,0]
	ds_write_b16 v167, v143 offset:640
	v_cvt_pk_bf16_f32 v143, v178, v137
	ds_write_b16 v167, v143 offset:768
	v_cvt_pk_bf16_f32 v143, v179, v137
	s_waitcnt lgkmcnt(13)
	v_pk_mul_f32 v[192:193], v[108:109], v[170:171] op_sel_hi:[1,0]
	ds_write_b16 v167, v143 offset:896
	v_cvt_pk_bf16_f32 v143, v192, v137
	ds_write_b16 v169, v143
	v_cvt_pk_bf16_f32 v143, v193, v137
	v_pk_mul_f32 v[190:191], v[110:111], v[170:171] op_sel_hi:[1,0]
	ds_write_b16 v169, v143 offset:128
	v_cvt_pk_bf16_f32 v143, v190, v137
	ds_write_b16 v169, v143 offset:256
	v_cvt_pk_bf16_f32 v143, v191, v137
	v_pk_mul_f32 v[196:197], v[104:105], v[170:171] op_sel_hi:[1,0]
	ds_write_b16 v169, v143 offset:384
	v_cvt_pk_bf16_f32 v143, v196, v137
	ds_write_b16 v169, v143 offset:512
	v_cvt_pk_bf16_f32 v143, v197, v137
	v_pk_mul_f32 v[194:195], v[106:107], v[170:171] op_sel_hi:[1,0]
	ds_write_b16 v169, v143 offset:640
	v_cvt_pk_bf16_f32 v143, v194, v137
	ds_write_b16 v169, v143 offset:768
	v_cvt_pk_bf16_f32 v143, v195, v137
	s_waitcnt lgkmcnt(14)
	v_pk_mul_f32 v[200:201], v[92:93], v[168:169] op_sel_hi:[1,0]
	ds_write_b16 v169, v143 offset:896
	v_cvt_pk_bf16_f32 v143, v200, v137
	ds_write_b16 v171, v143
	v_cvt_pk_bf16_f32 v143, v201, v137
	v_pk_mul_f32 v[198:199], v[94:95], v[168:169] op_sel_hi:[1,0]
	ds_write_b16 v171, v143 offset:128
	v_cvt_pk_bf16_f32 v143, v198, v137
	ds_write_b16 v171, v143 offset:256
	v_cvt_pk_bf16_f32 v143, v199, v137
	v_pk_mul_f32 v[204:205], v[88:89], v[168:169] op_sel_hi:[1,0]
	ds_write_b16 v171, v143 offset:384
	v_cvt_pk_bf16_f32 v143, v204, v137
	ds_write_b16 v171, v143 offset:512
	v_cvt_pk_bf16_f32 v143, v205, v137
	v_pk_mul_f32 v[202:203], v[90:91], v[168:169] op_sel_hi:[1,0]
	ds_write_b16 v171, v143 offset:640
	v_cvt_pk_bf16_f32 v143, v202, v137
	ds_write_b16 v171, v143 offset:768
	v_cvt_pk_bf16_f32 v143, v203, v137
	v_pk_mul_f32 v[208:209], v[76:77], v[166:167] op_sel_hi:[1,0]
	ds_write_b16 v171, v143 offset:896
	v_cvt_pk_bf16_f32 v143, v208, v137
	ds_write_b16 v173, v143
	v_cvt_pk_bf16_f32 v143, v209, v137
	v_pk_mul_f32 v[206:207], v[78:79], v[166:167] op_sel_hi:[1,0]
	ds_write_b16 v173, v143 offset:128
	v_cvt_pk_bf16_f32 v143, v206, v137
	ds_write_b16 v173, v143 offset:256
	v_cvt_pk_bf16_f32 v143, v207, v137
	v_pk_mul_f32 v[212:213], v[72:73], v[166:167] op_sel_hi:[1,0]
	ds_write_b16 v173, v143 offset:384
	v_cvt_pk_bf16_f32 v143, v212, v137
	ds_write_b16 v173, v143 offset:512
	v_cvt_pk_bf16_f32 v143, v213, v137
	v_pk_mul_f32 v[210:211], v[74:75], v[166:167] op_sel_hi:[1,0]
	ds_write_b16 v173, v143 offset:640
	v_cvt_pk_bf16_f32 v143, v210, v137
	s_ashr_i32 s67, s66, 31
	ds_write_b16 v173, v143 offset:768
	v_cvt_pk_bf16_f32 v143, v211, v137
	ds_write_b16 v173, v143 offset:896
	s_lshl_b64 s[70:71], s[66:67], 1
	s_waitcnt lgkmcnt(0)
	s_add_u32 s70, s68, s70
	ds_read_b128 v[176:179], v184
	ds_read_b128 v[190:193], v185
	s_addc_u32 s71, s69, s71
	v_lshl_add_u64 v[182:183], s[70:71], 0, v[136:137]
	s_mov_b32 s55, s19
	v_lshl_add_u64 v[180:181], v[182:183], 0, s[54:55]
	v_mov_b32_e32 v143, v137
	v_lshl_add_u64 v[174:175], v[180:181], 0, v[142:143]
	v_mov_b32_e32 v145, v137
	s_waitcnt lgkmcnt(1)
	global_store_dwordx4 v[174:175], v[176:179], off
	ds_read_b128 v[194:197], v186
	v_mov_b32_e32 v147, v137
	v_lshl_add_u64 v[176:177], v[180:181], 0, v[144:145]
	s_waitcnt lgkmcnt(1)
	global_store_dwordx4 v[176:177], v[190:193], off
	ds_read_b128 v[190:193], v187
	v_mov_b32_e32 v149, v137
	v_lshl_add_u64 v[178:179], v[180:181], 0, v[146:147]
	v_lshl_add_u64 v[180:181], v[180:181], 0, v[148:149]
	s_waitcnt lgkmcnt(1)
	global_store_dwordx4 v[178:179], v[194:197], off
	s_waitcnt lgkmcnt(0)
	global_store_dwordx4 v[180:181], v[190:193], off
	s_waitcnt lgkmcnt(0)
; #define LAS __attribute__((address_space(3)))
; __device__ __forceinline__ unsigned cvt_pk_bf16(float lo, float hi) { unsigned r; asm("v_cvt_pk_bf16_f32 %0, %1, %2" : "=v"(r) : "v"(lo), "v"(hi)); return r; }
; __device__ __forceinline__ void tstore_sub(const f32x4 (&v)[4][2], bf16_t* dst  , LAS unsigned char* x, int fr, int fq, int lane) {
; #pragma unroll
;     for (int m = 0; m < 4; ++m)
; #pragma unroll
;         for (int n = 0; n < 2; ++n)
; #pragma unroll
;             for (int j = 0; j < 4; ++j) {
;                 const int ch = 8 * fq + 4 * n + j, tok = 16 * m + fr;
;                 const unsigned b = cvt_pk_bf16(v[m][n][j], 0.f);
;                 *(LAS unsigned short*)(x + ch * 128 + ((((tok >> 3) ^ fq) << 4) | ((tok & 7) << 1))) = (unsigned short)b;
;             }
;     LDS_WAIT();
; #pragma unroll
;     for (int i = 0; i < 4; ++i) {
;         const int q = lane + 64 * i, ch = q >> 3, tc = q & 7;
;         const u32x4 o = *(const LAS u32x4*)(x + ch * 128 + ((tc ^ ((ch >> 3) & 3)) << 4));
;         *(u32x4*)(dst + (size_t)ch * T + tc * 8) = o;
;     }
;     LDS_WAIT();
; }
;     __device__ __forceinline__ void operator()(const f32x4 (&acc)[2][2][4][2], const Unit& u, int wr, int wc, int fr, int fq, LAS unsigned char* xs, int wid, int lane) const {
;     ...
; #pragma unroll
;             for (int ai = 0; ai < 2; ++ai)
; #pragma unroll
;                 for (int bj = 0; bj < 2; ++bj) {
;                     f32x4 v[4][2];
; #pragma unroll
;                     for (int m = 0; m < 4; ++m) { v[m][0] = acc[ai][bj][m][0] * rs[ai][m]; v[m][1] = acc[ai][bj][m][1] * rs[ai][m]; }
;                     if (ODD) {
;                         float* vss = (float*)(ws + OFF_VSS);
; #pragma unroll
;                         for (int m = 0; m < 4; ++m) {
;                             float s = 0.f;
; #pragma unroll
;                             for (int n = 0; n < 2; ++n) s += (v[m][n][0] * v[m][n][0] + v[m][n][1] * v[m][n][1]) + (v[m][n][2] * v[m][n][2] + v[m][n][3] * v[m][n][3]);
;                             s += __shfl_xor(s, 16); s += __shfl_xor(s, 32);
;                             if (fq == 0) vss[(size_t)(row0 + ai * 128 + m * 16 + fr) * 32 + (2 * (pn - 24) + bj) * 4 + wc] = s;
;                         }
;                     }
;                     tstore_sub(v, base + (size_t)(bj * 128 + wc * 32) * T + row0 + ai * 128, x, fr, fq, lane);
	v_pk_mul_f32 v[200:201], v[100:101], v[170:171] op_sel_hi:[1,0]
	v_pk_mul_f32 v[196:197], v[112:113], v[172:173] op_sel_hi:[1,0]
	v_pk_mul_f32 v[192:193], v[116:117], v[172:173] op_sel_hi:[1,0]
	v_pk_mul_f32 v[190:191], v[118:119], v[172:173] op_sel_hi:[1,0]
	v_cvt_pk_bf16_f32 v151, v192, v137
	ds_write_b16 v167, v151
	v_cvt_pk_bf16_f32 v151, v193, v137
	ds_write_b16 v167, v151 offset:128
	v_cvt_pk_bf16_f32 v151, v190, v137
	ds_write_b16 v167, v151 offset:256
	v_cvt_pk_bf16_f32 v151, v191, v137
	ds_write_b16 v167, v151 offset:384
	v_cvt_pk_bf16_f32 v151, v196, v137
	ds_write_b16 v167, v151 offset:512
	v_cvt_pk_bf16_f32 v151, v197, v137
	v_pk_mul_f32 v[194:195], v[114:115], v[172:173] op_sel_hi:[1,0]
	ds_write_b16 v167, v151 offset:640
	v_cvt_pk_bf16_f32 v151, v194, v137
	ds_write_b16 v167, v151 offset:768
	v_cvt_pk_bf16_f32 v151, v195, v137
	ds_write_b16 v167, v151 offset:896
	v_cvt_pk_bf16_f32 v151, v200, v137
	ds_write_b16 v169, v151
	v_cvt_pk_bf16_f32 v151, v201, v137
	v_pk_mul_f32 v[198:199], v[102:103], v[170:171] op_sel_hi:[1,0]
	ds_write_b16 v169, v151 offset:128
	v_cvt_pk_bf16_f32 v151, v198, v137
	ds_write_b16 v169, v151 offset:256
	v_cvt_pk_bf16_f32 v151, v199, v137
	v_pk_mul_f32 v[204:205], v[96:97], v[170:171] op_sel_hi:[1,0]
	ds_write_b16 v169, v151 offset:384
	v_cvt_pk_bf16_f32 v151, v204, v137
	ds_write_b16 v169, v151 offset:512
	v_cvt_pk_bf16_f32 v151, v205, v137
	v_pk_mul_f32 v[202:203], v[98:99], v[170:171] op_sel_hi:[1,0]
	ds_write_b16 v169, v151 offset:640
	v_cvt_pk_bf16_f32 v151, v202, v137
	ds_write_b16 v169, v151 offset:768
	v_cvt_pk_bf16_f32 v151, v203, v137
	v_pk_mul_f32 v[208:209], v[84:85], v[168:169] op_sel_hi:[1,0]
	ds_write_b16 v169, v151 offset:896
	v_cvt_pk_bf16_f32 v151, v208, v137
	ds_write_b16 v171, v151
	v_cvt_pk_bf16_f32 v151, v209, v137
	v_pk_mul_f32 v[206:207], v[86:87], v[168:169] op_sel_hi:[1,0]
	ds_write_b16 v171, v151 offset:128
	v_cvt_pk_bf16_f32 v151, v206, v137
	ds_write_b16 v171, v151 offset:256
	v_cvt_pk_bf16_f32 v151, v207, v137
	v_pk_mul_f32 v[212:213], v[80:81], v[168:169] op_sel_hi:[1,0]
	ds_write_b16 v171, v151 offset:384
	v_cvt_pk_bf16_f32 v151, v212, v137
	ds_write_b16 v171, v151 offset:512
	v_cvt_pk_bf16_f32 v151, v213, v137
	v_pk_mul_f32 v[210:211], v[82:83], v[168:169] op_sel_hi:[1,0]
	ds_write_b16 v171, v151 offset:640
	v_cvt_pk_bf16_f32 v151, v210, v137
	ds_write_b16 v171, v151 offset:768
	v_cvt_pk_bf16_f32 v151, v211, v137
	v_pk_mul_f32 v[216:217], v[68:69], v[166:167] op_sel_hi:[1,0]
	ds_write_b16 v171, v151 offset:896
	v_cvt_pk_bf16_f32 v151, v216, v137
	ds_write_b16 v173, v151
	v_cvt_pk_bf16_f32 v151, v217, v137
	v_pk_mul_f32 v[214:215], v[70:71], v[166:167] op_sel_hi:[1,0]
	ds_write_b16 v173, v151 offset:128
	v_cvt_pk_bf16_f32 v151, v214, v137
	ds_write_b16 v173, v151 offset:256
	v_cvt_pk_bf16_f32 v151, v215, v137
	v_pk_mul_f32 v[220:221], v[64:65], v[166:167] op_sel_hi:[1,0]
	ds_write_b16 v173, v151 offset:384
	v_cvt_pk_bf16_f32 v151, v220, v137
	ds_write_b16 v173, v151 offset:512
	v_cvt_pk_bf16_f32 v151, v221, v137
	v_pk_mul_f32 v[218:219], v[66:67], v[166:167] op_sel_hi:[1,0]
	ds_write_b16 v173, v151 offset:640
	v_cvt_pk_bf16_f32 v151, v218, v137
	ds_write_b16 v173, v151 offset:768
	v_cvt_pk_bf16_f32 v151, v219, v137
	ds_write_b16 v173, v151 offset:896
	s_waitcnt lgkmcnt(0)
	ds_read_b128 v[190:193], v184
	ds_read_b128 v[194:197], v185
	s_mov_b32 s57, s19
	v_lshl_add_u64 v[182:183], v[182:183], 0, s[56:57]
	v_lshl_add_u64 v[198:199], v[182:183], 0, v[142:143]
	s_waitcnt lgkmcnt(1)
	global_store_dwordx4 v[198:199], v[190:193], off
	ds_read_b128 v[190:193], v186
	ds_read_b128 v[198:201], v187
	v_lshl_add_u64 v[202:203], v[182:183], 0, v[144:145]
	s_waitcnt lgkmcnt(2)
	global_store_dwordx4 v[202:203], v[194:197], off
	v_pk_mul_f32 v[204:205], v[40:41], v[162:163] op_sel_hi:[1,0]
	v_pk_mul_f32 v[202:203], v[42:43], v[162:163] op_sel_hi:[1,0]
	v_lshl_add_u64 v[194:195], v[182:183], 0, v[146:147]
	s_waitcnt lgkmcnt(1)
	global_store_dwordx4 v[194:195], v[190:193], off
	v_pk_mul_f32 v[196:197], v[56:57], v[164:165] op_sel_hi:[1,0]
	v_pk_mul_f32 v[194:195], v[58:59], v[164:165] op_sel_hi:[1,0]
	v_lshl_add_u64 v[190:191], v[182:183], 0, v[148:149]
	s_waitcnt lgkmcnt(0)
	global_store_dwordx4 v[190:191], v[198:201], off
	v_pk_mul_f32 v[192:193], v[60:61], v[164:165] op_sel_hi:[1,0]
	s_waitcnt lgkmcnt(0)
; #define LAS __attribute__((address_space(3)))
; __device__ __forceinline__ unsigned cvt_pk_bf16(float lo, float hi) { unsigned r; asm("v_cvt_pk_bf16_f32 %0, %1, %2" : "=v"(r) : "v"(lo), "v"(hi)); return r; }
; __device__ __forceinline__ void tstore_sub(const f32x4 (&v)[4][2], bf16_t* dst  , LAS unsigned char* x, int fr, int fq, int lane) {
; #pragma unroll
;     for (int m = 0; m < 4; ++m)
; #pragma unroll
;         for (int n = 0; n < 2; ++n)
; #pragma unroll
;             for (int j = 0; j < 4; ++j) {
;                 const int ch = 8 * fq + 4 * n + j, tok = 16 * m + fr;
;                 const unsigned b = cvt_pk_bf16(v[m][n][j], 0.f);
;                 *(LAS unsigned short*)(x + ch * 128 + ((((tok >> 3) ^ fq) << 4) | ((tok & 7) << 1))) = (unsigned short)b;
;             }
;     LDS_WAIT();
; #pragma unroll
;     for (int i = 0; i < 4; ++i) {
;         const int q = lane + 64 * i, ch = q >> 3, tc = q & 7;
;         const u32x4 o = *(const LAS u32x4*)(x + ch * 128 + ((tc ^ ((ch >> 3) & 3)) << 4));
;         *(u32x4*)(dst + (size_t)ch * T + tc * 8) = o;
;     }
;     LDS_WAIT();
; }
;     __device__ __forceinline__ void operator()(const f32x4 (&acc)[2][2][4][2], const Unit& u, int wr, int wc, int fr, int fq, LAS unsigned char* xs, int wid, int lane) const {
;     ...
; #pragma unroll
;             for (int ai = 0; ai < 2; ++ai)
; #pragma unroll
;                 for (int bj = 0; bj < 2; ++bj) {
;                     f32x4 v[4][2];
; #pragma unroll
;                     for (int m = 0; m < 4; ++m) { v[m][0] = acc[ai][bj][m][0] * rs[ai][m]; v[m][1] = acc[ai][bj][m][1] * rs[ai][m]; }
;                     if (ODD) {
;                         float* vss = (float*)(ws + OFF_VSS);
; #pragma unroll
;                         for (int m = 0; m < 4; ++m) {
;                             float s = 0.f;
; #pragma unroll
;                             for (int n = 0; n < 2; ++n) s += (v[m][n][0] * v[m][n][0] + v[m][n][1] * v[m][n][1]) + (v[m][n][2] * v[m][n][2] + v[m][n][3] * v[m][n][3]);
;                             s += __shfl_xor(s, 16); s += __shfl_xor(s, 32);
;                             if (fq == 0) vss[(size_t)(row0 + ai * 128 + m * 16 + fr) * 32 + (2 * (pn - 24) + bj) * 4 + wc] = s;
;                         }
;                     }
;                     tstore_sub(v, base + (size_t)(bj * 128 + wc * 32) * T + row0 + ai * 128, x, fr, fq, lane);
	v_pk_mul_f32 v[190:191], v[62:63], v[164:165] op_sel_hi:[1,0]
	v_cvt_pk_bf16_f32 v151, v192, v137
	ds_write_b16 v167, v151
	v_cvt_pk_bf16_f32 v151, v193, v137
	ds_write_b16 v167, v151 offset:128
	v_cvt_pk_bf16_f32 v151, v190, v137
	ds_write_b16 v167, v151 offset:256
	v_cvt_pk_bf16_f32 v151, v191, v137
	ds_write_b16 v167, v151 offset:384
	v_cvt_pk_bf16_f32 v151, v196, v137
	ds_write_b16 v167, v151 offset:512
	v_cvt_pk_bf16_f32 v151, v197, v137
	ds_write_b16 v167, v151 offset:640
	v_cvt_pk_bf16_f32 v151, v194, v137
	ds_write_b16 v167, v151 offset:768
	v_cvt_pk_bf16_f32 v151, v195, v137
	v_pk_mul_f32 v[200:201], v[44:45], v[162:163] op_sel_hi:[1,0]
	ds_write_b16 v167, v151 offset:896
	v_cvt_pk_bf16_f32 v151, v200, v137
	ds_write_b16 v169, v151
	v_cvt_pk_bf16_f32 v151, v201, v137
	v_pk_mul_f32 v[198:199], v[46:47], v[162:163] op_sel_hi:[1,0]
	ds_write_b16 v169, v151 offset:128
	v_cvt_pk_bf16_f32 v151, v198, v137
	ds_write_b16 v169, v151 offset:256
	v_cvt_pk_bf16_f32 v151, v199, v137
	ds_write_b16 v169, v151 offset:384
	v_cvt_pk_bf16_f32 v151, v204, v137
	ds_write_b16 v169, v151 offset:512
	v_cvt_pk_bf16_f32 v151, v205, v137
	ds_write_b16 v169, v151 offset:640
	v_cvt_pk_bf16_f32 v151, v202, v137
	ds_write_b16 v169, v151 offset:768
	v_cvt_pk_bf16_f32 v151, v203, v137
	v_pk_mul_f32 v[208:209], v[28:29], v[160:161] op_sel_hi:[1,0]
	ds_write_b16 v169, v151 offset:896
	v_cvt_pk_bf16_f32 v151, v208, v137
	ds_write_b16 v171, v151
	v_cvt_pk_bf16_f32 v151, v209, v137
	v_pk_mul_f32 v[206:207], v[30:31], v[160:161] op_sel_hi:[1,0]
	ds_write_b16 v171, v151 offset:128
	v_cvt_pk_bf16_f32 v151, v206, v137
	ds_write_b16 v171, v151 offset:256
	v_cvt_pk_bf16_f32 v151, v207, v137
	v_pk_mul_f32 v[212:213], v[24:25], v[160:161] op_sel_hi:[1,0]
	ds_write_b16 v171, v151 offset:384
	v_cvt_pk_bf16_f32 v151, v212, v137
	ds_write_b16 v171, v151 offset:512
	v_cvt_pk_bf16_f32 v151, v213, v137
	v_pk_mul_f32 v[210:211], v[26:27], v[160:161] op_sel_hi:[1,0]
	ds_write_b16 v171, v151 offset:640
	v_cvt_pk_bf16_f32 v151, v210, v137
	ds_write_b16 v171, v151 offset:768
	v_cvt_pk_bf16_f32 v151, v211, v137
	v_pk_mul_f32 v[216:217], v[12:13], v[158:159] op_sel_hi:[1,0]
	ds_write_b16 v171, v151 offset:896
	v_cvt_pk_bf16_f32 v151, v216, v137
	ds_write_b16 v173, v151
	v_cvt_pk_bf16_f32 v151, v217, v137
	v_pk_mul_f32 v[214:215], v[14:15], v[158:159] op_sel_hi:[1,0]
	ds_write_b16 v173, v151 offset:128
	v_cvt_pk_bf16_f32 v151, v214, v137
	ds_write_b16 v173, v151 offset:256
	v_cvt_pk_bf16_f32 v151, v215, v137
	v_pk_mul_f32 v[220:221], v[8:9], v[158:159] op_sel_hi:[1,0]
	ds_write_b16 v173, v151 offset:384
	v_cvt_pk_bf16_f32 v151, v220, v137
	ds_write_b16 v173, v151 offset:512
	v_cvt_pk_bf16_f32 v151, v221, v137
	v_pk_mul_f32 v[218:219], v[10:11], v[158:159] op_sel_hi:[1,0]
	ds_write_b16 v173, v151 offset:640
	v_cvt_pk_bf16_f32 v151, v218, v137
	ds_write_b16 v173, v151 offset:768
	v_cvt_pk_bf16_f32 v151, v219, v137
	ds_write_b16 v173, v151 offset:896
	s_waitcnt lgkmcnt(0)
	ds_read_b128 v[190:193], v184
	ds_read_b128 v[194:197], v185
	ds_read_b128 v[198:201], v186
	ds_read_b128 v[202:205], v187
	s_waitcnt lgkmcnt(3)
	global_store_dwordx4 v[174:175], v[190:193], off offset:256
	s_waitcnt lgkmcnt(2)
	global_store_dwordx4 v[176:177], v[194:197], off offset:256
	s_waitcnt lgkmcnt(1)
	global_store_dwordx4 v[178:179], v[198:201], off offset:256
	s_waitcnt lgkmcnt(0)
	global_store_dwordx4 v[180:181], v[202:205], off offset:256
	v_pk_mul_f32 v[176:177], v[52:53], v[164:165] op_sel_hi:[1,0]
	s_waitcnt lgkmcnt(0)
	v_pk_mul_f32 v[174:175], v[54:55], v[164:165] op_sel_hi:[1,0]
	v_cvt_pk_bf16_f32 v151, v176, v137
	ds_write_b16 v167, v151
	v_cvt_pk_bf16_f32 v151, v177, v137
	ds_write_b16 v167, v151 offset:128
	v_cvt_pk_bf16_f32 v151, v174, v137
	ds_write_b16 v167, v151 offset:256
	v_cvt_pk_bf16_f32 v151, v175, v137
	v_pk_mul_f32 v[180:181], v[48:49], v[164:165] op_sel_hi:[1,0]
	ds_write_b16 v167, v151 offset:384
	v_cvt_pk_bf16_f32 v151, v180, v137
	ds_write_b16 v167, v151 offset:512
	v_cvt_pk_bf16_f32 v151, v181, v137
	v_pk_mul_f32 v[178:179], v[50:51], v[164:165] op_sel_hi:[1,0]
	ds_write_b16 v167, v151 offset:640
	v_cvt_pk_bf16_f32 v151, v178, v137
	ds_write_b16 v167, v151 offset:768
	v_cvt_pk_bf16_f32 v151, v179, v137
	v_pk_mul_f32 v[192:193], v[36:37], v[162:163] op_sel_hi:[1,0]
	ds_write_b16 v167, v151 offset:896
	v_cvt_pk_bf16_f32 v151, v192, v137
	ds_write_b16 v169, v151
	v_cvt_pk_bf16_f32 v151, v193, v137
	v_pk_mul_f32 v[190:191], v[38:39], v[162:163] op_sel_hi:[1,0]
	ds_write_b16 v169, v151 offset:128
	v_cvt_pk_bf16_f32 v151, v190, v137
	ds_write_b16 v169, v151 offset:256
	v_cvt_pk_bf16_f32 v151, v191, v137
	v_pk_mul_f32 v[196:197], v[32:33], v[162:163] op_sel_hi:[1,0]
	ds_write_b16 v169, v151 offset:384
	v_cvt_pk_bf16_f32 v151, v196, v137
	ds_write_b16 v169, v151 offset:512
	v_cvt_pk_bf16_f32 v151, v197, v137
	v_pk_mul_f32 v[194:195], v[34:35], v[162:163] op_sel_hi:[1,0]
	ds_write_b16 v169, v151 offset:640
	v_cvt_pk_bf16_f32 v151, v194, v137
	ds_write_b16 v169, v151 offset:768
	v_cvt_pk_bf16_f32 v151, v195, v137
	v_pk_mul_f32 v[200:201], v[20:21], v[160:161] op_sel_hi:[1,0]
	ds_write_b16 v169, v151 offset:896
	v_cvt_pk_bf16_f32 v151, v200, v137
	ds_write_b16 v171, v151
	v_cvt_pk_bf16_f32 v151, v201, v137
	v_pk_mul_f32 v[198:199], v[22:23], v[160:161] op_sel_hi:[1,0]
	ds_write_b16 v171, v151 offset:128
	v_cvt_pk_bf16_f32 v151, v198, v137
	ds_write_b16 v171, v151 offset:256
	v_cvt_pk_bf16_f32 v151, v199, v137
	v_pk_mul_f32 v[204:205], v[16:17], v[160:161] op_sel_hi:[1,0]
	ds_write_b16 v171, v151 offset:384
	v_cvt_pk_bf16_f32 v151, v204, v137
	ds_write_b16 v171, v151 offset:512
	v_cvt_pk_bf16_f32 v151, v205, v137
	v_pk_mul_f32 v[202:203], v[18:19], v[160:161] op_sel_hi:[1,0]
	ds_write_b16 v171, v151 offset:640
	v_cvt_pk_bf16_f32 v151, v202, v137
	ds_write_b16 v171, v151 offset:768
	v_cvt_pk_bf16_f32 v151, v203, v137
	v_pk_mul_f32 v[208:209], v[4:5], v[158:159] op_sel_hi:[1,0]
	ds_write_b16 v171, v151 offset:896
	v_cvt_pk_bf16_f32 v151, v208, v137
	ds_write_b16 v173, v151
	v_cvt_pk_bf16_f32 v151, v209, v137
	v_pk_mul_f32 v[206:207], v[6:7], v[158:159] op_sel_hi:[1,0]
	ds_write_b16 v173, v151 offset:128
	v_cvt_pk_bf16_f32 v151, v206, v137
	ds_write_b16 v173, v151 offset:256
	v_cvt_pk_bf16_f32 v151, v207, v137
	v_pk_mul_f32 v[212:213], v[0:1], v[158:159] op_sel_hi:[1,0]
	ds_write_b16 v173, v151 offset:384
	v_cvt_pk_bf16_f32 v151, v212, v137
	ds_write_b16 v173, v151 offset:512
	v_cvt_pk_bf16_f32 v151, v213, v137
	v_pk_mul_f32 v[210:211], v[2:3], v[158:159] op_sel_hi:[1,0]
	ds_write_b16 v173, v151 offset:640
	v_cvt_pk_bf16_f32 v151, v210, v137
	ds_write_b16 v173, v151 offset:768
	v_cvt_pk_bf16_f32 v151, v211, v137
	ds_write_b16 v173, v151 offset:896
	s_waitcnt lgkmcnt(0)
; #define LAS __attribute__((address_space(3)))
; __device__ __forceinline__ unsigned cvt_pk_bf16(float lo, float hi) { unsigned r; asm("v_cvt_pk_bf16_f32 %0, %1, %2" : "=v"(r) : "v"(lo), "v"(hi)); return r; }
; #define LDS_WAIT() asm volatile("s_waitcnt lgkmcnt(0)" ::: "memory")
; __device__ __forceinline__ void tstore_sub(const f32x4 (&v)[4][2], bf16_t* dst  , LAS unsigned char* x, int fr, int fq, int lane) {
; #pragma unroll
;     for (int m = 0; m < 4; ++m)
; #pragma unroll
;         for (int n = 0; n < 2; ++n)
; #pragma unroll
;             for (int j = 0; j < 4; ++j) {
;                 const int ch = 8 * fq + 4 * n + j, tok = 16 * m + fr;
;                 const unsigned b = cvt_pk_bf16(v[m][n][j], 0.f);
;                 *(LAS unsigned short*)(x + ch * 128 + ((((tok >> 3) ^ fq) << 4) | ((tok & 7) << 1))) = (unsigned short)b;
;             }
;     LDS_WAIT();
; #pragma unroll
;     for (int i = 0; i < 4; ++i) {
;         const int q = lane + 64 * i, ch = q >> 3, tc = q & 7;
;         const u32x4 o = *(const LAS u32x4*)(x + ch * 128 + ((tc ^ ((ch >> 3) & 3)) << 4));
;         *(u32x4*)(dst + (size_t)ch * T + tc * 8) = o;
;     }
;     LDS_WAIT();
; }
;     __device__ __forceinline__ void operator()(const f32x4 (&acc)[2][2][4][2], const Unit& u, int wr, int wc, int fr, int fq, LAS unsigned char* xs, int wid, int lane) const {
;     ...
;         if (mode == 0) {
; #pragma unroll
;             for (int ai = 0; ai < 2; ++ai)
; #pragma unroll
;                 for (int m = 0; m < 4; ++m) {
;                     const float r = rs[ai][m];
;                     bf16_t* rowp = base + (size_t)(row0 + ai * 128 + m * 16 + fr) * ldc + wc * 32 + 8 * fq;
; #pragma unroll
;                     for (int bj = 0; bj < 2; ++bj) { const f32x4 v0 = acc[ai][bj][m][0] * r, v1 = acc[ai][bj][m][1] * r;
;                         u32x4 w; w.x = cvt_pk_bf16(v0[0], v0[1]); w.y = cvt_pk_bf16(v0[2], v0[3]); w.z = cvt_pk_bf16(v1[0], v1[1]); w.w = cvt_pk_bf16(v1[2], v1[3]);
;                         *(u32x4*)(rowp + bj * 128) = w; }
;                     __builtin_amdgcn_sched_barrier(0);
;                 }
	ds_read_b128 v[174:177], v184
	ds_read_b128 v[178:181], v185
	s_mov_b64 s[70:71], 0x100
	v_lshl_add_u64 v[182:183], v[182:183], 0, s[70:71]
	v_lshl_add_u64 v[190:191], v[182:183], 0, v[142:143]
	s_waitcnt lgkmcnt(1)
	global_store_dwordx4 v[190:191], v[174:177], off
	ds_read_b128 v[174:177], v186
	ds_read_b128 v[190:193], v187
	v_lshl_add_u64 v[194:195], v[182:183], 0, v[144:145]
	s_waitcnt lgkmcnt(2)
	global_store_dwordx4 v[194:195], v[178:181], off
	s_nop 1
	v_lshl_add_u64 v[178:179], v[182:183], 0, v[146:147]
	s_waitcnt lgkmcnt(1)
	global_store_dwordx4 v[178:179], v[174:177], off
	s_nop 1
	v_lshl_add_u64 v[174:175], v[182:183], 0, v[148:149]
	s_waitcnt lgkmcnt(0)
	global_store_dwordx4 v[174:175], v[190:193], off
	s_waitcnt lgkmcnt(0)
	s_cbranch_execnz .LBB0_970
.LBB0_985:
	s_add_u32 s68, s68, s35
	v_or_b32_e32 v143, s66, v157
	s_addc_u32 s69, s69, 0
	s_ashr_i32 s0, s66, 31
	v_mov_b32_e32 v151, v137
	v_mul_lo_u32 v145, s11, v143
	s_mul_i32 s0, s10, s0
	v_mad_u64_u32 v[176:177], s[66:67], s10, v143, 0
	v_lshl_add_u64 v[174:175], s[68:69], 0, v[150:151]
	v_add3_u32 v177, v177, s0, v145
	v_lshl_add_u64 v[176:177], v[176:177], 1, v[174:175]
	s_waitcnt lgkmcnt(7)
	v_pk_mul_f32 v[126:127], v[126:127], v[172:173] op_sel_hi:[1,0]
	v_pk_mul_f32 v[124:125], v[124:125], v[172:173] op_sel_hi:[1,0]
	v_pk_mul_f32 v[178:179], v[122:123], v[172:173] op_sel_hi:[1,0]
	v_pk_mul_f32 v[122:123], v[120:121], v[172:173] op_sel_hi:[1,0]
	v_cvt_pk_bf16_f32 v120, v124, v125
	v_cvt_pk_bf16_f32 v121, v126, v127
	v_pk_mul_f32 v[118:119], v[118:119], v[172:173] op_sel_hi:[1,0]
	v_cvt_pk_bf16_f32 v122, v122, v123
	v_cvt_pk_bf16_f32 v123, v178, v179
	global_store_dwordx4 v[176:177], v[120:123], off
	v_pk_mul_f32 v[116:117], v[116:117], v[172:173] op_sel_hi:[1,0]
	s_nop 0
	v_pk_mul_f32 v[120:121], v[114:115], v[172:173] op_sel_hi:[1,0]
	v_pk_mul_f32 v[114:115], v[112:113], v[172:173] op_sel_hi:[1,0]
	v_cvt_pk_bf16_f32 v112, v116, v117
	v_cvt_pk_bf16_f32 v113, v118, v119
	s_nop 0
	v_cvt_pk_bf16_f32 v114, v114, v115
	v_cvt_pk_bf16_f32 v115, v120, v121
	global_store_dwordx4 v[176:177], v[112:115], off offset:256
	s_nop 1
	v_or_b32_e32 v112, 16, v143
	v_mul_lo_u32 v114, s11, v112
	v_mad_u64_u32 v[112:113], s[66:67], s10, v112, 0
	v_add3_u32 v113, v113, s0, v114
	v_lshl_add_u64 v[112:113], v[112:113], 1, v[174:175]
	s_waitcnt lgkmcnt(6)
	v_pk_mul_f32 v[110:111], v[110:111], v[170:171] op_sel_hi:[1,0]
	v_pk_mul_f32 v[108:109], v[108:109], v[170:171] op_sel_hi:[1,0]
	v_pk_mul_f32 v[114:115], v[106:107], v[170:171] op_sel_hi:[1,0]
	v_pk_mul_f32 v[106:107], v[104:105], v[170:171] op_sel_hi:[1,0]
	v_cvt_pk_bf16_f32 v104, v108, v109
	v_cvt_pk_bf16_f32 v105, v110, v111
	v_pk_mul_f32 v[102:103], v[102:103], v[170:171] op_sel_hi:[1,0]
	v_cvt_pk_bf16_f32 v106, v106, v107
	v_cvt_pk_bf16_f32 v107, v114, v115
	global_store_dwordx4 v[112:113], v[104:107], off
	v_pk_mul_f32 v[100:101], v[100:101], v[170:171] op_sel_hi:[1,0]
	s_nop 0
	v_pk_mul_f32 v[104:105], v[98:99], v[170:171] op_sel_hi:[1,0]
	v_pk_mul_f32 v[98:99], v[96:97], v[170:171] op_sel_hi:[1,0]
	v_cvt_pk_bf16_f32 v96, v100, v101
	v_cvt_pk_bf16_f32 v97, v102, v103
	s_nop 0
	v_cvt_pk_bf16_f32 v98, v98, v99
	v_cvt_pk_bf16_f32 v99, v104, v105
	global_store_dwordx4 v[112:113], v[96:99], off offset:256
	s_nop 1
	v_or_b32_e32 v96, 32, v143
	v_mul_lo_u32 v98, s11, v96
	v_mad_u64_u32 v[96:97], s[66:67], s10, v96, 0
	v_add3_u32 v97, v97, s0, v98
	v_lshl_add_u64 v[96:97], v[96:97], 1, v[174:175]
	s_waitcnt lgkmcnt(5)
	v_pk_mul_f32 v[94:95], v[94:95], v[168:169] op_sel_hi:[1,0]
	v_pk_mul_f32 v[92:93], v[92:93], v[168:169] op_sel_hi:[1,0]
	v_pk_mul_f32 v[98:99], v[90:91], v[168:169] op_sel_hi:[1,0]
	v_pk_mul_f32 v[90:91], v[88:89], v[168:169] op_sel_hi:[1,0]
	v_cvt_pk_bf16_f32 v88, v92, v93
	v_cvt_pk_bf16_f32 v89, v94, v95
	v_pk_mul_f32 v[86:87], v[86:87], v[168:169] op_sel_hi:[1,0]
	v_cvt_pk_bf16_f32 v90, v90, v91
	v_cvt_pk_bf16_f32 v91, v98, v99
	global_store_dwordx4 v[96:97], v[88:91], off
	v_pk_mul_f32 v[84:85], v[84:85], v[168:169] op_sel_hi:[1,0]
	s_nop 0
	v_pk_mul_f32 v[88:89], v[82:83], v[168:169] op_sel_hi:[1,0]
	v_pk_mul_f32 v[82:83], v[80:81], v[168:169] op_sel_hi:[1,0]
	v_cvt_pk_bf16_f32 v80, v84, v85
	v_cvt_pk_bf16_f32 v81, v86, v87
	s_nop 0
	v_cvt_pk_bf16_f32 v82, v82, v83
	v_cvt_pk_bf16_f32 v83, v88, v89
	global_store_dwordx4 v[96:97], v[80:83], off offset:256
	s_nop 1
	v_or_b32_e32 v80, 48, v143
	v_mul_lo_u32 v82, s11, v80
	v_mad_u64_u32 v[80:81], s[66:67], s10, v80, 0
	v_add3_u32 v81, v81, s0, v82
	v_lshl_add_u64 v[80:81], v[80:81], 1, v[174:175]
	s_waitcnt lgkmcnt(4)
; __device__ __forceinline__ unsigned cvt_pk_bf16(float lo, float hi) { unsigned r; asm("v_cvt_pk_bf16_f32 %0, %1, %2" : "=v"(r) : "v"(lo), "v"(hi)); return r; }
;     __device__ __forceinline__ void operator()(const f32x4 (&acc)[2][2][4][2], const Unit& u, int wr, int wc, int fr, int fq, LAS unsigned char* xs, int wid, int lane) const {
;     ...
;         if (mode == 0) {
; #pragma unroll
;             for (int ai = 0; ai < 2; ++ai)
; #pragma unroll
;                 for (int m = 0; m < 4; ++m) {
;                     const float r = rs[ai][m];
;                     bf16_t* rowp = base + (size_t)(row0 + ai * 128 + m * 16 + fr) * ldc + wc * 32 + 8 * fq;
; #pragma unroll
;                     for (int bj = 0; bj < 2; ++bj) { const f32x4 v0 = acc[ai][bj][m][0] * r, v1 = acc[ai][bj][m][1] * r;
;                         u32x4 w; w.x = cvt_pk_bf16(v0[0], v0[1]); w.y = cvt_pk_bf16(v0[2], v0[3]); w.z = cvt_pk_bf16(v1[0], v1[1]); w.w = cvt_pk_bf16(v1[2], v1[3]);
;                         *(u32x4*)(rowp + bj * 128) = w; }
;                     __builtin_amdgcn_sched_barrier(0);
;                 }
	v_pk_mul_f32 v[78:79], v[78:79], v[166:167] op_sel_hi:[1,0]
	v_pk_mul_f32 v[76:77], v[76:77], v[166:167] op_sel_hi:[1,0]
	v_pk_mul_f32 v[82:83], v[74:75], v[166:167] op_sel_hi:[1,0]
	v_pk_mul_f32 v[74:75], v[72:73], v[166:167] op_sel_hi:[1,0]
	v_cvt_pk_bf16_f32 v72, v76, v77
	v_cvt_pk_bf16_f32 v73, v78, v79
	v_pk_mul_f32 v[70:71], v[70:71], v[166:167] op_sel_hi:[1,0]
	v_cvt_pk_bf16_f32 v74, v74, v75
	v_cvt_pk_bf16_f32 v75, v82, v83
	global_store_dwordx4 v[80:81], v[72:75], off
	v_pk_mul_f32 v[68:69], v[68:69], v[166:167] op_sel_hi:[1,0]
	s_nop 0
	v_pk_mul_f32 v[72:73], v[66:67], v[166:167] op_sel_hi:[1,0]
	v_pk_mul_f32 v[66:67], v[64:65], v[166:167] op_sel_hi:[1,0]
	v_cvt_pk_bf16_f32 v64, v68, v69
	v_cvt_pk_bf16_f32 v65, v70, v71
	s_nop 0
	v_cvt_pk_bf16_f32 v66, v66, v67
	v_cvt_pk_bf16_f32 v67, v72, v73
	global_store_dwordx4 v[80:81], v[64:67], off offset:256
	s_nop 1
	v_add_u32_e32 v64, 0x80, v143
	v_ashrrev_i32_e32 v65, 31, v64
	v_mul_lo_u32 v66, s10, v65
	v_mul_lo_u32 v67, s11, v64
	v_mad_u64_u32 v[64:65], s[66:67], s10, v64, 0
	v_add3_u32 v65, v65, v66, v67
	v_lshl_add_u64 v[64:65], v[64:65], 1, v[174:175]
	s_waitcnt lgkmcnt(3)
	v_pk_mul_f32 v[62:63], v[62:63], v[164:165] op_sel_hi:[1,0]
	v_pk_mul_f32 v[60:61], v[60:61], v[164:165] op_sel_hi:[1,0]
	v_pk_mul_f32 v[66:67], v[58:59], v[164:165] op_sel_hi:[1,0]
	v_pk_mul_f32 v[58:59], v[56:57], v[164:165] op_sel_hi:[1,0]
	v_cvt_pk_bf16_f32 v56, v60, v61
	v_cvt_pk_bf16_f32 v57, v62, v63
	v_pk_mul_f32 v[54:55], v[54:55], v[164:165] op_sel_hi:[1,0]
	v_cvt_pk_bf16_f32 v58, v58, v59
	v_cvt_pk_bf16_f32 v59, v66, v67
	global_store_dwordx4 v[64:65], v[56:59], off
	v_pk_mul_f32 v[52:53], v[52:53], v[164:165] op_sel_hi:[1,0]
	s_nop 0
	v_pk_mul_f32 v[56:57], v[50:51], v[164:165] op_sel_hi:[1,0]
	v_pk_mul_f32 v[50:51], v[48:49], v[164:165] op_sel_hi:[1,0]
	v_cvt_pk_bf16_f32 v48, v52, v53
	v_cvt_pk_bf16_f32 v49, v54, v55
	s_nop 0
	v_cvt_pk_bf16_f32 v50, v50, v51
	v_cvt_pk_bf16_f32 v51, v56, v57
	global_store_dwordx4 v[64:65], v[48:51], off offset:256
	s_nop 1
	v_add_u32_e32 v48, 0x90, v143
	v_ashrrev_i32_e32 v49, 31, v48
	v_mul_lo_u32 v50, s10, v49
	v_mul_lo_u32 v51, s11, v48
	v_mad_u64_u32 v[48:49], s[66:67], s10, v48, 0
	v_add3_u32 v49, v49, v50, v51
	v_lshl_add_u64 v[48:49], v[48:49], 1, v[174:175]
	s_waitcnt lgkmcnt(2)
	v_pk_mul_f32 v[46:47], v[46:47], v[162:163] op_sel_hi:[1,0]
	v_pk_mul_f32 v[44:45], v[44:45], v[162:163] op_sel_hi:[1,0]
	v_pk_mul_f32 v[50:51], v[42:43], v[162:163] op_sel_hi:[1,0]
	v_pk_mul_f32 v[42:43], v[40:41], v[162:163] op_sel_hi:[1,0]
	v_cvt_pk_bf16_f32 v40, v44, v45
	v_cvt_pk_bf16_f32 v41, v46, v47
	v_pk_mul_f32 v[38:39], v[38:39], v[162:163] op_sel_hi:[1,0]
	v_cvt_pk_bf16_f32 v42, v42, v43
	v_cvt_pk_bf16_f32 v43, v50, v51
	global_store_dwordx4 v[48:49], v[40:43], off
	v_pk_mul_f32 v[36:37], v[36:37], v[162:163] op_sel_hi:[1,0]
	s_nop 0
	v_pk_mul_f32 v[40:41], v[34:35], v[162:163] op_sel_hi:[1,0]
	v_pk_mul_f32 v[34:35], v[32:33], v[162:163] op_sel_hi:[1,0]
	v_cvt_pk_bf16_f32 v32, v36, v37
	v_cvt_pk_bf16_f32 v33, v38, v39
	s_nop 0
	v_cvt_pk_bf16_f32 v34, v34, v35
	v_cvt_pk_bf16_f32 v35, v40, v41
	global_store_dwordx4 v[48:49], v[32:35], off offset:256
	s_nop 1
	v_add_u32_e32 v32, 0xa0, v143
	v_ashrrev_i32_e32 v33, 31, v32
	v_mul_lo_u32 v34, s10, v33
	v_mul_lo_u32 v35, s11, v32
	v_mad_u64_u32 v[32:33], s[66:67], s10, v32, 0
	v_add3_u32 v33, v33, v34, v35
	v_lshl_add_u64 v[32:33], v[32:33], 1, v[174:175]
	s_waitcnt lgkmcnt(1)
	v_pk_mul_f32 v[30:31], v[30:31], v[160:161] op_sel_hi:[1,0]
	v_pk_mul_f32 v[28:29], v[28:29], v[160:161] op_sel_hi:[1,0]
	v_pk_mul_f32 v[34:35], v[26:27], v[160:161] op_sel_hi:[1,0]
	v_pk_mul_f32 v[26:27], v[24:25], v[160:161] op_sel_hi:[1,0]
	v_cvt_pk_bf16_f32 v24, v28, v29
	v_cvt_pk_bf16_f32 v25, v30, v31
	v_pk_mul_f32 v[22:23], v[22:23], v[160:161] op_sel_hi:[1,0]
	v_cvt_pk_bf16_f32 v26, v26, v27
	v_cvt_pk_bf16_f32 v27, v34, v35
	global_store_dwordx4 v[32:33], v[24:27], off
	v_pk_mul_f32 v[20:21], v[20:21], v[160:161] op_sel_hi:[1,0]
	s_nop 0
	v_pk_mul_f32 v[24:25], v[18:19], v[160:161] op_sel_hi:[1,0]
	v_pk_mul_f32 v[18:19], v[16:17], v[160:161] op_sel_hi:[1,0]
	v_cvt_pk_bf16_f32 v16, v20, v21
	v_cvt_pk_bf16_f32 v17, v22, v23
	s_nop 0
	v_cvt_pk_bf16_f32 v18, v18, v19
	v_cvt_pk_bf16_f32 v19, v24, v25
	global_store_dwordx4 v[32:33], v[16:19], off offset:256
	s_nop 1
	v_add_u32_e32 v16, 0xb0, v143
	v_ashrrev_i32_e32 v17, 31, v16
	v_mul_lo_u32 v18, s10, v17
	v_mul_lo_u32 v19, s11, v16
	v_mad_u64_u32 v[16:17], s[10:11], s10, v16, 0
	v_add3_u32 v17, v17, v18, v19
	v_lshl_add_u64 v[16:17], v[16:17], 1, v[174:175]
	s_waitcnt lgkmcnt(0)
	v_pk_mul_f32 v[14:15], v[14:15], v[158:159] op_sel_hi:[1,0]
	v_pk_mul_f32 v[12:13], v[12:13], v[158:159] op_sel_hi:[1,0]
	v_pk_mul_f32 v[18:19], v[10:11], v[158:159] op_sel_hi:[1,0]
	v_pk_mul_f32 v[10:11], v[8:9], v[158:159] op_sel_hi:[1,0]
	v_cvt_pk_bf16_f32 v8, v12, v13
	v_cvt_pk_bf16_f32 v9, v14, v15
	v_pk_mul_f32 v[6:7], v[6:7], v[158:159] op_sel_hi:[1,0]
	v_cvt_pk_bf16_f32 v10, v10, v11
	v_cvt_pk_bf16_f32 v11, v18, v19
	global_store_dwordx4 v[16:17], v[8:11], off
	v_pk_mul_f32 v[4:5], v[4:5], v[158:159] op_sel_hi:[1,0]
	s_nop 0
	v_pk_mul_f32 v[8:9], v[2:3], v[158:159] op_sel_hi:[1,0]
	v_pk_mul_f32 v[2:3], v[0:1], v[158:159] op_sel_hi:[1,0]
	v_cvt_pk_bf16_f32 v0, v4, v5
	v_cvt_pk_bf16_f32 v1, v6, v7
	s_nop 0
	v_cvt_pk_bf16_f32 v2, v2, v3
	v_cvt_pk_bf16_f32 v3, v8, v9
	global_store_dwordx4 v[16:17], v[0:3], off offset:256
	s_andn2_b64 vcc, exec, s[8:9]
	s_mov_b64 s[8:9], -1
	s_cbranch_vccnz .LBB0_959

; __device__ __forceinline__ unsigned cvt_pk_bf16(float lo, float hi) { unsigned r; asm("v_cvt_pk_bf16_f32 %0, %1, %2" : "=v"(r) : "v"(lo), "v"(hi)); return r; }
;     __device__ __forceinline__ void operator()(const f32x4 (&acc)[2][2][4][2], const Unit& u, int wr, int wc, int fr, int fq, LAS unsigned char* xs, int wid, int lane) const {
;         const int S = lng ? 4096 : 2048, hp = lng ? 8 : 4;
;         const int cs = u.pm >= hp, k0 = (u.pm - hp * cs) * 256 + wr * 64;
;         const size_t tok0 = lng ? (size_t)TP + (size_t)u.aux * 4096 : (size_t)u.aux * 2048;
;         const float sc = lng ? 0.015625f : 0.02209708691207961f;
;         const float scm = cs ? -sc : sc;
;         float hv[2][8];
;         const float csm = cs ? 0.f : 1.f;
; #pragma unroll
;         for (int bj = 0; bj < 2; ++bj)
; #pragma unroll
;             for (int e = 0; e < 8; ++e) {
;                 const unsigned short h = ft[(size_t)(u.pn * 256 + bj * 128 + wc * 32 + 8 * fq + e) * T + tok0 + S / 2];
;                 const float v = __builtin_bit_cast(float, (unsigned)h << 16) * csm;
;                 hv[bj][e] = (fr & 1) ? -v : v;
;             }
; #pragma unroll
;         for (int ai = 0; ai < 2; ++ai)
; #pragma unroll
;             for (int m = 0; m < 4; ++m) {
;                 const int k = k0 + ai * 128 + m * 16 + fr;
; #pragma unroll
;                 for (int bj = 0; bj < 2; ++bj) {
;                     const int col = (2 * u.pn + bj) * 256 + cs * 128 + wc * 32 + 8 * fq;
;                     f32x4 a = acc[ai][bj][m][0], b = acc[ai][bj][m][1];
; #pragma unroll
;                     for (int j = 0; j < 4; ++j) { a[j] += hv[bj][j]; b[j] += hv[bj][4 + j]; }
;                     u32x4 w; w.x = cvt_pk_bf16(a[0] * sc, a[1] * sc); w.y = cvt_pk_bf16(a[2] * sc, a[3] * sc); w.z = cvt_pk_bf16(b[0] * sc, b[1] * sc); w.w = cvt_pk_bf16(b[2] * sc, b[3] * sc);
;                     *(u32x4*)(pq + (tok0 + k) * 1024 + col) = w;
.LBB0_1183:
	s_lshl_b32 s12, s85, 8
	s_and_b32 s63, s12, 0x700
	s_ashr_i32 s21, s20, 31
	s_add_i32 s63, s63, s27
	s_lshl_b64 s[12:13], s[20:21], 12
	s_add_u32 s20, s12, 0x4000
	s_addc_u32 s21, s13, 0
	s_lshl_b64 s[60:61], s[20:21], 1
	s_add_u32 s60, s46, s60
	v_lshlrev_b32_e32 v136, 16, v150
	v_readlane_b32 s74, v255, 20
	s_addc_u32 s61, s47, s61
	s_movk_i32 s57, 0x1000
	v_lshl_or_b32 v136, s74, 24, v136
	v_lshl_add_u64 v[146:147], s[60:61], 0, v[136:137]
	v_add_co_u32_e32 v156, vcc, s57, v146
	s_mov_b32 s57, 0x11000
	s_nop 0
	v_addc_co_u32_e32 v157, vcc, 0, v147, vcc
	global_load_ushort v136, v[156:157], off
	v_add_co_u32_e32 v156, vcc, s57, v146
	s_mov_b32 s57, 0x21000
	s_nop 0
	v_addc_co_u32_e32 v157, vcc, 0, v147, vcc
	global_load_ushort v158, v[156:157], off
	v_add_co_u32_e32 v156, vcc, s57, v146
	s_mov_b32 s57, 0x31000
	s_nop 0
	v_addc_co_u32_e32 v157, vcc, 0, v147, vcc
	global_load_ushort v159, v[156:157], off
	v_add_co_u32_e32 v156, vcc, s57, v146
	s_mov_b32 s57, 0x41000
	s_nop 0
	v_addc_co_u32_e32 v157, vcc, 0, v147, vcc
	global_load_ushort v160, v[156:157], off
	v_add_co_u32_e32 v156, vcc, s57, v146
	s_mov_b32 s57, 0x51000
	s_nop 0
	v_addc_co_u32_e32 v157, vcc, 0, v147, vcc
	global_load_ushort v161, v[156:157], off
	v_add_co_u32_e32 v156, vcc, s57, v146
	s_mov_b32 s57, 0x61000
	s_nop 0
	v_addc_co_u32_e32 v157, vcc, 0, v147, vcc
	global_load_ushort v162, v[156:157], off
	v_add_co_u32_e32 v156, vcc, s57, v146
	s_mov_b32 s57, 0x71000
	s_nop 0
	v_addc_co_u32_e32 v157, vcc, 0, v147, vcc
	global_load_ushort v163, v[156:157], off
	v_add_co_u32_e32 v156, vcc, s57, v146
	s_cmp_lt_u32 s85, 8
	s_nop 0
	v_addc_co_u32_e32 v157, vcc, 0, v147, vcc
	global_load_ushort v164, v[156:157], off
	v_add_co_u32_e32 v156, vcc, s39, v146
	s_waitcnt vmcnt(0)
	v_lshlrev_b32_e32 v136, 16, v136
	v_addc_co_u32_e32 v157, vcc, 0, v147, vcc
	global_load_ushort v165, v[156:157], off
	v_add_co_u32_e32 v156, vcc, s41, v146
	s_nop 1
	v_addc_co_u32_e32 v157, vcc, 0, v147, vcc
	global_load_ushort v166, v[156:157], off
	v_add_co_u32_e32 v156, vcc, s64, v146
	s_nop 1
	v_addc_co_u32_e32 v157, vcc, 0, v147, vcc
	global_load_ushort v167, v[156:157], off
	v_add_co_u32_e32 v156, vcc, s65, v146
	s_nop 1
	v_addc_co_u32_e32 v157, vcc, 0, v147, vcc
	global_load_ushort v168, v[156:157], off
	v_add_co_u32_e32 v156, vcc, s66, v146
	s_nop 1
	v_addc_co_u32_e32 v157, vcc, 0, v147, vcc
	global_load_ushort v169, v[156:157], off
	v_add_co_u32_e32 v156, vcc, s67, v146
	s_nop 1
	v_addc_co_u32_e32 v157, vcc, 0, v147, vcc
	global_load_ushort v170, v[156:157], off
	v_add_co_u32_e32 v156, vcc, s68, v146
	s_nop 1
	v_addc_co_u32_e32 v157, vcc, 0, v147, vcc
	v_add_co_u32_e32 v146, vcc, s69, v146
	global_load_ushort v171, v[156:157], off
	s_nop 0
	v_addc_co_u32_e32 v147, vcc, 0, v147, vcc
	global_load_ushort v172, v[146:147], off
	s_cselect_b64 vcc, -1, 0
	v_cndmask_b32_e64 v173, 0, 1.0, vcc
	v_mul_f32_e32 v136, v173, v136
	v_cndmask_b32_e64 v157, -v136, v136, s[8:9]
	v_lshlrev_b32_e32 v136, 16, v158
	v_mul_f32_e32 v136, v173, v136
	v_cndmask_b32_e64 v158, -v136, v136, s[8:9]
	v_lshlrev_b32_e32 v136, 16, v159
	v_mul_f32_e32 v136, v173, v136
	v_cndmask_b32_e64 v159, -v136, v136, s[8:9]
	v_lshlrev_b32_e32 v136, 16, v160
	v_mul_f32_e32 v136, v173, v136
	v_cndmask_b32_e64 v160, -v136, v136, s[8:9]
	v_lshlrev_b32_e32 v136, 16, v161
	v_mul_f32_e32 v136, v173, v136
	v_cndmask_b32_e64 v161, -v136, v136, s[8:9]
	v_lshlrev_b32_e32 v136, 16, v162
	v_mul_f32_e32 v136, v173, v136
	v_cndmask_b32_e64 v162, -v136, v136, s[8:9]
	v_lshlrev_b32_e32 v136, 16, v163
	v_mul_f32_e32 v136, v173, v136
	v_or_b32_e32 v146, s63, v148
	s_and_b64 s[60:61], vcc, exec
	v_cndmask_b32_e64 v163, -v136, v136, s[8:9]
	v_lshlrev_b32_e32 v136, 16, v164
	s_cselect_b32 s60, 0, 0x80
	s_add_u32 s57, s12, 0x5000
	v_ashrrev_i32_e32 v147, 31, v146
	v_mul_f32_e32 v136, v173, v136
	s_addc_u32 s62, s13, 0
	v_lshl_add_u64 v[174:175], s[20:21], 0, v[146:147]
	v_cndmask_b32_e64 v164, -v136, v136, s[8:9]
	v_lshlrev_b64 v[182:183], 11, v[174:175]
	v_sub_co_u32_e64 v174, s[12:13], s57, v146
	v_mov_b32_e32 v136, s62
	s_nop 0
	v_subb_co_u32_e64 v175, s[12:13], v136, v147, s[12:13]
	v_lshlrev_b64 v[184:185], 11, v[174:175]
	v_add_f32_e32 v147, v124, v157
	v_add_f32_e32 v174, v125, v158
	v_add_f32_e32 v124, v120, v161
	v_add_f32_e32 v125, v121, v162
	v_add_f32_e32 v175, v126, v159
	v_add_f32_e32 v176, v127, v160
	v_mul_f32_e32 v120, 0x3c800000, v147
	v_mul_f32_e32 v121, 0x3c800000, v174
	s_lshl_b32 s12, s74, 9
	v_cvt_pk_bf16_f32 v178, v120, v121
	v_mul_f32_e32 v120, 0x3c800000, v175
	v_mul_f32_e32 v121, 0x3c800000, v176
	v_add_f32_e32 v126, v122, v163
	v_add_f32_e32 v127, v123, v164
	s_or_b32 s12, s60, s12
	v_cvt_pk_bf16_f32 v179, v120, v121
	v_mul_f32_e32 v120, 0x3c800000, v124
	v_mul_f32_e32 v121, 0x3c800000, v125
	v_or_b32_e32 v122, s12, v150
	v_cvt_pk_bf16_f32 v180, v120, v121
	v_mul_f32_e32 v120, 0x3c800000, v126
	v_mul_f32_e32 v121, 0x3c800000, v127
	v_cvt_pk_bf16_f32 v181, v120, v121
	v_lshl_add_u64 v[120:121], s[16:17], 0, v[182:183]
	v_lshlrev_b32_e32 v136, 1, v122
	v_cndmask_b32_e32 v156, v154, v155, vcc
	v_cmp_lt_i32_e32 vcc, 0, v146
	v_lshl_add_u64 v[122:123], v[120:121], 0, v[136:137]
	v_lshl_add_u64 v[120:121], s[16:17], 0, v[184:185]
	global_store_dwordx4 v[122:123], v[178:181], off
	s_and_saveexec_b64 s[12:13], vcc
	s_cbranch_execz .LBB0_1185
	v_mul_f32_e32 v147, v156, v147
	v_mul_f32_e32 v174, v156, v174
	v_mul_f32_e32 v124, v156, v124
	v_mul_f32_e32 v125, v156, v125
	v_cvt_pk_bf16_f32 v174, v147, v174
	v_mul_f32_e32 v147, v156, v175
	v_mul_f32_e32 v175, v156, v176
	v_cvt_pk_bf16_f32 v176, v124, v125
	v_mul_f32_e32 v124, v156, v126
	v_mul_f32_e32 v125, v156, v127
	v_cvt_pk_bf16_f32 v177, v124, v125
	v_lshl_add_u64 v[124:125], v[120:121], 0, v[136:137]
	v_cvt_pk_bf16_f32 v175, v147, v175
	global_store_dwordx4 v[124:125], v[174:177], off
; __device__ __forceinline__ unsigned cvt_pk_bf16(float lo, float hi) { unsigned r; asm("v_cvt_pk_bf16_f32 %0, %1, %2" : "=v"(r) : "v"(lo), "v"(hi)); return r; }
;     __device__ __forceinline__ void operator()(const f32x4 (&acc)[2][2][4][2], const Unit& u, int wr, int wc, int fr, int fq, LAS unsigned char* xs, int wid, int lane) const {
;     ...
;         for (int bj = 0; bj < 2; ++bj)
; #pragma unroll
;             for (int e = 0; e < 8; ++e) {
;                 const unsigned short h = ft[(size_t)(u.pn * 256 + bj * 128 + wc * 32 + 8 * fq + e) * T + tok0 + S / 2];
;                 const float v = __builtin_bit_cast(float, (unsigned)h << 16) * csm;
;                 hv[bj][e] = (fr & 1) ? -v : v;
;             }
; #pragma unroll
;         for (int ai = 0; ai < 2; ++ai)
; #pragma unroll
;             for (int m = 0; m < 4; ++m) {
;                 const int k = k0 + ai * 128 + m * 16 + fr;
; #pragma unroll
;                 for (int bj = 0; bj < 2; ++bj) {
;                     const int col = (2 * u.pn + bj) * 256 + cs * 128 + wc * 32 + 8 * fq;
;                     f32x4 a = acc[ai][bj][m][0], b = acc[ai][bj][m][1];
; #pragma unroll
;                     for (int j = 0; j < 4; ++j) { a[j] += hv[bj][j]; b[j] += hv[bj][4 + j]; }
;                     u32x4 w; w.x = cvt_pk_bf16(a[0] * sc, a[1] * sc); w.y = cvt_pk_bf16(a[2] * sc, a[3] * sc); w.z = cvt_pk_bf16(b[0] * sc, b[1] * sc); w.w = cvt_pk_bf16(b[2] * sc, b[3] * sc);
;                     *(u32x4*)(pq + (tok0 + k) * 1024 + col) = w;
;                     if (k > 0) {
;                         u32x4 w2; w2.x = cvt_pk_bf16(a[0] * scm, a[1] * scm); w2.y = cvt_pk_bf16(a[2] * scm, a[3] * scm); w2.z = cvt_pk_bf16(b[0] * scm, b[1] * scm); w2.w = cvt_pk_bf16(b[2] * scm, b[3] * scm);
;                         *(u32x4*)(pq + (tok0 + S - k) * 1024 + col) = w2;
;                     }
;                 }
.LBB0_1185:
	s_or_b64 exec, exec, s[12:13]
	s_waitcnt vmcnt(8)
	v_lshlrev_b32_e32 v124, 16, v165
	s_waitcnt vmcnt(7)
	v_lshlrev_b32_e32 v125, 16, v166
	v_mul_f32_e32 v124, v173, v124
	v_mul_f32_e32 v125, v173, v125
	s_waitcnt vmcnt(6)
	v_lshlrev_b32_e32 v126, 16, v167
	s_waitcnt vmcnt(5)
	v_lshlrev_b32_e32 v127, 16, v168
	v_cndmask_b32_e64 v124, -v124, v124, s[8:9]
	v_cndmask_b32_e64 v125, -v125, v125, s[8:9]
	v_mul_f32_e32 v126, v173, v126
	v_mul_f32_e32 v127, v173, v127
	s_waitcnt vmcnt(4)
	v_lshlrev_b32_e32 v147, 16, v169
	s_waitcnt vmcnt(3)
	v_lshlrev_b32_e32 v165, 16, v170
	v_cndmask_b32_e64 v126, -v126, v126, s[8:9]
	v_cndmask_b32_e64 v127, -v127, v127, s[8:9]
	v_mul_f32_e32 v147, v173, v147
	v_mul_f32_e32 v165, v173, v165
	s_waitcnt vmcnt(2)
	v_lshlrev_b32_e32 v166, 16, v171
	v_add_f32_e32 v116, v116, v124
	v_add_f32_e32 v117, v117, v125
	v_cndmask_b32_e64 v147, -v147, v147, s[8:9]
	v_cndmask_b32_e64 v165, -v165, v165, s[8:9]
	v_mul_f32_e32 v166, v173, v166
	s_waitcnt vmcnt(1)
	v_lshlrev_b32_e32 v167, 16, v172
	v_add_f32_e32 v118, v118, v126
	v_add_f32_e32 v119, v119, v127
	v_mul_f32_e32 v168, 0x3c800000, v116
	v_mul_f32_e32 v169, 0x3c800000, v117
	v_cndmask_b32_e64 v166, -v166, v166, s[8:9]
	v_mul_f32_e32 v167, v173, v167
	v_add_f32_e32 v112, v112, v147
	v_add_f32_e32 v113, v113, v165
	v_cvt_pk_bf16_f32 v168, v168, v169
	v_mul_f32_e32 v169, 0x3c800000, v118
	v_mul_f32_e32 v170, 0x3c800000, v119
	v_cndmask_b32_e64 v167, -v167, v167, s[8:9]
	v_add_f32_e32 v114, v114, v166
	v_cvt_pk_bf16_f32 v169, v169, v170
	v_mul_f32_e32 v170, 0x3c800000, v112
	v_mul_f32_e32 v171, 0x3c800000, v113
	v_add_f32_e32 v115, v115, v167
	v_cvt_pk_bf16_f32 v170, v170, v171
	v_mul_f32_e32 v171, 0x3c800000, v114
	v_mul_f32_e32 v172, 0x3c800000, v115
	v_cvt_pk_bf16_f32 v171, v171, v172
	global_store_dwordx4 v[122:123], v[168:171], off offset:512
	s_and_saveexec_b64 s[12:13], vcc
	s_cbranch_execz .LBB0_1187
	v_mul_f32_e32 v116, v156, v116
	v_mul_f32_e32 v117, v156, v117
	v_cvt_pk_bf16_f32 v116, v116, v117
	v_mul_f32_e32 v117, v156, v118
	v_mul_f32_e32 v118, v156, v119
	v_mul_f32_e32 v112, v156, v112
	v_mul_f32_e32 v113, v156, v113
	v_cvt_pk_bf16_f32 v117, v117, v118
	v_cvt_pk_bf16_f32 v118, v112, v113
	v_mul_f32_e32 v112, v156, v114
	v_mul_f32_e32 v113, v156, v115
	v_cvt_pk_bf16_f32 v119, v112, v113
	v_lshl_add_u64 v[112:113], v[120:121], 0, v[136:137]
	global_store_dwordx4 v[112:113], v[116:119], off offset:512
.LBB0_1187:
	s_or_b64 exec, exec, s[12:13]
	v_or_b32_e32 v112, 16, v146
	v_ashrrev_i32_e32 v113, 31, v112
	v_lshl_add_u64 v[114:115], s[20:21], 0, v[112:113]
	v_lshlrev_b64 v[120:121], 11, v[114:115]
	v_mov_b32_e32 v114, s62
	v_sub_co_u32_e32 v112, vcc, s57, v112
	v_add_f32_e32 v115, v111, v160
	s_nop 0
	v_subb_co_u32_e32 v113, vcc, v114, v113, vcc
	v_lshlrev_b64 v[122:123], 11, v[112:113]
	v_add_f32_e32 v112, v108, v157
	v_add_f32_e32 v113, v109, v158
	v_add_f32_e32 v108, v104, v161
	v_add_f32_e32 v109, v105, v162
	v_add_f32_e32 v114, v110, v159
	v_mul_f32_e32 v104, 0x3c800000, v112
	v_mul_f32_e32 v105, 0x3c800000, v113
	v_cvt_pk_bf16_f32 v116, v104, v105
	v_mul_f32_e32 v104, 0x3c800000, v114
	v_mul_f32_e32 v105, 0x3c800000, v115
	v_add_f32_e32 v110, v106, v163
	v_add_f32_e32 v111, v107, v164
	v_cvt_pk_bf16_f32 v117, v104, v105
	v_mul_f32_e32 v104, 0x3c800000, v108
	v_mul_f32_e32 v105, 0x3c800000, v109
	v_cvt_pk_bf16_f32 v118, v104, v105
	v_mul_f32_e32 v104, 0x3c800000, v110
	v_mul_f32_e32 v105, 0x3c800000, v111
	s_cmp_gt_i32 s63, -1
	v_cvt_pk_bf16_f32 v119, v104, v105
	v_lshl_add_u64 v[104:105], s[16:17], 0, v[120:121]
	s_cselect_b64 s[60:61], -1, 0
	s_cmp_lt_i32 s63, 0
	v_lshl_add_u64 v[106:107], v[104:105], 0, v[136:137]
	v_lshl_add_u64 v[104:105], s[16:17], 0, v[122:123]
	global_store_dwordx4 v[106:107], v[116:119], off
	s_cbranch_scc1 .LBB0_1189
	v_mul_f32_e32 v112, v156, v112
	v_mul_f32_e32 v113, v156, v113
	v_cvt_pk_bf16_f32 v112, v112, v113
	v_mul_f32_e32 v113, v156, v114
	v_mul_f32_e32 v114, v156, v115
	v_mul_f32_e32 v108, v156, v108
	v_mul_f32_e32 v109, v156, v109
	v_cvt_pk_bf16_f32 v113, v113, v114
	v_cvt_pk_bf16_f32 v114, v108, v109
	v_mul_f32_e32 v108, v156, v110
	v_mul_f32_e32 v109, v156, v111
	v_cvt_pk_bf16_f32 v115, v108, v109
	v_lshl_add_u64 v[108:109], v[104:105], 0, v[136:137]
	global_store_dwordx4 v[108:109], v[112:115], off
.LBB0_1189:
	v_add_f32_e32 v100, v100, v124
	v_add_f32_e32 v101, v101, v125
	v_add_f32_e32 v102, v102, v126
	v_add_f32_e32 v103, v103, v127
	v_mul_f32_e32 v108, 0x3c800000, v100
	v_mul_f32_e32 v109, 0x3c800000, v101
	v_add_f32_e32 v96, v96, v147
	v_add_f32_e32 v97, v97, v165
	v_cvt_pk_bf16_f32 v108, v108, v109
	v_mul_f32_e32 v109, 0x3c800000, v102
	v_mul_f32_e32 v110, 0x3c800000, v103
	v_add_f32_e32 v98, v98, v166
	v_add_f32_e32 v99, v99, v167
	v_cvt_pk_bf16_f32 v109, v109, v110
	v_mul_f32_e32 v110, 0x3c800000, v96
	v_mul_f32_e32 v111, 0x3c800000, v97
	v_cvt_pk_bf16_f32 v110, v110, v111
	v_mul_f32_e32 v111, 0x3c800000, v98
	v_mul_f32_e32 v112, 0x3c800000, v99
	v_cvt_pk_bf16_f32 v111, v111, v112
	v_cndmask_b32_e64 v112, 0, 1, s[60:61]
	v_cmp_ne_u32_e64 s[12:13], 1, v112
	s_andn2_b64 vcc, exec, s[60:61]
	global_store_dwordx4 v[106:107], v[108:111], off offset:512
	s_cbranch_vccnz .LBB0_1191
	v_mul_f32_e32 v100, v156, v100
	v_mul_f32_e32 v101, v156, v101
	v_cvt_pk_bf16_f32 v100, v100, v101
	v_mul_f32_e32 v101, v156, v102
	v_mul_f32_e32 v102, v156, v103
	v_mul_f32_e32 v96, v156, v96
	v_mul_f32_e32 v97, v156, v97
	v_cvt_pk_bf16_f32 v101, v101, v102
	v_cvt_pk_bf16_f32 v102, v96, v97
	v_mul_f32_e32 v96, v156, v98
	v_mul_f32_e32 v97, v156, v99
	v_cvt_pk_bf16_f32 v103, v96, v97
	v_lshl_add_u64 v[96:97], v[104:105], 0, v[136:137]
	global_store_dwordx4 v[96:97], v[100:103], off offset:512
; __device__ __forceinline__ unsigned cvt_pk_bf16(float lo, float hi) { unsigned r; asm("v_cvt_pk_bf16_f32 %0, %1, %2" : "=v"(r) : "v"(lo), "v"(hi)); return r; }
;     __device__ __forceinline__ void operator()(const f32x4 (&acc)[2][2][4][2], const Unit& u, int wr, int wc, int fr, int fq, LAS unsigned char* xs, int wid, int lane) const {
;     ...
;         for (int ai = 0; ai < 2; ++ai)
; #pragma unroll
;             for (int m = 0; m < 4; ++m) {
;                 const int k = k0 + ai * 128 + m * 16 + fr;
; #pragma unroll
;                 for (int bj = 0; bj < 2; ++bj) {
;                     const int col = (2 * u.pn + bj) * 256 + cs * 128 + wc * 32 + 8 * fq;
;                     f32x4 a = acc[ai][bj][m][0], b = acc[ai][bj][m][1];
; #pragma unroll
;                     for (int j = 0; j < 4; ++j) { a[j] += hv[bj][j]; b[j] += hv[bj][4 + j]; }
;                     u32x4 w; w.x = cvt_pk_bf16(a[0] * sc, a[1] * sc); w.y = cvt_pk_bf16(a[2] * sc, a[3] * sc); w.z = cvt_pk_bf16(b[0] * sc, b[1] * sc); w.w = cvt_pk_bf16(b[2] * sc, b[3] * sc);
;                     *(u32x4*)(pq + (tok0 + k) * 1024 + col) = w;
;                     if (k > 0) {
;                         u32x4 w2; w2.x = cvt_pk_bf16(a[0] * scm, a[1] * scm); w2.y = cvt_pk_bf16(a[2] * scm, a[3] * scm); w2.z = cvt_pk_bf16(b[0] * scm, b[1] * scm); w2.w = cvt_pk_bf16(b[2] * scm, b[3] * scm);
;                         *(u32x4*)(pq + (tok0 + S - k) * 1024 + col) = w2;
;                     }
;                 }
.LBB0_1191:
	v_or_b32_e32 v96, 32, v146
	v_ashrrev_i32_e32 v97, 31, v96
	v_lshl_add_u64 v[98:99], s[20:21], 0, v[96:97]
	v_lshlrev_b64 v[104:105], 11, v[98:99]
	v_mov_b32_e32 v98, s62
	v_sub_co_u32_e32 v96, vcc, s57, v96
	v_add_f32_e32 v99, v95, v160
	s_nop 0
	v_subb_co_u32_e32 v97, vcc, v98, v97, vcc
	v_lshlrev_b64 v[106:107], 11, v[96:97]
	v_add_f32_e32 v96, v92, v157
	v_add_f32_e32 v97, v93, v158
	v_add_f32_e32 v92, v88, v161
	v_add_f32_e32 v93, v89, v162
	v_add_f32_e32 v98, v94, v159
	v_mul_f32_e32 v88, 0x3c800000, v96
	v_mul_f32_e32 v89, 0x3c800000, v97
	v_cvt_pk_bf16_f32 v100, v88, v89
	v_mul_f32_e32 v88, 0x3c800000, v98
	v_mul_f32_e32 v89, 0x3c800000, v99
	v_add_f32_e32 v94, v90, v163
	v_add_f32_e32 v95, v91, v164
	v_cvt_pk_bf16_f32 v101, v88, v89
	v_mul_f32_e32 v88, 0x3c800000, v92
	v_mul_f32_e32 v89, 0x3c800000, v93
	v_cvt_pk_bf16_f32 v102, v88, v89
	v_mul_f32_e32 v88, 0x3c800000, v94
	v_mul_f32_e32 v89, 0x3c800000, v95
	v_cvt_pk_bf16_f32 v103, v88, v89
	v_lshl_add_u64 v[88:89], s[16:17], 0, v[104:105]
	v_lshl_add_u64 v[90:91], v[88:89], 0, v[136:137]
	s_and_b64 vcc, exec, s[12:13]
	v_lshl_add_u64 v[88:89], s[16:17], 0, v[106:107]
	global_store_dwordx4 v[90:91], v[100:103], off
	s_cbranch_vccnz .LBB0_1193
	v_mul_f32_e32 v96, v156, v96
	v_mul_f32_e32 v97, v156, v97
	v_cvt_pk_bf16_f32 v96, v96, v97
	v_mul_f32_e32 v97, v156, v98
	v_mul_f32_e32 v98, v156, v99
	v_mul_f32_e32 v92, v156, v92
	v_mul_f32_e32 v93, v156, v93
	v_cvt_pk_bf16_f32 v97, v97, v98
	v_cvt_pk_bf16_f32 v98, v92, v93
	v_mul_f32_e32 v92, v156, v94
	v_mul_f32_e32 v93, v156, v95
	v_cvt_pk_bf16_f32 v99, v92, v93
	v_lshl_add_u64 v[92:93], v[88:89], 0, v[136:137]
	global_store_dwordx4 v[92:93], v[96:99], off
.LBB0_1193:
	v_add_f32_e32 v84, v84, v124
	v_add_f32_e32 v85, v85, v125
	v_add_f32_e32 v86, v86, v126
	v_add_f32_e32 v87, v87, v127
	v_mul_f32_e32 v92, 0x3c800000, v84
	v_mul_f32_e32 v93, 0x3c800000, v85
	v_add_f32_e32 v80, v80, v147
	v_add_f32_e32 v81, v81, v165
	v_cvt_pk_bf16_f32 v92, v92, v93
	v_mul_f32_e32 v93, 0x3c800000, v86
	v_mul_f32_e32 v94, 0x3c800000, v87
	v_add_f32_e32 v82, v82, v166
	v_cvt_pk_bf16_f32 v93, v93, v94
	v_mul_f32_e32 v94, 0x3c800000, v80
	v_mul_f32_e32 v95, 0x3c800000, v81
	v_add_f32_e32 v83, v83, v167
	v_cvt_pk_bf16_f32 v94, v94, v95
	v_mul_f32_e32 v95, 0x3c800000, v82
	s_and_b64 vcc, exec, s[12:13]
	v_mul_f32_e32 v96, 0x3c800000, v83
	v_cvt_pk_bf16_f32 v95, v95, v96
	global_store_dwordx4 v[90:91], v[92:95], off offset:512
	s_cbranch_vccnz .LBB0_1195
	v_mul_f32_e32 v84, v156, v84
	v_mul_f32_e32 v85, v156, v85
	v_cvt_pk_bf16_f32 v84, v84, v85
	v_mul_f32_e32 v85, v156, v86
	v_mul_f32_e32 v86, v156, v87
	v_mul_f32_e32 v80, v156, v80
	v_mul_f32_e32 v81, v156, v81
	v_cvt_pk_bf16_f32 v85, v85, v86
	v_cvt_pk_bf16_f32 v86, v80, v81
	v_mul_f32_e32 v80, v156, v82
	v_mul_f32_e32 v81, v156, v83
	v_cvt_pk_bf16_f32 v87, v80, v81
	v_lshl_add_u64 v[80:81], v[88:89], 0, v[136:137]
	global_store_dwordx4 v[80:81], v[84:87], off offset:512
.LBB0_1195:
	v_or_b32_e32 v80, 48, v146
	v_ashrrev_i32_e32 v81, 31, v80
	v_lshl_add_u64 v[82:83], s[20:21], 0, v[80:81]
	v_lshlrev_b64 v[88:89], 11, v[82:83]
	v_mov_b32_e32 v82, s62
	v_sub_co_u32_e32 v80, vcc, s57, v80
	v_add_f32_e32 v83, v79, v160
	s_nop 0
	v_subb_co_u32_e32 v81, vcc, v82, v81, vcc
	v_lshlrev_b64 v[90:91], 11, v[80:81]
	v_add_f32_e32 v80, v76, v157
	v_add_f32_e32 v81, v77, v158
	v_add_f32_e32 v76, v72, v161
	v_add_f32_e32 v77, v73, v162
	v_add_f32_e32 v82, v78, v159
	v_mul_f32_e32 v72, 0x3c800000, v80
	v_mul_f32_e32 v73, 0x3c800000, v81
	v_cvt_pk_bf16_f32 v84, v72, v73
	v_mul_f32_e32 v72, 0x3c800000, v82
	v_mul_f32_e32 v73, 0x3c800000, v83
	v_add_f32_e32 v78, v74, v163
	v_add_f32_e32 v79, v75, v164
	v_cvt_pk_bf16_f32 v85, v72, v73
	v_mul_f32_e32 v72, 0x3c800000, v76
	v_mul_f32_e32 v73, 0x3c800000, v77
	v_cvt_pk_bf16_f32 v86, v72, v73
	v_mul_f32_e32 v72, 0x3c800000, v78
	v_mul_f32_e32 v73, 0x3c800000, v79
	v_cvt_pk_bf16_f32 v87, v72, v73
	v_lshl_add_u64 v[72:73], s[16:17], 0, v[88:89]
	v_lshl_add_u64 v[74:75], v[72:73], 0, v[136:137]
	s_and_b64 vcc, exec, s[12:13]
	v_lshl_add_u64 v[72:73], s[16:17], 0, v[90:91]
	global_store_dwordx4 v[74:75], v[84:87], off
	s_cbranch_vccnz .LBB0_1197
	v_mul_f32_e32 v80, v156, v80
	v_mul_f32_e32 v81, v156, v81
	v_cvt_pk_bf16_f32 v80, v80, v81
	v_mul_f32_e32 v81, v156, v82
	v_mul_f32_e32 v82, v156, v83
	v_mul_f32_e32 v76, v156, v76
	v_mul_f32_e32 v77, v156, v77
	v_cvt_pk_bf16_f32 v81, v81, v82
	v_cvt_pk_bf16_f32 v82, v76, v77
	v_mul_f32_e32 v76, v156, v78
	v_mul_f32_e32 v77, v156, v79
	v_cvt_pk_bf16_f32 v83, v76, v77
	v_lshl_add_u64 v[76:77], v[72:73], 0, v[136:137]
	global_store_dwordx4 v[76:77], v[80:83], off
.LBB0_1197:
	v_add_f32_e32 v68, v68, v124
	v_add_f32_e32 v69, v69, v125
	v_add_f32_e32 v70, v70, v126
	v_add_f32_e32 v71, v71, v127
	v_mul_f32_e32 v76, 0x3c800000, v68
	v_mul_f32_e32 v77, 0x3c800000, v69
	v_add_f32_e32 v64, v64, v147
	v_add_f32_e32 v65, v65, v165
	v_cvt_pk_bf16_f32 v76, v76, v77
	v_mul_f32_e32 v77, 0x3c800000, v70
	v_mul_f32_e32 v78, 0x3c800000, v71
	v_add_f32_e32 v66, v66, v166
	v_cvt_pk_bf16_f32 v77, v77, v78
	v_mul_f32_e32 v78, 0x3c800000, v64
	v_mul_f32_e32 v79, 0x3c800000, v65
	v_add_f32_e32 v67, v67, v167
	v_cvt_pk_bf16_f32 v78, v78, v79
	v_mul_f32_e32 v79, 0x3c800000, v66
	s_and_b64 vcc, exec, s[12:13]
	v_mul_f32_e32 v80, 0x3c800000, v67
	v_cvt_pk_bf16_f32 v79, v79, v80
	global_store_dwordx4 v[74:75], v[76:79], off offset:512
	s_cbranch_vccnz .LBB0_1199
	v_mul_f32_e32 v68, v156, v68
	v_mul_f32_e32 v69, v156, v69
	v_cvt_pk_bf16_f32 v68, v68, v69
	v_mul_f32_e32 v69, v156, v70
	v_mul_f32_e32 v70, v156, v71
	v_mul_f32_e32 v64, v156, v64
	v_mul_f32_e32 v65, v156, v65
	v_cvt_pk_bf16_f32 v69, v69, v70
	v_cvt_pk_bf16_f32 v70, v64, v65
	v_mul_f32_e32 v64, v156, v66
	v_mul_f32_e32 v65, v156, v67
	v_cvt_pk_bf16_f32 v71, v64, v65
	v_lshl_add_u64 v[64:65], v[72:73], 0, v[136:137]
	global_store_dwordx4 v[64:65], v[68:71], off offset:512
; __device__ __forceinline__ unsigned cvt_pk_bf16(float lo, float hi) { unsigned r; asm("v_cvt_pk_bf16_f32 %0, %1, %2" : "=v"(r) : "v"(lo), "v"(hi)); return r; }
;     __device__ __forceinline__ void operator()(const f32x4 (&acc)[2][2][4][2], const Unit& u, int wr, int wc, int fr, int fq, LAS unsigned char* xs, int wid, int lane) const {
;     ...
;         for (int ai = 0; ai < 2; ++ai)
; #pragma unroll
;             for (int m = 0; m < 4; ++m) {
;                 const int k = k0 + ai * 128 + m * 16 + fr;
; #pragma unroll
;                 for (int bj = 0; bj < 2; ++bj) {
;                     const int col = (2 * u.pn + bj) * 256 + cs * 128 + wc * 32 + 8 * fq;
;                     f32x4 a = acc[ai][bj][m][0], b = acc[ai][bj][m][1];
; #pragma unroll
;                     for (int j = 0; j < 4; ++j) { a[j] += hv[bj][j]; b[j] += hv[bj][4 + j]; }
;                     u32x4 w; w.x = cvt_pk_bf16(a[0] * sc, a[1] * sc); w.y = cvt_pk_bf16(a[2] * sc, a[3] * sc); w.z = cvt_pk_bf16(b[0] * sc, b[1] * sc); w.w = cvt_pk_bf16(b[2] * sc, b[3] * sc);
;                     *(u32x4*)(pq + (tok0 + k) * 1024 + col) = w;
;                     if (k > 0) {
;                         u32x4 w2; w2.x = cvt_pk_bf16(a[0] * scm, a[1] * scm); w2.y = cvt_pk_bf16(a[2] * scm, a[3] * scm); w2.z = cvt_pk_bf16(b[0] * scm, b[1] * scm); w2.w = cvt_pk_bf16(b[2] * scm, b[3] * scm);
;                         *(u32x4*)(pq + (tok0 + S - k) * 1024 + col) = w2;
;                     }
;                 }
.LBB0_1199:
	v_add_u32_e32 v64, 0x80, v146
	v_ashrrev_i32_e32 v65, 31, v64
	v_lshl_add_u64 v[66:67], s[20:21], 0, v[64:65]
	v_lshlrev_b64 v[72:73], 11, v[66:67]
	v_mov_b32_e32 v66, s62
	v_sub_co_u32_e64 v64, s[12:13], s57, v64
	v_add_f32_e32 v67, v63, v160
	s_nop 0
	v_subb_co_u32_e64 v65, s[12:13], v66, v65, s[12:13]
	v_lshlrev_b64 v[74:75], 11, v[64:65]
	v_add_f32_e32 v64, v60, v157
	v_add_f32_e32 v65, v61, v158
	v_add_f32_e32 v60, v56, v161
	v_add_f32_e32 v61, v57, v162
	v_add_f32_e32 v66, v62, v159
	v_mul_f32_e32 v56, 0x3c800000, v64
	v_mul_f32_e32 v57, 0x3c800000, v65
	v_cvt_pk_bf16_f32 v68, v56, v57
	v_mul_f32_e32 v56, 0x3c800000, v66
	v_mul_f32_e32 v57, 0x3c800000, v67
	v_add_f32_e32 v62, v58, v163
	v_add_f32_e32 v63, v59, v164
	v_cvt_pk_bf16_f32 v69, v56, v57
	v_mul_f32_e32 v56, 0x3c800000, v60
	v_mul_f32_e32 v57, 0x3c800000, v61
	v_cvt_pk_bf16_f32 v70, v56, v57
	v_mul_f32_e32 v56, 0x3c800000, v62
	v_mul_f32_e32 v57, 0x3c800000, v63
	v_cvt_pk_bf16_f32 v71, v56, v57
	v_lshl_add_u64 v[56:57], s[16:17], 0, v[72:73]
	v_cmp_lt_i32_e32 vcc, s70, v146
	v_lshl_add_u64 v[58:59], v[56:57], 0, v[136:137]
	v_lshl_add_u64 v[56:57], s[16:17], 0, v[74:75]
	global_store_dwordx4 v[58:59], v[68:71], off
	s_and_saveexec_b64 s[12:13], vcc
	s_cbranch_execz .LBB0_1201
	v_mul_f32_e32 v64, v156, v64
	v_mul_f32_e32 v65, v156, v65
	v_cvt_pk_bf16_f32 v64, v64, v65
	v_mul_f32_e32 v65, v156, v66
	v_mul_f32_e32 v66, v156, v67
	v_mul_f32_e32 v60, v156, v60
	v_mul_f32_e32 v61, v156, v61
	v_cvt_pk_bf16_f32 v65, v65, v66
	v_cvt_pk_bf16_f32 v66, v60, v61
	v_mul_f32_e32 v60, v156, v62
	v_mul_f32_e32 v61, v156, v63
	v_cvt_pk_bf16_f32 v67, v60, v61
	v_lshl_add_u64 v[60:61], v[56:57], 0, v[136:137]
	global_store_dwordx4 v[60:61], v[64:67], off
.LBB0_1201:
	s_or_b64 exec, exec, s[12:13]
	v_add_f32_e32 v52, v52, v124
	v_add_f32_e32 v53, v53, v125
	v_add_f32_e32 v54, v54, v126
	v_add_f32_e32 v55, v55, v127
	v_mul_f32_e32 v60, 0x3c800000, v52
	v_mul_f32_e32 v61, 0x3c800000, v53
	v_add_f32_e32 v48, v48, v147
	v_add_f32_e32 v49, v49, v165
	v_cvt_pk_bf16_f32 v60, v60, v61
	v_mul_f32_e32 v61, 0x3c800000, v54
	v_mul_f32_e32 v62, 0x3c800000, v55
	v_add_f32_e32 v50, v50, v166
	v_cvt_pk_bf16_f32 v61, v61, v62
	v_mul_f32_e32 v62, 0x3c800000, v48
	v_mul_f32_e32 v63, 0x3c800000, v49
	v_add_f32_e32 v51, v51, v167
	v_cvt_pk_bf16_f32 v62, v62, v63
	v_mul_f32_e32 v63, 0x3c800000, v50
	v_mul_f32_e32 v64, 0x3c800000, v51
	v_cvt_pk_bf16_f32 v63, v63, v64
	global_store_dwordx4 v[58:59], v[60:63], off offset:512
	s_and_saveexec_b64 s[12:13], vcc
	s_cbranch_execz .LBB0_1203
	v_mul_f32_e32 v52, v156, v52
	v_mul_f32_e32 v53, v156, v53
	v_cvt_pk_bf16_f32 v52, v52, v53
	v_mul_f32_e32 v53, v156, v54
	v_mul_f32_e32 v54, v156, v55
	v_mul_f32_e32 v48, v156, v48
	v_mul_f32_e32 v49, v156, v49
	v_cvt_pk_bf16_f32 v53, v53, v54
	v_cvt_pk_bf16_f32 v54, v48, v49
	v_mul_f32_e32 v48, v156, v50
	v_mul_f32_e32 v49, v156, v51
	v_cvt_pk_bf16_f32 v55, v48, v49
	v_lshl_add_u64 v[48:49], v[56:57], 0, v[136:137]
	global_store_dwordx4 v[48:49], v[52:55], off offset:512
.LBB0_1203:
	s_or_b64 exec, exec, s[12:13]
	v_add_u32_e32 v48, 0x90, v146
	v_ashrrev_i32_e32 v49, 31, v48
	v_lshl_add_u64 v[50:51], s[20:21], 0, v[48:49]
	v_lshlrev_b64 v[56:57], 11, v[50:51]
	v_mov_b32_e32 v50, s62
	v_sub_co_u32_e64 v48, s[12:13], s57, v48
	v_add_f32_e32 v51, v47, v160
	s_nop 0
	v_subb_co_u32_e64 v49, s[12:13], v50, v49, s[12:13]
	v_lshlrev_b64 v[58:59], 11, v[48:49]
	v_add_f32_e32 v48, v44, v157
	v_add_f32_e32 v49, v45, v158
	v_add_f32_e32 v44, v40, v161
	v_add_f32_e32 v45, v41, v162
	v_add_f32_e32 v50, v46, v159
	v_mul_f32_e32 v40, 0x3c800000, v48
	v_mul_f32_e32 v41, 0x3c800000, v49
	v_cvt_pk_bf16_f32 v52, v40, v41
	v_mul_f32_e32 v40, 0x3c800000, v50
	v_mul_f32_e32 v41, 0x3c800000, v51
	v_add_f32_e32 v46, v42, v163
	v_add_f32_e32 v47, v43, v164
	v_cvt_pk_bf16_f32 v53, v40, v41
	v_mul_f32_e32 v40, 0x3c800000, v44
	v_mul_f32_e32 v41, 0x3c800000, v45
	v_cvt_pk_bf16_f32 v54, v40, v41
	v_mul_f32_e32 v40, 0x3c800000, v46
	v_mul_f32_e32 v41, 0x3c800000, v47
	v_cvt_pk_bf16_f32 v55, v40, v41
	v_lshl_add_u64 v[40:41], s[16:17], 0, v[56:57]
	v_cmp_lt_i32_e32 vcc, s71, v146
	v_lshl_add_u64 v[42:43], v[40:41], 0, v[136:137]
	v_lshl_add_u64 v[40:41], s[16:17], 0, v[58:59]
	global_store_dwordx4 v[42:43], v[52:55], off
	s_and_saveexec_b64 s[12:13], vcc
	s_cbranch_execz .LBB0_1205
	v_mul_f32_e32 v48, v156, v48
	v_mul_f32_e32 v49, v156, v49
	v_cvt_pk_bf16_f32 v48, v48, v49
	v_mul_f32_e32 v49, v156, v50
	v_mul_f32_e32 v50, v156, v51
	v_mul_f32_e32 v44, v156, v44
	v_mul_f32_e32 v45, v156, v45
	v_cvt_pk_bf16_f32 v49, v49, v50
	v_cvt_pk_bf16_f32 v50, v44, v45
	v_mul_f32_e32 v44, v156, v46
	v_mul_f32_e32 v45, v156, v47
	v_cvt_pk_bf16_f32 v51, v44, v45
	v_lshl_add_u64 v[44:45], v[40:41], 0, v[136:137]
	global_store_dwordx4 v[44:45], v[48:51], off
.LBB0_1205:
	s_or_b64 exec, exec, s[12:13]
	v_add_f32_e32 v36, v36, v124
	v_add_f32_e32 v37, v37, v125
	v_add_f32_e32 v38, v38, v126
	v_add_f32_e32 v39, v39, v127
	v_mul_f32_e32 v44, 0x3c800000, v36
	v_mul_f32_e32 v45, 0x3c800000, v37
	v_add_f32_e32 v32, v32, v147
	v_add_f32_e32 v33, v33, v165
	v_cvt_pk_bf16_f32 v44, v44, v45
	v_mul_f32_e32 v45, 0x3c800000, v38
	v_mul_f32_e32 v46, 0x3c800000, v39
	v_add_f32_e32 v34, v34, v166
	v_cvt_pk_bf16_f32 v45, v45, v46
	v_mul_f32_e32 v46, 0x3c800000, v32
	v_mul_f32_e32 v47, 0x3c800000, v33
	v_add_f32_e32 v35, v35, v167
	v_cvt_pk_bf16_f32 v46, v46, v47
	v_mul_f32_e32 v47, 0x3c800000, v34
	v_mul_f32_e32 v48, 0x3c800000, v35
	v_cvt_pk_bf16_f32 v47, v47, v48
	global_store_dwordx4 v[42:43], v[44:47], off offset:512
	s_and_saveexec_b64 s[12:13], vcc
	s_cbranch_execz .LBB0_1207
	v_mul_f32_e32 v36, v156, v36
	v_mul_f32_e32 v37, v156, v37
	v_cvt_pk_bf16_f32 v36, v36, v37
	v_mul_f32_e32 v37, v156, v38
	v_mul_f32_e32 v38, v156, v39
	v_mul_f32_e32 v32, v156, v32
	v_mul_f32_e32 v33, v156, v33
	v_cvt_pk_bf16_f32 v37, v37, v38
	v_cvt_pk_bf16_f32 v38, v32, v33
	v_mul_f32_e32 v32, v156, v34
	v_mul_f32_e32 v33, v156, v35
	v_cvt_pk_bf16_f32 v39, v32, v33
	v_lshl_add_u64 v[32:33], v[40:41], 0, v[136:137]
	global_store_dwordx4 v[32:33], v[36:39], off offset:512
; __device__ __forceinline__ unsigned cvt_pk_bf16(float lo, float hi) { unsigned r; asm("v_cvt_pk_bf16_f32 %0, %1, %2" : "=v"(r) : "v"(lo), "v"(hi)); return r; }
;     __device__ __forceinline__ void operator()(const f32x4 (&acc)[2][2][4][2], const Unit& u, int wr, int wc, int fr, int fq, LAS unsigned char* xs, int wid, int lane) const {
;     ...
;         for (int ai = 0; ai < 2; ++ai)
; #pragma unroll
;             for (int m = 0; m < 4; ++m) {
;                 const int k = k0 + ai * 128 + m * 16 + fr;
; #pragma unroll
;                 for (int bj = 0; bj < 2; ++bj) {
;                     const int col = (2 * u.pn + bj) * 256 + cs * 128 + wc * 32 + 8 * fq;
;                     f32x4 a = acc[ai][bj][m][0], b = acc[ai][bj][m][1];
; #pragma unroll
;                     for (int j = 0; j < 4; ++j) { a[j] += hv[bj][j]; b[j] += hv[bj][4 + j]; }
;                     u32x4 w; w.x = cvt_pk_bf16(a[0] * sc, a[1] * sc); w.y = cvt_pk_bf16(a[2] * sc, a[3] * sc); w.z = cvt_pk_bf16(b[0] * sc, b[1] * sc); w.w = cvt_pk_bf16(b[2] * sc, b[3] * sc);
;                     *(u32x4*)(pq + (tok0 + k) * 1024 + col) = w;
;                     if (k > 0) {
;                         u32x4 w2; w2.x = cvt_pk_bf16(a[0] * scm, a[1] * scm); w2.y = cvt_pk_bf16(a[2] * scm, a[3] * scm); w2.z = cvt_pk_bf16(b[0] * scm, b[1] * scm); w2.w = cvt_pk_bf16(b[2] * scm, b[3] * scm);
;                         *(u32x4*)(pq + (tok0 + S - k) * 1024 + col) = w2;
;                     }
;                 }
.LBB0_1207:
	s_or_b64 exec, exec, s[12:13]
	v_add_u32_e32 v32, 0xa0, v146
	v_ashrrev_i32_e32 v33, 31, v32
	v_lshl_add_u64 v[34:35], s[20:21], 0, v[32:33]
	v_lshlrev_b64 v[40:41], 11, v[34:35]
	v_mov_b32_e32 v34, s62
	v_sub_co_u32_e64 v32, s[12:13], s57, v32
	v_add_f32_e32 v35, v31, v160
	s_nop 0
	v_subb_co_u32_e64 v33, s[12:13], v34, v33, s[12:13]
	v_lshlrev_b64 v[42:43], 11, v[32:33]
	v_add_f32_e32 v32, v28, v157
	v_add_f32_e32 v33, v29, v158
	v_add_f32_e32 v28, v24, v161
	v_add_f32_e32 v29, v25, v162
	v_add_f32_e32 v34, v30, v159
	v_mul_f32_e32 v24, 0x3c800000, v32
	v_mul_f32_e32 v25, 0x3c800000, v33
	v_cvt_pk_bf16_f32 v36, v24, v25
	v_mul_f32_e32 v24, 0x3c800000, v34
	v_mul_f32_e32 v25, 0x3c800000, v35
	v_add_f32_e32 v30, v26, v163
	v_add_f32_e32 v31, v27, v164
	v_cvt_pk_bf16_f32 v37, v24, v25
	v_mul_f32_e32 v24, 0x3c800000, v28
	v_mul_f32_e32 v25, 0x3c800000, v29
	v_cvt_pk_bf16_f32 v38, v24, v25
	v_mul_f32_e32 v24, 0x3c800000, v30
	v_mul_f32_e32 v25, 0x3c800000, v31
	v_cvt_pk_bf16_f32 v39, v24, v25
	v_lshl_add_u64 v[24:25], s[16:17], 0, v[40:41]
	v_cmp_lt_i32_e32 vcc, s72, v146
	v_lshl_add_u64 v[26:27], v[24:25], 0, v[136:137]
	v_lshl_add_u64 v[24:25], s[16:17], 0, v[42:43]
	global_store_dwordx4 v[26:27], v[36:39], off
	s_and_saveexec_b64 s[12:13], vcc
	s_cbranch_execz .LBB0_1209
	v_mul_f32_e32 v32, v156, v32
	v_mul_f32_e32 v33, v156, v33
	v_cvt_pk_bf16_f32 v32, v32, v33
	v_mul_f32_e32 v33, v156, v34
	v_mul_f32_e32 v34, v156, v35
	v_mul_f32_e32 v28, v156, v28
	v_mul_f32_e32 v29, v156, v29
	v_cvt_pk_bf16_f32 v33, v33, v34
	v_cvt_pk_bf16_f32 v34, v28, v29
	v_mul_f32_e32 v28, v156, v30
	v_mul_f32_e32 v29, v156, v31
	v_cvt_pk_bf16_f32 v35, v28, v29
	v_lshl_add_u64 v[28:29], v[24:25], 0, v[136:137]
	global_store_dwordx4 v[28:29], v[32:35], off
.LBB0_1209:
	s_or_b64 exec, exec, s[12:13]
	v_add_f32_e32 v20, v20, v124
	v_add_f32_e32 v21, v21, v125
	v_add_f32_e32 v22, v22, v126
	v_add_f32_e32 v23, v23, v127
	v_mul_f32_e32 v28, 0x3c800000, v20
	v_mul_f32_e32 v29, 0x3c800000, v21
	v_add_f32_e32 v16, v16, v147
	v_add_f32_e32 v17, v17, v165
	v_cvt_pk_bf16_f32 v28, v28, v29
	v_mul_f32_e32 v29, 0x3c800000, v22
	v_mul_f32_e32 v30, 0x3c800000, v23
	v_add_f32_e32 v18, v18, v166
	v_cvt_pk_bf16_f32 v29, v29, v30
	v_mul_f32_e32 v30, 0x3c800000, v16
	v_mul_f32_e32 v31, 0x3c800000, v17
	v_add_f32_e32 v19, v19, v167
	v_cvt_pk_bf16_f32 v30, v30, v31
	v_mul_f32_e32 v31, 0x3c800000, v18
	v_mul_f32_e32 v32, 0x3c800000, v19
	v_cvt_pk_bf16_f32 v31, v31, v32
	global_store_dwordx4 v[26:27], v[28:31], off offset:512
	s_and_saveexec_b64 s[12:13], vcc
	s_cbranch_execz .LBB0_1211
	v_mul_f32_e32 v20, v156, v20
	v_mul_f32_e32 v21, v156, v21
	v_cvt_pk_bf16_f32 v20, v20, v21
	v_mul_f32_e32 v21, v156, v22
	v_mul_f32_e32 v22, v156, v23
	v_mul_f32_e32 v16, v156, v16
	v_mul_f32_e32 v17, v156, v17
	v_cvt_pk_bf16_f32 v21, v21, v22
	v_cvt_pk_bf16_f32 v22, v16, v17
	v_mul_f32_e32 v16, v156, v18
	v_mul_f32_e32 v17, v156, v19
	v_cvt_pk_bf16_f32 v23, v16, v17
	v_lshl_add_u64 v[16:17], v[24:25], 0, v[136:137]
	global_store_dwordx4 v[16:17], v[20:23], off offset:512
.LBB0_1211:
	s_or_b64 exec, exec, s[12:13]
	v_add_u32_e32 v16, 0xb0, v146
	v_ashrrev_i32_e32 v17, 31, v16
	v_lshl_add_u64 v[18:19], s[20:21], 0, v[16:17]
	v_lshlrev_b64 v[24:25], 11, v[18:19]
	v_mov_b32_e32 v18, s62
	v_sub_co_u32_e64 v16, s[12:13], s57, v16
	v_add_f32_e32 v19, v15, v160
	s_nop 0
	v_subb_co_u32_e64 v17, s[12:13], v18, v17, s[12:13]
	v_lshlrev_b64 v[26:27], 11, v[16:17]
	v_add_f32_e32 v16, v12, v157
	v_add_f32_e32 v17, v13, v158
	v_add_f32_e32 v12, v8, v161
	v_add_f32_e32 v13, v9, v162
	v_add_f32_e32 v18, v14, v159
	v_mul_f32_e32 v8, 0x3c800000, v16
	v_mul_f32_e32 v9, 0x3c800000, v17
	v_cvt_pk_bf16_f32 v20, v8, v9
	v_mul_f32_e32 v8, 0x3c800000, v18
	v_mul_f32_e32 v9, 0x3c800000, v19
	v_add_f32_e32 v14, v10, v163
	v_add_f32_e32 v15, v11, v164
	v_cvt_pk_bf16_f32 v21, v8, v9
	v_mul_f32_e32 v8, 0x3c800000, v12
	v_mul_f32_e32 v9, 0x3c800000, v13
	v_cvt_pk_bf16_f32 v22, v8, v9
	v_mul_f32_e32 v8, 0x3c800000, v14
	v_mul_f32_e32 v9, 0x3c800000, v15
	v_cvt_pk_bf16_f32 v23, v8, v9
	v_lshl_add_u64 v[8:9], s[16:17], 0, v[24:25]
	v_cmp_lt_i32_e32 vcc, s73, v146
	v_lshl_add_u64 v[10:11], v[8:9], 0, v[136:137]
	v_lshl_add_u64 v[8:9], s[16:17], 0, v[26:27]
	global_store_dwordx4 v[10:11], v[20:23], off
	s_and_saveexec_b64 s[12:13], vcc
	s_cbranch_execz .LBB0_1213
	v_mul_f32_e32 v16, v156, v16
	v_mul_f32_e32 v17, v156, v17
	v_cvt_pk_bf16_f32 v16, v16, v17
	v_mul_f32_e32 v17, v156, v18
	v_mul_f32_e32 v18, v156, v19
	v_mul_f32_e32 v12, v156, v12
	v_mul_f32_e32 v13, v156, v13
	v_cvt_pk_bf16_f32 v17, v17, v18
	v_cvt_pk_bf16_f32 v18, v12, v13
	v_mul_f32_e32 v12, v156, v14
	v_mul_f32_e32 v13, v156, v15
	v_cvt_pk_bf16_f32 v19, v12, v13
	v_lshl_add_u64 v[12:13], v[8:9], 0, v[136:137]
	global_store_dwordx4 v[12:13], v[16:19], off
.LBB0_1213:
	s_or_b64 exec, exec, s[12:13]
	v_add_f32_e32 v4, v4, v124
	v_add_f32_e32 v5, v5, v125
	v_add_f32_e32 v6, v6, v126
	v_add_f32_e32 v7, v7, v127
	v_mul_f32_e32 v12, 0x3c800000, v4
	v_mul_f32_e32 v13, 0x3c800000, v5
	v_add_f32_e32 v0, v0, v147
	v_add_f32_e32 v1, v1, v165
	v_cvt_pk_bf16_f32 v12, v12, v13
	v_mul_f32_e32 v13, 0x3c800000, v6
	v_mul_f32_e32 v14, 0x3c800000, v7
	v_add_f32_e32 v2, v2, v166
	v_cvt_pk_bf16_f32 v13, v13, v14
	v_mul_f32_e32 v14, 0x3c800000, v0
	v_mul_f32_e32 v15, 0x3c800000, v1
	v_add_f32_e32 v3, v3, v167
	v_cvt_pk_bf16_f32 v14, v14, v15
	v_mul_f32_e32 v15, 0x3c800000, v2
	v_mul_f32_e32 v16, 0x3c800000, v3
	v_cvt_pk_bf16_f32 v15, v15, v16
	global_store_dwordx4 v[10:11], v[12:15], off offset:512
	s_and_saveexec_b64 s[12:13], vcc
	s_cbranch_execz .LBB0_1215
	v_mul_f32_e32 v4, v156, v4
	v_mul_f32_e32 v5, v156, v5
	v_cvt_pk_bf16_f32 v4, v4, v5
	v_mul_f32_e32 v5, v156, v6
	v_mul_f32_e32 v6, v156, v7
	v_mul_f32_e32 v0, v156, v0
	v_mul_f32_e32 v1, v156, v1
	v_cvt_pk_bf16_f32 v5, v5, v6
	v_cvt_pk_bf16_f32 v6, v0, v1
	v_mul_f32_e32 v0, v156, v2
	v_mul_f32_e32 v1, v156, v3
	v_cvt_pk_bf16_f32 v7, v0, v1
	v_lshl_add_u64 v[0:1], v[8:9], 0, v[136:137]
	global_store_dwordx4 v[0:1], v[4:7], off offset:512

; __device__ __forceinline__ unsigned cvt_pk_bf16(float lo, float hi) { unsigned r; asm("v_cvt_pk_bf16_f32 %0, %1, %2" : "=v"(r) : "v"(lo), "v"(hi)); return r; }
;     __device__ __forceinline__ void operator()(const f32x4 (&acc)[2][2][4][2], const Unit& u, int wr, int wc, int fr, int fq, LAS unsigned char* xs, int wid, int lane) const {
;         const int S = lng ? 4096 : 2048, hp = lng ? 8 : 4;
;         const int cs = u.pm >= hp, k0 = (u.pm - hp * cs) * 256 + wr * 64;
;         const size_t tok0 = lng ? (size_t)TP + (size_t)u.aux * 4096 : (size_t)u.aux * 2048;
;         const float sc = lng ? 0.015625f : 0.02209708691207961f;
;         const float scm = cs ? -sc : sc;
;         float hv[2][8];
;         const float csm = cs ? 0.f : 1.f;
; #pragma unroll
;         for (int bj = 0; bj < 2; ++bj)
; #pragma unroll
;             for (int e = 0; e < 8; ++e) {
;                 const unsigned short h = ft[(size_t)(u.pn * 256 + bj * 128 + wc * 32 + 8 * fq + e) * T + tok0 + S / 2];
;                 const float v = __builtin_bit_cast(float, (unsigned)h << 16) * csm;
;                 hv[bj][e] = (fr & 1) ? -v : v;
;             }
; #pragma unroll
;         for (int ai = 0; ai < 2; ++ai)
; #pragma unroll
;             for (int m = 0; m < 4; ++m) {
;                 const int k = k0 + ai * 128 + m * 16 + fr;
; #pragma unroll
;                 for (int bj = 0; bj < 2; ++bj) {
;                     const int col = (2 * u.pn + bj) * 256 + cs * 128 + wc * 32 + 8 * fq;
;                     f32x4 a = acc[ai][bj][m][0], b = acc[ai][bj][m][1];
; #pragma unroll
;                     for (int j = 0; j < 4; ++j) { a[j] += hv[bj][j]; b[j] += hv[bj][4 + j]; }
;                     u32x4 w; w.x = cvt_pk_bf16(a[0] * sc, a[1] * sc); w.y = cvt_pk_bf16(a[2] * sc, a[3] * sc); w.z = cvt_pk_bf16(b[0] * sc, b[1] * sc); w.w = cvt_pk_bf16(b[2] * sc, b[3] * sc);
;                     *(u32x4*)(pq + (tok0 + k) * 1024 + col) = w;
;                     if (k > 0) {
;                         u32x4 w2; w2.x = cvt_pk_bf16(a[0] * scm, a[1] * scm); w2.y = cvt_pk_bf16(a[2] * scm, a[3] * scm); w2.z = cvt_pk_bf16(b[0] * scm, b[1] * scm); w2.w = cvt_pk_bf16(b[2] * scm, b[3] * scm);
;                         *(u32x4*)(pq + (tok0 + S - k) * 1024 + col) = w2;
;                     }
.LBB0_1233:
	s_lshl_b32 s12, s87, 8
	s_and_b32 s57, s12, 0x300
	s_ashr_i32 s23, s22, 31
	s_add_i32 s57, s57, s35
	s_lshl_b64 s[54:55], s[22:23], 11
	s_lshl_b64 s[12:13], s[22:23], 12
	s_add_u32 s12, s46, s12
	v_lshlrev_b32_e32 v136, 16, v150
	s_addc_u32 s13, s47, s13
	v_lshl_or_b32 v136, s86, 24, v136
	v_lshl_add_u64 v[146:147], s[12:13], 0, v[136:137]
	global_load_ushort v136, v136, s[12:13] offset:2048
	s_mov_b32 s12, 0x10000
	v_add_co_u32_e32 v156, vcc, s12, v146
	s_mov_b32 s12, 0x800000
	s_nop 0
	v_addc_co_u32_e32 v157, vcc, 0, v147, vcc
	v_add_co_u32_e32 v158, vcc, s61, v146
	s_cmp_lt_u32 s87, 4
	s_nop 0
	v_addc_co_u32_e32 v159, vcc, 0, v147, vcc
	v_add_co_u32_e32 v160, vcc, s62, v146
	s_waitcnt vmcnt(0)
	v_lshlrev_b32_e32 v136, 16, v136
	v_addc_co_u32_e32 v161, vcc, 0, v147, vcc
	v_add_co_u32_e32 v162, vcc, s63, v146
	s_nop 1
	v_addc_co_u32_e32 v163, vcc, 0, v147, vcc
	global_load_ushort v164, v[156:157], off offset:2048
	global_load_ushort v176, v[158:159], off offset:2048
	global_load_ushort v177, v[160:161], off offset:2048
	global_load_ushort v178, v[162:163], off offset:2048
	v_add_co_u32_e32 v156, vcc, s64, v146
	s_nop 1
	v_addc_co_u32_e32 v157, vcc, 0, v147, vcc
	v_add_co_u32_e32 v158, vcc, s65, v146
	s_nop 1
	v_addc_co_u32_e32 v159, vcc, 0, v147, vcc
	global_load_ushort v179, v[156:157], off offset:2048
	global_load_ushort v180, v[158:159], off offset:2048
	v_add_co_u32_e32 v156, vcc, s66, v146
	s_nop 1
	v_addc_co_u32_e32 v157, vcc, 0, v147, vcc
	global_load_ushort v181, v[156:157], off offset:2048
	v_add_co_u32_e32 v156, vcc, s12, v146
	s_nop 1
	v_addc_co_u32_e32 v157, vcc, 0, v147, vcc
	global_load_ushort v165, v[156:157], off offset:2048
	v_add_co_u32_e32 v156, vcc, s67, v146
	s_nop 1
	v_addc_co_u32_e32 v157, vcc, 0, v147, vcc
	v_add_co_u32_e32 v158, vcc, s68, v146
	s_nop 1
	v_addc_co_u32_e32 v159, vcc, 0, v147, vcc
	v_add_co_u32_e32 v160, vcc, s69, v146
	s_nop 1
	v_addc_co_u32_e32 v161, vcc, 0, v147, vcc
	v_add_co_u32_e32 v162, vcc, s70, v146
	s_nop 1
	v_addc_co_u32_e32 v163, vcc, 0, v147, vcc
	v_add_co_u32_e32 v166, vcc, s71, v146
	s_nop 1
	v_addc_co_u32_e32 v167, vcc, 0, v147, vcc
	v_add_co_u32_e32 v174, vcc, s72, v146
	s_nop 1
	v_addc_co_u32_e32 v175, vcc, 0, v147, vcc
	v_add_co_u32_e32 v146, vcc, s73, v146
	s_nop 1
	v_addc_co_u32_e32 v147, vcc, 0, v147, vcc
	global_load_ushort v173, v[156:157], off offset:2048
	global_load_ushort v172, v[158:159], off offset:2048
	global_load_ushort v171, v[160:161], off offset:2048
	global_load_ushort v170, v[162:163], off offset:2048
	global_load_ushort v168, v[166:167], off offset:2048
	s_nop 0
	global_load_ushort v166, v[174:175], off offset:2048
	global_load_ushort v167, v[146:147], off offset:2048
	s_cselect_b64 vcc, -1, 0
	v_cndmask_b32_e64 v169, 0, 1.0, vcc
	v_mul_f32_e32 v136, v169, v136
	v_cndmask_b32_e64 v157, -v136, v136, s[8:9]
	v_or_b32_e32 v146, s57, v148
	s_and_b64 s[12:13], vcc, exec
	s_cselect_b32 s22, 0, 0x80
	s_add_u32 s51, s54, 0x800
	v_ashrrev_i32_e32 v147, 31, v146
	s_addc_u32 s56, s55, 0
	v_lshl_add_u64 v[174:175], s[54:55], 0, v[146:147]
	v_lshlrev_b64 v[182:183], 11, v[174:175]
	v_sub_co_u32_e64 v174, s[12:13], s51, v146
	v_cndmask_b32_e32 v156, v154, v155, vcc
	v_cmp_lt_i32_e32 vcc, 0, v146
	s_waitcnt vmcnt(14)
	v_lshlrev_b32_e32 v136, 16, v164
	v_mul_f32_e32 v136, v169, v136
	v_cndmask_b32_e64 v158, -v136, v136, s[8:9]
	s_waitcnt vmcnt(13)
	v_lshlrev_b32_e32 v136, 16, v176
	v_mul_f32_e32 v136, v169, v136
	v_cndmask_b32_e64 v159, -v136, v136, s[8:9]
	s_waitcnt vmcnt(12)
	v_lshlrev_b32_e32 v136, 16, v177
	v_mul_f32_e32 v136, v169, v136
	v_cndmask_b32_e64 v160, -v136, v136, s[8:9]
	s_waitcnt vmcnt(11)
	v_lshlrev_b32_e32 v136, 16, v178
	v_mul_f32_e32 v136, v169, v136
	v_cndmask_b32_e64 v161, -v136, v136, s[8:9]
	v_add_f32_e32 v176, v127, v160
	s_waitcnt vmcnt(10)
	v_lshlrev_b32_e32 v136, 16, v179
	v_mul_f32_e32 v136, v169, v136
	v_cndmask_b32_e64 v162, -v136, v136, s[8:9]
	s_waitcnt vmcnt(9)
	v_lshlrev_b32_e32 v136, 16, v180
	v_mul_f32_e32 v136, v169, v136
	v_cndmask_b32_e64 v163, -v136, v136, s[8:9]
	s_waitcnt vmcnt(8)
	v_lshlrev_b32_e32 v136, 16, v181
	v_mul_f32_e32 v136, v169, v136
	v_cndmask_b32_e64 v164, -v136, v136, s[8:9]
	v_mov_b32_e32 v136, s56
	v_subb_co_u32_e64 v175, s[12:13], v136, v147, s[12:13]
	v_lshlrev_b64 v[184:185], 11, v[174:175]
	v_add_f32_e32 v147, v124, v157
	v_add_f32_e32 v174, v125, v158
	v_add_f32_e32 v124, v120, v161
	v_add_f32_e32 v125, v121, v162
	v_add_f32_e32 v175, v126, v159
	v_mul_f32_e32 v120, 0x3cb504f3, v147
	v_mul_f32_e32 v121, 0x3cb504f3, v174
	s_lshl_b32 s12, s86, 9
	v_cvt_pk_bf16_f32 v178, v120, v121
	v_mul_f32_e32 v120, 0x3cb504f3, v175
	v_mul_f32_e32 v121, 0x3cb504f3, v176
	v_add_f32_e32 v126, v122, v163
	v_add_f32_e32 v127, v123, v164
	s_or_b32 s12, s22, s12
	v_cvt_pk_bf16_f32 v179, v120, v121
	v_mul_f32_e32 v120, 0x3cb504f3, v124
	v_mul_f32_e32 v121, 0x3cb504f3, v125
	v_or_b32_e32 v122, s12, v150
	v_cvt_pk_bf16_f32 v180, v120, v121
	v_mul_f32_e32 v120, 0x3cb504f3, v126
	v_mul_f32_e32 v121, 0x3cb504f3, v127
	v_cvt_pk_bf16_f32 v181, v120, v121
	v_lshl_add_u64 v[120:121], s[16:17], 0, v[182:183]
	v_lshlrev_b32_e32 v136, 1, v122
	v_lshl_add_u64 v[122:123], v[120:121], 0, v[136:137]
	v_lshl_add_u64 v[120:121], s[16:17], 0, v[184:185]
	global_store_dwordx4 v[122:123], v[178:181], off
	s_and_saveexec_b64 s[12:13], vcc
	s_cbranch_execz .LBB0_1235
	v_mul_f32_e32 v147, v156, v147
	v_mul_f32_e32 v174, v156, v174
	v_mul_f32_e32 v124, v156, v124
	v_mul_f32_e32 v125, v156, v125
	v_cvt_pk_bf16_f32 v174, v147, v174
	v_mul_f32_e32 v147, v156, v175
	v_mul_f32_e32 v175, v156, v176
	v_cvt_pk_bf16_f32 v176, v124, v125
	v_mul_f32_e32 v124, v156, v126
	v_mul_f32_e32 v125, v156, v127
	v_cvt_pk_bf16_f32 v177, v124, v125
	v_lshl_add_u64 v[124:125], v[120:121], 0, v[136:137]
	v_cvt_pk_bf16_f32 v175, v147, v175
	global_store_dwordx4 v[124:125], v[174:177], off
; __device__ __forceinline__ unsigned cvt_pk_bf16(float lo, float hi) { unsigned r; asm("v_cvt_pk_bf16_f32 %0, %1, %2" : "=v"(r) : "v"(lo), "v"(hi)); return r; }
;     __device__ __forceinline__ void operator()(const f32x4 (&acc)[2][2][4][2], const Unit& u, int wr, int wc, int fr, int fq, LAS unsigned char* xs, int wid, int lane) const {
;     ...
; #pragma unroll
;         for (int ai = 0; ai < 2; ++ai)
; #pragma unroll
;             for (int m = 0; m < 4; ++m) {
;                 const int k = k0 + ai * 128 + m * 16 + fr;
; #pragma unroll
;                 for (int bj = 0; bj < 2; ++bj) {
;                     const int col = (2 * u.pn + bj) * 256 + cs * 128 + wc * 32 + 8 * fq;
;                     f32x4 a = acc[ai][bj][m][0], b = acc[ai][bj][m][1];
; #pragma unroll
;                     for (int j = 0; j < 4; ++j) { a[j] += hv[bj][j]; b[j] += hv[bj][4 + j]; }
;                     u32x4 w; w.x = cvt_pk_bf16(a[0] * sc, a[1] * sc); w.y = cvt_pk_bf16(a[2] * sc, a[3] * sc); w.z = cvt_pk_bf16(b[0] * sc, b[1] * sc); w.w = cvt_pk_bf16(b[2] * sc, b[3] * sc);
;                     *(u32x4*)(pq + (tok0 + k) * 1024 + col) = w;
;                     if (k > 0) {
;                         u32x4 w2; w2.x = cvt_pk_bf16(a[0] * scm, a[1] * scm); w2.y = cvt_pk_bf16(a[2] * scm, a[3] * scm); w2.z = cvt_pk_bf16(b[0] * scm, b[1] * scm); w2.w = cvt_pk_bf16(b[2] * scm, b[3] * scm);
;                         *(u32x4*)(pq + (tok0 + S - k) * 1024 + col) = w2;
;                     }
;                 }
;                 __builtin_amdgcn_sched_barrier(0);
;             }
.LBB0_1235:
	s_or_b64 exec, exec, s[12:13]
	s_waitcnt vmcnt(8)
	v_lshlrev_b32_e32 v124, 16, v165
	s_waitcnt vmcnt(7)
	v_lshlrev_b32_e32 v125, 16, v173
	v_mul_f32_e32 v124, v169, v124
	v_mul_f32_e32 v125, v169, v125
	s_waitcnt vmcnt(6)
	v_lshlrev_b32_e32 v126, 16, v172
	s_waitcnt vmcnt(5)
	v_lshlrev_b32_e32 v127, 16, v171
	v_cndmask_b32_e64 v124, -v124, v124, s[8:9]
	v_cndmask_b32_e64 v125, -v125, v125, s[8:9]
	v_mul_f32_e32 v126, v169, v126
	v_mul_f32_e32 v127, v169, v127
	s_waitcnt vmcnt(4)
	v_lshlrev_b32_e32 v147, 16, v170
	s_waitcnt vmcnt(3)
	v_lshlrev_b32_e32 v165, 16, v168
	v_cndmask_b32_e64 v126, -v126, v126, s[8:9]
	v_cndmask_b32_e64 v127, -v127, v127, s[8:9]
	v_mul_f32_e32 v147, v169, v147
	v_mul_f32_e32 v165, v169, v165
	s_waitcnt vmcnt(2)
	v_lshlrev_b32_e32 v166, 16, v166
	s_waitcnt vmcnt(1)
	v_lshlrev_b32_e32 v167, 16, v167
	v_add_f32_e32 v116, v116, v124
	v_add_f32_e32 v117, v117, v125
	v_cndmask_b32_e64 v147, -v147, v147, s[8:9]
	v_cndmask_b32_e64 v165, -v165, v165, s[8:9]
	v_mul_f32_e32 v166, v169, v166
	v_mul_f32_e32 v167, v169, v167
	v_add_f32_e32 v118, v118, v126
	v_add_f32_e32 v119, v119, v127
	v_mul_f32_e32 v168, 0x3cb504f3, v116
	v_mul_f32_e32 v169, 0x3cb504f3, v117
	v_cndmask_b32_e64 v166, -v166, v166, s[8:9]
	v_add_f32_e32 v112, v112, v147
	v_add_f32_e32 v113, v113, v165
	v_cvt_pk_bf16_f32 v168, v168, v169
	v_mul_f32_e32 v169, 0x3cb504f3, v118
	v_mul_f32_e32 v170, 0x3cb504f3, v119
	v_cndmask_b32_e64 v167, -v167, v167, s[8:9]
	v_add_f32_e32 v114, v114, v166
	v_cvt_pk_bf16_f32 v169, v169, v170
	v_mul_f32_e32 v170, 0x3cb504f3, v112
	v_mul_f32_e32 v171, 0x3cb504f3, v113
	v_add_f32_e32 v115, v115, v167
	v_cvt_pk_bf16_f32 v170, v170, v171
	v_mul_f32_e32 v171, 0x3cb504f3, v114
	v_mul_f32_e32 v172, 0x3cb504f3, v115
	v_cvt_pk_bf16_f32 v171, v171, v172
	global_store_dwordx4 v[122:123], v[168:171], off offset:512
	s_and_saveexec_b64 s[12:13], vcc
	s_cbranch_execz .LBB0_1237
	v_mul_f32_e32 v116, v156, v116
	v_mul_f32_e32 v117, v156, v117
	v_cvt_pk_bf16_f32 v116, v116, v117
	v_mul_f32_e32 v117, v156, v118
	v_mul_f32_e32 v118, v156, v119
	v_mul_f32_e32 v112, v156, v112
	v_mul_f32_e32 v113, v156, v113
	v_cvt_pk_bf16_f32 v117, v117, v118
	v_cvt_pk_bf16_f32 v118, v112, v113
	v_mul_f32_e32 v112, v156, v114
	v_mul_f32_e32 v113, v156, v115
	v_cvt_pk_bf16_f32 v119, v112, v113
	v_lshl_add_u64 v[112:113], v[120:121], 0, v[136:137]
	global_store_dwordx4 v[112:113], v[116:119], off offset:512
.LBB0_1237:
	s_or_b64 exec, exec, s[12:13]
	v_or_b32_e32 v112, 16, v146
	v_ashrrev_i32_e32 v113, 31, v112
	v_lshl_add_u64 v[114:115], s[54:55], 0, v[112:113]
	v_lshlrev_b64 v[120:121], 11, v[114:115]
	v_mov_b32_e32 v114, s56
	v_sub_co_u32_e32 v112, vcc, s51, v112
	v_add_f32_e32 v115, v111, v160
	s_nop 0
	v_subb_co_u32_e32 v113, vcc, v114, v113, vcc
	v_lshlrev_b64 v[122:123], 11, v[112:113]
	v_add_f32_e32 v112, v108, v157
	v_add_f32_e32 v113, v109, v158
	v_add_f32_e32 v108, v104, v161
	v_add_f32_e32 v109, v105, v162
	v_add_f32_e32 v114, v110, v159
	v_mul_f32_e32 v104, 0x3cb504f3, v112
	v_mul_f32_e32 v105, 0x3cb504f3, v113
	v_cvt_pk_bf16_f32 v116, v104, v105
	v_mul_f32_e32 v104, 0x3cb504f3, v114
	v_mul_f32_e32 v105, 0x3cb504f3, v115
	v_add_f32_e32 v110, v106, v163
	v_add_f32_e32 v111, v107, v164
	v_cvt_pk_bf16_f32 v117, v104, v105
	v_mul_f32_e32 v104, 0x3cb504f3, v108
	v_mul_f32_e32 v105, 0x3cb504f3, v109
	v_cvt_pk_bf16_f32 v118, v104, v105
	v_mul_f32_e32 v104, 0x3cb504f3, v110
	v_mul_f32_e32 v105, 0x3cb504f3, v111
	s_cmp_gt_i32 s57, -1
	v_cvt_pk_bf16_f32 v119, v104, v105
	v_lshl_add_u64 v[104:105], s[16:17], 0, v[120:121]
	s_cselect_b64 s[22:23], -1, 0
	s_cmp_lt_i32 s57, 0
	v_lshl_add_u64 v[106:107], v[104:105], 0, v[136:137]
	v_lshl_add_u64 v[104:105], s[16:17], 0, v[122:123]
	global_store_dwordx4 v[106:107], v[116:119], off
	s_cbranch_scc1 .LBB0_1239
	v_mul_f32_e32 v112, v156, v112
	v_mul_f32_e32 v113, v156, v113
	v_cvt_pk_bf16_f32 v112, v112, v113
	v_mul_f32_e32 v113, v156, v114
	v_mul_f32_e32 v114, v156, v115
	v_mul_f32_e32 v108, v156, v108
	v_mul_f32_e32 v109, v156, v109
	v_cvt_pk_bf16_f32 v113, v113, v114
	v_cvt_pk_bf16_f32 v114, v108, v109
	v_mul_f32_e32 v108, v156, v110
	v_mul_f32_e32 v109, v156, v111
	v_cvt_pk_bf16_f32 v115, v108, v109
	v_lshl_add_u64 v[108:109], v[104:105], 0, v[136:137]
	global_store_dwordx4 v[108:109], v[112:115], off
.LBB0_1239:
	v_add_f32_e32 v100, v100, v124
	v_add_f32_e32 v101, v101, v125
	v_add_f32_e32 v102, v102, v126
	v_add_f32_e32 v103, v103, v127
	v_mul_f32_e32 v108, 0x3cb504f3, v100
	v_mul_f32_e32 v109, 0x3cb504f3, v101
	v_add_f32_e32 v96, v96, v147
	v_add_f32_e32 v97, v97, v165
	v_cvt_pk_bf16_f32 v108, v108, v109
	v_mul_f32_e32 v109, 0x3cb504f3, v102
	v_mul_f32_e32 v110, 0x3cb504f3, v103
	v_add_f32_e32 v98, v98, v166
	v_add_f32_e32 v99, v99, v167
	v_cvt_pk_bf16_f32 v109, v109, v110
	v_mul_f32_e32 v110, 0x3cb504f3, v96
	v_mul_f32_e32 v111, 0x3cb504f3, v97
	v_cvt_pk_bf16_f32 v110, v110, v111
	v_mul_f32_e32 v111, 0x3cb504f3, v98
	v_mul_f32_e32 v112, 0x3cb504f3, v99
	v_cvt_pk_bf16_f32 v111, v111, v112
	v_cndmask_b32_e64 v112, 0, 1, s[22:23]
	v_cmp_ne_u32_e64 s[12:13], 1, v112
	s_andn2_b64 vcc, exec, s[22:23]
	global_store_dwordx4 v[106:107], v[108:111], off offset:512
	s_cbranch_vccnz .LBB0_1241
	v_mul_f32_e32 v100, v156, v100
	v_mul_f32_e32 v101, v156, v101
	v_cvt_pk_bf16_f32 v100, v100, v101
	v_mul_f32_e32 v101, v156, v102
	v_mul_f32_e32 v102, v156, v103
	v_mul_f32_e32 v96, v156, v96
	v_mul_f32_e32 v97, v156, v97
	v_cvt_pk_bf16_f32 v101, v101, v102
	v_cvt_pk_bf16_f32 v102, v96, v97
	v_mul_f32_e32 v96, v156, v98
	v_mul_f32_e32 v97, v156, v99
	v_cvt_pk_bf16_f32 v103, v96, v97
	v_lshl_add_u64 v[96:97], v[104:105], 0, v[136:137]
	global_store_dwordx4 v[96:97], v[100:103], off offset:512
; __device__ __forceinline__ unsigned cvt_pk_bf16(float lo, float hi) { unsigned r; asm("v_cvt_pk_bf16_f32 %0, %1, %2" : "=v"(r) : "v"(lo), "v"(hi)); return r; }
;     __device__ __forceinline__ void operator()(const f32x4 (&acc)[2][2][4][2], const Unit& u, int wr, int wc, int fr, int fq, LAS unsigned char* xs, int wid, int lane) const {
;     ...
; #pragma unroll
;         for (int ai = 0; ai < 2; ++ai)
; #pragma unroll
;             for (int m = 0; m < 4; ++m) {
;                 const int k = k0 + ai * 128 + m * 16 + fr;
; #pragma unroll
;                 for (int bj = 0; bj < 2; ++bj) {
;                     const int col = (2 * u.pn + bj) * 256 + cs * 128 + wc * 32 + 8 * fq;
;                     f32x4 a = acc[ai][bj][m][0], b = acc[ai][bj][m][1];
; #pragma unroll
;                     for (int j = 0; j < 4; ++j) { a[j] += hv[bj][j]; b[j] += hv[bj][4 + j]; }
;                     u32x4 w; w.x = cvt_pk_bf16(a[0] * sc, a[1] * sc); w.y = cvt_pk_bf16(a[2] * sc, a[3] * sc); w.z = cvt_pk_bf16(b[0] * sc, b[1] * sc); w.w = cvt_pk_bf16(b[2] * sc, b[3] * sc);
;                     *(u32x4*)(pq + (tok0 + k) * 1024 + col) = w;
;                     if (k > 0) {
;                         u32x4 w2; w2.x = cvt_pk_bf16(a[0] * scm, a[1] * scm); w2.y = cvt_pk_bf16(a[2] * scm, a[3] * scm); w2.z = cvt_pk_bf16(b[0] * scm, b[1] * scm); w2.w = cvt_pk_bf16(b[2] * scm, b[3] * scm);
;                         *(u32x4*)(pq + (tok0 + S - k) * 1024 + col) = w2;
;                     }
;                 }
;                 __builtin_amdgcn_sched_barrier(0);
;             }
.LBB0_1241:
	v_or_b32_e32 v96, 32, v146
	v_ashrrev_i32_e32 v97, 31, v96
	v_lshl_add_u64 v[98:99], s[54:55], 0, v[96:97]
	v_lshlrev_b64 v[104:105], 11, v[98:99]
	v_mov_b32_e32 v98, s56
	v_sub_co_u32_e32 v96, vcc, s51, v96
	v_add_f32_e32 v99, v95, v160
	s_nop 0
	v_subb_co_u32_e32 v97, vcc, v98, v97, vcc
	v_lshlrev_b64 v[106:107], 11, v[96:97]
	v_add_f32_e32 v96, v92, v157
	v_add_f32_e32 v97, v93, v158
	v_add_f32_e32 v92, v88, v161
	v_add_f32_e32 v93, v89, v162
	v_add_f32_e32 v98, v94, v159
	v_mul_f32_e32 v88, 0x3cb504f3, v96
	v_mul_f32_e32 v89, 0x3cb504f3, v97
	v_cvt_pk_bf16_f32 v100, v88, v89
	v_mul_f32_e32 v88, 0x3cb504f3, v98
	v_mul_f32_e32 v89, 0x3cb504f3, v99
	v_add_f32_e32 v94, v90, v163
	v_add_f32_e32 v95, v91, v164
	v_cvt_pk_bf16_f32 v101, v88, v89
	v_mul_f32_e32 v88, 0x3cb504f3, v92
	v_mul_f32_e32 v89, 0x3cb504f3, v93
	v_cvt_pk_bf16_f32 v102, v88, v89
	v_mul_f32_e32 v88, 0x3cb504f3, v94
	v_mul_f32_e32 v89, 0x3cb504f3, v95
	v_cvt_pk_bf16_f32 v103, v88, v89
	v_lshl_add_u64 v[88:89], s[16:17], 0, v[104:105]
	v_lshl_add_u64 v[90:91], v[88:89], 0, v[136:137]
	s_and_b64 vcc, exec, s[12:13]
	v_lshl_add_u64 v[88:89], s[16:17], 0, v[106:107]
	global_store_dwordx4 v[90:91], v[100:103], off
	s_cbranch_vccnz .LBB0_1243
	v_mul_f32_e32 v96, v156, v96
	v_mul_f32_e32 v97, v156, v97
	v_cvt_pk_bf16_f32 v96, v96, v97
	v_mul_f32_e32 v97, v156, v98
	v_mul_f32_e32 v98, v156, v99
	v_mul_f32_e32 v92, v156, v92
	v_mul_f32_e32 v93, v156, v93
	v_cvt_pk_bf16_f32 v97, v97, v98
	v_cvt_pk_bf16_f32 v98, v92, v93
	v_mul_f32_e32 v92, v156, v94
	v_mul_f32_e32 v93, v156, v95
	v_cvt_pk_bf16_f32 v99, v92, v93
	v_lshl_add_u64 v[92:93], v[88:89], 0, v[136:137]
	global_store_dwordx4 v[92:93], v[96:99], off
.LBB0_1243:
	v_add_f32_e32 v84, v84, v124
	v_add_f32_e32 v85, v85, v125
	v_add_f32_e32 v86, v86, v126
	v_add_f32_e32 v87, v87, v127
	v_mul_f32_e32 v92, 0x3cb504f3, v84
	v_mul_f32_e32 v93, 0x3cb504f3, v85
	v_add_f32_e32 v80, v80, v147
	v_add_f32_e32 v81, v81, v165
	v_cvt_pk_bf16_f32 v92, v92, v93
	v_mul_f32_e32 v93, 0x3cb504f3, v86
	v_mul_f32_e32 v94, 0x3cb504f3, v87
	v_add_f32_e32 v82, v82, v166
	v_cvt_pk_bf16_f32 v93, v93, v94
	v_mul_f32_e32 v94, 0x3cb504f3, v80
	v_mul_f32_e32 v95, 0x3cb504f3, v81
	v_add_f32_e32 v83, v83, v167
	v_cvt_pk_bf16_f32 v94, v94, v95
	v_mul_f32_e32 v95, 0x3cb504f3, v82
	s_and_b64 vcc, exec, s[12:13]
	v_mul_f32_e32 v96, 0x3cb504f3, v83
	v_cvt_pk_bf16_f32 v95, v95, v96
	global_store_dwordx4 v[90:91], v[92:95], off offset:512
	s_cbranch_vccnz .LBB0_1245
	v_mul_f32_e32 v84, v156, v84
	v_mul_f32_e32 v85, v156, v85
	v_cvt_pk_bf16_f32 v84, v84, v85
	v_mul_f32_e32 v85, v156, v86
	v_mul_f32_e32 v86, v156, v87
	v_mul_f32_e32 v80, v156, v80
	v_mul_f32_e32 v81, v156, v81
	v_cvt_pk_bf16_f32 v85, v85, v86
	v_cvt_pk_bf16_f32 v86, v80, v81
	v_mul_f32_e32 v80, v156, v82
	v_mul_f32_e32 v81, v156, v83
	v_cvt_pk_bf16_f32 v87, v80, v81
	v_lshl_add_u64 v[80:81], v[88:89], 0, v[136:137]
	global_store_dwordx4 v[80:81], v[84:87], off offset:512
.LBB0_1245:
	v_or_b32_e32 v80, 48, v146
	v_ashrrev_i32_e32 v81, 31, v80
	v_lshl_add_u64 v[82:83], s[54:55], 0, v[80:81]
	v_lshlrev_b64 v[88:89], 11, v[82:83]
	v_mov_b32_e32 v82, s56
	v_sub_co_u32_e32 v80, vcc, s51, v80
	v_add_f32_e32 v83, v79, v160
	s_nop 0
	v_subb_co_u32_e32 v81, vcc, v82, v81, vcc
	v_lshlrev_b64 v[90:91], 11, v[80:81]
	v_add_f32_e32 v80, v76, v157
	v_add_f32_e32 v81, v77, v158
	v_add_f32_e32 v76, v72, v161
	v_add_f32_e32 v77, v73, v162
	v_add_f32_e32 v82, v78, v159
	v_mul_f32_e32 v72, 0x3cb504f3, v80
	v_mul_f32_e32 v73, 0x3cb504f3, v81
	v_cvt_pk_bf16_f32 v84, v72, v73
	v_mul_f32_e32 v72, 0x3cb504f3, v82
	v_mul_f32_e32 v73, 0x3cb504f3, v83
	v_add_f32_e32 v78, v74, v163
	v_add_f32_e32 v79, v75, v164
	v_cvt_pk_bf16_f32 v85, v72, v73
	v_mul_f32_e32 v72, 0x3cb504f3, v76
	v_mul_f32_e32 v73, 0x3cb504f3, v77
	v_cvt_pk_bf16_f32 v86, v72, v73
	v_mul_f32_e32 v72, 0x3cb504f3, v78
	v_mul_f32_e32 v73, 0x3cb504f3, v79
	v_cvt_pk_bf16_f32 v87, v72, v73
	v_lshl_add_u64 v[72:73], s[16:17], 0, v[88:89]
	v_lshl_add_u64 v[74:75], v[72:73], 0, v[136:137]
	s_and_b64 vcc, exec, s[12:13]
	v_lshl_add_u64 v[72:73], s[16:17], 0, v[90:91]
	global_store_dwordx4 v[74:75], v[84:87], off
	s_cbranch_vccnz .LBB0_1247
	v_mul_f32_e32 v80, v156, v80
	v_mul_f32_e32 v81, v156, v81
	v_cvt_pk_bf16_f32 v80, v80, v81
	v_mul_f32_e32 v81, v156, v82
	v_mul_f32_e32 v82, v156, v83
	v_mul_f32_e32 v76, v156, v76
	v_mul_f32_e32 v77, v156, v77
	v_cvt_pk_bf16_f32 v81, v81, v82
	v_cvt_pk_bf16_f32 v82, v76, v77
	v_mul_f32_e32 v76, v156, v78
	v_mul_f32_e32 v77, v156, v79
	v_cvt_pk_bf16_f32 v83, v76, v77
	v_lshl_add_u64 v[76:77], v[72:73], 0, v[136:137]
	global_store_dwordx4 v[76:77], v[80:83], off
.LBB0_1247:
	v_add_f32_e32 v68, v68, v124
	v_add_f32_e32 v69, v69, v125
	v_add_f32_e32 v70, v70, v126
	v_add_f32_e32 v71, v71, v127
	v_mul_f32_e32 v76, 0x3cb504f3, v68
	v_mul_f32_e32 v77, 0x3cb504f3, v69
	v_add_f32_e32 v64, v64, v147
	v_add_f32_e32 v65, v65, v165
	v_cvt_pk_bf16_f32 v76, v76, v77
	v_mul_f32_e32 v77, 0x3cb504f3, v70
	v_mul_f32_e32 v78, 0x3cb504f3, v71
	v_add_f32_e32 v66, v66, v166
	v_cvt_pk_bf16_f32 v77, v77, v78
	v_mul_f32_e32 v78, 0x3cb504f3, v64
	v_mul_f32_e32 v79, 0x3cb504f3, v65
	v_add_f32_e32 v67, v67, v167
	v_cvt_pk_bf16_f32 v78, v78, v79
	v_mul_f32_e32 v79, 0x3cb504f3, v66
	s_and_b64 vcc, exec, s[12:13]
	v_mul_f32_e32 v80, 0x3cb504f3, v67
	v_cvt_pk_bf16_f32 v79, v79, v80
	global_store_dwordx4 v[74:75], v[76:79], off offset:512
	s_cbranch_vccnz .LBB0_1249
	v_mul_f32_e32 v68, v156, v68
	v_mul_f32_e32 v69, v156, v69
	v_cvt_pk_bf16_f32 v68, v68, v69
	v_mul_f32_e32 v69, v156, v70
	v_mul_f32_e32 v70, v156, v71
	v_mul_f32_e32 v64, v156, v64
	v_mul_f32_e32 v65, v156, v65
	v_cvt_pk_bf16_f32 v69, v69, v70
	v_cvt_pk_bf16_f32 v70, v64, v65
	v_mul_f32_e32 v64, v156, v66
	v_mul_f32_e32 v65, v156, v67
	v_cvt_pk_bf16_f32 v71, v64, v65
	v_lshl_add_u64 v[64:65], v[72:73], 0, v[136:137]
	global_store_dwordx4 v[64:65], v[68:71], off offset:512
; __device__ __forceinline__ unsigned cvt_pk_bf16(float lo, float hi) { unsigned r; asm("v_cvt_pk_bf16_f32 %0, %1, %2" : "=v"(r) : "v"(lo), "v"(hi)); return r; }
;     __device__ __forceinline__ void operator()(const f32x4 (&acc)[2][2][4][2], const Unit& u, int wr, int wc, int fr, int fq, LAS unsigned char* xs, int wid, int lane) const {
;     ...
; #pragma unroll
;         for (int ai = 0; ai < 2; ++ai)
; #pragma unroll
;             for (int m = 0; m < 4; ++m) {
;                 const int k = k0 + ai * 128 + m * 16 + fr;
; #pragma unroll
;                 for (int bj = 0; bj < 2; ++bj) {
;                     const int col = (2 * u.pn + bj) * 256 + cs * 128 + wc * 32 + 8 * fq;
;                     f32x4 a = acc[ai][bj][m][0], b = acc[ai][bj][m][1];
; #pragma unroll
;                     for (int j = 0; j < 4; ++j) { a[j] += hv[bj][j]; b[j] += hv[bj][4 + j]; }
;                     u32x4 w; w.x = cvt_pk_bf16(a[0] * sc, a[1] * sc); w.y = cvt_pk_bf16(a[2] * sc, a[3] * sc); w.z = cvt_pk_bf16(b[0] * sc, b[1] * sc); w.w = cvt_pk_bf16(b[2] * sc, b[3] * sc);
;                     *(u32x4*)(pq + (tok0 + k) * 1024 + col) = w;
;                     if (k > 0) {
;                         u32x4 w2; w2.x = cvt_pk_bf16(a[0] * scm, a[1] * scm); w2.y = cvt_pk_bf16(a[2] * scm, a[3] * scm); w2.z = cvt_pk_bf16(b[0] * scm, b[1] * scm); w2.w = cvt_pk_bf16(b[2] * scm, b[3] * scm);
;                         *(u32x4*)(pq + (tok0 + S - k) * 1024 + col) = w2;
;                     }
;                 }
;                 __builtin_amdgcn_sched_barrier(0);
;             }
.LBB0_1249:
	v_add_u32_e32 v64, 0x80, v146
	v_ashrrev_i32_e32 v65, 31, v64
	v_lshl_add_u64 v[66:67], s[54:55], 0, v[64:65]
	v_lshlrev_b64 v[72:73], 11, v[66:67]
	v_mov_b32_e32 v66, s56
	v_sub_co_u32_e64 v64, s[12:13], s51, v64
	v_add_f32_e32 v67, v63, v160
	s_nop 0
	v_subb_co_u32_e64 v65, s[12:13], v66, v65, s[12:13]
	v_lshlrev_b64 v[74:75], 11, v[64:65]
	v_add_f32_e32 v64, v60, v157
	v_add_f32_e32 v65, v61, v158
	v_add_f32_e32 v60, v56, v161
	v_add_f32_e32 v61, v57, v162
	v_add_f32_e32 v66, v62, v159
	v_mul_f32_e32 v56, 0x3cb504f3, v64
	v_mul_f32_e32 v57, 0x3cb504f3, v65
	v_cvt_pk_bf16_f32 v68, v56, v57
	v_mul_f32_e32 v56, 0x3cb504f3, v66
	v_mul_f32_e32 v57, 0x3cb504f3, v67
	v_add_f32_e32 v62, v58, v163
	v_add_f32_e32 v63, v59, v164
	v_cvt_pk_bf16_f32 v69, v56, v57
	v_mul_f32_e32 v56, 0x3cb504f3, v60
	v_mul_f32_e32 v57, 0x3cb504f3, v61
	v_cvt_pk_bf16_f32 v70, v56, v57
	v_mul_f32_e32 v56, 0x3cb504f3, v62
	v_mul_f32_e32 v57, 0x3cb504f3, v63
	v_cvt_pk_bf16_f32 v71, v56, v57
	v_lshl_add_u64 v[56:57], s[16:17], 0, v[72:73]
	v_cmp_lt_i32_e32 vcc, s74, v146
	v_lshl_add_u64 v[58:59], v[56:57], 0, v[136:137]
	v_lshl_add_u64 v[56:57], s[16:17], 0, v[74:75]
	global_store_dwordx4 v[58:59], v[68:71], off
	s_and_saveexec_b64 s[12:13], vcc
	s_cbranch_execz .LBB0_1251
	v_mul_f32_e32 v64, v156, v64
	v_mul_f32_e32 v65, v156, v65
	v_cvt_pk_bf16_f32 v64, v64, v65
	v_mul_f32_e32 v65, v156, v66
	v_mul_f32_e32 v66, v156, v67
	v_mul_f32_e32 v60, v156, v60
	v_mul_f32_e32 v61, v156, v61
	v_cvt_pk_bf16_f32 v65, v65, v66
	v_cvt_pk_bf16_f32 v66, v60, v61
	v_mul_f32_e32 v60, v156, v62
	v_mul_f32_e32 v61, v156, v63
	v_cvt_pk_bf16_f32 v67, v60, v61
	v_lshl_add_u64 v[60:61], v[56:57], 0, v[136:137]
	global_store_dwordx4 v[60:61], v[64:67], off
.LBB0_1251:
	s_or_b64 exec, exec, s[12:13]
	v_add_f32_e32 v52, v52, v124
	v_add_f32_e32 v53, v53, v125
	v_add_f32_e32 v54, v54, v126
	v_add_f32_e32 v55, v55, v127
	v_mul_f32_e32 v60, 0x3cb504f3, v52
	v_mul_f32_e32 v61, 0x3cb504f3, v53
	v_add_f32_e32 v48, v48, v147
	v_add_f32_e32 v49, v49, v165
	v_cvt_pk_bf16_f32 v60, v60, v61
	v_mul_f32_e32 v61, 0x3cb504f3, v54
	v_mul_f32_e32 v62, 0x3cb504f3, v55
	v_add_f32_e32 v50, v50, v166
	v_cvt_pk_bf16_f32 v61, v61, v62
	v_mul_f32_e32 v62, 0x3cb504f3, v48
	v_mul_f32_e32 v63, 0x3cb504f3, v49
	v_add_f32_e32 v51, v51, v167
	v_cvt_pk_bf16_f32 v62, v62, v63
	v_mul_f32_e32 v63, 0x3cb504f3, v50
	v_mul_f32_e32 v64, 0x3cb504f3, v51
	v_cvt_pk_bf16_f32 v63, v63, v64
	global_store_dwordx4 v[58:59], v[60:63], off offset:512
	s_and_saveexec_b64 s[12:13], vcc
	s_cbranch_execz .LBB0_1253
	v_mul_f32_e32 v52, v156, v52
	v_mul_f32_e32 v53, v156, v53
	v_cvt_pk_bf16_f32 v52, v52, v53
	v_mul_f32_e32 v53, v156, v54
	v_mul_f32_e32 v54, v156, v55
	v_mul_f32_e32 v48, v156, v48
	v_mul_f32_e32 v49, v156, v49
	v_cvt_pk_bf16_f32 v53, v53, v54
	v_cvt_pk_bf16_f32 v54, v48, v49
	v_mul_f32_e32 v48, v156, v50
	v_mul_f32_e32 v49, v156, v51
	v_cvt_pk_bf16_f32 v55, v48, v49
	v_lshl_add_u64 v[48:49], v[56:57], 0, v[136:137]
	global_store_dwordx4 v[48:49], v[52:55], off offset:512
.LBB0_1253:
	s_or_b64 exec, exec, s[12:13]
	v_add_u32_e32 v48, 0x90, v146
	v_ashrrev_i32_e32 v49, 31, v48
	v_lshl_add_u64 v[50:51], s[54:55], 0, v[48:49]
	v_lshlrev_b64 v[56:57], 11, v[50:51]
	v_mov_b32_e32 v50, s56
	v_sub_co_u32_e64 v48, s[12:13], s51, v48
	v_add_f32_e32 v51, v47, v160
	s_nop 0
	v_subb_co_u32_e64 v49, s[12:13], v50, v49, s[12:13]
	v_lshlrev_b64 v[58:59], 11, v[48:49]
	v_add_f32_e32 v48, v44, v157
	v_add_f32_e32 v49, v45, v158
	v_add_f32_e32 v44, v40, v161
	v_add_f32_e32 v45, v41, v162
	v_add_f32_e32 v50, v46, v159
	v_mul_f32_e32 v40, 0x3cb504f3, v48
	v_mul_f32_e32 v41, 0x3cb504f3, v49
	v_cvt_pk_bf16_f32 v52, v40, v41
	v_mul_f32_e32 v40, 0x3cb504f3, v50
	v_mul_f32_e32 v41, 0x3cb504f3, v51
	v_add_f32_e32 v46, v42, v163
	v_add_f32_e32 v47, v43, v164
	v_cvt_pk_bf16_f32 v53, v40, v41
	v_mul_f32_e32 v40, 0x3cb504f3, v44
	v_mul_f32_e32 v41, 0x3cb504f3, v45
	v_cvt_pk_bf16_f32 v54, v40, v41
	v_mul_f32_e32 v40, 0x3cb504f3, v46
	v_mul_f32_e32 v41, 0x3cb504f3, v47
	v_cvt_pk_bf16_f32 v55, v40, v41
	v_lshl_add_u64 v[40:41], s[16:17], 0, v[56:57]
	v_cmp_lt_i32_e32 vcc, s75, v146
	v_lshl_add_u64 v[42:43], v[40:41], 0, v[136:137]
	v_lshl_add_u64 v[40:41], s[16:17], 0, v[58:59]
	global_store_dwordx4 v[42:43], v[52:55], off
	s_and_saveexec_b64 s[12:13], vcc
	s_cbranch_execz .LBB0_1255
	v_mul_f32_e32 v48, v156, v48
	v_mul_f32_e32 v49, v156, v49
	v_cvt_pk_bf16_f32 v48, v48, v49
	v_mul_f32_e32 v49, v156, v50
	v_mul_f32_e32 v50, v156, v51
	v_mul_f32_e32 v44, v156, v44
	v_mul_f32_e32 v45, v156, v45
	v_cvt_pk_bf16_f32 v49, v49, v50
	v_cvt_pk_bf16_f32 v50, v44, v45
	v_mul_f32_e32 v44, v156, v46
	v_mul_f32_e32 v45, v156, v47
	v_cvt_pk_bf16_f32 v51, v44, v45
	v_lshl_add_u64 v[44:45], v[40:41], 0, v[136:137]
	global_store_dwordx4 v[44:45], v[48:51], off
.LBB0_1255:
	s_or_b64 exec, exec, s[12:13]
	v_add_f32_e32 v36, v36, v124
	v_add_f32_e32 v37, v37, v125
	v_add_f32_e32 v38, v38, v126
	v_add_f32_e32 v39, v39, v127
	v_mul_f32_e32 v44, 0x3cb504f3, v36
	v_mul_f32_e32 v45, 0x3cb504f3, v37
	v_add_f32_e32 v32, v32, v147
	v_add_f32_e32 v33, v33, v165
	v_cvt_pk_bf16_f32 v44, v44, v45
	v_mul_f32_e32 v45, 0x3cb504f3, v38
	v_mul_f32_e32 v46, 0x3cb504f3, v39
	v_add_f32_e32 v34, v34, v166
	v_cvt_pk_bf16_f32 v45, v45, v46
	v_mul_f32_e32 v46, 0x3cb504f3, v32
	v_mul_f32_e32 v47, 0x3cb504f3, v33
	v_add_f32_e32 v35, v35, v167
	v_cvt_pk_bf16_f32 v46, v46, v47
	v_mul_f32_e32 v47, 0x3cb504f3, v34
	v_mul_f32_e32 v48, 0x3cb504f3, v35
	v_cvt_pk_bf16_f32 v47, v47, v48
	global_store_dwordx4 v[42:43], v[44:47], off offset:512
	s_and_saveexec_b64 s[12:13], vcc
	s_cbranch_execz .LBB0_1257
	v_mul_f32_e32 v36, v156, v36
	v_mul_f32_e32 v37, v156, v37
	v_cvt_pk_bf16_f32 v36, v36, v37
	v_mul_f32_e32 v37, v156, v38
	v_mul_f32_e32 v38, v156, v39
	v_mul_f32_e32 v32, v156, v32
	v_mul_f32_e32 v33, v156, v33
	v_cvt_pk_bf16_f32 v37, v37, v38
	v_cvt_pk_bf16_f32 v38, v32, v33
	v_mul_f32_e32 v32, v156, v34
	v_mul_f32_e32 v33, v156, v35
	v_cvt_pk_bf16_f32 v39, v32, v33
	v_lshl_add_u64 v[32:33], v[40:41], 0, v[136:137]
	global_store_dwordx4 v[32:33], v[36:39], off offset:512
; __device__ __forceinline__ unsigned cvt_pk_bf16(float lo, float hi) { unsigned r; asm("v_cvt_pk_bf16_f32 %0, %1, %2" : "=v"(r) : "v"(lo), "v"(hi)); return r; }
;     __device__ __forceinline__ void operator()(const f32x4 (&acc)[2][2][4][2], const Unit& u, int wr, int wc, int fr, int fq, LAS unsigned char* xs, int wid, int lane) const {
;     ...
; #pragma unroll
;         for (int ai = 0; ai < 2; ++ai)
; #pragma unroll
;             for (int m = 0; m < 4; ++m) {
;                 const int k = k0 + ai * 128 + m * 16 + fr;
; #pragma unroll
;                 for (int bj = 0; bj < 2; ++bj) {
;                     const int col = (2 * u.pn + bj) * 256 + cs * 128 + wc * 32 + 8 * fq;
;                     f32x4 a = acc[ai][bj][m][0], b = acc[ai][bj][m][1];
; #pragma unroll
;                     for (int j = 0; j < 4; ++j) { a[j] += hv[bj][j]; b[j] += hv[bj][4 + j]; }
;                     u32x4 w; w.x = cvt_pk_bf16(a[0] * sc, a[1] * sc); w.y = cvt_pk_bf16(a[2] * sc, a[3] * sc); w.z = cvt_pk_bf16(b[0] * sc, b[1] * sc); w.w = cvt_pk_bf16(b[2] * sc, b[3] * sc);
;                     *(u32x4*)(pq + (tok0 + k) * 1024 + col) = w;
;                     if (k > 0) {
;                         u32x4 w2; w2.x = cvt_pk_bf16(a[0] * scm, a[1] * scm); w2.y = cvt_pk_bf16(a[2] * scm, a[3] * scm); w2.z = cvt_pk_bf16(b[0] * scm, b[1] * scm); w2.w = cvt_pk_bf16(b[2] * scm, b[3] * scm);
;                         *(u32x4*)(pq + (tok0 + S - k) * 1024 + col) = w2;
;                     }
;                 }
;                 __builtin_amdgcn_sched_barrier(0);
;             }
.LBB0_1257:
	s_or_b64 exec, exec, s[12:13]
	v_add_u32_e32 v32, 0xa0, v146
	v_ashrrev_i32_e32 v33, 31, v32
	v_lshl_add_u64 v[34:35], s[54:55], 0, v[32:33]
	v_lshlrev_b64 v[40:41], 11, v[34:35]
	v_mov_b32_e32 v34, s56
	v_sub_co_u32_e64 v32, s[12:13], s51, v32
	v_add_f32_e32 v35, v31, v160
	s_nop 0
	v_subb_co_u32_e64 v33, s[12:13], v34, v33, s[12:13]
	v_lshlrev_b64 v[42:43], 11, v[32:33]
	v_add_f32_e32 v32, v28, v157
	v_add_f32_e32 v33, v29, v158
	v_add_f32_e32 v28, v24, v161
	v_add_f32_e32 v29, v25, v162
	v_add_f32_e32 v34, v30, v159
	v_mul_f32_e32 v24, 0x3cb504f3, v32
	v_mul_f32_e32 v25, 0x3cb504f3, v33
	v_cvt_pk_bf16_f32 v36, v24, v25
	v_mul_f32_e32 v24, 0x3cb504f3, v34
	v_mul_f32_e32 v25, 0x3cb504f3, v35
	v_add_f32_e32 v30, v26, v163
	v_add_f32_e32 v31, v27, v164
	v_cvt_pk_bf16_f32 v37, v24, v25
	v_mul_f32_e32 v24, 0x3cb504f3, v28
	v_mul_f32_e32 v25, 0x3cb504f3, v29
	v_cvt_pk_bf16_f32 v38, v24, v25
	v_mul_f32_e32 v24, 0x3cb504f3, v30
	v_mul_f32_e32 v25, 0x3cb504f3, v31
	v_cvt_pk_bf16_f32 v39, v24, v25
	v_lshl_add_u64 v[24:25], s[16:17], 0, v[40:41]
	v_cmp_lt_i32_e32 vcc, s76, v146
	v_lshl_add_u64 v[26:27], v[24:25], 0, v[136:137]
	v_lshl_add_u64 v[24:25], s[16:17], 0, v[42:43]
	global_store_dwordx4 v[26:27], v[36:39], off
	s_and_saveexec_b64 s[12:13], vcc
	s_cbranch_execz .LBB0_1259
	v_mul_f32_e32 v32, v156, v32
	v_mul_f32_e32 v33, v156, v33
	v_cvt_pk_bf16_f32 v32, v32, v33
	v_mul_f32_e32 v33, v156, v34
	v_mul_f32_e32 v34, v156, v35
	v_mul_f32_e32 v28, v156, v28
	v_mul_f32_e32 v29, v156, v29
	v_cvt_pk_bf16_f32 v33, v33, v34
	v_cvt_pk_bf16_f32 v34, v28, v29
	v_mul_f32_e32 v28, v156, v30
	v_mul_f32_e32 v29, v156, v31
	v_cvt_pk_bf16_f32 v35, v28, v29
	v_lshl_add_u64 v[28:29], v[24:25], 0, v[136:137]
	global_store_dwordx4 v[28:29], v[32:35], off
.LBB0_1259:
	s_or_b64 exec, exec, s[12:13]
	v_add_f32_e32 v20, v20, v124
	v_add_f32_e32 v21, v21, v125
	v_add_f32_e32 v22, v22, v126
	v_add_f32_e32 v23, v23, v127
	v_mul_f32_e32 v28, 0x3cb504f3, v20
	v_mul_f32_e32 v29, 0x3cb504f3, v21
	v_add_f32_e32 v16, v16, v147
	v_add_f32_e32 v17, v17, v165
	v_cvt_pk_bf16_f32 v28, v28, v29
	v_mul_f32_e32 v29, 0x3cb504f3, v22
	v_mul_f32_e32 v30, 0x3cb504f3, v23
	v_add_f32_e32 v18, v18, v166
	v_cvt_pk_bf16_f32 v29, v29, v30
	v_mul_f32_e32 v30, 0x3cb504f3, v16
	v_mul_f32_e32 v31, 0x3cb504f3, v17
	v_add_f32_e32 v19, v19, v167
	v_cvt_pk_bf16_f32 v30, v30, v31
	v_mul_f32_e32 v31, 0x3cb504f3, v18
	v_mul_f32_e32 v32, 0x3cb504f3, v19
	v_cvt_pk_bf16_f32 v31, v31, v32
	global_store_dwordx4 v[26:27], v[28:31], off offset:512
	s_and_saveexec_b64 s[12:13], vcc
	s_cbranch_execz .LBB0_1261
	v_mul_f32_e32 v20, v156, v20
	v_mul_f32_e32 v21, v156, v21
	v_cvt_pk_bf16_f32 v20, v20, v21
	v_mul_f32_e32 v21, v156, v22
	v_mul_f32_e32 v22, v156, v23
	v_mul_f32_e32 v16, v156, v16
	v_mul_f32_e32 v17, v156, v17
	v_cvt_pk_bf16_f32 v21, v21, v22
	v_cvt_pk_bf16_f32 v22, v16, v17
	v_mul_f32_e32 v16, v156, v18
	v_mul_f32_e32 v17, v156, v19
	v_cvt_pk_bf16_f32 v23, v16, v17
	v_lshl_add_u64 v[16:17], v[24:25], 0, v[136:137]
	global_store_dwordx4 v[16:17], v[20:23], off offset:512
.LBB0_1261:
	s_or_b64 exec, exec, s[12:13]
	v_add_u32_e32 v16, 0xb0, v146
	v_ashrrev_i32_e32 v17, 31, v16
	v_lshl_add_u64 v[18:19], s[54:55], 0, v[16:17]
	v_lshlrev_b64 v[24:25], 11, v[18:19]
	v_mov_b32_e32 v18, s56
	v_sub_co_u32_e64 v16, s[12:13], s51, v16
	v_add_f32_e32 v19, v15, v160
	s_nop 0
	v_subb_co_u32_e64 v17, s[12:13], v18, v17, s[12:13]
	v_lshlrev_b64 v[26:27], 11, v[16:17]
	v_add_f32_e32 v16, v12, v157
	v_add_f32_e32 v17, v13, v158
	v_add_f32_e32 v12, v8, v161
	v_add_f32_e32 v13, v9, v162
	v_add_f32_e32 v18, v14, v159
	v_mul_f32_e32 v8, 0x3cb504f3, v16
	v_mul_f32_e32 v9, 0x3cb504f3, v17
	v_cvt_pk_bf16_f32 v20, v8, v9
	v_mul_f32_e32 v8, 0x3cb504f3, v18
	v_mul_f32_e32 v9, 0x3cb504f3, v19
	v_add_f32_e32 v14, v10, v163
	v_add_f32_e32 v15, v11, v164
	v_cvt_pk_bf16_f32 v21, v8, v9
	v_mul_f32_e32 v8, 0x3cb504f3, v12
	v_mul_f32_e32 v9, 0x3cb504f3, v13
	v_cvt_pk_bf16_f32 v22, v8, v9
	v_mul_f32_e32 v8, 0x3cb504f3, v14
	v_mul_f32_e32 v9, 0x3cb504f3, v15
	v_cvt_pk_bf16_f32 v23, v8, v9
	v_lshl_add_u64 v[8:9], s[16:17], 0, v[24:25]
	v_cmp_lt_i32_e32 vcc, s77, v146
	v_lshl_add_u64 v[10:11], v[8:9], 0, v[136:137]
	v_lshl_add_u64 v[8:9], s[16:17], 0, v[26:27]
	global_store_dwordx4 v[10:11], v[20:23], off
	s_and_saveexec_b64 s[12:13], vcc
	s_cbranch_execz .LBB0_1263
	v_mul_f32_e32 v16, v156, v16
	v_mul_f32_e32 v17, v156, v17
	v_cvt_pk_bf16_f32 v16, v16, v17
	v_mul_f32_e32 v17, v156, v18
	v_mul_f32_e32 v18, v156, v19
	v_mul_f32_e32 v12, v156, v12
	v_mul_f32_e32 v13, v156, v13
	v_cvt_pk_bf16_f32 v17, v17, v18
	v_cvt_pk_bf16_f32 v18, v12, v13
	v_mul_f32_e32 v12, v156, v14
	v_mul_f32_e32 v13, v156, v15
	v_cvt_pk_bf16_f32 v19, v12, v13
	v_lshl_add_u64 v[12:13], v[8:9], 0, v[136:137]
	global_store_dwordx4 v[12:13], v[16:19], off
.LBB0_1263:
	s_or_b64 exec, exec, s[12:13]
	v_add_f32_e32 v4, v4, v124
	v_add_f32_e32 v5, v5, v125
	v_add_f32_e32 v6, v6, v126
	v_add_f32_e32 v7, v7, v127
	v_mul_f32_e32 v12, 0x3cb504f3, v4
	v_mul_f32_e32 v13, 0x3cb504f3, v5
	v_add_f32_e32 v0, v0, v147
	v_add_f32_e32 v1, v1, v165
	v_cvt_pk_bf16_f32 v12, v12, v13
	v_mul_f32_e32 v13, 0x3cb504f3, v6
	v_mul_f32_e32 v14, 0x3cb504f3, v7
	v_add_f32_e32 v2, v2, v166
	v_cvt_pk_bf16_f32 v13, v13, v14
	v_mul_f32_e32 v14, 0x3cb504f3, v0
	v_mul_f32_e32 v15, 0x3cb504f3, v1
	v_add_f32_e32 v3, v3, v167
	v_cvt_pk_bf16_f32 v14, v14, v15
	v_mul_f32_e32 v15, 0x3cb504f3, v2
	v_mul_f32_e32 v16, 0x3cb504f3, v3
	v_cvt_pk_bf16_f32 v15, v15, v16
	global_store_dwordx4 v[10:11], v[12:15], off offset:512
	s_and_saveexec_b64 s[12:13], vcc
	s_cbranch_execz .LBB0_1265
	v_mul_f32_e32 v4, v156, v4
	v_mul_f32_e32 v5, v156, v5
	v_cvt_pk_bf16_f32 v4, v4, v5
	v_mul_f32_e32 v5, v156, v6
	v_mul_f32_e32 v6, v156, v7
	v_mul_f32_e32 v0, v156, v0
	v_mul_f32_e32 v1, v156, v1
	v_cvt_pk_bf16_f32 v5, v5, v6
	v_cvt_pk_bf16_f32 v6, v0, v1
	v_mul_f32_e32 v0, v156, v2
	v_mul_f32_e32 v1, v156, v3
	v_cvt_pk_bf16_f32 v7, v0, v1
	v_lshl_add_u64 v[0:1], v[8:9], 0, v[136:137]
	global_store_dwordx4 v[0:1], v[4:7], off offset:512

;     __device__ __forceinline__ void operator()(const f32x4 (&acc)[2][2][4][2], const Unit& u, int wr, int wc, int fr, int fq, LAS unsigned char* xs, int wid, int lane) const {
;     ...
;         u32x4 raw[2][4][2];
;         if (!SRCF32) {
; #pragma unroll
;             for (int ai = 0; ai < 2; ++ai)
; #pragma unroll
;                 for (int m = 0; m < 4; ++m)
; #pragma unroll
;                     for (int bj = 0; bj < 2; ++bj) raw[ai][m][bj] = *(const u32x4*)(xb + (size_t)(row0 + ai * 128 + m * 16 + fr) * D + col0 + bj * 128);
;         }
; #pragma unroll
;         for (int ai = 0; ai < 2; ++ai) {
;             f32x4 xf[4][2][2];
;             if (SRCF32) {
; #pragma unroll
;                 for (int m = 0; m < 4; ++m)
; #pragma unroll
;                     for (int bj = 0; bj < 2; ++bj) { const size_t o = (size_t)(row0 + ai * 128 + m * 16 + fr) * D + col0 + bj * 128; xf[m][bj][0] = *(const f32x4*)(xo + o); xf[m][bj][1] = *(const f32x4*)(xo + o + 4); }
;             }
; #pragma unroll
;             for (int m = 0; m < 4; ++m) {
;                 const size_t row = (size_t)(row0 + ai * 128 + m * 16 + fr);
;                 float ss = 0.f;
; #pragma unroll
;                 for (int bj = 0; bj < 2; ++bj) {
;                     const size_t o = row * D + col0 + bj * 128;
;                     f32x4 x0, x1;
;                     if (SRCF32) { x0 = xf[m][bj][0]; x1 = xf[m][bj][1]; }
;                     else { const u32x4 r = raw[ai][m][bj]; x0 = (f32x4){bf_lo(r.x), bf_hi(r.x), bf_lo(r.y), bf_hi(r.y)}; x1 = (f32x4){bf_lo(r.z), bf_hi(r.z), bf_lo(r.w), bf_hi(r.w)}; }
;                     const f32x4 v0 = x0 + acc[ai][bj][m][0], v1 = x1 + acc[ai][bj][m][1];
;                     if (LAST) { *(f32x4*)(out + o) = v0; *(f32x4*)(out + o + 4) = v1; }
;                     else {
;                         ss += (v0[0] * v0[0] + v0[1] * v0[1]) + (v0[2] * v0[2] + v0[3] * v0[3]) + (v1[0] * v1[0] + v1[1] * v1[1]) + (v1[2] * v1[2] + v1[3] * v1[3]);
;                         u32x4 w; w.x = cvt_pk_bf16(v0[0], v0[1]); w.y = cvt_pk_bf16(v0[2], v0[3]); w.z = cvt_pk_bf16(v1[0], v1[1]); w.w = cvt_pk_bf16(v1[2], v1[3]); *(u32x4*)(xb + o) = w;
;                     }
;                 }
;                 if (!LAST) { ss += __shfl_xor(ss, 16); ss += __shfl_xor(ss, 32);
;                     if (fq == 0) P[(ai * 128 + wr * 64 + m * 16 + fr) * 4 + wc] = ss; }
.LBB0_1375:
	s_lshl_b32 s17, s50, 8
	v_lshl_or_b32 v200, s16, 8, v218
	v_add_u32_e32 v104, s17, v216
	v_ashrrev_i32_e32 v201, 31, v200
	v_lshlrev_b64 v[234:235], 1, v[200:201]
	v_ashrrev_i32_e32 v105, 31, v104
	v_lshl_add_u64 v[106:107], s[42:43], 0, v[234:235]
	v_lshlrev_b64 v[236:237], 12, v[104:105]
	v_lshl_add_u64 v[112:113], v[106:107], 0, v[236:237]
	global_load_dwordx4 v[226:229], v[112:113], off
	global_load_dwordx4 v[230:233], v[112:113], off offset:256
	v_or_b32_e32 v112, 16, v104
	v_or_b32_e32 v114, 32, v104
	v_or_b32_e32 v124, 48, v104
	v_add_u32_e32 v126, 0x80, v104
	v_add_u32_e32 v140, 0x90, v104
	v_add_u32_e32 v142, 0xa0, v104
	v_add_u32_e32 v104, 0xb0, v104
	v_ashrrev_i32_e32 v113, 31, v112
	v_ashrrev_i32_e32 v115, 31, v114
	v_ashrrev_i32_e32 v125, 31, v124
	v_ashrrev_i32_e32 v127, 31, v126
	v_ashrrev_i32_e32 v141, 31, v140
	v_ashrrev_i32_e32 v143, 31, v142
	v_ashrrev_i32_e32 v105, 31, v104
	v_lshlrev_b64 v[214:215], 12, v[112:113]
	v_lshlrev_b64 v[212:213], 12, v[114:115]
	v_lshlrev_b64 v[210:211], 12, v[124:125]
	v_lshlrev_b64 v[208:209], 12, v[126:127]
	v_lshlrev_b64 v[206:207], 12, v[140:141]
	v_lshlrev_b64 v[204:205], 12, v[142:143]
	v_lshlrev_b64 v[202:203], 12, v[104:105]
	v_lshl_add_u64 v[104:105], v[106:107], 0, v[214:215]
	v_lshl_add_u64 v[112:113], v[106:107], 0, v[212:213]
	v_lshl_add_u64 v[114:115], v[106:107], 0, v[210:211]
	v_lshl_add_u64 v[124:125], v[106:107], 0, v[208:209]
	v_lshl_add_u64 v[126:127], v[106:107], 0, v[206:207]
	v_lshl_add_u64 v[238:239], v[106:107], 0, v[204:205]
	v_lshl_add_u64 v[106:107], v[106:107], 0, v[202:203]
	global_load_dwordx4 v[180:183], v[104:105], off
	global_load_dwordx4 v[176:179], v[104:105], off offset:256
	global_load_dwordx4 v[172:175], v[112:113], off
	global_load_dwordx4 v[168:171], v[112:113], off offset:256
	global_load_dwordx4 v[164:167], v[114:115], off
	global_load_dwordx4 v[160:163], v[114:115], off offset:256
	global_load_dwordx4 v[156:159], v[124:125], off
	global_load_dwordx4 v[152:155], v[124:125], off offset:256
	global_load_dwordx4 v[148:151], v[126:127], off
	global_load_dwordx4 v[144:147], v[126:127], off offset:256
	global_load_dwordx4 v[140:143], v[238:239], off
	s_nop 0
	global_load_dwordx4 v[124:127], v[238:239], off offset:256
	global_load_dwordx4 v[112:115], v[106:107], off
	s_nop 0
	global_load_dwordx4 v[104:107], v[106:107], off offset:256
	s_waitcnt vmcnt(0)
	v_lshlrev_b32_e32 v238, 16, v226
	v_and_b32_e32 v239, 0xffff0000, v226
	v_lshlrev_b32_e32 v226, 16, v227
	v_and_b32_e32 v227, 0xffff0000, v227
	v_lshlrev_b32_e32 v240, 16, v228
	v_and_b32_e32 v241, 0xffff0000, v228
	v_lshlrev_b32_e32 v242, 16, v230
	v_and_b32_e32 v243, 0xffff0000, v230
	v_lshlrev_b32_e32 v230, 16, v231
	v_and_b32_e32 v231, 0xffff0000, v231
	v_lshlrev_b32_e32 v244, 16, v232
	v_and_b32_e32 v245, 0xffff0000, v232
	v_lshlrev_b32_e32 v232, 16, v233
	v_and_b32_e32 v233, 0xffff0000, v233
	v_pk_add_f32 v[138:139], v[138:139], v[226:227]
	v_pk_add_f32 v[136:137], v[136:137], v[238:239]
	v_pk_add_f32 v[132:133], v[132:133], v[240:241]
	v_pk_add_f32 v[226:227], v[130:131], v[230:231]
	v_pk_add_f32 v[230:231], v[122:123], v[232:233]
	v_pk_add_f32 v[232:233], v[120:121], v[244:245]
	v_mul_f32_e32 v120, v137, v137
	v_mul_f32_e32 v121, v139, v139
	v_lshlrev_b32_e32 v228, 16, v229
	v_and_b32_e32 v229, 0xffff0000, v229
	v_mul_f32_e32 v122, v133, v133
	v_fmac_f32_e32 v120, v136, v136
	v_fmac_f32_e32 v121, v138, v138
	v_pk_add_f32 v[134:135], v[134:135], v[228:229]
	v_pk_add_f32 v[228:229], v[128:129], v[242:243]
	v_fmac_f32_e32 v122, v132, v132
	v_add_f32_e32 v120, v120, v121
	v_add_f32_e32 v120, v122, v120
	v_mul_f32_e32 v121, v229, v229
	v_mul_f32_e32 v122, v227, v227
	v_fmac_f32_e32 v121, v228, v228
	v_fmac_f32_e32 v122, v226, v226
	v_add_f32_e32 v121, v121, v122
	v_mul_f32_e32 v122, v233, v233
	v_fmac_f32_e32 v122, v232, v232
	v_mul_f32_e32 v123, v135, v135
	v_add_f32_e32 v121, v122, v121
	v_mul_f32_e32 v122, v231, v231
	v_fmac_f32_e32 v123, v134, v134
	v_fmac_f32_e32 v122, v230, v230
	v_add_f32_e32 v120, v123, v120
	v_add_f32_e32 v121, v122, v121
	v_and_b32_e32 v122, 64, v223
	v_cvt_pk_bf16_f32 v131, v134, v135
	v_add_f32_e32 v121, v120, v121
	v_xor_b32_e32 v120, 16, v223
	v_add_u32_e32 v134, 64, v122
	v_cmp_lt_i32_e32 vcc, v120, v134
	v_lshl_add_u64 v[122:123], s[42:43], 0, v[236:237]
	v_cvt_pk_bf16_f32 v130, v132, v133
	v_lshl_add_u64 v[132:133], v[122:123], 0, v[234:235]
	v_cndmask_b32_e32 v120, v223, v120, vcc
	v_lshlrev_b32_e32 v120, 2, v120
	ds_bpermute_b32 v135, v120, v121
	v_cvt_pk_bf16_f32 v128, v136, v137
	v_cvt_pk_bf16_f32 v129, v138, v139
	global_store_dwordx4 v[132:133], v[128:131], off
	s_waitcnt lgkmcnt(0)
	v_add_f32_e32 v122, v121, v135
	v_xor_b32_e32 v121, 32, v223
	v_cmp_lt_i32_e32 vcc, v121, v134
	v_cvt_pk_bf16_f32 v128, v228, v229
	v_cvt_pk_bf16_f32 v129, v226, v227
	v_cvt_pk_bf16_f32 v130, v232, v233
	v_cvt_pk_bf16_f32 v131, v230, v231
	global_store_dwordx4 v[132:133], v[128:131], off offset:256
	s_nop 0
	v_cndmask_b32_e32 v121, v223, v121, vcc
	v_lshlrev_b32_e32 v121, 2, v121
	ds_bpermute_b32 v123, v121, v122
	s_and_saveexec_b64 s[50:51], s[8:9]
	s_cbranch_execz .LBB0_1377
	s_waitcnt lgkmcnt(0)
	v_add_f32_e32 v122, v122, v123
	ds_write_b32 v225, v122
; __device__ __forceinline__ unsigned cvt_pk_bf16(float lo, float hi) { unsigned r; asm("v_cvt_pk_bf16_f32 %0, %1, %2" : "=v"(r) : "v"(lo), "v"(hi)); return r; }
;     __device__ __forceinline__ void operator()(const f32x4 (&acc)[2][2][4][2], const Unit& u, int wr, int wc, int fr, int fq, LAS unsigned char* xs, int wid, int lane) const {
;     ...
; #pragma unroll
;             for (int m = 0; m < 4; ++m) {
;                 const size_t row = (size_t)(row0 + ai * 128 + m * 16 + fr);
;                 float ss = 0.f;
; #pragma unroll
;                 for (int bj = 0; bj < 2; ++bj) {
;                     const size_t o = row * D + col0 + bj * 128;
;                     f32x4 x0, x1;
;                     if (SRCF32) { x0 = xf[m][bj][0]; x1 = xf[m][bj][1]; }
;                     else { const u32x4 r = raw[ai][m][bj]; x0 = (f32x4){bf_lo(r.x), bf_hi(r.x), bf_lo(r.y), bf_hi(r.y)}; x1 = (f32x4){bf_lo(r.z), bf_hi(r.z), bf_lo(r.w), bf_hi(r.w)}; }
;                     const f32x4 v0 = x0 + acc[ai][bj][m][0], v1 = x1 + acc[ai][bj][m][1];
;                     if (LAST) { *(f32x4*)(out + o) = v0; *(f32x4*)(out + o + 4) = v1; }
;                     else {
;                         ss += (v0[0] * v0[0] + v0[1] * v0[1]) + (v0[2] * v0[2] + v0[3] * v0[3]) + (v1[0] * v1[0] + v1[1] * v1[1]) + (v1[2] * v1[2] + v1[3] * v1[3]);
;                         u32x4 w; w.x = cvt_pk_bf16(v0[0], v0[1]); w.y = cvt_pk_bf16(v0[2], v0[3]); w.z = cvt_pk_bf16(v1[0], v1[1]); w.w = cvt_pk_bf16(v1[2], v1[3]); *(u32x4*)(xb + o) = w;
;                     }
;                 }
;                 if (!LAST) { ss += __shfl_xor(ss, 16); ss += __shfl_xor(ss, 32);
;                     if (fq == 0) P[(ai * 128 + wr * 64 + m * 16 + fr) * 4 + wc] = ss; }
.LBB0_1377:
	s_or_b64 exec, exec, s[50:51]
	v_lshlrev_b32_e32 v122, 16, v180
	s_waitcnt lgkmcnt(0)
	v_and_b32_e32 v123, 0xffff0000, v180
	v_lshlrev_b32_e32 v128, 16, v181
	v_and_b32_e32 v129, 0xffff0000, v181
	v_lshlrev_b32_e32 v130, 16, v182
	v_and_b32_e32 v131, 0xffff0000, v182
	v_lshlrev_b32_e32 v132, 16, v183
	v_and_b32_e32 v133, 0xffff0000, v183
	v_pk_add_f32 v[118:119], v[118:119], v[128:129]
	v_pk_add_f32 v[116:117], v[116:117], v[122:123]
	v_pk_add_f32 v[122:123], v[110:111], v[132:133]
	v_pk_add_f32 v[110:111], v[108:109], v[130:131]
	v_mul_f32_e32 v108, v117, v117
	v_mul_f32_e32 v109, v119, v119
	v_fmac_f32_e32 v108, v116, v116
	v_fmac_f32_e32 v109, v118, v118
	v_add_f32_e32 v108, v108, v109
	v_mul_f32_e32 v109, v111, v111
	v_fmac_f32_e32 v109, v110, v110
	v_add_f32_e32 v108, v109, v108
	v_mul_f32_e32 v109, v123, v123
	v_fmac_f32_e32 v109, v122, v122
	v_add_f32_e32 v130, v109, v108
	v_cvt_pk_bf16_f32 v108, v116, v117
	v_cvt_pk_bf16_f32 v109, v118, v119
	v_lshlrev_b32_e32 v116, 16, v176
	v_and_b32_e32 v117, 0xffff0000, v176
	v_lshlrev_b32_e32 v118, 16, v177
	v_and_b32_e32 v119, 0xffff0000, v177
	v_cvt_pk_bf16_f32 v110, v110, v111
	v_cvt_pk_bf16_f32 v111, v122, v123
	v_lshlrev_b32_e32 v122, 16, v178
	v_and_b32_e32 v123, 0xffff0000, v178
	v_pk_add_f32 v[102:103], v[102:103], v[118:119]
	v_pk_add_f32 v[100:101], v[100:101], v[116:117]
	v_pk_add_f32 v[118:119], v[96:97], v[122:123]
	v_mul_f32_e32 v96, v101, v101
	v_mul_f32_e32 v97, v103, v103
	v_fmac_f32_e32 v96, v100, v100
	v_fmac_f32_e32 v97, v102, v102
	v_lshlrev_b32_e32 v128, 16, v179
	v_and_b32_e32 v129, 0xffff0000, v179
	v_add_f32_e32 v96, v96, v97
	v_mul_f32_e32 v97, v119, v119
	v_pk_add_f32 v[116:117], v[98:99], v[128:129]
	v_fmac_f32_e32 v97, v118, v118
	v_add_f32_e32 v96, v97, v96
	v_mul_f32_e32 v97, v117, v117
	v_fmac_f32_e32 v97, v116, v116
	v_add_f32_e32 v96, v97, v96
	v_add_f32_e32 v99, v130, v96
	ds_bpermute_b32 v128, v120, v99
	v_lshl_add_u64 v[96:97], s[42:43], 0, v[214:215]
	v_lshl_add_u64 v[122:123], v[200:201], 1, v[96:97]
	global_store_dwordx4 v[122:123], v[108:111], off
	v_cvt_pk_bf16_f32 v98, v100, v101
	s_waitcnt lgkmcnt(0)
	v_add_f32_e32 v96, v99, v128
	ds_bpermute_b32 v97, v121, v96
	v_cvt_pk_bf16_f32 v99, v102, v103
	v_cvt_pk_bf16_f32 v100, v118, v119
	v_cvt_pk_bf16_f32 v101, v116, v117
	global_store_dwordx4 v[122:123], v[98:101], off offset:256
	s_and_saveexec_b64 s[50:51], s[8:9]
	s_cbranch_execz .LBB0_1379
	s_waitcnt lgkmcnt(0)
	v_add_f32_e32 v96, v96, v97
	ds_write_b32 v225, v96 offset:256
.LBB0_1379:
	s_or_b64 exec, exec, s[50:51]
	v_lshlrev_b32_e32 v96, 16, v172
	s_waitcnt lgkmcnt(0)
	v_and_b32_e32 v97, 0xffff0000, v172
	v_lshlrev_b32_e32 v98, 16, v173
	v_and_b32_e32 v99, 0xffff0000, v173
	v_lshlrev_b32_e32 v100, 16, v174
	v_and_b32_e32 v101, 0xffff0000, v174
	v_lshlrev_b32_e32 v102, 16, v175
	v_and_b32_e32 v103, 0xffff0000, v175
	v_pk_add_f32 v[94:95], v[94:95], v[98:99]
	v_pk_add_f32 v[92:93], v[92:93], v[96:97]
	v_pk_add_f32 v[96:97], v[90:91], v[102:103]
	v_pk_add_f32 v[90:91], v[88:89], v[100:101]
	v_mul_f32_e32 v88, v93, v93
	v_mul_f32_e32 v89, v95, v95
	v_fmac_f32_e32 v88, v92, v92
	v_fmac_f32_e32 v89, v94, v94
	v_add_f32_e32 v88, v88, v89
	v_mul_f32_e32 v89, v91, v91
	v_fmac_f32_e32 v89, v90, v90
	v_add_f32_e32 v88, v89, v88
	v_mul_f32_e32 v89, v97, v97
	v_fmac_f32_e32 v89, v96, v96
	v_add_f32_e32 v100, v89, v88
	v_cvt_pk_bf16_f32 v88, v92, v93
	v_cvt_pk_bf16_f32 v89, v94, v95
	v_lshlrev_b32_e32 v92, 16, v168
	v_and_b32_e32 v93, 0xffff0000, v168
	v_lshlrev_b32_e32 v94, 16, v169
	v_and_b32_e32 v95, 0xffff0000, v169
	v_cvt_pk_bf16_f32 v90, v90, v91
	v_cvt_pk_bf16_f32 v91, v96, v97
	v_lshlrev_b32_e32 v96, 16, v170
	v_and_b32_e32 v97, 0xffff0000, v170
	v_pk_add_f32 v[86:87], v[86:87], v[94:95]
	v_pk_add_f32 v[84:85], v[84:85], v[92:93]
	v_pk_add_f32 v[94:95], v[80:81], v[96:97]
	v_mul_f32_e32 v80, v85, v85
	v_mul_f32_e32 v81, v87, v87
	v_fmac_f32_e32 v80, v84, v84
	v_fmac_f32_e32 v81, v86, v86
	v_lshlrev_b32_e32 v98, 16, v171
	v_and_b32_e32 v99, 0xffff0000, v171
	v_add_f32_e32 v80, v80, v81
	v_mul_f32_e32 v81, v95, v95
	v_pk_add_f32 v[92:93], v[82:83], v[98:99]
	v_fmac_f32_e32 v81, v94, v94
	v_add_f32_e32 v80, v81, v80
	v_mul_f32_e32 v81, v93, v93
	v_fmac_f32_e32 v81, v92, v92
	v_add_f32_e32 v80, v81, v80
	v_add_f32_e32 v83, v100, v80
	ds_bpermute_b32 v98, v120, v83
	v_lshl_add_u64 v[80:81], s[42:43], 0, v[212:213]
	v_lshl_add_u64 v[96:97], v[200:201], 1, v[80:81]
	global_store_dwordx4 v[96:97], v[88:91], off
	v_cvt_pk_bf16_f32 v82, v84, v85
	s_waitcnt lgkmcnt(0)
	v_add_f32_e32 v80, v83, v98
	ds_bpermute_b32 v81, v121, v80
	v_cvt_pk_bf16_f32 v83, v86, v87
	v_cvt_pk_bf16_f32 v84, v94, v95
	v_cvt_pk_bf16_f32 v85, v92, v93
	global_store_dwordx4 v[96:97], v[82:85], off offset:256
	s_and_saveexec_b64 s[50:51], s[8:9]
	s_cbranch_execz .LBB0_1381
	s_waitcnt lgkmcnt(0)
	v_add_f32_e32 v80, v80, v81
	ds_write_b32 v225, v80 offset:512
; __device__ __forceinline__ unsigned cvt_pk_bf16(float lo, float hi) { unsigned r; asm("v_cvt_pk_bf16_f32 %0, %1, %2" : "=v"(r) : "v"(lo), "v"(hi)); return r; }
;     __device__ __forceinline__ void operator()(const f32x4 (&acc)[2][2][4][2], const Unit& u, int wr, int wc, int fr, int fq, LAS unsigned char* xs, int wid, int lane) const {
;     ...
; #pragma unroll
;             for (int m = 0; m < 4; ++m) {
;                 const size_t row = (size_t)(row0 + ai * 128 + m * 16 + fr);
;                 float ss = 0.f;
; #pragma unroll
;                 for (int bj = 0; bj < 2; ++bj) {
;                     const size_t o = row * D + col0 + bj * 128;
;                     f32x4 x0, x1;
;                     if (SRCF32) { x0 = xf[m][bj][0]; x1 = xf[m][bj][1]; }
;                     else { const u32x4 r = raw[ai][m][bj]; x0 = (f32x4){bf_lo(r.x), bf_hi(r.x), bf_lo(r.y), bf_hi(r.y)}; x1 = (f32x4){bf_lo(r.z), bf_hi(r.z), bf_lo(r.w), bf_hi(r.w)}; }
;                     const f32x4 v0 = x0 + acc[ai][bj][m][0], v1 = x1 + acc[ai][bj][m][1];
;                     if (LAST) { *(f32x4*)(out + o) = v0; *(f32x4*)(out + o + 4) = v1; }
;                     else {
;                         ss += (v0[0] * v0[0] + v0[1] * v0[1]) + (v0[2] * v0[2] + v0[3] * v0[3]) + (v1[0] * v1[0] + v1[1] * v1[1]) + (v1[2] * v1[2] + v1[3] * v1[3]);
;                         u32x4 w; w.x = cvt_pk_bf16(v0[0], v0[1]); w.y = cvt_pk_bf16(v0[2], v0[3]); w.z = cvt_pk_bf16(v1[0], v1[1]); w.w = cvt_pk_bf16(v1[2], v1[3]); *(u32x4*)(xb + o) = w;
;                     }
;                 }
;                 if (!LAST) { ss += __shfl_xor(ss, 16); ss += __shfl_xor(ss, 32);
;                     if (fq == 0) P[(ai * 128 + wr * 64 + m * 16 + fr) * 4 + wc] = ss; }
.LBB0_1381:
	s_or_b64 exec, exec, s[50:51]
	v_lshlrev_b32_e32 v80, 16, v164
	s_waitcnt lgkmcnt(0)
	v_and_b32_e32 v81, 0xffff0000, v164
	v_lshlrev_b32_e32 v82, 16, v165
	v_and_b32_e32 v83, 0xffff0000, v165
	v_lshlrev_b32_e32 v84, 16, v166
	v_and_b32_e32 v85, 0xffff0000, v166
	v_lshlrev_b32_e32 v86, 16, v167
	v_and_b32_e32 v87, 0xffff0000, v167
	v_pk_add_f32 v[78:79], v[78:79], v[82:83]
	v_pk_add_f32 v[76:77], v[76:77], v[80:81]
	v_pk_add_f32 v[80:81], v[74:75], v[86:87]
	v_pk_add_f32 v[74:75], v[72:73], v[84:85]
	v_mul_f32_e32 v72, v77, v77
	v_mul_f32_e32 v73, v79, v79
	v_fmac_f32_e32 v72, v76, v76
	v_fmac_f32_e32 v73, v78, v78
	v_add_f32_e32 v72, v72, v73
	v_mul_f32_e32 v73, v75, v75
	v_fmac_f32_e32 v73, v74, v74
	v_add_f32_e32 v72, v73, v72
	v_mul_f32_e32 v73, v81, v81
	v_fmac_f32_e32 v73, v80, v80
	v_add_f32_e32 v84, v73, v72
	v_cvt_pk_bf16_f32 v72, v76, v77
	v_cvt_pk_bf16_f32 v73, v78, v79
	v_lshlrev_b32_e32 v76, 16, v160
	v_and_b32_e32 v77, 0xffff0000, v160
	v_lshlrev_b32_e32 v78, 16, v161
	v_and_b32_e32 v79, 0xffff0000, v161
	v_cvt_pk_bf16_f32 v74, v74, v75
	v_cvt_pk_bf16_f32 v75, v80, v81
	v_lshlrev_b32_e32 v80, 16, v162
	v_and_b32_e32 v81, 0xffff0000, v162
	v_pk_add_f32 v[70:71], v[70:71], v[78:79]
	v_pk_add_f32 v[68:69], v[68:69], v[76:77]
	v_pk_add_f32 v[78:79], v[64:65], v[80:81]
	v_mul_f32_e32 v64, v69, v69
	v_mul_f32_e32 v65, v71, v71
	v_fmac_f32_e32 v64, v68, v68
	v_fmac_f32_e32 v65, v70, v70
	v_lshlrev_b32_e32 v82, 16, v163
	v_and_b32_e32 v83, 0xffff0000, v163
	v_add_f32_e32 v64, v64, v65
	v_mul_f32_e32 v65, v79, v79
	v_pk_add_f32 v[76:77], v[66:67], v[82:83]
	v_fmac_f32_e32 v65, v78, v78
	v_add_f32_e32 v64, v65, v64
	v_mul_f32_e32 v65, v77, v77
	v_fmac_f32_e32 v65, v76, v76
	v_add_f32_e32 v64, v65, v64
	v_add_f32_e32 v67, v84, v64
	ds_bpermute_b32 v82, v120, v67
	v_lshl_add_u64 v[64:65], s[42:43], 0, v[210:211]
	v_lshl_add_u64 v[80:81], v[200:201], 1, v[64:65]
	global_store_dwordx4 v[80:81], v[72:75], off
	v_cvt_pk_bf16_f32 v66, v68, v69
	s_waitcnt lgkmcnt(0)
	v_add_f32_e32 v64, v67, v82
	ds_bpermute_b32 v65, v121, v64
	v_cvt_pk_bf16_f32 v67, v70, v71
	v_cvt_pk_bf16_f32 v68, v78, v79
	v_cvt_pk_bf16_f32 v69, v76, v77
	global_store_dwordx4 v[80:81], v[66:69], off offset:256
	s_and_saveexec_b64 s[50:51], s[8:9]
	s_cbranch_execz .LBB0_1383
	s_waitcnt lgkmcnt(0)
	v_add_f32_e32 v64, v64, v65
	ds_write_b32 v225, v64 offset:768
.LBB0_1383:
	s_or_b64 exec, exec, s[50:51]
	v_lshlrev_b32_e32 v64, 16, v156
	s_waitcnt lgkmcnt(0)
	v_and_b32_e32 v65, 0xffff0000, v156
	v_lshlrev_b32_e32 v66, 16, v157
	v_and_b32_e32 v67, 0xffff0000, v157
	v_lshlrev_b32_e32 v68, 16, v158
	v_and_b32_e32 v69, 0xffff0000, v158
	v_lshlrev_b32_e32 v70, 16, v159
	v_and_b32_e32 v71, 0xffff0000, v159
	v_pk_add_f32 v[62:63], v[62:63], v[66:67]
	v_pk_add_f32 v[60:61], v[60:61], v[64:65]
	v_pk_add_f32 v[64:65], v[58:59], v[70:71]
	v_pk_add_f32 v[58:59], v[56:57], v[68:69]
	v_mul_f32_e32 v56, v61, v61
	v_mul_f32_e32 v57, v63, v63
	v_fmac_f32_e32 v56, v60, v60
	v_fmac_f32_e32 v57, v62, v62
	v_add_f32_e32 v56, v56, v57
	v_mul_f32_e32 v57, v59, v59
	v_fmac_f32_e32 v57, v58, v58
	v_add_f32_e32 v56, v57, v56
	v_mul_f32_e32 v57, v65, v65
	v_fmac_f32_e32 v57, v64, v64
	v_add_f32_e32 v68, v57, v56
	v_cvt_pk_bf16_f32 v56, v60, v61
	v_cvt_pk_bf16_f32 v57, v62, v63
	v_lshlrev_b32_e32 v60, 16, v152
	v_and_b32_e32 v61, 0xffff0000, v152
	v_lshlrev_b32_e32 v62, 16, v153
	v_and_b32_e32 v63, 0xffff0000, v153
	v_cvt_pk_bf16_f32 v58, v58, v59
	v_cvt_pk_bf16_f32 v59, v64, v65
	v_lshlrev_b32_e32 v64, 16, v154
	v_and_b32_e32 v65, 0xffff0000, v154
	v_pk_add_f32 v[54:55], v[54:55], v[62:63]
	v_pk_add_f32 v[52:53], v[52:53], v[60:61]
	v_pk_add_f32 v[62:63], v[48:49], v[64:65]
	v_mul_f32_e32 v48, v53, v53
	v_mul_f32_e32 v49, v55, v55
	v_fmac_f32_e32 v48, v52, v52
	v_fmac_f32_e32 v49, v54, v54
	v_lshlrev_b32_e32 v66, 16, v155
	v_and_b32_e32 v67, 0xffff0000, v155
	v_add_f32_e32 v48, v48, v49
	v_mul_f32_e32 v49, v63, v63
	v_pk_add_f32 v[60:61], v[50:51], v[66:67]
	v_fmac_f32_e32 v49, v62, v62
	v_add_f32_e32 v48, v49, v48
	v_mul_f32_e32 v49, v61, v61
	v_fmac_f32_e32 v49, v60, v60
	v_add_f32_e32 v48, v49, v48
	v_add_f32_e32 v51, v68, v48
	ds_bpermute_b32 v66, v120, v51
	v_lshl_add_u64 v[48:49], s[42:43], 0, v[208:209]
	v_lshl_add_u64 v[64:65], v[200:201], 1, v[48:49]
	global_store_dwordx4 v[64:65], v[56:59], off
	v_cvt_pk_bf16_f32 v50, v52, v53
	s_waitcnt lgkmcnt(0)
	v_add_f32_e32 v48, v51, v66
	ds_bpermute_b32 v49, v121, v48
	v_cvt_pk_bf16_f32 v51, v54, v55
	v_cvt_pk_bf16_f32 v52, v62, v63
	v_cvt_pk_bf16_f32 v53, v60, v61
	global_store_dwordx4 v[64:65], v[50:53], off offset:256
	s_and_saveexec_b64 s[50:51], s[8:9]
	s_cbranch_execz .LBB0_1385
	s_waitcnt lgkmcnt(0)
	v_add_f32_e32 v48, v48, v49
	ds_write_b32 v225, v48 offset:2048
; __device__ __forceinline__ unsigned cvt_pk_bf16(float lo, float hi) { unsigned r; asm("v_cvt_pk_bf16_f32 %0, %1, %2" : "=v"(r) : "v"(lo), "v"(hi)); return r; }
;     __device__ __forceinline__ void operator()(const f32x4 (&acc)[2][2][4][2], const Unit& u, int wr, int wc, int fr, int fq, LAS unsigned char* xs, int wid, int lane) const {
;     ...
; #pragma unroll
;             for (int m = 0; m < 4; ++m) {
;                 const size_t row = (size_t)(row0 + ai * 128 + m * 16 + fr);
;                 float ss = 0.f;
; #pragma unroll
;                 for (int bj = 0; bj < 2; ++bj) {
;                     const size_t o = row * D + col0 + bj * 128;
;                     f32x4 x0, x1;
;                     if (SRCF32) { x0 = xf[m][bj][0]; x1 = xf[m][bj][1]; }
;                     else { const u32x4 r = raw[ai][m][bj]; x0 = (f32x4){bf_lo(r.x), bf_hi(r.x), bf_lo(r.y), bf_hi(r.y)}; x1 = (f32x4){bf_lo(r.z), bf_hi(r.z), bf_lo(r.w), bf_hi(r.w)}; }
;                     const f32x4 v0 = x0 + acc[ai][bj][m][0], v1 = x1 + acc[ai][bj][m][1];
;                     if (LAST) { *(f32x4*)(out + o) = v0; *(f32x4*)(out + o + 4) = v1; }
;                     else {
;                         ss += (v0[0] * v0[0] + v0[1] * v0[1]) + (v0[2] * v0[2] + v0[3] * v0[3]) + (v1[0] * v1[0] + v1[1] * v1[1]) + (v1[2] * v1[2] + v1[3] * v1[3]);
;                         u32x4 w; w.x = cvt_pk_bf16(v0[0], v0[1]); w.y = cvt_pk_bf16(v0[2], v0[3]); w.z = cvt_pk_bf16(v1[0], v1[1]); w.w = cvt_pk_bf16(v1[2], v1[3]); *(u32x4*)(xb + o) = w;
;                     }
;                 }
;                 if (!LAST) { ss += __shfl_xor(ss, 16); ss += __shfl_xor(ss, 32);
;                     if (fq == 0) P[(ai * 128 + wr * 64 + m * 16 + fr) * 4 + wc] = ss; }
.LBB0_1385:
	s_or_b64 exec, exec, s[50:51]
	v_lshlrev_b32_e32 v48, 16, v148
	s_waitcnt lgkmcnt(0)
	v_and_b32_e32 v49, 0xffff0000, v148
	v_lshlrev_b32_e32 v50, 16, v149
	v_and_b32_e32 v51, 0xffff0000, v149
	v_lshlrev_b32_e32 v52, 16, v150
	v_and_b32_e32 v53, 0xffff0000, v150
	v_lshlrev_b32_e32 v54, 16, v151
	v_and_b32_e32 v55, 0xffff0000, v151
	v_pk_add_f32 v[46:47], v[46:47], v[50:51]
	v_pk_add_f32 v[44:45], v[44:45], v[48:49]
	v_pk_add_f32 v[48:49], v[42:43], v[54:55]
	v_pk_add_f32 v[42:43], v[40:41], v[52:53]
	v_mul_f32_e32 v40, v45, v45
	v_mul_f32_e32 v41, v47, v47
	v_fmac_f32_e32 v40, v44, v44
	v_fmac_f32_e32 v41, v46, v46
	v_add_f32_e32 v40, v40, v41
	v_mul_f32_e32 v41, v43, v43
	v_fmac_f32_e32 v41, v42, v42
	v_add_f32_e32 v40, v41, v40
	v_mul_f32_e32 v41, v49, v49
	v_fmac_f32_e32 v41, v48, v48
	v_add_f32_e32 v52, v41, v40
	v_cvt_pk_bf16_f32 v40, v44, v45
	v_cvt_pk_bf16_f32 v41, v46, v47
	v_lshlrev_b32_e32 v44, 16, v144
	v_and_b32_e32 v45, 0xffff0000, v144
	v_lshlrev_b32_e32 v46, 16, v145
	v_and_b32_e32 v47, 0xffff0000, v145
	v_cvt_pk_bf16_f32 v42, v42, v43
	v_cvt_pk_bf16_f32 v43, v48, v49
	v_lshlrev_b32_e32 v48, 16, v146
	v_and_b32_e32 v49, 0xffff0000, v146
	v_pk_add_f32 v[38:39], v[38:39], v[46:47]
	v_pk_add_f32 v[36:37], v[36:37], v[44:45]
	v_pk_add_f32 v[46:47], v[32:33], v[48:49]
	v_mul_f32_e32 v32, v37, v37
	v_mul_f32_e32 v33, v39, v39
	v_fmac_f32_e32 v32, v36, v36
	v_fmac_f32_e32 v33, v38, v38
	v_lshlrev_b32_e32 v50, 16, v147
	v_and_b32_e32 v51, 0xffff0000, v147
	v_add_f32_e32 v32, v32, v33
	v_mul_f32_e32 v33, v47, v47
	v_pk_add_f32 v[44:45], v[34:35], v[50:51]
	v_fmac_f32_e32 v33, v46, v46
	v_add_f32_e32 v32, v33, v32
	v_mul_f32_e32 v33, v45, v45
	v_fmac_f32_e32 v33, v44, v44
	v_add_f32_e32 v32, v33, v32
	v_add_f32_e32 v35, v52, v32
	ds_bpermute_b32 v50, v120, v35
	v_lshl_add_u64 v[32:33], s[42:43], 0, v[206:207]
	v_lshl_add_u64 v[48:49], v[200:201], 1, v[32:33]
	global_store_dwordx4 v[48:49], v[40:43], off
	v_cvt_pk_bf16_f32 v34, v36, v37
	s_waitcnt lgkmcnt(0)
	v_add_f32_e32 v32, v35, v50
	ds_bpermute_b32 v33, v121, v32
	v_cvt_pk_bf16_f32 v35, v38, v39
	v_cvt_pk_bf16_f32 v36, v46, v47
	v_cvt_pk_bf16_f32 v37, v44, v45
	global_store_dwordx4 v[48:49], v[34:37], off offset:256
	s_and_saveexec_b64 s[50:51], s[8:9]
	s_cbranch_execz .LBB0_1387
	s_waitcnt lgkmcnt(0)
	v_add_f32_e32 v32, v32, v33
	ds_write_b32 v225, v32 offset:2304
; __device__ __forceinline__ unsigned cvt_pk_bf16(float lo, float hi) { unsigned r; asm("v_cvt_pk_bf16_f32 %0, %1, %2" : "=v"(r) : "v"(lo), "v"(hi)); return r; }
;     __device__ __forceinline__ void operator()(const f32x4 (&acc)[2][2][4][2], const Unit& u, int wr, int wc, int fr, int fq, LAS unsigned char* xs, int wid, int lane) const {
;     ...
; #pragma unroll
;             for (int m = 0; m < 4; ++m) {
;                 const size_t row = (size_t)(row0 + ai * 128 + m * 16 + fr);
;                 float ss = 0.f;
; #pragma unroll
;                 for (int bj = 0; bj < 2; ++bj) {
;                     const size_t o = row * D + col0 + bj * 128;
;                     f32x4 x0, x1;
;                     if (SRCF32) { x0 = xf[m][bj][0]; x1 = xf[m][bj][1]; }
;                     else { const u32x4 r = raw[ai][m][bj]; x0 = (f32x4){bf_lo(r.x), bf_hi(r.x), bf_lo(r.y), bf_hi(r.y)}; x1 = (f32x4){bf_lo(r.z), bf_hi(r.z), bf_lo(r.w), bf_hi(r.w)}; }
;                     const f32x4 v0 = x0 + acc[ai][bj][m][0], v1 = x1 + acc[ai][bj][m][1];
;                     if (LAST) { *(f32x4*)(out + o) = v0; *(f32x4*)(out + o + 4) = v1; }
;                     else {
;                         ss += (v0[0] * v0[0] + v0[1] * v0[1]) + (v0[2] * v0[2] + v0[3] * v0[3]) + (v1[0] * v1[0] + v1[1] * v1[1]) + (v1[2] * v1[2] + v1[3] * v1[3]);
;                         u32x4 w; w.x = cvt_pk_bf16(v0[0], v0[1]); w.y = cvt_pk_bf16(v0[2], v0[3]); w.z = cvt_pk_bf16(v1[0], v1[1]); w.w = cvt_pk_bf16(v1[2], v1[3]); *(u32x4*)(xb + o) = w;
;                     }
;                 }
;                 if (!LAST) { ss += __shfl_xor(ss, 16); ss += __shfl_xor(ss, 32);
;                     if (fq == 0) P[(ai * 128 + wr * 64 + m * 16 + fr) * 4 + wc] = ss; }
.LBB0_1387:
	s_or_b64 exec, exec, s[50:51]
	v_lshlrev_b32_e32 v32, 16, v140
	s_waitcnt lgkmcnt(0)
	v_and_b32_e32 v33, 0xffff0000, v140
	v_lshlrev_b32_e32 v34, 16, v141
	v_and_b32_e32 v35, 0xffff0000, v141
	v_lshlrev_b32_e32 v36, 16, v142
	v_and_b32_e32 v37, 0xffff0000, v142
	v_lshlrev_b32_e32 v38, 16, v143
	v_and_b32_e32 v39, 0xffff0000, v143
	v_pk_add_f32 v[30:31], v[30:31], v[34:35]
	v_pk_add_f32 v[28:29], v[28:29], v[32:33]
	v_pk_add_f32 v[32:33], v[26:27], v[38:39]
	v_pk_add_f32 v[26:27], v[24:25], v[36:37]
	v_mul_f32_e32 v24, v29, v29
	v_mul_f32_e32 v25, v31, v31
	v_fmac_f32_e32 v24, v28, v28
	v_fmac_f32_e32 v25, v30, v30
	v_add_f32_e32 v24, v24, v25
	v_mul_f32_e32 v25, v27, v27
	v_fmac_f32_e32 v25, v26, v26
	v_add_f32_e32 v24, v25, v24
	v_mul_f32_e32 v25, v33, v33
	v_fmac_f32_e32 v25, v32, v32
	v_add_f32_e32 v36, v25, v24
	v_cvt_pk_bf16_f32 v24, v28, v29
	v_cvt_pk_bf16_f32 v25, v30, v31
	v_lshlrev_b32_e32 v28, 16, v124
	v_and_b32_e32 v29, 0xffff0000, v124
	v_lshlrev_b32_e32 v30, 16, v125
	v_and_b32_e32 v31, 0xffff0000, v125
	v_cvt_pk_bf16_f32 v26, v26, v27
	v_cvt_pk_bf16_f32 v27, v32, v33
	v_lshlrev_b32_e32 v32, 16, v126
	v_and_b32_e32 v33, 0xffff0000, v126
	v_pk_add_f32 v[22:23], v[22:23], v[30:31]
	v_pk_add_f32 v[20:21], v[20:21], v[28:29]
	v_pk_add_f32 v[30:31], v[16:17], v[32:33]
	v_mul_f32_e32 v16, v21, v21
	v_mul_f32_e32 v17, v23, v23
	v_fmac_f32_e32 v16, v20, v20
	v_fmac_f32_e32 v17, v22, v22
	v_lshlrev_b32_e32 v34, 16, v127
	v_and_b32_e32 v35, 0xffff0000, v127
	v_add_f32_e32 v16, v16, v17
	v_mul_f32_e32 v17, v31, v31
	v_pk_add_f32 v[28:29], v[18:19], v[34:35]
	v_fmac_f32_e32 v17, v30, v30
	v_add_f32_e32 v16, v17, v16
	v_mul_f32_e32 v17, v29, v29
	v_fmac_f32_e32 v17, v28, v28
	v_add_f32_e32 v16, v17, v16
	v_add_f32_e32 v19, v36, v16
	ds_bpermute_b32 v34, v120, v19
	v_lshl_add_u64 v[16:17], s[42:43], 0, v[204:205]
	v_lshl_add_u64 v[32:33], v[200:201], 1, v[16:17]
	global_store_dwordx4 v[32:33], v[24:27], off
	v_cvt_pk_bf16_f32 v18, v20, v21
	s_waitcnt lgkmcnt(0)
	v_add_f32_e32 v16, v19, v34
	ds_bpermute_b32 v17, v121, v16
	v_cvt_pk_bf16_f32 v19, v22, v23
	v_cvt_pk_bf16_f32 v20, v30, v31
	v_cvt_pk_bf16_f32 v21, v28, v29
	global_store_dwordx4 v[32:33], v[18:21], off offset:256
	s_and_saveexec_b64 s[50:51], s[8:9]
	s_cbranch_execz .LBB0_1389
	s_waitcnt lgkmcnt(0)
	v_add_f32_e32 v16, v16, v17
	ds_write_b32 v225, v16 offset:2560
.LBB0_1389:
	s_or_b64 exec, exec, s[50:51]
	v_lshlrev_b32_e32 v16, 16, v112
	s_waitcnt lgkmcnt(0)
	v_and_b32_e32 v17, 0xffff0000, v112
	v_lshlrev_b32_e32 v18, 16, v113
	v_and_b32_e32 v19, 0xffff0000, v113
	v_lshlrev_b32_e32 v20, 16, v114
	v_and_b32_e32 v21, 0xffff0000, v114
	v_lshlrev_b32_e32 v22, 16, v115
	v_and_b32_e32 v23, 0xffff0000, v115
	v_pk_add_f32 v[14:15], v[14:15], v[18:19]
	v_pk_add_f32 v[12:13], v[12:13], v[16:17]
	v_pk_add_f32 v[16:17], v[10:11], v[22:23]
	v_pk_add_f32 v[10:11], v[8:9], v[20:21]
	v_mul_f32_e32 v8, v13, v13
	v_mul_f32_e32 v9, v15, v15
	v_fmac_f32_e32 v8, v12, v12
	v_fmac_f32_e32 v9, v14, v14
	v_add_f32_e32 v8, v8, v9
	v_mul_f32_e32 v9, v11, v11
	v_fmac_f32_e32 v9, v10, v10
	v_add_f32_e32 v8, v9, v8
	v_mul_f32_e32 v9, v17, v17
	v_fmac_f32_e32 v9, v16, v16
	v_add_f32_e32 v20, v9, v8
	v_cvt_pk_bf16_f32 v8, v12, v13
	v_cvt_pk_bf16_f32 v9, v14, v15
	v_lshlrev_b32_e32 v12, 16, v104
	v_and_b32_e32 v13, 0xffff0000, v104
	v_lshlrev_b32_e32 v14, 16, v105
	v_and_b32_e32 v15, 0xffff0000, v105
	v_cvt_pk_bf16_f32 v10, v10, v11
	v_cvt_pk_bf16_f32 v11, v16, v17
	v_lshlrev_b32_e32 v16, 16, v106
	v_and_b32_e32 v17, 0xffff0000, v106
	v_pk_add_f32 v[6:7], v[6:7], v[14:15]
	v_pk_add_f32 v[4:5], v[4:5], v[12:13]
	v_pk_add_f32 v[14:15], v[0:1], v[16:17]
	v_mul_f32_e32 v0, v5, v5
	v_mul_f32_e32 v1, v7, v7
	v_fmac_f32_e32 v0, v4, v4
	v_fmac_f32_e32 v1, v6, v6
	v_lshlrev_b32_e32 v18, 16, v107
	v_and_b32_e32 v19, 0xffff0000, v107
	v_add_f32_e32 v0, v0, v1
	v_mul_f32_e32 v1, v15, v15
	v_pk_add_f32 v[12:13], v[2:3], v[18:19]
	v_fmac_f32_e32 v1, v14, v14
	v_add_f32_e32 v0, v1, v0
	v_mul_f32_e32 v1, v13, v13
	v_fmac_f32_e32 v1, v12, v12
	v_add_f32_e32 v0, v1, v0
	v_add_f32_e32 v3, v20, v0
	ds_bpermute_b32 v18, v120, v3
	v_lshl_add_u64 v[0:1], s[42:43], 0, v[202:203]
	v_lshl_add_u64 v[16:17], v[200:201], 1, v[0:1]
	global_store_dwordx4 v[16:17], v[8:11], off
	v_cvt_pk_bf16_f32 v2, v4, v5
	s_waitcnt lgkmcnt(0)
	v_add_f32_e32 v0, v3, v18
	ds_bpermute_b32 v1, v121, v0
	v_cvt_pk_bf16_f32 v3, v6, v7
	v_cvt_pk_bf16_f32 v4, v14, v15
	v_cvt_pk_bf16_f32 v5, v12, v13
	global_store_dwordx4 v[16:17], v[2:5], off offset:256
	s_and_saveexec_b64 s[50:51], s[8:9]
	s_cbranch_execz .LBB0_1391
	s_waitcnt lgkmcnt(0)
	v_add_f32_e32 v0, v0, v1
	ds_write_b32 v225, v0 offset:2816

; #define LAS __attribute__((address_space(3)))
; __device__ __forceinline__ unsigned cvt_pk_bf16(float lo, float hi) { unsigned r; asm("v_cvt_pk_bf16_f32 %0, %1, %2" : "=v"(r) : "v"(lo), "v"(hi)); return r; }
; __device__ __forceinline__ void tstore_sub(const f32x4 (&v)[4][2], bf16_t* dst  , LAS unsigned char* x, int fr, int fq, int lane) {
; #pragma unroll
;     for (int m = 0; m < 4; ++m)
; #pragma unroll
;         for (int n = 0; n < 2; ++n)
; #pragma unroll
;             for (int j = 0; j < 4; ++j) {
;                 const int ch = 8 * fq + 4 * n + j, tok = 16 * m + fr;
;                 const unsigned b = cvt_pk_bf16(v[m][n][j], 0.f);
;                 *(LAS unsigned short*)(x + ch * 128 + ((((tok >> 3) ^ fq) << 4) | ((tok & 7) << 1))) = (unsigned short)b;
;             }
;     LDS_WAIT();
; #pragma unroll
;     for (int i = 0; i < 4; ++i) {
;         const int q = lane + 64 * i, ch = q >> 3, tc = q & 7;
;         const u32x4 o = *(const LAS u32x4*)(x + ch * 128 + ((tc ^ ((ch >> 3) & 3)) << 4));
;         *(u32x4*)(dst + (size_t)ch * T + tc * 8) = o;
;     }
;     LDS_WAIT();
; }
;     __device__ __forceinline__ void operator()(const f32x4 (&acc)[2][2][4][2], const Unit& u, int wr, int wc, int fr, int fq, LAS unsigned char* xs, int wid, int lane) const {
;     ...
; #pragma unroll
;             for (int ai = 0; ai < 2; ++ai)
; #pragma unroll
;                 for (int bj = 0; bj < 2; ++bj) {
;                     f32x4 v[4][2];
; #pragma unroll
;                     for (int m = 0; m < 4; ++m) { v[m][0] = acc[ai][bj][m][0] * rs[ai][m]; v[m][1] = acc[ai][bj][m][1] * rs[ai][m]; }
;                     if (ODD) {
;                         float* vss = (float*)(ws + OFF_VSS);
; #pragma unroll
;                         for (int m = 0; m < 4; ++m) {
;                             float s = 0.f;
; #pragma unroll
;                             for (int n = 0; n < 2; ++n) s += (v[m][n][0] * v[m][n][0] + v[m][n][1] * v[m][n][1]) + (v[m][n][2] * v[m][n][2] + v[m][n][3] * v[m][n][3]);
;                             s += __shfl_xor(s, 16); s += __shfl_xor(s, 32);
;                             if (fq == 0) vss[(size_t)(row0 + ai * 128 + m * 16 + fr) * 32 + (2 * (pn - 24) + bj) * 4 + wc] = s;
;                         }
;                     }
;                     tstore_sub(v, base + (size_t)(bj * 128 + wc * 32) * T + row0 + ai * 128, x, fr, fq, lane);
.LBB0_1469:
	s_or_b64 exec, exec, s[60:61]
	v_cvt_pk_bf16_f32 v159, v184, v137
	ds_write_b16 v237, v159
	v_cvt_pk_bf16_f32 v159, v185, v137
	ds_write_b16 v237, v159 offset:128
	v_cvt_pk_bf16_f32 v159, v182, v137
	ds_write_b16 v237, v159 offset:256
	v_cvt_pk_bf16_f32 v159, v183, v137
	ds_write_b16 v237, v159 offset:384
	v_cvt_pk_bf16_f32 v159, v180, v137
	ds_write_b16 v237, v159 offset:512
	v_cvt_pk_bf16_f32 v159, v181, v137
	ds_write_b16 v237, v159 offset:640
	v_cvt_pk_bf16_f32 v159, v178, v137
	ds_write_b16 v237, v159 offset:768
	v_cvt_pk_bf16_f32 v159, v179, v137
	ds_write_b16 v237, v159 offset:896
	v_cvt_pk_bf16_f32 v159, v192, v137
	ds_write_b16 v238, v159
	v_cvt_pk_bf16_f32 v159, v193, v137
	ds_write_b16 v238, v159 offset:128
	v_cvt_pk_bf16_f32 v159, v190, v137
	ds_write_b16 v238, v159 offset:256
	v_cvt_pk_bf16_f32 v159, v191, v137
	ds_write_b16 v238, v159 offset:384
	v_cvt_pk_bf16_f32 v159, v188, v137
	ds_write_b16 v238, v159 offset:512
	v_cvt_pk_bf16_f32 v159, v189, v137
	ds_write_b16 v238, v159 offset:640
	v_cvt_pk_bf16_f32 v159, v186, v137
	ds_write_b16 v238, v159 offset:768
	v_cvt_pk_bf16_f32 v159, v187, v137
	ds_write_b16 v238, v159 offset:896
	v_cvt_pk_bf16_f32 v159, v206, v137
	ds_write_b16 v239, v159
	v_cvt_pk_bf16_f32 v159, v207, v137
	ds_write_b16 v239, v159 offset:128
	v_cvt_pk_bf16_f32 v159, v204, v137
	ds_write_b16 v239, v159 offset:256
	v_cvt_pk_bf16_f32 v159, v205, v137
	ds_write_b16 v239, v159 offset:384
	v_cvt_pk_bf16_f32 v159, v202, v137
	ds_write_b16 v239, v159 offset:512
	v_cvt_pk_bf16_f32 v159, v203, v137
	ds_write_b16 v239, v159 offset:640
	v_cvt_pk_bf16_f32 v159, v200, v137
	ds_write_b16 v239, v159 offset:768
	v_cvt_pk_bf16_f32 v159, v201, v137
	ds_write_b16 v239, v159 offset:896
	v_cvt_pk_bf16_f32 v159, v214, v137
	ds_write_b16 v240, v159
	v_cvt_pk_bf16_f32 v159, v215, v137
	ds_write_b16 v240, v159 offset:128
	v_cvt_pk_bf16_f32 v159, v212, v137
	ds_write_b16 v240, v159 offset:256
	v_cvt_pk_bf16_f32 v159, v213, v137
	ds_write_b16 v240, v159 offset:384
	v_cvt_pk_bf16_f32 v159, v210, v137
	ds_write_b16 v240, v159 offset:512
	v_cvt_pk_bf16_f32 v159, v211, v137
	ds_write_b16 v240, v159 offset:640
	v_cvt_pk_bf16_f32 v159, v208, v137
	s_ashr_i32 s57, s56, 31
	ds_write_b16 v240, v159 offset:768
	v_cvt_pk_bf16_f32 v159, v209, v137
	ds_write_b16 v240, v159 offset:896
	s_lshl_b64 s[0:1], s[56:57], 1
	s_waitcnt lgkmcnt(0)
	s_add_u32 s0, s58, s0
	ds_read_b128 v[182:185], v241
	ds_read_b128 v[190:193], v242
	s_addc_u32 s1, s59, s1
	v_lshl_add_u64 v[176:177], s[0:1], 0, v[136:137]
	v_lshl_add_u64 v[212:213], v[176:177], 0, s[20:21]
	v_lshlrev_b32_e32 v180, 1, v138
	v_mov_b32_e32 v181, v137
	ds_read_b128 v[200:203], v243
	ds_read_b128 v[208:211], v244
	v_lshl_add_u64 v[186:187], v[212:213], 0, v[180:181]
	v_mov_b32_e32 v175, v174
	s_waitcnt lgkmcnt(3)
	global_store_dwordx4 v[186:187], v[182:185], off
	v_lshlrev_b32_e32 v178, 1, v142
	v_mov_b32_e32 v179, v137
	v_lshlrev_b32_e32 v182, 1, v140
	v_mov_b32_e32 v183, v137
	v_mov_b32_e32 v184, v174
	v_mov_b32_e32 v185, v174
	v_lshl_add_u64 v[188:189], v[212:213], 0, v[182:183]
	v_pk_mul_f32 v[204:205], v[122:123], v[184:185]
	v_pk_mul_f32 v[206:207], v[120:121], v[174:175]
	s_waitcnt lgkmcnt(2)
	global_store_dwordx4 v[188:189], v[190:193], off
	v_mul_f32_e32 v159, v207, v207
	v_mul_f32_e32 v161, v205, v205
	v_lshl_add_u64 v[190:191], v[212:213], 0, v[178:179]
	s_waitcnt lgkmcnt(1)
	global_store_dwordx4 v[190:191], v[200:203], off
	v_fmac_f32_e32 v159, v206, v206
	v_fmac_f32_e32 v161, v204, v204
	v_pk_mul_f32 v[200:201], v[114:115], v[184:185]
	v_pk_mul_f32 v[202:203], v[112:113], v[174:175]
	v_add_f32_e32 v159, v159, v161
	v_mul_f32_e32 v161, v203, v203
	v_mul_f32_e32 v165, v201, v201
	v_fmac_f32_e32 v161, v202, v202
	v_fmac_f32_e32 v165, v200, v200
	v_add_f32_e32 v161, v161, v165
	v_add_f32_e32 v159, v159, v161
	ds_bpermute_b32 v161, v151, v159
	v_lshlrev_b32_e32 v184, 1, v144
	v_mov_b32_e32 v185, v137
	v_lshl_add_u64 v[192:193], v[212:213], 0, v[184:185]
	s_waitcnt lgkmcnt(1)
	global_store_dwordx4 v[192:193], v[208:211], off
	s_waitcnt lgkmcnt(0)
	v_add_f32_e32 v159, v159, v161
	ds_bpermute_b32 v161, v245, v159
	s_waitcnt lgkmcnt(0)
	s_and_saveexec_b64 s[60:61], s[6:7]
	s_cbranch_execz .LBB0_1471
	v_lshlrev_b64 v[208:209], 7, v[162:163]
	v_lshl_add_u64 v[208:209], s[54:55], 0, v[208:209]
	s_waitcnt lgkmcnt(0)
	v_add_f32_e32 v159, v159, v161
	global_store_dword v[208:209], v159, off offset:-752

; #define LAS __attribute__((address_space(3)))
; __device__ __forceinline__ unsigned cvt_pk_bf16(float lo, float hi) { unsigned r; asm("v_cvt_pk_bf16_f32 %0, %1, %2" : "=v"(r) : "v"(lo), "v"(hi)); return r; }
; __device__ __forceinline__ void tstore_sub(const f32x4 (&v)[4][2], bf16_t* dst  , LAS unsigned char* x, int fr, int fq, int lane) {
; #pragma unroll
;     for (int m = 0; m < 4; ++m)
; #pragma unroll
;         for (int n = 0; n < 2; ++n)
; #pragma unroll
;             for (int j = 0; j < 4; ++j) {
;                 const int ch = 8 * fq + 4 * n + j, tok = 16 * m + fr;
;                 const unsigned b = cvt_pk_bf16(v[m][n][j], 0.f);
;                 *(LAS unsigned short*)(x + ch * 128 + ((((tok >> 3) ^ fq) << 4) | ((tok & 7) << 1))) = (unsigned short)b;
;             }
;     LDS_WAIT();
; #pragma unroll
;     for (int i = 0; i < 4; ++i) {
;         const int q = lane + 64 * i, ch = q >> 3, tc = q & 7;
;         const u32x4 o = *(const LAS u32x4*)(x + ch * 128 + ((tc ^ ((ch >> 3) & 3)) << 4));
;         *(u32x4*)(dst + (size_t)ch * T + tc * 8) = o;
;     }
;     LDS_WAIT();
; }
;     __device__ __forceinline__ void operator()(const f32x4 (&acc)[2][2][4][2], const Unit& u, int wr, int wc, int fr, int fq, LAS unsigned char* xs, int wid, int lane) const {
;     ...
; #pragma unroll
;             for (int ai = 0; ai < 2; ++ai)
; #pragma unroll
;                 for (int bj = 0; bj < 2; ++bj) {
;                     f32x4 v[4][2];
; #pragma unroll
;                     for (int m = 0; m < 4; ++m) { v[m][0] = acc[ai][bj][m][0] * rs[ai][m]; v[m][1] = acc[ai][bj][m][1] * rs[ai][m]; }
;                     if (ODD) {
;                         float* vss = (float*)(ws + OFF_VSS);
; #pragma unroll
;                         for (int m = 0; m < 4; ++m) {
;                             float s = 0.f;
; #pragma unroll
;                             for (int n = 0; n < 2; ++n) s += (v[m][n][0] * v[m][n][0] + v[m][n][1] * v[m][n][1]) + (v[m][n][2] * v[m][n][2] + v[m][n][3] * v[m][n][3]);
;                             s += __shfl_xor(s, 16); s += __shfl_xor(s, 32);
;                             if (fq == 0) vss[(size_t)(row0 + ai * 128 + m * 16 + fr) * 32 + (2 * (pn - 24) + bj) * 4 + wc] = s;
;                         }
;                     }
;                     tstore_sub(v, base + (size_t)(bj * 128 + wc * 32) * T + row0 + ai * 128, x, fr, fq, lane);
.LBB0_1477:
	s_or_b64 exec, exec, s[60:61]
	v_cvt_pk_bf16_f32 v159, v206, v137
	ds_write_b16 v237, v159
	v_cvt_pk_bf16_f32 v159, v207, v137
	ds_write_b16 v237, v159 offset:128
	v_cvt_pk_bf16_f32 v159, v204, v137
	ds_write_b16 v237, v159 offset:256
	v_cvt_pk_bf16_f32 v159, v205, v137
	ds_write_b16 v237, v159 offset:384
	v_cvt_pk_bf16_f32 v159, v202, v137
	ds_write_b16 v237, v159 offset:512
	v_cvt_pk_bf16_f32 v159, v203, v137
	ds_write_b16 v237, v159 offset:640
	v_cvt_pk_bf16_f32 v159, v200, v137
	ds_write_b16 v237, v159 offset:768
	v_cvt_pk_bf16_f32 v159, v201, v137
	ds_write_b16 v237, v159 offset:896
	v_cvt_pk_bf16_f32 v159, v214, v137
	ds_write_b16 v238, v159
	v_cvt_pk_bf16_f32 v159, v215, v137
	ds_write_b16 v238, v159 offset:128
	v_cvt_pk_bf16_f32 v159, v212, v137
	ds_write_b16 v238, v159 offset:256
	v_cvt_pk_bf16_f32 v159, v213, v137
	ds_write_b16 v238, v159 offset:384
	v_cvt_pk_bf16_f32 v159, v210, v137
	ds_write_b16 v238, v159 offset:512
	v_cvt_pk_bf16_f32 v159, v211, v137
	ds_write_b16 v238, v159 offset:640
	v_cvt_pk_bf16_f32 v159, v208, v137
	ds_write_b16 v238, v159 offset:768
	v_cvt_pk_bf16_f32 v159, v209, v137
	ds_write_b16 v238, v159 offset:896
	v_cvt_pk_bf16_f32 v159, v220, v137
	ds_write_b16 v239, v159
	v_cvt_pk_bf16_f32 v159, v221, v137
	ds_write_b16 v239, v159 offset:128
	v_cvt_pk_bf16_f32 v159, v218, v137
	ds_write_b16 v239, v159 offset:256
	v_cvt_pk_bf16_f32 v159, v219, v137
	ds_write_b16 v239, v159 offset:384
	v_cvt_pk_bf16_f32 v159, v216, v137
	ds_write_b16 v239, v159 offset:512
	v_cvt_pk_bf16_f32 v159, v217, v137
	ds_write_b16 v239, v159 offset:640
	v_cvt_pk_bf16_f32 v159, v198, v137
	ds_write_b16 v239, v159 offset:768
	v_cvt_pk_bf16_f32 v159, v199, v137
	ds_write_b16 v239, v159 offset:896
	v_cvt_pk_bf16_f32 v159, v226, v137
	ds_write_b16 v240, v159
	v_cvt_pk_bf16_f32 v159, v227, v137
	ds_write_b16 v240, v159 offset:128
	v_cvt_pk_bf16_f32 v159, v224, v137
	ds_write_b16 v240, v159 offset:256
	v_cvt_pk_bf16_f32 v159, v225, v137
	ds_write_b16 v240, v159 offset:384
	v_cvt_pk_bf16_f32 v159, v222, v137
	ds_write_b16 v240, v159 offset:512
	v_cvt_pk_bf16_f32 v159, v223, v137
	ds_write_b16 v240, v159 offset:640
	v_cvt_pk_bf16_f32 v159, v196, v137
	ds_write_b16 v240, v159 offset:768
	v_cvt_pk_bf16_f32 v159, v197, v137
	ds_write_b16 v240, v159 offset:896
	s_waitcnt lgkmcnt(0)
	ds_read_b128 v[194:197], v241
	ds_read_b128 v[198:201], v242
	s_lshl_b32 s60, s68, 1
	s_mov_b32 s61, s21
	v_lshl_add_u64 v[210:211], v[176:177], 0, s[60:61]
	v_mov_b32_e32 v181, v137
	v_pk_mul_f32 v[206:207], v[62:63], v[166:167] op_sel_hi:[1,0]
	v_pk_mul_f32 v[208:209], v[60:61], v[166:167] op_sel_hi:[1,0]
	v_lshl_add_u64 v[202:203], v[210:211], 0, v[180:181]
	v_mul_f32_e32 v159, v209, v209
	s_waitcnt lgkmcnt(14)
	v_mul_f32_e32 v161, v207, v207
	s_waitcnt lgkmcnt(1)
	global_store_dwordx4 v[202:203], v[194:197], off
	v_pk_mul_f32 v[202:203], v[54:55], v[166:167] op_sel_hi:[1,0]
	v_pk_mul_f32 v[204:205], v[52:53], v[166:167] op_sel_hi:[1,0]
	v_fmac_f32_e32 v159, v208, v208
	v_fmac_f32_e32 v161, v206, v206
	v_add_f32_e32 v159, v159, v161
	v_mul_f32_e32 v161, v205, v205
	v_mul_f32_e32 v163, v203, v203
	v_fmac_f32_e32 v161, v204, v204
	v_fmac_f32_e32 v163, v202, v202
	v_add_f32_e32 v161, v161, v163
	v_mov_b32_e32 v183, v137
	v_add_f32_e32 v159, v159, v161
	v_lshl_add_u64 v[194:195], v[210:211], 0, v[182:183]
	ds_bpermute_b32 v161, v151, v159
	s_waitcnt lgkmcnt(1)
	global_store_dwordx4 v[194:195], v[198:201], off
	ds_read_b128 v[194:197], v243
	ds_read_b128 v[198:201], v244
	v_mov_b32_e32 v179, v137
	v_lshl_add_u64 v[212:213], v[210:211], 0, v[178:179]
	v_mov_b32_e32 v185, v137
	s_waitcnt lgkmcnt(2)
	v_add_f32_e32 v159, v159, v161
	s_waitcnt lgkmcnt(1)
	global_store_dwordx4 v[212:213], v[194:197], off
	ds_bpermute_b32 v161, v245, v159
	s_nop 0
	v_lshl_add_u64 v[194:195], v[210:211], 0, v[184:185]
	s_waitcnt lgkmcnt(1)
	global_store_dwordx4 v[194:195], v[198:201], off
	s_waitcnt lgkmcnt(0)
	s_nop 1
	v_add_u32_e32 v200, 0x80, v162
	v_ashrrev_i32_e32 v201, 31, v200
	s_and_saveexec_b64 s[62:63], s[6:7]
	s_cbranch_execz .LBB0_1479
	v_lshlrev_b64 v[194:195], 7, v[200:201]
	v_lshl_add_u64 v[194:195], s[54:55], 0, v[194:195]
	s_waitcnt lgkmcnt(0)
	v_add_f32_e32 v159, v159, v161
	global_store_dword v[194:195], v159, off offset:-768

; #define LAS __attribute__((address_space(3)))
; __device__ __forceinline__ unsigned cvt_pk_bf16(float lo, float hi) { unsigned r; asm("v_cvt_pk_bf16_f32 %0, %1, %2" : "=v"(r) : "v"(lo), "v"(hi)); return r; }
; __device__ __forceinline__ void tstore_sub(const f32x4 (&v)[4][2], bf16_t* dst  , LAS unsigned char* x, int fr, int fq, int lane) {
; #pragma unroll
;     for (int m = 0; m < 4; ++m)
; #pragma unroll
;         for (int n = 0; n < 2; ++n)
; #pragma unroll
;             for (int j = 0; j < 4; ++j) {
;                 const int ch = 8 * fq + 4 * n + j, tok = 16 * m + fr;
;                 const unsigned b = cvt_pk_bf16(v[m][n][j], 0.f);
;                 *(LAS unsigned short*)(x + ch * 128 + ((((tok >> 3) ^ fq) << 4) | ((tok & 7) << 1))) = (unsigned short)b;
;             }
;     LDS_WAIT();
; #pragma unroll
;     for (int i = 0; i < 4; ++i) {
;         const int q = lane + 64 * i, ch = q >> 3, tc = q & 7;
;         const u32x4 o = *(const LAS u32x4*)(x + ch * 128 + ((tc ^ ((ch >> 3) & 3)) << 4));
;         *(u32x4*)(dst + (size_t)ch * T + tc * 8) = o;
;     }
;     LDS_WAIT();
; }
;     __device__ __forceinline__ void operator()(const f32x4 (&acc)[2][2][4][2], const Unit& u, int wr, int wc, int fr, int fq, LAS unsigned char* xs, int wid, int lane) const {
;     ...
; #pragma unroll
;             for (int ai = 0; ai < 2; ++ai)
; #pragma unroll
;                 for (int bj = 0; bj < 2; ++bj) {
;                     f32x4 v[4][2];
; #pragma unroll
;                     for (int m = 0; m < 4; ++m) { v[m][0] = acc[ai][bj][m][0] * rs[ai][m]; v[m][1] = acc[ai][bj][m][1] * rs[ai][m]; }
;                     if (ODD) {
;                         float* vss = (float*)(ws + OFF_VSS);
; #pragma unroll
;                         for (int m = 0; m < 4; ++m) {
;                             float s = 0.f;
; #pragma unroll
;                             for (int n = 0; n < 2; ++n) s += (v[m][n][0] * v[m][n][0] + v[m][n][1] * v[m][n][1]) + (v[m][n][2] * v[m][n][2] + v[m][n][3] * v[m][n][3]);
;                             s += __shfl_xor(s, 16); s += __shfl_xor(s, 32);
;                             if (fq == 0) vss[(size_t)(row0 + ai * 128 + m * 16 + fr) * 32 + (2 * (pn - 24) + bj) * 4 + wc] = s;
;                         }
;                     }
;                     tstore_sub(v, base + (size_t)(bj * 128 + wc * 32) * T + row0 + ai * 128, x, fr, fq, lane);
.LBB0_1485:
	s_or_b64 exec, exec, s[62:63]
	v_cvt_pk_bf16_f32 v159, v208, v137
	ds_write_b16 v237, v159
	v_cvt_pk_bf16_f32 v159, v209, v137
	ds_write_b16 v237, v159 offset:128
	v_cvt_pk_bf16_f32 v159, v206, v137
	ds_write_b16 v237, v159 offset:256
	v_cvt_pk_bf16_f32 v159, v207, v137
	ds_write_b16 v237, v159 offset:384
	v_cvt_pk_bf16_f32 v159, v204, v137
	ds_write_b16 v237, v159 offset:512
	v_cvt_pk_bf16_f32 v159, v205, v137
	ds_write_b16 v237, v159 offset:640
	v_cvt_pk_bf16_f32 v159, v202, v137
	ds_write_b16 v237, v159 offset:768
	v_cvt_pk_bf16_f32 v159, v203, v137
	ds_write_b16 v237, v159 offset:896
	v_cvt_pk_bf16_f32 v159, v216, v137
	ds_write_b16 v238, v159
	v_cvt_pk_bf16_f32 v159, v217, v137
	ds_write_b16 v238, v159 offset:128
	v_cvt_pk_bf16_f32 v159, v214, v137
	ds_write_b16 v238, v159 offset:256
	v_cvt_pk_bf16_f32 v159, v215, v137
	ds_write_b16 v238, v159 offset:384
	v_cvt_pk_bf16_f32 v159, v212, v137
	ds_write_b16 v238, v159 offset:512
	v_cvt_pk_bf16_f32 v159, v213, v137
	ds_write_b16 v238, v159 offset:640
	v_cvt_pk_bf16_f32 v159, v210, v137
	ds_write_b16 v238, v159 offset:768
	v_cvt_pk_bf16_f32 v159, v211, v137
	ds_write_b16 v238, v159 offset:896
	v_cvt_pk_bf16_f32 v159, v224, v137
	ds_write_b16 v239, v159
	v_cvt_pk_bf16_f32 v159, v225, v137
	ds_write_b16 v239, v159 offset:128
	v_cvt_pk_bf16_f32 v159, v222, v137
	ds_write_b16 v239, v159 offset:256
	v_cvt_pk_bf16_f32 v159, v223, v137
	ds_write_b16 v239, v159 offset:384
	v_cvt_pk_bf16_f32 v159, v220, v137
	ds_write_b16 v239, v159 offset:512
	v_cvt_pk_bf16_f32 v159, v221, v137
	ds_write_b16 v239, v159 offset:640
	v_cvt_pk_bf16_f32 v159, v218, v137
	ds_write_b16 v239, v159 offset:768
	v_cvt_pk_bf16_f32 v159, v219, v137
	ds_write_b16 v239, v159 offset:896
	v_cvt_pk_bf16_f32 v159, v232, v137
	ds_write_b16 v240, v159
	v_cvt_pk_bf16_f32 v159, v233, v137
	ds_write_b16 v240, v159 offset:128
	v_cvt_pk_bf16_f32 v159, v230, v137
	ds_write_b16 v240, v159 offset:256
	v_cvt_pk_bf16_f32 v159, v231, v137
	ds_write_b16 v240, v159 offset:384
	v_cvt_pk_bf16_f32 v159, v228, v137
	ds_write_b16 v240, v159 offset:512
	v_cvt_pk_bf16_f32 v159, v229, v137
	v_mov_b32_e32 v167, v166
	ds_write_b16 v240, v159 offset:640
	v_cvt_pk_bf16_f32 v159, v226, v137
	v_mov_b32_e32 v202, v166
	v_mov_b32_e32 v203, v166
	ds_write_b16 v240, v159 offset:768
	v_cvt_pk_bf16_f32 v159, v227, v137
	v_pk_mul_f32 v[206:207], v[58:59], v[202:203]
	v_pk_mul_f32 v[208:209], v[56:57], v[166:167]
	ds_write_b16 v240, v159 offset:896
	v_mul_f32_e32 v159, v209, v209
	s_waitcnt lgkmcnt(14)
	v_mul_f32_e32 v161, v207, v207
	v_pk_mul_f32 v[202:203], v[50:51], v[202:203]
	v_pk_mul_f32 v[204:205], v[48:49], v[166:167]
	v_fmac_f32_e32 v159, v208, v208
	v_fmac_f32_e32 v161, v206, v206
	v_add_f32_e32 v159, v159, v161
	v_mul_f32_e32 v161, v205, v205
	v_mul_f32_e32 v163, v203, v203
	v_fmac_f32_e32 v161, v204, v204
	v_fmac_f32_e32 v163, v202, v202
	v_add_f32_e32 v161, v161, v163
	v_add_f32_e32 v159, v159, v161
	ds_bpermute_b32 v161, v151, v159
	s_waitcnt lgkmcnt(0)
	ds_read_b128 v[210:213], v241
	ds_read_b128 v[214:217], v242
	ds_read_b128 v[218:221], v243
	ds_read_b128 v[222:225], v244
	s_waitcnt lgkmcnt(3)
	global_store_dwordx4 v[186:187], v[210:213], off offset:256
	s_waitcnt lgkmcnt(2)
	global_store_dwordx4 v[188:189], v[214:217], off offset:256
	s_waitcnt lgkmcnt(1)
	global_store_dwordx4 v[190:191], v[218:221], off offset:256
	s_waitcnt lgkmcnt(0)
	global_store_dwordx4 v[192:193], v[222:225], off offset:256
	v_add_f32_e32 v159, v159, v161
	ds_bpermute_b32 v161, v245, v159
	s_waitcnt lgkmcnt(0)
	s_and_saveexec_b64 s[62:63], s[6:7]
	s_cbranch_execz .LBB0_1487
	v_lshlrev_b64 v[186:187], 7, v[200:201]
	v_lshl_add_u64 v[186:187], s[54:55], 0, v[186:187]
	s_waitcnt lgkmcnt(0)
	v_add_f32_e32 v159, v159, v161
	global_store_dword v[186:187], v159, off offset:-752

; #define LAS __attribute__((address_space(3)))
; __device__ __forceinline__ unsigned cvt_pk_bf16(float lo, float hi) { unsigned r; asm("v_cvt_pk_bf16_f32 %0, %1, %2" : "=v"(r) : "v"(lo), "v"(hi)); return r; }
; __device__ __forceinline__ float silu_f(float x) { return x * __builtin_amdgcn_rcpf(1.f + __builtin_amdgcn_exp2f(-LOG2E * x)); }
; #define LDS_WAIT() asm volatile("s_waitcnt lgkmcnt(0)" ::: "memory")
; __device__ __forceinline__ void tstore_sub(const f32x4 (&v)[4][2], bf16_t* dst  , LAS unsigned char* x, int fr, int fq, int lane) {
; #pragma unroll
;     for (int m = 0; m < 4; ++m)
; #pragma unroll
;         for (int n = 0; n < 2; ++n)
; #pragma unroll
;             for (int j = 0; j < 4; ++j) {
;                 const int ch = 8 * fq + 4 * n + j, tok = 16 * m + fr;
;                 const unsigned b = cvt_pk_bf16(v[m][n][j], 0.f);
;                 *(LAS unsigned short*)(x + ch * 128 + ((((tok >> 3) ^ fq) << 4) | ((tok & 7) << 1))) = (unsigned short)b;
;             }
;     LDS_WAIT();
; #pragma unroll
;     for (int i = 0; i < 4; ++i) {
;         const int q = lane + 64 * i, ch = q >> 3, tc = q & 7;
;         const u32x4 o = *(const LAS u32x4*)(x + ch * 128 + ((tc ^ ((ch >> 3) & 3)) << 4));
;         *(u32x4*)(dst + (size_t)ch * T + tc * 8) = o;
;     }
;     LDS_WAIT();
; }
;     __device__ __forceinline__ void operator()(const f32x4 (&acc)[2][2][4][2], const Unit& u, int wr, int wc, int fr, int fq, LAS unsigned char* xs, int wid, int lane) const {
;     ...
;         } else if (mode == 1 || mode == 2) {
; #pragma unroll
;             for (int ai = 0; ai < 2; ++ai)
; #pragma unroll
;                 for (int m = 0; m < 4; ++m) {
;                     const float r = rs[ai][m];
;                     bf16_t* rowp = base + (size_t)(row0 + ai * 128 + m * 16 + fr) * ldc + wc * 32 + 8 * fq;
;                     float o[8];
; #pragma unroll
;                     for (int n = 0; n < 2; ++n)
; #pragma unroll
;                         for (int j = 0; j < 4; ++j) { const float a = acc[ai][0][m][n][j] * r, b = acc[ai][1][m][n][j] * r; o[4 * n + j] = (mode == 1) ? a * b : a * silu_f(b); }
;                     u32x4 w; w.x = cvt_pk_bf16(o[0], o[1]); w.y = cvt_pk_bf16(o[2], o[3]); w.z = cvt_pk_bf16(o[4], o[5]); w.w = cvt_pk_bf16(o[6], o[7]);
;                     *(u32x4*)rowp = w;
;                     __builtin_amdgcn_sched_barrier(0);
;                 }
.LBB0_1493:
	s_or_b64 exec, exec, s[62:63]
	v_cvt_pk_bf16_f32 v151, v208, v137
	ds_write_b16 v237, v151
	v_cvt_pk_bf16_f32 v151, v209, v137
	ds_write_b16 v237, v151 offset:128
	v_cvt_pk_bf16_f32 v151, v206, v137
	ds_write_b16 v237, v151 offset:256
	v_cvt_pk_bf16_f32 v151, v207, v137
	ds_write_b16 v237, v151 offset:384
	v_cvt_pk_bf16_f32 v151, v204, v137
	ds_write_b16 v237, v151 offset:512
	v_cvt_pk_bf16_f32 v151, v205, v137
	ds_write_b16 v237, v151 offset:640
	v_cvt_pk_bf16_f32 v151, v202, v137
	ds_write_b16 v237, v151 offset:768
	v_cvt_pk_bf16_f32 v151, v203, v137
	ds_write_b16 v237, v151 offset:896
	v_cvt_pk_bf16_f32 v151, v192, v137
	ds_write_b16 v238, v151
	v_cvt_pk_bf16_f32 v151, v193, v137
	ds_write_b16 v238, v151 offset:128
	v_cvt_pk_bf16_f32 v151, v190, v137
	ds_write_b16 v238, v151 offset:256
	v_cvt_pk_bf16_f32 v151, v191, v137
	ds_write_b16 v238, v151 offset:384
	v_cvt_pk_bf16_f32 v151, v188, v137
	ds_write_b16 v238, v151 offset:512
	v_cvt_pk_bf16_f32 v151, v189, v137
	ds_write_b16 v238, v151 offset:640
	v_cvt_pk_bf16_f32 v151, v186, v137
	ds_write_b16 v238, v151 offset:768
	v_cvt_pk_bf16_f32 v151, v187, v137
	ds_write_b16 v238, v151 offset:896
	v_cvt_pk_bf16_f32 v151, v212, v137
	ds_write_b16 v239, v151
	v_cvt_pk_bf16_f32 v151, v213, v137
	ds_write_b16 v239, v151 offset:128
	v_cvt_pk_bf16_f32 v151, v210, v137
	ds_write_b16 v239, v151 offset:256
	v_cvt_pk_bf16_f32 v151, v211, v137
	ds_write_b16 v239, v151 offset:384
	v_cvt_pk_bf16_f32 v151, v200, v137
	ds_write_b16 v239, v151 offset:512
	v_cvt_pk_bf16_f32 v151, v201, v137
	ds_write_b16 v239, v151 offset:640
	v_cvt_pk_bf16_f32 v151, v198, v137
	ds_write_b16 v239, v151 offset:768
	v_cvt_pk_bf16_f32 v151, v199, v137
	ds_write_b16 v239, v151 offset:896
	v_cvt_pk_bf16_f32 v151, v218, v137
	ds_write_b16 v240, v151
	v_cvt_pk_bf16_f32 v151, v219, v137
	ds_write_b16 v240, v151 offset:128
	v_cvt_pk_bf16_f32 v151, v216, v137
	ds_write_b16 v240, v151 offset:256
	v_cvt_pk_bf16_f32 v151, v217, v137
	ds_write_b16 v240, v151 offset:384
	v_cvt_pk_bf16_f32 v151, v214, v137
	ds_write_b16 v240, v151 offset:512
	v_cvt_pk_bf16_f32 v151, v215, v137
	ds_write_b16 v240, v151 offset:640
	v_cvt_pk_bf16_f32 v151, v196, v137
	ds_write_b16 v240, v151 offset:768
	v_cvt_pk_bf16_f32 v151, v197, v137
	ds_write_b16 v240, v151 offset:896
	s_waitcnt lgkmcnt(0)
	ds_read_b128 v[186:189], v241
	ds_read_b128 v[190:193], v242
	s_mov_b32 s61, s21
	v_lshl_add_u64 v[176:177], v[176:177], 0, s[60:61]
	v_lshl_add_u64 v[176:177], v[176:177], 0, s[36:37]
	v_mov_b32_e32 v181, v137
	v_lshl_add_u64 v[180:181], v[176:177], 0, v[180:181]
	v_mov_b32_e32 v183, v137
	s_waitcnt lgkmcnt(1)
	global_store_dwordx4 v[180:181], v[186:189], off
	v_mov_b32_e32 v179, v137
	v_mov_b32_e32 v185, v137
	v_lshl_add_u64 v[186:187], v[176:177], 0, v[182:183]
	ds_read_b128 v[180:183], v243
	s_waitcnt lgkmcnt(1)
	global_store_dwordx4 v[186:187], v[190:193], off
	ds_read_b128 v[186:189], v244
	v_lshl_add_u64 v[178:179], v[176:177], 0, v[178:179]
	v_lshl_add_u64 v[176:177], v[176:177], 0, v[184:185]
	s_waitcnt lgkmcnt(1)
	global_store_dwordx4 v[178:179], v[180:183], off
	s_waitcnt lgkmcnt(0)
	global_store_dwordx4 v[176:177], v[186:189], off
	s_waitcnt lgkmcnt(0)
	s_branch .LBB0_1460
.LBB0_1494:
	s_waitcnt lgkmcnt(7)
	v_mul_f32_e32 v120, v120, v174
	v_mul_f32_e32 v159, 0xbfb8aa3b, v120
	s_add_u32 s0, s58, s75
	v_exp_f32_e32 v159, v159
	s_addc_u32 s1, s59, 0
	v_mov_b32_e32 v151, v137
	v_lshl_add_u64 v[176:177], s[0:1], 0, v[150:151]
	s_ashr_i32 s0, s56, 31
	v_mul_lo_u32 v151, s53, v162
	s_mul_i32 s0, s52, s0
	v_mad_u64_u32 v[178:179], s[54:55], s52, v162, 0
	v_add3_u32 v179, v179, s0, v151
	v_add_f32_e32 v151, 1.0, v159
	v_rcp_f32_e32 v151, v151
	v_mul_f32_e32 v121, v121, v174
	v_mul_f32_e32 v159, 0xbfb8aa3b, v121
	v_exp_f32_e32 v159, v159
	v_mul_f32_e32 v151, v120, v151
	v_mul_f32_e32 v124, v124, v174
	v_cndmask_b32_e64 v120, v151, v120, s[10:11]
	v_mul_f32_e32 v120, v124, v120
	v_add_f32_e32 v124, 1.0, v159
	v_mul_f32_e32 v122, v122, v174
	v_rcp_f32_e32 v124, v124
	v_mul_f32_e32 v151, 0xbfb8aa3b, v122
	v_exp_f32_e32 v151, v151
	v_mul_f32_e32 v123, v123, v174
	v_mul_f32_e32 v124, v121, v124
	v_cndmask_b32_e64 v121, v124, v121, s[10:11]
	v_add_f32_e32 v124, 1.0, v151
	v_mul_f32_e32 v151, 0xbfb8aa3b, v123
	v_exp_f32_e32 v151, v151
	v_mul_f32_e32 v125, v125, v174
	v_rcp_f32_e32 v124, v124
	v_mul_f32_e32 v121, v125, v121
	v_mul_f32_e32 v125, v126, v174
	v_add_f32_e32 v126, 1.0, v151
	v_rcp_f32_e32 v126, v126
	v_mul_f32_e32 v124, v122, v124
	v_cndmask_b32_e64 v122, v124, v122, s[10:11]
	v_mul_f32_e32 v112, v112, v174
	v_mul_f32_e32 v122, v125, v122
	v_mul_f32_e32 v125, v123, v126
	v_mul_f32_e32 v126, 0xbfb8aa3b, v112
	v_exp_f32_e32 v126, v126
	v_mul_f32_e32 v124, v127, v174
	v_cndmask_b32_e64 v123, v125, v123, s[10:11]
	v_mul_f32_e32 v123, v124, v123
	v_add_f32_e32 v124, 1.0, v126
	v_rcp_f32_e32 v124, v124
	v_mul_f32_e32 v113, v113, v174
	v_mul_f32_e32 v125, 0xbfb8aa3b, v113
	v_exp_f32_e32 v125, v125
	v_mul_f32_e32 v124, v112, v124
	v_mul_f32_e32 v116, v116, v174
	v_cndmask_b32_e64 v112, v124, v112, s[10:11]
	v_mul_f32_e32 v124, v116, v112
	v_add_f32_e32 v112, 1.0, v125
	v_mul_f32_e32 v114, v114, v174
	v_rcp_f32_e32 v112, v112
	v_mul_f32_e32 v116, 0xbfb8aa3b, v114
	v_exp_f32_e32 v116, v116
	v_mul_f32_e32 v115, v115, v174
	v_mul_f32_e32 v112, v113, v112
	v_cndmask_b32_e64 v112, v112, v113, s[10:11]
	v_add_f32_e32 v113, 1.0, v116
	v_mul_f32_e32 v116, 0xbfb8aa3b, v115
	v_exp_f32_e32 v116, v116
	v_rcp_f32_e32 v113, v113
	v_mul_f32_e32 v117, v117, v174
	v_mul_f32_e32 v125, v117, v112
	v_add_f32_e32 v116, 1.0, v116
	v_rcp_f32_e32 v116, v116
	v_mul_f32_e32 v113, v114, v113
	v_mul_f32_e32 v112, v118, v174
	v_cndmask_b32_e64 v113, v113, v114, s[10:11]
	v_mul_f32_e32 v118, v112, v113
	v_mul_f32_e32 v113, v115, v116
	v_mul_f32_e32 v112, v119, v174
	v_cndmask_b32_e64 v113, v113, v115, s[10:11]
	v_mul_f32_e32 v115, v112, v113
	v_lshl_add_u64 v[116:117], v[178:179], 1, v[176:177]
	v_cvt_pk_bf16_f32 v112, v120, v121
	v_cvt_pk_bf16_f32 v113, v122, v123
	v_cvt_pk_bf16_f32 v114, v124, v125
	v_cvt_pk_bf16_f32 v115, v118, v115
	global_store_dwordx4 v[116:117], v[112:115], off
	s_waitcnt lgkmcnt(6)
; __device__ __forceinline__ unsigned cvt_pk_bf16(float lo, float hi) { unsigned r; asm("v_cvt_pk_bf16_f32 %0, %1, %2" : "=v"(r) : "v"(lo), "v"(hi)); return r; }
; __device__ __forceinline__ float silu_f(float x) { return x * __builtin_amdgcn_rcpf(1.f + __builtin_amdgcn_exp2f(-LOG2E * x)); }
;     __device__ __forceinline__ void operator()(const f32x4 (&acc)[2][2][4][2], const Unit& u, int wr, int wc, int fr, int fq, LAS unsigned char* xs, int wid, int lane) const {
;     ...
;         } else if (mode == 1 || mode == 2) {
; #pragma unroll
;             for (int ai = 0; ai < 2; ++ai)
; #pragma unroll
;                 for (int m = 0; m < 4; ++m) {
;                     const float r = rs[ai][m];
;                     bf16_t* rowp = base + (size_t)(row0 + ai * 128 + m * 16 + fr) * ldc + wc * 32 + 8 * fq;
;                     float o[8];
; #pragma unroll
;                     for (int n = 0; n < 2; ++n)
; #pragma unroll
;                         for (int j = 0; j < 4; ++j) { const float a = acc[ai][0][m][n][j] * r, b = acc[ai][1][m][n][j] * r; o[4 * n + j] = (mode == 1) ? a * b : a * silu_f(b); }
;                     u32x4 w; w.x = cvt_pk_bf16(o[0], o[1]); w.y = cvt_pk_bf16(o[2], o[3]); w.z = cvt_pk_bf16(o[4], o[5]); w.w = cvt_pk_bf16(o[6], o[7]);
;                     *(u32x4*)rowp = w;
;                     __builtin_amdgcn_sched_barrier(0);
;                 }
	v_mul_f32_e32 v104, v104, v172
	v_mul_f32_e32 v113, 0xbfb8aa3b, v104
	v_exp_f32_e32 v115, v113
	v_or_b32_e32 v112, 16, v162
	v_mul_lo_u32 v114, s53, v112
	v_mad_u64_u32 v[112:113], s[54:55], s52, v112, 0
	v_add3_u32 v113, v113, s0, v114
	v_add_f32_e32 v114, 1.0, v115
	v_rcp_f32_e32 v114, v114
	v_mul_f32_e32 v105, v105, v172
	v_mul_f32_e32 v115, 0xbfb8aa3b, v105
	v_exp_f32_e32 v115, v115
	v_mul_f32_e32 v114, v104, v114
	v_mul_f32_e32 v108, v108, v172
	v_cndmask_b32_e64 v104, v114, v104, s[10:11]
	v_mul_f32_e32 v104, v108, v104
	v_add_f32_e32 v108, 1.0, v115
	v_mul_f32_e32 v106, v106, v172
	v_rcp_f32_e32 v108, v108
	v_mul_f32_e32 v114, 0xbfb8aa3b, v106
	v_exp_f32_e32 v114, v114
	v_mul_f32_e32 v107, v107, v172
	v_mul_f32_e32 v108, v105, v108
	v_cndmask_b32_e64 v105, v108, v105, s[10:11]
	v_add_f32_e32 v108, 1.0, v114
	v_mul_f32_e32 v114, 0xbfb8aa3b, v107
	v_exp_f32_e32 v114, v114
	v_mul_f32_e32 v109, v109, v172
	v_rcp_f32_e32 v108, v108
	v_mul_f32_e32 v105, v109, v105
	v_mul_f32_e32 v109, v110, v172
	v_add_f32_e32 v110, 1.0, v114
	v_rcp_f32_e32 v110, v110
	v_mul_f32_e32 v108, v106, v108
	v_cndmask_b32_e64 v106, v108, v106, s[10:11]
	v_mul_f32_e32 v96, v96, v172
	v_mul_f32_e32 v106, v109, v106
	v_mul_f32_e32 v109, v107, v110
	v_mul_f32_e32 v110, 0xbfb8aa3b, v96
	v_exp_f32_e32 v110, v110
	v_mul_f32_e32 v108, v111, v172
	v_cndmask_b32_e64 v107, v109, v107, s[10:11]
	v_mul_f32_e32 v107, v108, v107
	v_add_f32_e32 v108, 1.0, v110
	v_rcp_f32_e32 v108, v108
	v_mul_f32_e32 v97, v97, v172
	v_mul_f32_e32 v109, 0xbfb8aa3b, v97
	v_exp_f32_e32 v109, v109
	v_mul_f32_e32 v108, v96, v108
	v_mul_f32_e32 v100, v100, v172
	v_cndmask_b32_e64 v96, v108, v96, s[10:11]
	v_mul_f32_e32 v108, v100, v96
	v_add_f32_e32 v96, 1.0, v109
	v_mul_f32_e32 v98, v98, v172
	v_rcp_f32_e32 v96, v96
	v_mul_f32_e32 v100, 0xbfb8aa3b, v98
	v_exp_f32_e32 v100, v100
	v_mul_f32_e32 v99, v99, v172
	v_mul_f32_e32 v96, v97, v96
	v_cndmask_b32_e64 v96, v96, v97, s[10:11]
	v_add_f32_e32 v97, 1.0, v100
	v_mul_f32_e32 v100, 0xbfb8aa3b, v99
	v_exp_f32_e32 v100, v100
	v_rcp_f32_e32 v97, v97
	v_mul_f32_e32 v101, v101, v172
	v_mul_f32_e32 v109, v101, v96
	v_add_f32_e32 v100, 1.0, v100
	v_rcp_f32_e32 v100, v100
	v_mul_f32_e32 v97, v98, v97
	v_mul_f32_e32 v96, v102, v172
	v_cndmask_b32_e64 v97, v97, v98, s[10:11]
	v_mul_f32_e32 v102, v96, v97
	v_mul_f32_e32 v97, v99, v100
	v_mul_f32_e32 v96, v103, v172
	v_cndmask_b32_e64 v97, v97, v99, s[10:11]
	v_mul_f32_e32 v99, v96, v97
	v_lshl_add_u64 v[100:101], v[112:113], 1, v[176:177]
	v_cvt_pk_bf16_f32 v96, v104, v105
	v_cvt_pk_bf16_f32 v97, v106, v107
	v_cvt_pk_bf16_f32 v98, v108, v109
	v_cvt_pk_bf16_f32 v99, v102, v99
	global_store_dwordx4 v[100:101], v[96:99], off
	s_waitcnt lgkmcnt(5)
	v_mul_f32_e32 v88, v88, v170
	v_mul_f32_e32 v97, 0xbfb8aa3b, v88
	v_exp_f32_e32 v99, v97
	v_or_b32_e32 v96, 32, v162
	v_mul_lo_u32 v98, s53, v96
	v_mad_u64_u32 v[96:97], s[54:55], s52, v96, 0
	v_add3_u32 v97, v97, s0, v98
	v_add_f32_e32 v98, 1.0, v99
	v_rcp_f32_e32 v98, v98
	v_mul_f32_e32 v89, v89, v170
	v_mul_f32_e32 v99, 0xbfb8aa3b, v89
	v_exp_f32_e32 v99, v99
	v_mul_f32_e32 v98, v88, v98
	v_mul_f32_e32 v92, v92, v170
	v_cndmask_b32_e64 v88, v98, v88, s[10:11]
	v_mul_f32_e32 v88, v92, v88
	v_add_f32_e32 v92, 1.0, v99
	v_mul_f32_e32 v90, v90, v170
	v_rcp_f32_e32 v92, v92
	v_mul_f32_e32 v98, 0xbfb8aa3b, v90
	v_exp_f32_e32 v98, v98
	v_mul_f32_e32 v91, v91, v170
	v_mul_f32_e32 v92, v89, v92
	v_cndmask_b32_e64 v89, v92, v89, s[10:11]
	v_add_f32_e32 v92, 1.0, v98
	v_mul_f32_e32 v98, 0xbfb8aa3b, v91
	v_exp_f32_e32 v98, v98
	v_mul_f32_e32 v93, v93, v170
	v_rcp_f32_e32 v92, v92
	v_mul_f32_e32 v89, v93, v89
	v_mul_f32_e32 v93, v94, v170
	v_add_f32_e32 v94, 1.0, v98
	v_rcp_f32_e32 v94, v94
	v_mul_f32_e32 v92, v90, v92
	v_cndmask_b32_e64 v90, v92, v90, s[10:11]
	v_mul_f32_e32 v80, v80, v170
	v_mul_f32_e32 v90, v93, v90
	v_mul_f32_e32 v93, v91, v94
	v_mul_f32_e32 v94, 0xbfb8aa3b, v80
	v_exp_f32_e32 v94, v94
	v_mul_f32_e32 v92, v95, v170
	v_cndmask_b32_e64 v91, v93, v91, s[10:11]
	v_mul_f32_e32 v91, v92, v91
	v_add_f32_e32 v92, 1.0, v94
	v_rcp_f32_e32 v92, v92
	v_mul_f32_e32 v81, v81, v170
	v_mul_f32_e32 v93, 0xbfb8aa3b, v81
	v_exp_f32_e32 v93, v93
	v_mul_f32_e32 v92, v80, v92
	v_mul_f32_e32 v84, v84, v170
	v_cndmask_b32_e64 v80, v92, v80, s[10:11]
	v_mul_f32_e32 v92, v84, v80
	v_add_f32_e32 v80, 1.0, v93
	v_mul_f32_e32 v82, v82, v170
	v_rcp_f32_e32 v80, v80
	v_mul_f32_e32 v84, 0xbfb8aa3b, v82
	v_exp_f32_e32 v84, v84
	v_mul_f32_e32 v83, v83, v170
	v_mul_f32_e32 v80, v81, v80
	v_cndmask_b32_e64 v80, v80, v81, s[10:11]
	v_add_f32_e32 v81, 1.0, v84
	v_mul_f32_e32 v84, 0xbfb8aa3b, v83
	v_exp_f32_e32 v84, v84
	v_rcp_f32_e32 v81, v81
	v_mul_f32_e32 v85, v85, v170
	v_mul_f32_e32 v93, v85, v80
	v_add_f32_e32 v84, 1.0, v84
	v_rcp_f32_e32 v84, v84
	v_mul_f32_e32 v81, v82, v81
	v_mul_f32_e32 v80, v86, v170
	v_cndmask_b32_e64 v81, v81, v82, s[10:11]
	v_mul_f32_e32 v86, v80, v81
	v_mul_f32_e32 v81, v83, v84
	v_mul_f32_e32 v80, v87, v170
	v_cndmask_b32_e64 v81, v81, v83, s[10:11]
	v_mul_f32_e32 v83, v80, v81
	v_lshl_add_u64 v[84:85], v[96:97], 1, v[176:177]
	v_cvt_pk_bf16_f32 v80, v88, v89
	v_cvt_pk_bf16_f32 v81, v90, v91
	v_cvt_pk_bf16_f32 v82, v92, v93
	v_cvt_pk_bf16_f32 v83, v86, v83
	global_store_dwordx4 v[84:85], v[80:83], off
	s_waitcnt lgkmcnt(4)
; __device__ __forceinline__ unsigned cvt_pk_bf16(float lo, float hi) { unsigned r; asm("v_cvt_pk_bf16_f32 %0, %1, %2" : "=v"(r) : "v"(lo), "v"(hi)); return r; }
; __device__ __forceinline__ float silu_f(float x) { return x * __builtin_amdgcn_rcpf(1.f + __builtin_amdgcn_exp2f(-LOG2E * x)); }
;     __device__ __forceinline__ void operator()(const f32x4 (&acc)[2][2][4][2], const Unit& u, int wr, int wc, int fr, int fq, LAS unsigned char* xs, int wid, int lane) const {
;     ...
;         } else if (mode == 1 || mode == 2) {
; #pragma unroll
;             for (int ai = 0; ai < 2; ++ai)
; #pragma unroll
;                 for (int m = 0; m < 4; ++m) {
;                     const float r = rs[ai][m];
;                     bf16_t* rowp = base + (size_t)(row0 + ai * 128 + m * 16 + fr) * ldc + wc * 32 + 8 * fq;
;                     float o[8];
; #pragma unroll
;                     for (int n = 0; n < 2; ++n)
; #pragma unroll
;                         for (int j = 0; j < 4; ++j) { const float a = acc[ai][0][m][n][j] * r, b = acc[ai][1][m][n][j] * r; o[4 * n + j] = (mode == 1) ? a * b : a * silu_f(b); }
;                     u32x4 w; w.x = cvt_pk_bf16(o[0], o[1]); w.y = cvt_pk_bf16(o[2], o[3]); w.z = cvt_pk_bf16(o[4], o[5]); w.w = cvt_pk_bf16(o[6], o[7]);
;                     *(u32x4*)rowp = w;
;                     __builtin_amdgcn_sched_barrier(0);
;                 }
	v_mul_f32_e32 v72, v72, v168
	v_mul_f32_e32 v81, 0xbfb8aa3b, v72
	v_exp_f32_e32 v83, v81
	v_or_b32_e32 v80, 48, v162
	v_mul_lo_u32 v82, s53, v80
	v_mad_u64_u32 v[80:81], s[54:55], s52, v80, 0
	v_add3_u32 v81, v81, s0, v82
	v_add_f32_e32 v82, 1.0, v83
	v_rcp_f32_e32 v82, v82
	v_mul_f32_e32 v73, v73, v168
	v_mul_f32_e32 v83, 0xbfb8aa3b, v73
	v_exp_f32_e32 v83, v83
	v_mul_f32_e32 v82, v72, v82
	v_mul_f32_e32 v76, v76, v168
	v_cndmask_b32_e64 v72, v82, v72, s[10:11]
	v_mul_f32_e32 v72, v76, v72
	v_add_f32_e32 v76, 1.0, v83
	v_mul_f32_e32 v74, v74, v168
	v_rcp_f32_e32 v76, v76
	v_mul_f32_e32 v82, 0xbfb8aa3b, v74
	v_exp_f32_e32 v82, v82
	v_mul_f32_e32 v75, v75, v168
	v_mul_f32_e32 v76, v73, v76
	v_cndmask_b32_e64 v73, v76, v73, s[10:11]
	v_add_f32_e32 v76, 1.0, v82
	v_mul_f32_e32 v82, 0xbfb8aa3b, v75
	v_exp_f32_e32 v82, v82
	v_mul_f32_e32 v77, v77, v168
	v_rcp_f32_e32 v76, v76
	v_mul_f32_e32 v73, v77, v73
	v_mul_f32_e32 v77, v78, v168
	v_add_f32_e32 v78, 1.0, v82
	v_rcp_f32_e32 v78, v78
	v_mul_f32_e32 v76, v74, v76
	v_cndmask_b32_e64 v74, v76, v74, s[10:11]
	v_mul_f32_e32 v64, v64, v168
	v_mul_f32_e32 v74, v77, v74
	v_mul_f32_e32 v77, v75, v78
	v_mul_f32_e32 v78, 0xbfb8aa3b, v64
	v_exp_f32_e32 v78, v78
	v_mul_f32_e32 v76, v79, v168
	v_cndmask_b32_e64 v75, v77, v75, s[10:11]
	v_mul_f32_e32 v75, v76, v75
	v_add_f32_e32 v76, 1.0, v78
	v_rcp_f32_e32 v76, v76
	v_mul_f32_e32 v65, v65, v168
	v_mul_f32_e32 v77, 0xbfb8aa3b, v65
	v_exp_f32_e32 v77, v77
	v_mul_f32_e32 v76, v64, v76
	v_mul_f32_e32 v68, v68, v168
	v_cndmask_b32_e64 v64, v76, v64, s[10:11]
	v_mul_f32_e32 v76, v68, v64
	v_add_f32_e32 v64, 1.0, v77
	v_mul_f32_e32 v66, v66, v168
	v_rcp_f32_e32 v64, v64
	v_mul_f32_e32 v68, 0xbfb8aa3b, v66
	v_exp_f32_e32 v68, v68
	v_mul_f32_e32 v67, v67, v168
	v_mul_f32_e32 v64, v65, v64
	v_cndmask_b32_e64 v64, v64, v65, s[10:11]
	v_add_f32_e32 v65, 1.0, v68
	v_mul_f32_e32 v68, 0xbfb8aa3b, v67
	v_exp_f32_e32 v68, v68
	v_rcp_f32_e32 v65, v65
	v_mul_f32_e32 v69, v69, v168
	v_mul_f32_e32 v77, v69, v64
	v_add_f32_e32 v68, 1.0, v68
	v_rcp_f32_e32 v68, v68
	v_mul_f32_e32 v65, v66, v65
	v_mul_f32_e32 v64, v70, v168
	v_cndmask_b32_e64 v65, v65, v66, s[10:11]
	v_mul_f32_e32 v70, v64, v65
	v_mul_f32_e32 v65, v67, v68
	v_mul_f32_e32 v64, v71, v168
	v_cndmask_b32_e64 v65, v65, v67, s[10:11]
	v_mul_f32_e32 v67, v64, v65
	v_lshl_add_u64 v[68:69], v[80:81], 1, v[176:177]
	v_cvt_pk_bf16_f32 v64, v72, v73
	v_cvt_pk_bf16_f32 v65, v74, v75
	v_cvt_pk_bf16_f32 v66, v76, v77
	v_cvt_pk_bf16_f32 v67, v70, v67
	global_store_dwordx4 v[68:69], v[64:67], off
	s_nop 1
	v_add_u32_e32 v64, 0x80, v162
	v_ashrrev_i32_e32 v65, 31, v64
	s_waitcnt lgkmcnt(3)
	v_mul_f32_e32 v56, v56, v166
	v_mul_lo_u32 v66, s52, v65
	v_mul_f32_e32 v65, 0xbfb8aa3b, v56
	v_exp_f32_e32 v68, v65
	v_mul_lo_u32 v67, s53, v64
	v_mad_u64_u32 v[64:65], s[0:1], s52, v64, 0
	v_add3_u32 v65, v65, v66, v67
	v_add_f32_e32 v66, 1.0, v68
	v_rcp_f32_e32 v66, v66
	v_mul_f32_e32 v57, v57, v166
	v_mul_f32_e32 v67, 0xbfb8aa3b, v57
	v_exp_f32_e32 v67, v67
	v_mul_f32_e32 v66, v56, v66
	v_mul_f32_e32 v60, v60, v166
	v_cndmask_b32_e64 v56, v66, v56, s[10:11]
	v_mul_f32_e32 v56, v60, v56
	v_add_f32_e32 v60, 1.0, v67
	v_mul_f32_e32 v58, v58, v166
	v_rcp_f32_e32 v60, v60
	v_mul_f32_e32 v66, 0xbfb8aa3b, v58
	v_exp_f32_e32 v66, v66
	v_mul_f32_e32 v59, v59, v166
	v_mul_f32_e32 v60, v57, v60
	v_cndmask_b32_e64 v57, v60, v57, s[10:11]
	v_add_f32_e32 v60, 1.0, v66
	v_mul_f32_e32 v66, 0xbfb8aa3b, v59
	v_exp_f32_e32 v66, v66
	v_mul_f32_e32 v61, v61, v166
	v_rcp_f32_e32 v60, v60
	v_mul_f32_e32 v57, v61, v57
	v_mul_f32_e32 v61, v62, v166
	v_add_f32_e32 v62, 1.0, v66
	v_rcp_f32_e32 v62, v62
	v_mul_f32_e32 v60, v58, v60
	v_cndmask_b32_e64 v58, v60, v58, s[10:11]
	v_mul_f32_e32 v48, v48, v166
	v_mul_f32_e32 v58, v61, v58
	v_mul_f32_e32 v61, v59, v62
	v_mul_f32_e32 v62, 0xbfb8aa3b, v48
	v_exp_f32_e32 v62, v62
	v_mul_f32_e32 v60, v63, v166
	v_cndmask_b32_e64 v59, v61, v59, s[10:11]
	v_mul_f32_e32 v59, v60, v59
	v_add_f32_e32 v60, 1.0, v62
	v_rcp_f32_e32 v60, v60
	v_mul_f32_e32 v49, v49, v166
	v_mul_f32_e32 v61, 0xbfb8aa3b, v49
	v_exp_f32_e32 v61, v61
	v_mul_f32_e32 v60, v48, v60
	v_mul_f32_e32 v52, v52, v166
	v_cndmask_b32_e64 v48, v60, v48, s[10:11]
	v_mul_f32_e32 v60, v52, v48
	v_add_f32_e32 v48, 1.0, v61
	v_mul_f32_e32 v50, v50, v166
	v_rcp_f32_e32 v48, v48
	v_mul_f32_e32 v52, 0xbfb8aa3b, v50
	v_exp_f32_e32 v52, v52
	v_mul_f32_e32 v51, v51, v166
	v_mul_f32_e32 v48, v49, v48
	v_cndmask_b32_e64 v48, v48, v49, s[10:11]
	v_add_f32_e32 v49, 1.0, v52
	v_mul_f32_e32 v52, 0xbfb8aa3b, v51
	v_exp_f32_e32 v52, v52
	v_rcp_f32_e32 v49, v49
	v_mul_f32_e32 v53, v53, v166
	v_mul_f32_e32 v61, v53, v48
	v_add_f32_e32 v52, 1.0, v52
	v_rcp_f32_e32 v52, v52
	v_mul_f32_e32 v49, v50, v49
	v_mul_f32_e32 v48, v54, v166
	v_cndmask_b32_e64 v49, v49, v50, s[10:11]
	v_mul_f32_e32 v54, v48, v49
	v_mul_f32_e32 v49, v51, v52
	v_mul_f32_e32 v48, v55, v166
	v_cndmask_b32_e64 v49, v49, v51, s[10:11]
	v_mul_f32_e32 v51, v48, v49
	v_lshl_add_u64 v[52:53], v[64:65], 1, v[176:177]
	v_cvt_pk_bf16_f32 v48, v56, v57
	v_cvt_pk_bf16_f32 v49, v58, v59
	v_cvt_pk_bf16_f32 v50, v60, v61
	v_cvt_pk_bf16_f32 v51, v54, v51
	global_store_dwordx4 v[52:53], v[48:51], off
	s_nop 1
	v_add_u32_e32 v48, 0x90, v162
	v_ashrrev_i32_e32 v49, 31, v48
	s_waitcnt lgkmcnt(2)
; __device__ __forceinline__ unsigned cvt_pk_bf16(float lo, float hi) { unsigned r; asm("v_cvt_pk_bf16_f32 %0, %1, %2" : "=v"(r) : "v"(lo), "v"(hi)); return r; }
; __device__ __forceinline__ float silu_f(float x) { return x * __builtin_amdgcn_rcpf(1.f + __builtin_amdgcn_exp2f(-LOG2E * x)); }
;     __device__ __forceinline__ void operator()(const f32x4 (&acc)[2][2][4][2], const Unit& u, int wr, int wc, int fr, int fq, LAS unsigned char* xs, int wid, int lane) const {
;     ...
;         } else if (mode == 1 || mode == 2) {
; #pragma unroll
;             for (int ai = 0; ai < 2; ++ai)
; #pragma unroll
;                 for (int m = 0; m < 4; ++m) {
;                     const float r = rs[ai][m];
;                     bf16_t* rowp = base + (size_t)(row0 + ai * 128 + m * 16 + fr) * ldc + wc * 32 + 8 * fq;
;                     float o[8];
; #pragma unroll
;                     for (int n = 0; n < 2; ++n)
; #pragma unroll
;                         for (int j = 0; j < 4; ++j) { const float a = acc[ai][0][m][n][j] * r, b = acc[ai][1][m][n][j] * r; o[4 * n + j] = (mode == 1) ? a * b : a * silu_f(b); }
;                     u32x4 w; w.x = cvt_pk_bf16(o[0], o[1]); w.y = cvt_pk_bf16(o[2], o[3]); w.z = cvt_pk_bf16(o[4], o[5]); w.w = cvt_pk_bf16(o[6], o[7]);
;                     *(u32x4*)rowp = w;
;                     __builtin_amdgcn_sched_barrier(0);
;                 }
	v_mul_f32_e32 v40, v40, v164
	v_mul_lo_u32 v50, s52, v49
	v_mul_f32_e32 v49, 0xbfb8aa3b, v40
	v_exp_f32_e32 v52, v49
	v_mul_lo_u32 v51, s53, v48
	v_mad_u64_u32 v[48:49], s[0:1], s52, v48, 0
	v_add3_u32 v49, v49, v50, v51
	v_add_f32_e32 v50, 1.0, v52
	v_rcp_f32_e32 v50, v50
	v_mul_f32_e32 v41, v41, v164
	v_mul_f32_e32 v51, 0xbfb8aa3b, v41
	v_exp_f32_e32 v51, v51
	v_mul_f32_e32 v50, v40, v50
	v_mul_f32_e32 v44, v44, v164
	v_cndmask_b32_e64 v40, v50, v40, s[10:11]
	v_mul_f32_e32 v40, v44, v40
	v_add_f32_e32 v44, 1.0, v51
	v_mul_f32_e32 v42, v42, v164
	v_rcp_f32_e32 v44, v44
	v_mul_f32_e32 v50, 0xbfb8aa3b, v42
	v_exp_f32_e32 v50, v50
	v_mul_f32_e32 v43, v43, v164
	v_mul_f32_e32 v44, v41, v44
	v_cndmask_b32_e64 v41, v44, v41, s[10:11]
	v_add_f32_e32 v44, 1.0, v50
	v_mul_f32_e32 v50, 0xbfb8aa3b, v43
	v_exp_f32_e32 v50, v50
	v_mul_f32_e32 v45, v45, v164
	v_rcp_f32_e32 v44, v44
	v_mul_f32_e32 v41, v45, v41
	v_mul_f32_e32 v45, v46, v164
	v_add_f32_e32 v46, 1.0, v50
	v_rcp_f32_e32 v46, v46
	v_mul_f32_e32 v44, v42, v44
	v_cndmask_b32_e64 v42, v44, v42, s[10:11]
	v_mul_f32_e32 v32, v32, v164
	v_mul_f32_e32 v42, v45, v42
	v_mul_f32_e32 v45, v43, v46
	v_mul_f32_e32 v46, 0xbfb8aa3b, v32
	v_exp_f32_e32 v46, v46
	v_mul_f32_e32 v44, v47, v164
	v_cndmask_b32_e64 v43, v45, v43, s[10:11]
	v_mul_f32_e32 v43, v44, v43
	v_add_f32_e32 v44, 1.0, v46
	v_rcp_f32_e32 v44, v44
	v_mul_f32_e32 v33, v33, v164
	v_mul_f32_e32 v45, 0xbfb8aa3b, v33
	v_exp_f32_e32 v45, v45
	v_mul_f32_e32 v44, v32, v44
	v_mul_f32_e32 v36, v36, v164
	v_cndmask_b32_e64 v32, v44, v32, s[10:11]
	v_mul_f32_e32 v44, v36, v32
	v_add_f32_e32 v32, 1.0, v45
	v_mul_f32_e32 v34, v34, v164
	v_rcp_f32_e32 v32, v32
	v_mul_f32_e32 v36, 0xbfb8aa3b, v34
	v_exp_f32_e32 v36, v36
	v_mul_f32_e32 v35, v35, v164
	v_mul_f32_e32 v32, v33, v32
	v_cndmask_b32_e64 v32, v32, v33, s[10:11]
	v_add_f32_e32 v33, 1.0, v36
	v_mul_f32_e32 v36, 0xbfb8aa3b, v35
	v_exp_f32_e32 v36, v36
	v_rcp_f32_e32 v33, v33
	v_mul_f32_e32 v37, v37, v164
	v_mul_f32_e32 v45, v37, v32
	v_add_f32_e32 v36, 1.0, v36
	v_rcp_f32_e32 v36, v36
	v_mul_f32_e32 v33, v34, v33
	v_mul_f32_e32 v32, v38, v164
	v_cndmask_b32_e64 v33, v33, v34, s[10:11]
	v_mul_f32_e32 v38, v32, v33
	v_mul_f32_e32 v33, v35, v36
	v_mul_f32_e32 v32, v39, v164
	v_cndmask_b32_e64 v33, v33, v35, s[10:11]
	v_mul_f32_e32 v35, v32, v33
	v_lshl_add_u64 v[36:37], v[48:49], 1, v[176:177]
	v_cvt_pk_bf16_f32 v32, v40, v41
	v_cvt_pk_bf16_f32 v33, v42, v43
	v_cvt_pk_bf16_f32 v34, v44, v45
	v_cvt_pk_bf16_f32 v35, v38, v35
	global_store_dwordx4 v[36:37], v[32:35], off
	s_nop 1
	v_add_u32_e32 v32, 0xa0, v162
	v_ashrrev_i32_e32 v33, 31, v32
	s_waitcnt lgkmcnt(1)
; __device__ __forceinline__ unsigned cvt_pk_bf16(float lo, float hi) { unsigned r; asm("v_cvt_pk_bf16_f32 %0, %1, %2" : "=v"(r) : "v"(lo), "v"(hi)); return r; }
; __device__ __forceinline__ float silu_f(float x) { return x * __builtin_amdgcn_rcpf(1.f + __builtin_amdgcn_exp2f(-LOG2E * x)); }
;     __device__ __forceinline__ void operator()(const f32x4 (&acc)[2][2][4][2], const Unit& u, int wr, int wc, int fr, int fq, LAS unsigned char* xs, int wid, int lane) const {
;     ...
;         } else if (mode == 1 || mode == 2) {
; #pragma unroll
;             for (int ai = 0; ai < 2; ++ai)
; #pragma unroll
;                 for (int m = 0; m < 4; ++m) {
;                     const float r = rs[ai][m];
;                     bf16_t* rowp = base + (size_t)(row0 + ai * 128 + m * 16 + fr) * ldc + wc * 32 + 8 * fq;
;                     float o[8];
; #pragma unroll
;                     for (int n = 0; n < 2; ++n)
; #pragma unroll
;                         for (int j = 0; j < 4; ++j) { const float a = acc[ai][0][m][n][j] * r, b = acc[ai][1][m][n][j] * r; o[4 * n + j] = (mode == 1) ? a * b : a * silu_f(b); }
;                     u32x4 w; w.x = cvt_pk_bf16(o[0], o[1]); w.y = cvt_pk_bf16(o[2], o[3]); w.z = cvt_pk_bf16(o[4], o[5]); w.w = cvt_pk_bf16(o[6], o[7]);
;                     *(u32x4*)rowp = w;
;                     __builtin_amdgcn_sched_barrier(0);
;                 }
	v_mul_f32_e32 v24, v24, v160
	v_mul_lo_u32 v34, s52, v33
	v_mul_f32_e32 v33, 0xbfb8aa3b, v24
	v_exp_f32_e32 v36, v33
	v_mul_lo_u32 v35, s53, v32
	v_mad_u64_u32 v[32:33], s[0:1], s52, v32, 0
	v_add3_u32 v33, v33, v34, v35
	v_add_f32_e32 v34, 1.0, v36
	v_rcp_f32_e32 v34, v34
	v_mul_f32_e32 v25, v25, v160
	v_mul_f32_e32 v35, 0xbfb8aa3b, v25
	v_exp_f32_e32 v35, v35
	v_mul_f32_e32 v34, v24, v34
	v_mul_f32_e32 v28, v28, v160
	v_cndmask_b32_e64 v24, v34, v24, s[10:11]
	v_mul_f32_e32 v24, v28, v24
	v_add_f32_e32 v28, 1.0, v35
	v_mul_f32_e32 v26, v26, v160
	v_rcp_f32_e32 v28, v28
	v_mul_f32_e32 v34, 0xbfb8aa3b, v26
	v_exp_f32_e32 v34, v34
	v_mul_f32_e32 v27, v27, v160
	v_mul_f32_e32 v28, v25, v28
	v_cndmask_b32_e64 v25, v28, v25, s[10:11]
	v_add_f32_e32 v28, 1.0, v34
	v_mul_f32_e32 v34, 0xbfb8aa3b, v27
	v_exp_f32_e32 v34, v34
	v_mul_f32_e32 v29, v29, v160
	v_rcp_f32_e32 v28, v28
	v_mul_f32_e32 v25, v29, v25
	v_mul_f32_e32 v29, v30, v160
	v_add_f32_e32 v30, 1.0, v34
	v_rcp_f32_e32 v30, v30
	v_mul_f32_e32 v28, v26, v28
	v_cndmask_b32_e64 v26, v28, v26, s[10:11]
	v_mul_f32_e32 v16, v16, v160
	v_mul_f32_e32 v26, v29, v26
	v_mul_f32_e32 v29, v27, v30
	v_mul_f32_e32 v30, 0xbfb8aa3b, v16
	v_exp_f32_e32 v30, v30
	v_mul_f32_e32 v28, v31, v160
	v_cndmask_b32_e64 v27, v29, v27, s[10:11]
	v_mul_f32_e32 v27, v28, v27
	v_add_f32_e32 v28, 1.0, v30
	v_rcp_f32_e32 v28, v28
	v_mul_f32_e32 v17, v17, v160
	v_mul_f32_e32 v29, 0xbfb8aa3b, v17
	v_exp_f32_e32 v29, v29
	v_mul_f32_e32 v28, v16, v28
	v_mul_f32_e32 v20, v20, v160
	v_cndmask_b32_e64 v16, v28, v16, s[10:11]
	v_mul_f32_e32 v28, v20, v16
	v_add_f32_e32 v16, 1.0, v29
	v_mul_f32_e32 v18, v18, v160
	v_rcp_f32_e32 v16, v16
	v_mul_f32_e32 v20, 0xbfb8aa3b, v18
	v_exp_f32_e32 v20, v20
	v_mul_f32_e32 v19, v19, v160
	v_mul_f32_e32 v16, v17, v16
	v_cndmask_b32_e64 v16, v16, v17, s[10:11]
	v_add_f32_e32 v17, 1.0, v20
	v_mul_f32_e32 v20, 0xbfb8aa3b, v19
	v_exp_f32_e32 v20, v20
	v_rcp_f32_e32 v17, v17
	v_mul_f32_e32 v21, v21, v160
	v_mul_f32_e32 v29, v21, v16
	v_add_f32_e32 v20, 1.0, v20
	v_rcp_f32_e32 v20, v20
	v_mul_f32_e32 v17, v18, v17
	v_mul_f32_e32 v16, v22, v160
	v_cndmask_b32_e64 v17, v17, v18, s[10:11]
	v_mul_f32_e32 v22, v16, v17
	v_mul_f32_e32 v17, v19, v20
	v_mul_f32_e32 v16, v23, v160
	v_cndmask_b32_e64 v17, v17, v19, s[10:11]
	v_mul_f32_e32 v19, v16, v17
	v_lshl_add_u64 v[20:21], v[32:33], 1, v[176:177]
	v_cvt_pk_bf16_f32 v16, v24, v25
	v_cvt_pk_bf16_f32 v17, v26, v27
	v_cvt_pk_bf16_f32 v18, v28, v29
	v_cvt_pk_bf16_f32 v19, v22, v19
	global_store_dwordx4 v[20:21], v[16:19], off
	s_nop 1
	v_add_u32_e32 v16, 0xb0, v162
	v_ashrrev_i32_e32 v17, 31, v16
	s_waitcnt lgkmcnt(0)
	v_mul_f32_e32 v8, v8, v158
	v_mul_lo_u32 v18, s52, v17
	v_mul_f32_e32 v17, 0xbfb8aa3b, v8
	v_exp_f32_e32 v20, v17
	v_mul_lo_u32 v19, s53, v16
	v_mad_u64_u32 v[16:17], s[0:1], s52, v16, 0
	v_add3_u32 v17, v17, v18, v19
	v_add_f32_e32 v18, 1.0, v20
	v_rcp_f32_e32 v18, v18
	v_mul_f32_e32 v9, v9, v158
	v_mul_f32_e32 v19, 0xbfb8aa3b, v9
	v_exp_f32_e32 v19, v19
	v_mul_f32_e32 v18, v8, v18
	v_mul_f32_e32 v12, v12, v158
	v_cndmask_b32_e64 v8, v18, v8, s[10:11]
	v_mul_f32_e32 v8, v12, v8
	v_add_f32_e32 v12, 1.0, v19
	v_mul_f32_e32 v10, v10, v158
	v_rcp_f32_e32 v12, v12
	v_mul_f32_e32 v18, 0xbfb8aa3b, v10
	v_exp_f32_e32 v18, v18
	v_mul_f32_e32 v11, v11, v158
	v_mul_f32_e32 v12, v9, v12
	v_cndmask_b32_e64 v9, v12, v9, s[10:11]
	v_add_f32_e32 v12, 1.0, v18
	v_mul_f32_e32 v18, 0xbfb8aa3b, v11
	v_exp_f32_e32 v18, v18
	v_mul_f32_e32 v13, v13, v158
	v_rcp_f32_e32 v12, v12
	v_mul_f32_e32 v9, v13, v9
	v_mul_f32_e32 v13, v14, v158
	v_add_f32_e32 v14, 1.0, v18
	v_rcp_f32_e32 v14, v14
	v_mul_f32_e32 v12, v10, v12
	v_cndmask_b32_e64 v10, v12, v10, s[10:11]
	v_mul_f32_e32 v0, v0, v158
	v_mul_f32_e32 v10, v13, v10
	v_mul_f32_e32 v13, v11, v14
	v_mul_f32_e32 v14, 0xbfb8aa3b, v0
	v_exp_f32_e32 v14, v14
	v_mul_f32_e32 v12, v15, v158
	v_cndmask_b32_e64 v11, v13, v11, s[10:11]
	v_mul_f32_e32 v11, v12, v11
	v_add_f32_e32 v12, 1.0, v14
	v_rcp_f32_e32 v12, v12
	v_mul_f32_e32 v1, v1, v158
	v_mul_f32_e32 v13, 0xbfb8aa3b, v1
	v_exp_f32_e32 v13, v13
	v_mul_f32_e32 v12, v0, v12
	v_mul_f32_e32 v4, v4, v158
	v_cndmask_b32_e64 v0, v12, v0, s[10:11]
	v_mul_f32_e32 v12, v4, v0
	v_add_f32_e32 v0, 1.0, v13
	v_mul_f32_e32 v2, v2, v158
	v_rcp_f32_e32 v0, v0
	v_mul_f32_e32 v4, 0xbfb8aa3b, v2
	v_exp_f32_e32 v4, v4
	v_mul_f32_e32 v3, v3, v158
	v_mul_f32_e32 v0, v1, v0
	v_cndmask_b32_e64 v0, v0, v1, s[10:11]
	v_add_f32_e32 v1, 1.0, v4
	v_mul_f32_e32 v4, 0xbfb8aa3b, v3
	v_exp_f32_e32 v4, v4
	v_rcp_f32_e32 v1, v1
	v_mul_f32_e32 v5, v5, v158
	v_mul_f32_e32 v13, v5, v0
	v_add_f32_e32 v4, 1.0, v4
	v_rcp_f32_e32 v4, v4
	v_mul_f32_e32 v1, v2, v1
	v_mul_f32_e32 v0, v6, v158
	v_cndmask_b32_e64 v1, v1, v2, s[10:11]
	v_mul_f32_e32 v6, v0, v1
	v_mul_f32_e32 v1, v3, v4
	v_mul_f32_e32 v0, v7, v158
	v_cndmask_b32_e64 v1, v1, v3, s[10:11]
	v_mul_f32_e32 v3, v0, v1
	v_lshl_add_u64 v[4:5], v[16:17], 1, v[176:177]
	v_cvt_pk_bf16_f32 v0, v8, v9
	v_cvt_pk_bf16_f32 v1, v10, v11
	v_cvt_pk_bf16_f32 v2, v12, v13
	v_cvt_pk_bf16_f32 v3, v6, v3
	global_store_dwordx4 v[4:5], v[0:3], off
	s_andn2_b64 vcc, exec, s[8:9]
	s_mov_b64 s[8:9], -1
	s_cbranch_vccnz .LBB0_1444

;     __device__ __forceinline__ void operator()(const f32x4 (&acc)[2][2][4][2], const Unit& u, int wr, int wc, int fr, int fq, LAS unsigned char* xs, int wid, int lane) const {
;     ...
;         u32x4 raw[2][4][2];
;         if (!SRCF32) {
; #pragma unroll
;             for (int ai = 0; ai < 2; ++ai)
; #pragma unroll
;                 for (int m = 0; m < 4; ++m)
; #pragma unroll
;                     for (int bj = 0; bj < 2; ++bj) raw[ai][m][bj] = *(const u32x4*)(xb + (size_t)(row0 + ai * 128 + m * 16 + fr) * D + col0 + bj * 128);
;         }
; #pragma unroll
;         for (int ai = 0; ai < 2; ++ai) {
;             f32x4 xf[4][2][2];
;             if (SRCF32) {
; #pragma unroll
;                 for (int m = 0; m < 4; ++m)
; #pragma unroll
;                     for (int bj = 0; bj < 2; ++bj) { const size_t o = (size_t)(row0 + ai * 128 + m * 16 + fr) * D + col0 + bj * 128; xf[m][bj][0] = *(const f32x4*)(xo + o); xf[m][bj][1] = *(const f32x4*)(xo + o + 4); }
;             }
; #pragma unroll
;             for (int m = 0; m < 4; ++m) {
;                 const size_t row = (size_t)(row0 + ai * 128 + m * 16 + fr);
;                 float ss = 0.f;
; #pragma unroll
;                 for (int bj = 0; bj < 2; ++bj) {
;                     const size_t o = row * D + col0 + bj * 128;
;                     f32x4 x0, x1;
;                     if (SRCF32) { x0 = xf[m][bj][0]; x1 = xf[m][bj][1]; }
;                     else { const u32x4 r = raw[ai][m][bj]; x0 = (f32x4){bf_lo(r.x), bf_hi(r.x), bf_lo(r.y), bf_hi(r.y)}; x1 = (f32x4){bf_lo(r.z), bf_hi(r.z), bf_lo(r.w), bf_hi(r.w)}; }
;                     const f32x4 v0 = x0 + acc[ai][bj][m][0], v1 = x1 + acc[ai][bj][m][1];
;                     if (LAST) { *(f32x4*)(out + o) = v0; *(f32x4*)(out + o + 4) = v1; }
.LBB0_1628:
	v_lshl_or_b32 v128, s46, 8, v196
	v_lshl_add_u32 v130, s26, 8, v194
	v_ashrrev_i32_e32 v129, 31, v128
	v_ashrrev_i32_e32 v131, 31, v130
	v_lshl_add_u64 v[132:133], v[128:129], 1, s[16:17]
	v_lshlrev_b64 v[134:135], 12, v[130:131]
	v_or_b32_e32 v228, 16, v130
	v_lshl_add_u64 v[134:135], v[132:133], 0, v[134:135]
	v_ashrrev_i32_e32 v229, 31, v228
	global_load_dwordx4 v[200:203], v[134:135], off
	global_load_dwordx4 v[204:207], v[134:135], off offset:256
	v_lshlrev_b64 v[134:135], 12, v[228:229]
	v_lshl_add_u64 v[134:135], v[132:133], 0, v[134:135]
	global_load_dwordx4 v[208:211], v[134:135], off
	v_or_b32_e32 v192, 32, v130
	v_ashrrev_i32_e32 v193, 31, v192
	global_load_dwordx4 v[212:215], v[134:135], off offset:256
	v_lshlrev_b64 v[182:183], 2, v[128:129]
	v_lshlrev_b64 v[128:129], 12, v[192:193]
	v_lshl_add_u64 v[128:129], v[132:133], 0, v[128:129]
	global_load_dwordx4 v[216:219], v[128:129], off
	v_or_b32_e32 v190, 48, v130
	v_add_u32_e32 v188, 0x80, v130
	v_add_u32_e32 v186, 0x90, v130
	v_add_u32_e32 v184, 0xa0, v130
	v_add_u32_e32 v180, 0xb0, v130
	v_ashrrev_i32_e32 v191, 31, v190
	v_ashrrev_i32_e32 v189, 31, v188
	v_ashrrev_i32_e32 v187, 31, v186
	v_ashrrev_i32_e32 v185, 31, v184
	v_ashrrev_i32_e32 v181, 31, v180
	v_lshlrev_b64 v[130:131], 13, v[130:131]
	v_lshlrev_b64 v[134:135], 12, v[190:191]
	v_lshlrev_b64 v[136:137], 12, v[188:189]
	v_lshlrev_b64 v[138:139], 12, v[186:187]
	v_lshlrev_b64 v[140:141], 12, v[184:185]
	v_lshlrev_b64 v[142:143], 12, v[180:181]
	v_lshl_add_u64 v[130:131], s[4:5], 0, v[130:131]
	v_lshl_add_u64 v[134:135], v[132:133], 0, v[134:135]
	v_lshl_add_u64 v[136:137], v[132:133], 0, v[136:137]
	v_lshl_add_u64 v[138:139], v[132:133], 0, v[138:139]
	v_lshl_add_u64 v[230:231], v[132:133], 0, v[140:141]
	v_lshl_add_u64 v[232:233], v[132:133], 0, v[142:143]
	v_lshl_add_u64 v[234:235], v[130:131], 0, v[182:183]
	global_load_dwordx4 v[220:223], v[128:129], off offset:256
	global_load_dwordx4 v[224:227], v[134:135], off
	global_load_dwordx4 v[160:163], v[134:135], off offset:256
	global_load_dwordx4 v[156:159], v[136:137], off
	global_load_dwordx4 v[152:155], v[136:137], off offset:256
	global_load_dwordx4 v[148:151], v[138:139], off
	global_load_dwordx4 v[144:147], v[138:139], off offset:256
	global_load_dwordx4 v[140:143], v[230:231], off
	s_nop 0
	global_load_dwordx4 v[136:139], v[230:231], off offset:256
	global_load_dwordx4 v[132:135], v[232:233], off
	global_load_dwordx4 v[128:131], v[232:233], off offset:256
	s_andn2_b64 vcc, exec, s[0:1]
	s_mov_b64 s[0:1], -1
	s_waitcnt vmcnt(0)
	v_lshlrev_b32_e32 v230, 16, v200
	v_and_b32_e32 v231, 0xffff0000, v200
	v_lshlrev_b32_e32 v200, 16, v201
	v_and_b32_e32 v201, 0xffff0000, v201
	v_lshlrev_b32_e32 v238, 16, v206
	v_and_b32_e32 v239, 0xffff0000, v206
	v_lshlrev_b32_e32 v232, 16, v202
	v_and_b32_e32 v233, 0xffff0000, v202
	v_lshlrev_b32_e32 v202, 16, v203
	v_and_b32_e32 v203, 0xffff0000, v203
	v_lshlrev_b32_e32 v236, 16, v204
	v_and_b32_e32 v237, 0xffff0000, v204
	v_lshlrev_b32_e32 v204, 16, v205
	v_and_b32_e32 v205, 0xffff0000, v205
	v_lshlrev_b32_e32 v206, 16, v207
	v_and_b32_e32 v207, 0xffff0000, v207
	v_pk_add_f32 v[126:127], v[126:127], v[200:201]
	v_pk_add_f32 v[124:125], v[124:125], v[230:231]
	v_pk_add_f32 v[112:113], v[112:113], v[238:239]
	v_pk_add_f32 v[122:123], v[122:123], v[202:203]
	v_pk_add_f32 v[120:121], v[120:121], v[232:233]
	v_pk_add_f32 v[118:119], v[118:119], v[204:205]
	v_pk_add_f32 v[116:117], v[116:117], v[236:237]
	v_pk_add_f32 v[114:115], v[114:115], v[206:207]
	global_store_dwordx4 v[234:235], v[124:127], off
	global_store_dwordx4 v[234:235], v[120:123], off offset:16
	global_store_dwordx4 v[234:235], v[116:119], off offset:512
	global_store_dwordx4 v[234:235], v[112:115], off offset:528
	v_lshlrev_b32_e32 v200, 16, v208
	v_and_b32_e32 v201, 0xffff0000, v208
	v_lshlrev_b32_e32 v112, 16, v210
	v_and_b32_e32 v113, 0xffff0000, v210
	v_pk_add_f32 v[104:105], v[104:105], v[112:113]
	v_lshlrev_b64 v[112:113], 13, v[228:229]
	v_lshlrev_b32_e32 v202, 16, v209
	v_and_b32_e32 v203, 0xffff0000, v209
	v_lshlrev_b32_e32 v114, 16, v211
	v_and_b32_e32 v115, 0xffff0000, v211
	v_lshl_add_u64 v[112:113], s[4:5], 0, v[112:113]
	v_pk_add_f32 v[110:111], v[110:111], v[202:203]
	v_pk_add_f32 v[108:109], v[108:109], v[200:201]
	v_pk_add_f32 v[106:107], v[106:107], v[114:115]
	v_lshl_add_u64 v[112:113], v[112:113], 0, v[182:183]
	global_store_dwordx4 v[112:113], v[108:111], off
	global_store_dwordx4 v[112:113], v[104:107], off offset:16
	s_nop 0
	v_lshlrev_b32_e32 v108, 16, v214
	v_lshlrev_b32_e32 v104, 16, v212
	v_and_b32_e32 v105, 0xffff0000, v212
	v_lshlrev_b32_e32 v106, 16, v213
	v_and_b32_e32 v107, 0xffff0000, v213
	v_and_b32_e32 v109, 0xffff0000, v214
	v_lshlrev_b32_e32 v110, 16, v215
	v_and_b32_e32 v111, 0xffff0000, v215
	v_pk_add_f32 v[102:103], v[102:103], v[106:107]
	v_pk_add_f32 v[100:101], v[100:101], v[104:105]
	v_pk_add_f32 v[92:93], v[92:93], v[108:109]
	v_pk_add_f32 v[94:95], v[94:95], v[110:111]
	global_store_dwordx4 v[112:113], v[100:103], off offset:512
	global_store_dwordx4 v[112:113], v[92:95], off offset:528
	s_nop 0
	v_lshlrev_b32_e32 v100, 16, v218
	v_lshlrev_b32_e32 v92, 16, v216
	v_and_b32_e32 v93, 0xffff0000, v216
	v_pk_add_f32 v[92:93], v[96:97], v[92:93]
	v_lshlrev_b64 v[96:97], 13, v[192:193]
	v_lshlrev_b32_e32 v94, 16, v217
	v_and_b32_e32 v95, 0xffff0000, v217
	v_and_b32_e32 v101, 0xffff0000, v218
	v_lshlrev_b32_e32 v102, 16, v219
	v_and_b32_e32 v103, 0xffff0000, v219
	v_lshl_add_u64 v[96:97], s[4:5], 0, v[96:97]
	v_pk_add_f32 v[94:95], v[98:99], v[94:95]
	v_pk_add_f32 v[90:91], v[90:91], v[102:103]
;     __device__ __forceinline__ void operator()(const f32x4 (&acc)[2][2][4][2], const Unit& u, int wr, int wc, int fr, int fq, LAS unsigned char* xs, int wid, int lane) const {
;     ...
; #pragma unroll
;             for (int m = 0; m < 4; ++m) {
;                 const size_t row = (size_t)(row0 + ai * 128 + m * 16 + fr);
;                 float ss = 0.f;
; #pragma unroll
;                 for (int bj = 0; bj < 2; ++bj) {
;                     const size_t o = row * D + col0 + bj * 128;
;                     f32x4 x0, x1;
;                     if (SRCF32) { x0 = xf[m][bj][0]; x1 = xf[m][bj][1]; }
;                     else { const u32x4 r = raw[ai][m][bj]; x0 = (f32x4){bf_lo(r.x), bf_hi(r.x), bf_lo(r.y), bf_hi(r.y)}; x1 = (f32x4){bf_lo(r.z), bf_hi(r.z), bf_lo(r.w), bf_hi(r.w)}; }
;                     const f32x4 v0 = x0 + acc[ai][bj][m][0], v1 = x1 + acc[ai][bj][m][1];
;                     if (LAST) { *(f32x4*)(out + o) = v0; *(f32x4*)(out + o + 4) = v1; }
	v_pk_add_f32 v[88:89], v[88:89], v[100:101]
	v_lshl_add_u64 v[96:97], v[96:97], 0, v[182:183]
	global_store_dwordx4 v[96:97], v[92:95], off
	global_store_dwordx4 v[96:97], v[88:91], off offset:16
	s_nop 0
	v_lshlrev_b32_e32 v92, 16, v222
	v_lshlrev_b32_e32 v88, 16, v220
	v_and_b32_e32 v89, 0xffff0000, v220
	v_lshlrev_b32_e32 v90, 16, v221
	v_and_b32_e32 v91, 0xffff0000, v221
	v_and_b32_e32 v93, 0xffff0000, v222
	v_lshlrev_b32_e32 v94, 16, v223
	v_and_b32_e32 v95, 0xffff0000, v223
	v_pk_add_f32 v[86:87], v[86:87], v[90:91]
	v_pk_add_f32 v[84:85], v[84:85], v[88:89]
	v_pk_add_f32 v[76:77], v[76:77], v[92:93]
	v_pk_add_f32 v[78:79], v[78:79], v[94:95]
	global_store_dwordx4 v[96:97], v[84:87], off offset:512
	global_store_dwordx4 v[96:97], v[76:79], off offset:528
	s_nop 0
	v_lshlrev_b32_e32 v84, 16, v226
	v_lshlrev_b32_e32 v76, 16, v224
	v_and_b32_e32 v77, 0xffff0000, v224
	v_pk_add_f32 v[76:77], v[80:81], v[76:77]
	v_lshlrev_b64 v[80:81], 13, v[190:191]
	v_lshlrev_b32_e32 v78, 16, v225
	v_and_b32_e32 v79, 0xffff0000, v225
	v_and_b32_e32 v85, 0xffff0000, v226
	v_lshlrev_b32_e32 v86, 16, v227
	v_and_b32_e32 v87, 0xffff0000, v227
	v_lshl_add_u64 v[80:81], s[4:5], 0, v[80:81]
	v_pk_add_f32 v[78:79], v[82:83], v[78:79]
	v_pk_add_f32 v[74:75], v[74:75], v[86:87]
	v_pk_add_f32 v[72:73], v[72:73], v[84:85]
	v_lshl_add_u64 v[80:81], v[80:81], 0, v[182:183]
	global_store_dwordx4 v[80:81], v[76:79], off
	global_store_dwordx4 v[80:81], v[72:75], off offset:16
	s_nop 0
	v_lshlrev_b32_e32 v76, 16, v162
	v_lshlrev_b32_e32 v72, 16, v160
	v_and_b32_e32 v73, 0xffff0000, v160
	v_lshlrev_b32_e32 v74, 16, v161
	v_and_b32_e32 v75, 0xffff0000, v161
	v_and_b32_e32 v77, 0xffff0000, v162
	v_lshlrev_b32_e32 v78, 16, v163
	v_and_b32_e32 v79, 0xffff0000, v163
	v_pk_add_f32 v[70:71], v[70:71], v[74:75]
	v_pk_add_f32 v[68:69], v[68:69], v[72:73]
	v_pk_add_f32 v[64:65], v[64:65], v[76:77]
	v_pk_add_f32 v[66:67], v[66:67], v[78:79]
	global_store_dwordx4 v[80:81], v[68:71], off offset:512
	global_store_dwordx4 v[80:81], v[64:67], off offset:528
	s_nop 0
	v_lshlrev_b32_e32 v68, 16, v158
	v_lshlrev_b32_e32 v64, 16, v156
	v_and_b32_e32 v65, 0xffff0000, v156
	v_pk_add_f32 v[60:61], v[60:61], v[64:65]
	v_lshlrev_b64 v[64:65], 13, v[188:189]
	v_lshlrev_b32_e32 v66, 16, v157
	v_and_b32_e32 v67, 0xffff0000, v157
	v_and_b32_e32 v69, 0xffff0000, v158
	v_lshlrev_b32_e32 v70, 16, v159
	v_and_b32_e32 v71, 0xffff0000, v159
	v_lshl_add_u64 v[64:65], s[4:5], 0, v[64:65]
	v_pk_add_f32 v[62:63], v[62:63], v[66:67]
	v_pk_add_f32 v[58:59], v[58:59], v[70:71]
	v_pk_add_f32 v[56:57], v[56:57], v[68:69]
	v_lshl_add_u64 v[64:65], v[64:65], 0, v[182:183]
	global_store_dwordx4 v[64:65], v[60:63], off
	global_store_dwordx4 v[64:65], v[56:59], off offset:16
	s_nop 0
	v_lshlrev_b32_e32 v60, 16, v154
	v_lshlrev_b32_e32 v56, 16, v152
	v_and_b32_e32 v57, 0xffff0000, v152
	v_lshlrev_b32_e32 v58, 16, v153
	v_and_b32_e32 v59, 0xffff0000, v153
	v_and_b32_e32 v61, 0xffff0000, v154
	v_lshlrev_b32_e32 v62, 16, v155
	v_and_b32_e32 v63, 0xffff0000, v155
	v_pk_add_f32 v[54:55], v[54:55], v[58:59]
	v_pk_add_f32 v[52:53], v[52:53], v[56:57]
	v_pk_add_f32 v[44:45], v[44:45], v[60:61]
	v_pk_add_f32 v[46:47], v[46:47], v[62:63]
	global_store_dwordx4 v[64:65], v[52:55], off offset:512
	global_store_dwordx4 v[64:65], v[44:47], off offset:528
	s_nop 0
	v_lshlrev_b32_e32 v52, 16, v150
	v_lshlrev_b32_e32 v44, 16, v148
	v_and_b32_e32 v45, 0xffff0000, v148
	v_pk_add_f32 v[44:45], v[48:49], v[44:45]
	v_lshlrev_b64 v[48:49], 13, v[186:187]
	v_lshlrev_b32_e32 v46, 16, v149
	v_and_b32_e32 v47, 0xffff0000, v149
	v_and_b32_e32 v53, 0xffff0000, v150
; #define PG8_BAR __builtin_amdgcn_s_barrier()
; template <class Epi, class Sched>
; __device__ __forceinline__ void gemm_phase(LAS unsigned char* lds, const int K, const int lda, const int ldb, const Sched& S, const Epi& E) {
;     ...
;         if (!has_next) break;
; #pragma unroll
;         for (int a = 0; a < 2; ++a)
; #pragma unroll
;             for (int b = 0; b < 2; ++b)
; #pragma unroll
;                 for (int m = 0; m < 4; ++m)
; #pragma unroll
;                     for (int n = 0; n < 2; ++n) acc[a][b][m][n] = (f32x4){0.f, 0.f, 0.f, 0.f};
;         cur = nxt; cA = nA; cB = nB; ++ui;
;         if (wr == 1) PG8_BAR;
;     }
;     __device__ __forceinline__ void operator()(const f32x4 (&acc)[2][2][4][2], const Unit& u, int wr, int wc, int fr, int fq, LAS unsigned char* xs, int wid, int lane) const {
;     ...
; #pragma unroll
;             for (int m = 0; m < 4; ++m) {
;                 const size_t row = (size_t)(row0 + ai * 128 + m * 16 + fr);
;                 float ss = 0.f;
; #pragma unroll
;                 for (int bj = 0; bj < 2; ++bj) {
;                     const size_t o = row * D + col0 + bj * 128;
;                     f32x4 x0, x1;
;                     if (SRCF32) { x0 = xf[m][bj][0]; x1 = xf[m][bj][1]; }
;                     else { const u32x4 r = raw[ai][m][bj]; x0 = (f32x4){bf_lo(r.x), bf_hi(r.x), bf_lo(r.y), bf_hi(r.y)}; x1 = (f32x4){bf_lo(r.z), bf_hi(r.z), bf_lo(r.w), bf_hi(r.w)}; }
;                     const f32x4 v0 = x0 + acc[ai][bj][m][0], v1 = x1 + acc[ai][bj][m][1];
;                     if (LAST) { *(f32x4*)(out + o) = v0; *(f32x4*)(out + o + 4) = v1; }
	v_lshlrev_b32_e32 v54, 16, v151
	v_and_b32_e32 v55, 0xffff0000, v151
	v_lshl_add_u64 v[48:49], s[4:5], 0, v[48:49]
	v_pk_add_f32 v[46:47], v[50:51], v[46:47]
	v_pk_add_f32 v[42:43], v[42:43], v[54:55]
	v_pk_add_f32 v[40:41], v[40:41], v[52:53]
	v_lshl_add_u64 v[48:49], v[48:49], 0, v[182:183]
	global_store_dwordx4 v[48:49], v[44:47], off
	global_store_dwordx4 v[48:49], v[40:43], off offset:16
	s_nop 0
	v_lshlrev_b32_e32 v44, 16, v146
	v_lshlrev_b32_e32 v40, 16, v144
	v_and_b32_e32 v41, 0xffff0000, v144
	v_lshlrev_b32_e32 v42, 16, v145
	v_and_b32_e32 v43, 0xffff0000, v145
	v_and_b32_e32 v45, 0xffff0000, v146
	v_lshlrev_b32_e32 v46, 16, v147
	v_and_b32_e32 v47, 0xffff0000, v147
	v_pk_add_f32 v[38:39], v[38:39], v[42:43]
	v_pk_add_f32 v[36:37], v[36:37], v[40:41]
	v_pk_add_f32 v[28:29], v[28:29], v[44:45]
	v_pk_add_f32 v[30:31], v[30:31], v[46:47]
	global_store_dwordx4 v[48:49], v[36:39], off offset:512
	global_store_dwordx4 v[48:49], v[28:31], off offset:528
	s_nop 0
	v_lshlrev_b32_e32 v36, 16, v142
	v_lshlrev_b32_e32 v28, 16, v140
	v_and_b32_e32 v29, 0xffff0000, v140
	v_pk_add_f32 v[28:29], v[32:33], v[28:29]
	v_lshlrev_b64 v[32:33], 13, v[184:185]
	v_lshlrev_b32_e32 v30, 16, v141
	v_and_b32_e32 v31, 0xffff0000, v141
	v_and_b32_e32 v37, 0xffff0000, v142
	v_lshlrev_b32_e32 v38, 16, v143
	v_and_b32_e32 v39, 0xffff0000, v143
	v_lshl_add_u64 v[32:33], s[4:5], 0, v[32:33]
	v_pk_add_f32 v[30:31], v[34:35], v[30:31]
	v_pk_add_f32 v[26:27], v[26:27], v[38:39]
	v_pk_add_f32 v[24:25], v[24:25], v[36:37]
	v_lshl_add_u64 v[32:33], v[32:33], 0, v[182:183]
	global_store_dwordx4 v[32:33], v[28:31], off
	global_store_dwordx4 v[32:33], v[24:27], off offset:16
	s_nop 0
	v_lshlrev_b32_e32 v28, 16, v138
	v_lshlrev_b32_e32 v24, 16, v136
	v_and_b32_e32 v25, 0xffff0000, v136
	v_lshlrev_b32_e32 v26, 16, v137
	v_and_b32_e32 v27, 0xffff0000, v137
	v_and_b32_e32 v29, 0xffff0000, v138
	v_lshlrev_b32_e32 v30, 16, v139
	v_and_b32_e32 v31, 0xffff0000, v139
	v_pk_add_f32 v[22:23], v[22:23], v[26:27]
	v_pk_add_f32 v[20:21], v[20:21], v[24:25]
	v_pk_add_f32 v[12:13], v[12:13], v[28:29]
	v_pk_add_f32 v[14:15], v[14:15], v[30:31]
	global_store_dwordx4 v[32:33], v[20:23], off offset:512
	global_store_dwordx4 v[32:33], v[12:15], off offset:528
	s_nop 0
	v_lshlrev_b32_e32 v20, 16, v134
	v_lshlrev_b32_e32 v12, 16, v132
	v_and_b32_e32 v13, 0xffff0000, v132
	v_pk_add_f32 v[12:13], v[16:17], v[12:13]
	v_lshlrev_b64 v[16:17], 13, v[180:181]
	v_lshlrev_b32_e32 v14, 16, v133
	v_and_b32_e32 v15, 0xffff0000, v133
	v_and_b32_e32 v21, 0xffff0000, v134
	v_lshlrev_b32_e32 v22, 16, v135
	v_and_b32_e32 v23, 0xffff0000, v135
	v_lshl_add_u64 v[16:17], s[4:5], 0, v[16:17]
	v_pk_add_f32 v[14:15], v[18:19], v[14:15]
	v_pk_add_f32 v[10:11], v[10:11], v[22:23]
	v_pk_add_f32 v[8:9], v[8:9], v[20:21]
	v_lshl_add_u64 v[16:17], v[16:17], 0, v[182:183]
	global_store_dwordx4 v[16:17], v[12:15], off
	global_store_dwordx4 v[16:17], v[8:11], off offset:16
	s_nop 0
	v_lshlrev_b32_e32 v12, 16, v130
	v_lshlrev_b32_e32 v8, 16, v128
	v_and_b32_e32 v9, 0xffff0000, v128
	v_lshlrev_b32_e32 v10, 16, v129
	v_and_b32_e32 v11, 0xffff0000, v129
	v_and_b32_e32 v13, 0xffff0000, v130
	v_lshlrev_b32_e32 v14, 16, v131
	v_and_b32_e32 v15, 0xffff0000, v131
	v_pk_add_f32 v[6:7], v[6:7], v[10:11]
	v_pk_add_f32 v[4:5], v[4:5], v[8:9]
	v_pk_add_f32 v[2:3], v[2:3], v[14:15]
	v_pk_add_f32 v[0:1], v[0:1], v[12:13]
	global_store_dwordx4 v[16:17], v[4:7], off offset:512
	global_store_dwordx4 v[16:17], v[0:3], off offset:528
	s_cbranch_vccnz .LBB0_1617
	s_andn2_b64 vcc, exec, s[6:7]
	s_cbranch_vccnz .LBB0_1616
	s_barrier
	s_branch .LBB0_1616

; #define LAS __attribute__((address_space(3)))
; __device__ __forceinline__ unsigned xb_add(unsigned* p, unsigned v) { return __hip_atomic_fetch_add(p, v, __ATOMIC_RELAXED, __HIP_MEMORY_SCOPE_AGENT); }
; __device__ __forceinline__ unsigned xb_xcc_id() { return (unsigned)__builtin_amdgcn_s_getreg((3 << 11) | 20) & 0xFu; }
; __global__ void __launch_bounds__(512, 2) hybrid_fwd(Params p) {
;     extern __shared__ __attribute__((aligned(16))) unsigned char lds_raw[];
;     LAS unsigned char* lds = (LAS unsigned char*)lds_raw;
;     cg::grid_group grid = cg::this_grid();
;     unsigned char* ws = p.ws;
;     XcdBarrier xb; xb.bar = (unsigned*)(ws + OFF_BAR); xb.x = xb_xcc_id();
;     if (threadIdx.x == 0) (void)xb_add(&xb.bar[XB_XCNT(xb.x)], 1u);
;     const int G = gridDim.x, NGW = G * 8, NT = G * 512;
;     bf16_t* XB = (bf16_t*)(ws + OFF_XB); float* RSS = (float*)(ws + OFF_RSS);
;     bf16_t* WIN = (bf16_t*)(ws + OFF_WIN); bf16_t* WOUT = (bf16_t*)(ws + OFF_WOUT);
	.amdhsa_kernel _Z10hybrid_fwd6Params
		.amdhsa_group_segment_fixed_size 0
		.amdhsa_private_segment_fixed_size 0
		.amdhsa_kernarg_size 408
		.amdhsa_user_sgpr_count 2
		.amdhsa_user_sgpr_dispatch_ptr 0
		.amdhsa_user_sgpr_queue_ptr 0
		.amdhsa_user_sgpr_kernarg_segment_ptr 1
		.amdhsa_user_sgpr_dispatch_id 0
		.amdhsa_user_sgpr_kernarg_preload_length 0
		.amdhsa_user_sgpr_kernarg_preload_offset 0
		.amdhsa_user_sgpr_private_segment_size 0
		.amdhsa_uses_dynamic_stack 0
		.amdhsa_enable_private_segment 0
		.amdhsa_system_sgpr_workgroup_id_x 1
		.amdhsa_system_sgpr_workgroup_id_y 0
		.amdhsa_system_sgpr_workgroup_id_z 0
		.amdhsa_system_sgpr_workgroup_info 0
		.amdhsa_system_vgpr_workitem_id 2
		.amdhsa_next_free_vgpr 256
		.amdhsa_next_free_sgpr 100
		.amdhsa_accum_offset 256
		.amdhsa_reserve_vcc 1
		.amdhsa_float_round_mode_32 0
		.amdhsa_float_round_mode_16_64 0
		.amdhsa_float_denorm_mode_32 3
		.amdhsa_float_denorm_mode_16_64 3
		.amdhsa_dx10_clamp 1
		.amdhsa_ieee_mode 1
		.amdhsa_fp16_overflow 0
		.amdhsa_tg_split 0
		.amdhsa_exception_fp_ieee_invalid_op 0
		.amdhsa_exception_fp_denorm_src 0
		.amdhsa_exception_fp_ieee_div_zero 0
		.amdhsa_exception_fp_ieee_overflow 0
		.amdhsa_exception_fp_ieee_underflow 0
		.amdhsa_exception_fp_ieee_inexact 0
		.amdhsa_exception_int_div_zero 0
	.end_amdhsa_kernel

; #define LAS __attribute__((address_space(3)))
; __device__ __forceinline__ unsigned xb_add(unsigned* p, unsigned v) { return __hip_atomic_fetch_add(p, v, __ATOMIC_RELAXED, __HIP_MEMORY_SCOPE_AGENT); }
; __device__ __forceinline__ unsigned xb_xcc_id() { return (unsigned)__builtin_amdgcn_s_getreg((3 << 11) | 20) & 0xFu; }
; __global__ void __launch_bounds__(512, 2) hybrid_fwd(Params p) {
;     extern __shared__ __attribute__((aligned(16))) unsigned char lds_raw[];
;     LAS unsigned char* lds = (LAS unsigned char*)lds_raw;
;     cg::grid_group grid = cg::this_grid();
;     unsigned char* ws = p.ws;
;     XcdBarrier xb; xb.bar = (unsigned*)(ws + OFF_BAR); xb.x = xb_xcc_id();
;     if (threadIdx.x == 0) (void)xb_add(&xb.bar[XB_XCNT(xb.x)], 1u);
;     const int G = gridDim.x, NGW = G * 8, NT = G * 512;
;     bf16_t* XB = (bf16_t*)(ws + OFF_XB); float* RSS = (float*)(ws + OFF_RSS);
;     bf16_t* WIN = (bf16_t*)(ws + OFF_WIN); bf16_t* WOUT = (bf16_t*)(ws + OFF_WOUT);
amdhsa.kernels:
  - .agpr_count:     0
    .args:
      - .offset:         0
        .size:           152
        .value_kind:     by_value
      - .offset:         152
        .size:           4
        .value_kind:     hidden_block_count_x
      - .offset:         156
        .size:           4
        .value_kind:     hidden_block_count_y
      - .offset:         160
        .size:           4
        .value_kind:     hidden_block_count_z
      - .offset:         164
        .size:           2
        .value_kind:     hidden_group_size_x
      - .offset:         166
        .size:           2
        .value_kind:     hidden_group_size_y
      - .offset:         168
        .size:           2
        .value_kind:     hidden_group_size_z
      - .offset:         170
        .size:           2
        .value_kind:     hidden_remainder_x
      - .offset:         172
        .size:           2
        .value_kind:     hidden_remainder_y
      - .offset:         174
        .size:           2
        .value_kind:     hidden_remainder_z
      - .offset:         192
        .size:           8
        .value_kind:     hidden_global_offset_x
      - .offset:         200
        .size:           8
        .value_kind:     hidden_global_offset_y
      - .offset:         208
        .size:           8
        .value_kind:     hidden_global_offset_z
      - .offset:         216
        .size:           2
        .value_kind:     hidden_grid_dims
      - .offset:         240
        .size:           8
        .value_kind:     hidden_multigrid_sync_arg
      - .offset:         272
        .size:           4
        .value_kind:     hidden_dynamic_lds_size
    .group_segment_fixed_size: 0
    .kernarg_segment_align: 8
    .kernarg_segment_size: 408
    .language:       OpenCL C
    .language_version:
      - 2
      - 0
    .max_flat_workgroup_size: 512
    .name:           _Z10hybrid_fwd6Params
    .private_segment_fixed_size: 0
    .sgpr_count:     106
    .sgpr_spill_count: 35
    .symbol:         _Z10hybrid_fwd6Params.kd
    .uniform_work_group_size: 1
    .uses_dynamic_stack: false
    .vgpr_count:     256
    .vgpr_spill_count: 0
    .wavefront_size: 64
